# stack1b re-measure: QK de-serialization+permlane, XCD barrier for cg sync, hw-log log1p, K-loop setprio/wait trims
# speedup vs baseline: 1.0076x; 1.0076x over previous
; #define PG8_STAGE(bufoff, gbase, voff) do { _Pragma("unroll") for (int _i = 0; _i < 2; ++_i) \
;         __builtin_amdgcn_global_load_lds((const unsigned*)((const char*)(gbase) + (voff)[_i]), (PG8_LAS unsigned*)(lds + (bufoff) + ldsw + _i * 8192), 16, 0, 0); } while (0)
; #define PG8_LDA(dst, b, h) do { _Pragma("unroll") for (int m = 0; m < 4; ++m) _Pragma("unroll") for (int k = 0; k < 2; ++k) dst[m][k] = *(const PG8_LAS bf16x8*)(lds + PG8_SA(b, h) + aoff + m * 2048 + k * 1024); } while (0)
; #define PG8_LDB(dst, b, h) do { _Pragma("unroll") for (int n = 0; n < 2; ++n) _Pragma("unroll") for (int k = 0; k < 2; ++k) dst[n][k] = *(const PG8_LAS bf16x8*)(lds + PG8_SB(b, h) + boff + n * 2048 + k * 1024); } while (0)
; #define PG8_MMA(ai, bj, At, Bt) do { __builtin_amdgcn_s_setprio(1); _Pragma("unroll") for (int m = 0; m < 4; ++m) _Pragma("unroll") for (int n = 0; n < 2; ++n) _Pragma("unroll") for (int k = 0; k < 2; ++k) \
;         acc[ai][bj][m][n] = __builtin_amdgcn_mfma_f32_16x16x32_bf16(Bt[n][k], At[m][k], acc[ai][bj][m][n], 0, 0, 0); __builtin_amdgcn_s_setprio(0); } while (0)
; #define PG8_WAIT_V(n) asm volatile("s_waitcnt vmcnt(" #n ")" ::: "memory")
; #define PG8_WAIT_L(n) asm volatile("s_waitcnt lgkmcnt(" #n ")" ::: "memory")
; #define PG8_BAR __builtin_amdgcn_s_barrier()
; #define PG8_SCHED __builtin_amdgcn_sched_barrier(0)
; template <class Epi, class Sched, bool ALIGN_EPI = false, bool SP2 = false>
; __device__ __forceinline__ void gemm_phase(PG8_LAS unsigned char* lds, const Gemm g, const Sched& S, const Epi& E) {
;     ...
;         for (int t = 0; t < nt; t += 2) {
;             const bool last = (t == nt - 2);
;             const char* a1 = cA + (size_t)(t + 1) * kstep;
;             const char* a2 = last ? nA : cA + (size_t)(t + 2) * kstep; const char* b2 = last ? nB : cB + (size_t)(t + 2) * kstep;
;             const char* a3 = a2 + kstep; const char* b3 = b2 + kstep;
;             if (last && has_next) S.a_ready(nxt);
;             if constexpr (SP2) {
;             PG8_LDB(B0, 0, 0); PG8_LDB(B1, 0, 1); PG8_SCHED; PG8_LDA(At, 0, 0); PG8_STAGE(PG8_SA(1, 1), a1 + hstep, voffA);
;             PG8_WAIT_V(8); PG8_WAIT_L(0); PG8_BAR; PG8_MMA(0, 0, At, B0); PG8_MMA(0, 1, At, B1); PG8_BAR; PG8_SCHED;
;             PG8_LDA(At, 0, 1); PG8_STAGE(PG8_SB(0, 0), b2, voffB); PG8_STAGE(PG8_SB(0, 1), b2 + hstep, voffB); PG8_STAGE(PG8_SA(0, 0), a2, voffA);
.LBB0_304:
	v_add_u32_e32 v166, s54, v169
	v_add_u32_e32 v168, s55, v169
	ds_read_b128 v[162:165], v166
	ds_read_b128 v[182:185], v166 offset:1024
	ds_read_b128 v[186:189], v166 offset:2048
	ds_read_b128 v[190:193], v166 offset:3072
	ds_read_b128 v[194:197], v168
	ds_read_b128 v[198:201], v168 offset:1024
	ds_read_b128 v[202:205], v168 offset:2048
	ds_read_b128 v[206:209], v168 offset:3072
	s_cmp_eq_u32 s53, s10
	v_lshl_add_u64 v[172:173], v[160:161], 0, s[22:23]
	s_cselect_b64 vcc, -1, 0
	s_add_i32 s10, s10, 2
	v_cndmask_b32_e32 v173, v173, v153, vcc
	v_cndmask_b32_e32 v172, v172, v152, vcc
	v_cndmask_b32_e32 v245, v159, v155, vcc
	v_cndmask_b32_e32 v244, v158, v154, vcc
	s_mov_b32 m0, s56
	v_lshl_add_u64 v[246:247], v[160:161], 0, v[148:149]
	ds_read_b128 v[210:213], v179
	ds_read_b128 v[216:219], v179 offset:1024
	ds_read_b128 v[220:223], v179 offset:2048
	ds_read_b128 v[224:227], v179 offset:3072
	ds_read_b128 v[228:231], v179 offset:4096
	ds_read_b128 v[232:235], v179 offset:5120
	ds_read_b128 v[236:239], v179 offset:6144
	ds_read_b128 v[240:243], v179 offset:7168
	global_load_lds_dwordx4 v[246:247], off
	v_lshl_add_u64 v[246:247], v[160:161], 0, v[146:147]
	s_mov_b32 m0, s57
	s_nop 0
	global_load_lds_dwordx4 v[246:247], off
	s_waitcnt vmcnt(8)
	s_waitcnt lgkmcnt(0)
	s_setprio 1
	s_barrier
	v_mfma_f32_16x16x32_bf16 v[124:127], v[162:165], v[210:213], v[124:127]
	v_mfma_f32_16x16x32_bf16 v[116:119], v[186:189], v[210:213], v[116:119]
	v_mfma_f32_16x16x32_bf16 v[108:111], v[162:165], v[220:223], v[108:111]
	v_mfma_f32_16x16x32_bf16 v[100:103], v[186:189], v[220:223], v[100:103]
	v_mfma_f32_16x16x32_bf16 v[92:95], v[162:165], v[228:231], v[92:95]
	v_mfma_f32_16x16x32_bf16 v[84:87], v[186:189], v[228:231], v[84:87]
	v_mfma_f32_16x16x32_bf16 v[76:79], v[162:165], v[236:239], v[76:79]
	v_mfma_f32_16x16x32_bf16 v[68:71], v[186:189], v[236:239], v[68:71]
	v_mfma_f32_16x16x32_bf16 v[124:127], v[182:185], v[216:219], v[124:127]
	v_mfma_f32_16x16x32_bf16 v[116:119], v[190:193], v[216:219], v[116:119]
	v_mfma_f32_16x16x32_bf16 v[108:111], v[182:185], v[224:227], v[108:111]
	v_mfma_f32_16x16x32_bf16 v[100:103], v[190:193], v[224:227], v[100:103]
	v_mfma_f32_16x16x32_bf16 v[92:95], v[182:185], v[232:235], v[92:95]
	v_mfma_f32_16x16x32_bf16 v[84:87], v[190:193], v[232:235], v[84:87]
	v_mfma_f32_16x16x32_bf16 v[76:79], v[182:185], v[240:243], v[76:79]
	v_mfma_f32_16x16x32_bf16 v[68:71], v[190:193], v[240:243], v[68:71]
	v_mfma_f32_16x16x32_bf16 v[120:123], v[194:197], v[210:213], v[120:123]
	v_mfma_f32_16x16x32_bf16 v[112:115], v[202:205], v[210:213], v[112:115]
	v_mfma_f32_16x16x32_bf16 v[104:107], v[194:197], v[220:223], v[104:107]
	v_mfma_f32_16x16x32_bf16 v[96:99], v[202:205], v[220:223], v[96:99]
	v_mfma_f32_16x16x32_bf16 v[88:91], v[194:197], v[228:231], v[88:91]
	v_mfma_f32_16x16x32_bf16 v[80:83], v[202:205], v[228:231], v[80:83]
	v_mfma_f32_16x16x32_bf16 v[72:75], v[194:197], v[236:239], v[72:75]
	v_mfma_f32_16x16x32_bf16 v[64:67], v[202:205], v[236:239], v[64:67]
	v_mfma_f32_16x16x32_bf16 v[120:123], v[198:201], v[216:219], v[120:123]
	v_mfma_f32_16x16x32_bf16 v[112:115], v[206:209], v[216:219], v[112:115]
	v_mfma_f32_16x16x32_bf16 v[104:107], v[198:201], v[224:227], v[104:107]
	v_mfma_f32_16x16x32_bf16 v[96:99], v[206:209], v[224:227], v[96:99]
	v_mfma_f32_16x16x32_bf16 v[88:91], v[198:201], v[232:235], v[88:91]
	v_mfma_f32_16x16x32_bf16 v[80:83], v[206:209], v[232:235], v[80:83]
	v_mfma_f32_16x16x32_bf16 v[72:75], v[198:201], v[240:243], v[72:75]
	v_mfma_f32_16x16x32_bf16 v[64:67], v[206:209], v[240:243], v[64:67]
	s_setprio 0
	s_barrier
	s_mov_b32 m0, s60
	v_lshl_add_u64 v[246:247], v[244:245], 0, v[138:139]
	ds_read_b128 v[210:213], v179 offset:16384
	ds_read_b128 v[216:219], v179 offset:17408
	ds_read_b128 v[220:223], v179 offset:18432
	ds_read_b128 v[224:227], v179 offset:19456
	ds_read_b128 v[228:231], v179 offset:20480
	ds_read_b128 v[232:235], v179 offset:21504
	ds_read_b128 v[236:239], v179 offset:22528
	ds_read_b128 v[240:243], v179 offset:23552
	global_load_lds_dwordx4 v[246:247], off
	v_lshl_add_u64 v[248:249], v[244:245], 0, v[134:135]
	s_mov_b32 m0, s61
	v_lshl_add_u64 v[244:245], v[244:245], 0, s[14:15]
	global_load_lds_dwordx4 v[248:249], off
	v_lshl_add_u64 v[250:251], v[244:245], 0, v[138:139]
	s_mov_b32 m0, s62
	v_lshl_add_u64 v[244:245], v[244:245], 0, v[134:135]
	global_load_lds_dwordx4 v[250:251], off
	s_add_i32 m0, s62, 0x2000
	v_lshl_add_u64 v[252:253], v[172:173], 0, v[140:141]
	global_load_lds_dwordx4 v[244:245], off
	s_mov_b32 m0, s46
	v_lshl_add_u64 v[214:215], v[172:173], 0, v[136:137]
	global_load_lds_dwordx4 v[252:253], off
	s_mov_b32 m0, s47
	s_nop 0
	global_load_lds_dwordx4 v[214:215], off
	s_waitcnt vmcnt(8)
	s_waitcnt lgkmcnt(0)
	s_setprio 1
	s_barrier
; #define PG8_STAGE(bufoff, gbase, voff) do { _Pragma("unroll") for (int _i = 0; _i < 2; ++_i) \
;         __builtin_amdgcn_global_load_lds((const unsigned*)((const char*)(gbase) + (voff)[_i]), (PG8_LAS unsigned*)(lds + (bufoff) + ldsw + _i * 8192), 16, 0, 0); } while (0)
; #define PG8_LDA(dst, b, h) do { _Pragma("unroll") for (int m = 0; m < 4; ++m) _Pragma("unroll") for (int k = 0; k < 2; ++k) dst[m][k] = *(const PG8_LAS bf16x8*)(lds + PG8_SA(b, h) + aoff + m * 2048 + k * 1024); } while (0)
; #define PG8_LDB(dst, b, h) do { _Pragma("unroll") for (int n = 0; n < 2; ++n) _Pragma("unroll") for (int k = 0; k < 2; ++k) dst[n][k] = *(const PG8_LAS bf16x8*)(lds + PG8_SB(b, h) + boff + n * 2048 + k * 1024); } while (0)
; #define PG8_MMA(ai, bj, At, Bt) do { __builtin_amdgcn_s_setprio(1); _Pragma("unroll") for (int m = 0; m < 4; ++m) _Pragma("unroll") for (int n = 0; n < 2; ++n) _Pragma("unroll") for (int k = 0; k < 2; ++k) \
;         acc[ai][bj][m][n] = __builtin_amdgcn_mfma_f32_16x16x32_bf16(Bt[n][k], At[m][k], acc[ai][bj][m][n], 0, 0, 0); __builtin_amdgcn_s_setprio(0); } while (0)
; #define PG8_WAIT_V(n) asm volatile("s_waitcnt vmcnt(" #n ")" ::: "memory")
; #define PG8_WAIT_L(n) asm volatile("s_waitcnt lgkmcnt(" #n ")" ::: "memory")
; #define PG8_BAR __builtin_amdgcn_s_barrier()
; #define PG8_SCHED __builtin_amdgcn_sched_barrier(0)
; template <class Epi, class Sched, bool ALIGN_EPI = false, bool SP2 = false>
; __device__ __forceinline__ void gemm_phase(PG8_LAS unsigned char* lds, const Gemm g, const Sched& S, const Epi& E) {
;     ...
;             PG8_WAIT_V(8); PG8_WAIT_L(0); PG8_BAR; PG8_MMA(1, 0, At, B0); PG8_MMA(1, 1, At, B1); PG8_BAR; PG8_SCHED;
;             PG8_LDB(B0, 1, 0); PG8_LDB(B1, 1, 1); PG8_SCHED; PG8_LDA(At, 1, 0); PG8_STAGE(PG8_SA(0, 1), a2 + hstep, voffA);
;             PG8_WAIT_V(8); PG8_WAIT_L(0); PG8_BAR; PG8_MMA(0, 0, At, B0); PG8_MMA(0, 1, At, B1); PG8_BAR; PG8_SCHED;
	v_mfma_f32_16x16x32_bf16 v[60:63], v[162:165], v[210:213], v[60:63]
	v_mfma_f32_16x16x32_bf16 v[52:55], v[186:189], v[210:213], v[52:55]
	v_mfma_f32_16x16x32_bf16 v[44:47], v[162:165], v[220:223], v[44:47]
	v_mfma_f32_16x16x32_bf16 v[36:39], v[186:189], v[220:223], v[36:39]
	v_mfma_f32_16x16x32_bf16 v[28:31], v[162:165], v[228:231], v[28:31]
	v_mfma_f32_16x16x32_bf16 v[20:23], v[186:189], v[228:231], v[20:23]
	v_mfma_f32_16x16x32_bf16 v[12:15], v[162:165], v[236:239], v[12:15]
	v_mfma_f32_16x16x32_bf16 v[4:7], v[186:189], v[236:239], v[4:7]
	v_mfma_f32_16x16x32_bf16 v[60:63], v[182:185], v[216:219], v[60:63]
	v_mfma_f32_16x16x32_bf16 v[52:55], v[190:193], v[216:219], v[52:55]
	v_mfma_f32_16x16x32_bf16 v[44:47], v[182:185], v[224:227], v[44:47]
	v_mfma_f32_16x16x32_bf16 v[36:39], v[190:193], v[224:227], v[36:39]
	v_mfma_f32_16x16x32_bf16 v[28:31], v[182:185], v[232:235], v[28:31]
	v_mfma_f32_16x16x32_bf16 v[20:23], v[190:193], v[232:235], v[20:23]
	v_mfma_f32_16x16x32_bf16 v[12:15], v[182:185], v[240:243], v[12:15]
	v_mfma_f32_16x16x32_bf16 v[4:7], v[190:193], v[240:243], v[4:7]
	v_mfma_f32_16x16x32_bf16 v[56:59], v[194:197], v[210:213], v[56:59]
	v_mfma_f32_16x16x32_bf16 v[48:51], v[202:205], v[210:213], v[48:51]
	v_mfma_f32_16x16x32_bf16 v[40:43], v[194:197], v[220:223], v[40:43]
	v_mfma_f32_16x16x32_bf16 v[32:35], v[202:205], v[220:223], v[32:35]
	v_mfma_f32_16x16x32_bf16 v[24:27], v[194:197], v[228:231], v[24:27]
	v_mfma_f32_16x16x32_bf16 v[16:19], v[202:205], v[228:231], v[16:19]
	v_mfma_f32_16x16x32_bf16 v[8:11], v[194:197], v[236:239], v[8:11]
	v_mfma_f32_16x16x32_bf16 v[0:3], v[202:205], v[236:239], v[0:3]
	v_mfma_f32_16x16x32_bf16 v[56:59], v[198:201], v[216:219], v[56:59]
	v_mfma_f32_16x16x32_bf16 v[48:51], v[206:209], v[216:219], v[48:51]
	v_mfma_f32_16x16x32_bf16 v[40:43], v[198:201], v[224:227], v[40:43]
	v_mfma_f32_16x16x32_bf16 v[32:35], v[206:209], v[224:227], v[32:35]
	v_mfma_f32_16x16x32_bf16 v[24:27], v[198:201], v[232:235], v[24:27]
	v_mfma_f32_16x16x32_bf16 v[16:19], v[206:209], v[232:235], v[16:19]
	v_mfma_f32_16x16x32_bf16 v[8:11], v[198:201], v[240:243], v[8:11]
	v_mfma_f32_16x16x32_bf16 v[0:3], v[206:209], v[240:243], v[0:3]
	s_setprio 0
	s_barrier
	s_add_i32 s11, 0, 0x18000
	v_add_u32_e32 v166, s11, v169
	s_add_i32 s13, 0, 0x1c000
	ds_read_b128 v[162:165], v166
	ds_read_b128 v[182:185], v166 offset:1024
	ds_read_b128 v[186:189], v166 offset:2048
	ds_read_b128 v[190:193], v166 offset:3072
	v_add_u32_e32 v166, s13, v169
	ds_read_b128 v[194:197], v166
	ds_read_b128 v[198:201], v166 offset:1024
	ds_read_b128 v[202:205], v166 offset:2048
	ds_read_b128 v[206:209], v166 offset:3072
	v_lshl_add_u64 v[172:173], v[172:173], 0, s[14:15]
	s_mov_b32 m0, s48
	v_lshl_add_u64 v[170:171], v[172:173], 0, v[140:141]
	ds_read_b128 v[210:213], v179 offset:32768
	ds_read_b128 v[216:219], v179 offset:33792
	ds_read_b128 v[220:223], v179 offset:34816
	ds_read_b128 v[224:227], v179 offset:35840
	ds_read_b128 v[228:231], v179 offset:36864
	ds_read_b128 v[232:235], v179 offset:37888
	ds_read_b128 v[236:239], v179 offset:38912
	ds_read_b128 v[240:243], v179 offset:39936
	global_load_lds_dwordx4 v[170:171], off
	v_lshl_add_u64 v[170:171], v[172:173], 0, v[136:137]
	s_mov_b32 m0, s49
	s_nop 0
	global_load_lds_dwordx4 v[170:171], off
	s_waitcnt vmcnt(8)
	s_waitcnt lgkmcnt(0)
	s_setprio 1
	s_barrier
	v_mfma_f32_16x16x32_bf16 v[124:127], v[162:165], v[210:213], v[124:127]
	v_mfma_f32_16x16x32_bf16 v[116:119], v[186:189], v[210:213], v[116:119]
	v_mfma_f32_16x16x32_bf16 v[108:111], v[162:165], v[220:223], v[108:111]
	v_mfma_f32_16x16x32_bf16 v[100:103], v[186:189], v[220:223], v[100:103]
	v_mfma_f32_16x16x32_bf16 v[92:95], v[162:165], v[228:231], v[92:95]
	v_mfma_f32_16x16x32_bf16 v[84:87], v[186:189], v[228:231], v[84:87]
	v_mfma_f32_16x16x32_bf16 v[76:79], v[162:165], v[236:239], v[76:79]
	v_mfma_f32_16x16x32_bf16 v[68:71], v[186:189], v[236:239], v[68:71]
	v_mfma_f32_16x16x32_bf16 v[124:127], v[182:185], v[216:219], v[124:127]
	v_mfma_f32_16x16x32_bf16 v[116:119], v[190:193], v[216:219], v[116:119]
	v_mfma_f32_16x16x32_bf16 v[108:111], v[182:185], v[224:227], v[108:111]
	v_mfma_f32_16x16x32_bf16 v[100:103], v[190:193], v[224:227], v[100:103]
	v_mfma_f32_16x16x32_bf16 v[92:95], v[182:185], v[232:235], v[92:95]
	v_mfma_f32_16x16x32_bf16 v[84:87], v[190:193], v[232:235], v[84:87]
	v_mfma_f32_16x16x32_bf16 v[76:79], v[182:185], v[240:243], v[76:79]
	v_mfma_f32_16x16x32_bf16 v[68:71], v[190:193], v[240:243], v[68:71]
	v_mfma_f32_16x16x32_bf16 v[120:123], v[194:197], v[210:213], v[120:123]
	v_mfma_f32_16x16x32_bf16 v[112:115], v[202:205], v[210:213], v[112:115]
	v_mfma_f32_16x16x32_bf16 v[104:107], v[194:197], v[220:223], v[104:107]
	v_mfma_f32_16x16x32_bf16 v[96:99], v[202:205], v[220:223], v[96:99]
	v_mfma_f32_16x16x32_bf16 v[88:91], v[194:197], v[228:231], v[88:91]
	v_mfma_f32_16x16x32_bf16 v[80:83], v[202:205], v[228:231], v[80:83]
	v_mfma_f32_16x16x32_bf16 v[72:75], v[194:197], v[236:239], v[72:75]
	v_mfma_f32_16x16x32_bf16 v[64:67], v[202:205], v[236:239], v[64:67]
	v_mfma_f32_16x16x32_bf16 v[120:123], v[198:201], v[216:219], v[120:123]
	v_mfma_f32_16x16x32_bf16 v[112:115], v[206:209], v[216:219], v[112:115]
	v_mfma_f32_16x16x32_bf16 v[104:107], v[198:201], v[224:227], v[104:107]
	v_mfma_f32_16x16x32_bf16 v[96:99], v[206:209], v[224:227], v[96:99]
	v_mfma_f32_16x16x32_bf16 v[88:91], v[198:201], v[232:235], v[88:91]
	v_mfma_f32_16x16x32_bf16 v[80:83], v[206:209], v[232:235], v[80:83]
	v_mfma_f32_16x16x32_bf16 v[72:75], v[198:201], v[240:243], v[72:75]
	v_mfma_f32_16x16x32_bf16 v[64:67], v[206:209], v[240:243], v[64:67]
	s_setprio 0
	s_barrier
; #define PG8_STAGE(bufoff, gbase, voff) do { _Pragma("unroll") for (int _i = 0; _i < 2; ++_i) \
;         __builtin_amdgcn_global_load_lds((const unsigned*)((const char*)(gbase) + (voff)[_i]), (PG8_LAS unsigned*)(lds + (bufoff) + ldsw + _i * 8192), 16, 0, 0); } while (0)
; #define PG8_LDA(dst, b, h) do { _Pragma("unroll") for (int m = 0; m < 4; ++m) _Pragma("unroll") for (int k = 0; k < 2; ++k) dst[m][k] = *(const PG8_LAS bf16x8*)(lds + PG8_SA(b, h) + aoff + m * 2048 + k * 1024); } while (0)
; #define PG8_MMA(ai, bj, At, Bt) do { __builtin_amdgcn_s_setprio(1); _Pragma("unroll") for (int m = 0; m < 4; ++m) _Pragma("unroll") for (int n = 0; n < 2; ++n) _Pragma("unroll") for (int k = 0; k < 2; ++k) \
;         acc[ai][bj][m][n] = __builtin_amdgcn_mfma_f32_16x16x32_bf16(Bt[n][k], At[m][k], acc[ai][bj][m][n], 0, 0, 0); __builtin_amdgcn_s_setprio(0); } while (0)
; #define PG8_WAIT_V(n) asm volatile("s_waitcnt vmcnt(" #n ")" ::: "memory")
; #define PG8_WAIT_L(n) asm volatile("s_waitcnt lgkmcnt(" #n ")" ::: "memory")
; #define PG8_BAR __builtin_amdgcn_s_barrier()
; #define PG8_SCHED __builtin_amdgcn_sched_barrier(0)
; template <class Epi, class Sched, bool ALIGN_EPI = false, bool SP2 = false>
; __device__ __forceinline__ void gemm_phase(PG8_LAS unsigned char* lds, const Gemm g, const Sched& S, const Epi& E) {
;     ...
;             PG8_LDA(At, 1, 1); PG8_STAGE(PG8_SB(1, 0), b3, voffB); PG8_STAGE(PG8_SB(1, 1), b3 + hstep, voffB); PG8_STAGE(PG8_SA(1, 0), a3, voffA);
;             PG8_WAIT_V(8); PG8_WAIT_L(0); PG8_BAR; PG8_MMA(1, 0, At, B0); PG8_MMA(1, 1, At, B1); PG8_BAR; PG8_SCHED;
	s_add_i32 s11, s11, s29
	v_lshl_add_u64 v[170:171], v[246:247], 0, s[22:23]
	s_mov_b32 m0, s11
	ds_read_b128 v[210:213], v179 offset:49152
	ds_read_b128 v[216:219], v179 offset:50176
	ds_read_b128 v[220:223], v179 offset:51200
	ds_read_b128 v[224:227], v179 offset:52224
	ds_read_b128 v[228:231], v179 offset:53248
	ds_read_b128 v[232:235], v179 offset:54272
	ds_read_b128 v[236:239], v179 offset:55296
	ds_read_b128 v[240:243], v179 offset:56320
	global_load_lds_dwordx4 v[170:171], off
	v_lshl_add_u64 v[170:171], v[248:249], 0, s[22:23]
	s_add_i32 m0, s11, 0x2000
	s_add_i32 s11, s13, s29
	global_load_lds_dwordx4 v[170:171], off
	v_lshl_add_u64 v[170:171], v[250:251], 0, s[22:23]
	s_mov_b32 m0, s11
	s_nop 0
	global_load_lds_dwordx4 v[170:171], off
	v_lshl_add_u64 v[170:171], v[244:245], 0, s[22:23]
	s_add_i32 m0, s11, 0x2000
	s_nop 0
	global_load_lds_dwordx4 v[170:171], off
	v_lshl_add_u64 v[170:171], v[252:253], 0, s[22:23]
	s_mov_b32 m0, s50
	s_nop 0
	global_load_lds_dwordx4 v[170:171], off
	v_lshl_add_u64 v[170:171], v[214:215], 0, s[22:23]
	s_mov_b32 m0, s51
	s_nop 0
	global_load_lds_dwordx4 v[170:171], off
	s_waitcnt vmcnt(8)
	s_waitcnt lgkmcnt(0)
	s_setprio 1
	s_barrier
	v_mfma_f32_16x16x32_bf16 v[60:63], v[162:165], v[210:213], v[60:63]
	v_mfma_f32_16x16x32_bf16 v[52:55], v[186:189], v[210:213], v[52:55]
	v_mfma_f32_16x16x32_bf16 v[44:47], v[162:165], v[220:223], v[44:47]
	v_mfma_f32_16x16x32_bf16 v[36:39], v[186:189], v[220:223], v[36:39]
	v_mfma_f32_16x16x32_bf16 v[28:31], v[162:165], v[228:231], v[28:31]
	v_mfma_f32_16x16x32_bf16 v[20:23], v[186:189], v[228:231], v[20:23]
	v_mfma_f32_16x16x32_bf16 v[12:15], v[162:165], v[236:239], v[12:15]
	v_mfma_f32_16x16x32_bf16 v[4:7], v[186:189], v[236:239], v[4:7]
	v_mfma_f32_16x16x32_bf16 v[60:63], v[182:185], v[216:219], v[60:63]
	v_mfma_f32_16x16x32_bf16 v[52:55], v[190:193], v[216:219], v[52:55]
	v_mfma_f32_16x16x32_bf16 v[44:47], v[182:185], v[224:227], v[44:47]
	v_mfma_f32_16x16x32_bf16 v[36:39], v[190:193], v[224:227], v[36:39]
	v_mfma_f32_16x16x32_bf16 v[28:31], v[182:185], v[232:235], v[28:31]
	v_mfma_f32_16x16x32_bf16 v[20:23], v[190:193], v[232:235], v[20:23]
	v_mfma_f32_16x16x32_bf16 v[12:15], v[182:185], v[240:243], v[12:15]
	v_mfma_f32_16x16x32_bf16 v[4:7], v[190:193], v[240:243], v[4:7]
	v_mfma_f32_16x16x32_bf16 v[56:59], v[194:197], v[210:213], v[56:59]
	v_mfma_f32_16x16x32_bf16 v[48:51], v[202:205], v[210:213], v[48:51]
	v_mfma_f32_16x16x32_bf16 v[40:43], v[194:197], v[220:223], v[40:43]
	v_mfma_f32_16x16x32_bf16 v[32:35], v[202:205], v[220:223], v[32:35]
	v_mfma_f32_16x16x32_bf16 v[24:27], v[194:197], v[228:231], v[24:27]
	v_mfma_f32_16x16x32_bf16 v[16:19], v[202:205], v[228:231], v[16:19]
	v_mfma_f32_16x16x32_bf16 v[8:11], v[194:197], v[236:239], v[8:11]
	v_mfma_f32_16x16x32_bf16 v[0:3], v[202:205], v[236:239], v[0:3]
	v_mfma_f32_16x16x32_bf16 v[56:59], v[198:201], v[216:219], v[56:59]
	v_mfma_f32_16x16x32_bf16 v[48:51], v[206:209], v[216:219], v[48:51]
	v_mfma_f32_16x16x32_bf16 v[40:43], v[198:201], v[224:227], v[40:43]
	v_mfma_f32_16x16x32_bf16 v[32:35], v[206:209], v[224:227], v[32:35]
	v_mfma_f32_16x16x32_bf16 v[24:27], v[198:201], v[232:235], v[24:27]
	v_mfma_f32_16x16x32_bf16 v[16:19], v[206:209], v[232:235], v[16:19]
	v_mfma_f32_16x16x32_bf16 v[8:11], v[198:201], v[240:243], v[8:11]
	v_mfma_f32_16x16x32_bf16 v[0:3], v[206:209], v[240:243], v[0:3]
	s_setprio 0
	s_barrier
	v_lshl_add_u64 v[158:159], v[158:159], 0, s[26:27]
	s_cmp_ge_i32 s10, s52
	v_lshl_add_u64 v[160:161], v[160:161], 0, s[26:27]
	s_cbranch_scc0 .LBB0_304

; #define PG8_STAGE(bufoff, gbase, voff) do { _Pragma("unroll") for (int _i = 0; _i < 2; ++_i) \
;         __builtin_amdgcn_global_load_lds((const unsigned*)((const char*)(gbase) + (voff)[_i]), (PG8_LAS unsigned*)(lds + (bufoff) + ldsw + _i * 8192), 16, 0, 0); } while (0)
; #define PG8_LDA(dst, b, h) do { _Pragma("unroll") for (int m = 0; m < 4; ++m) _Pragma("unroll") for (int k = 0; k < 2; ++k) dst[m][k] = *(const PG8_LAS bf16x8*)(lds + PG8_SA(b, h) + aoff + m * 2048 + k * 1024); } while (0)
; #define PG8_LDB(dst, b, h) do { _Pragma("unroll") for (int n = 0; n < 2; ++n) _Pragma("unroll") for (int k = 0; k < 2; ++k) dst[n][k] = *(const PG8_LAS bf16x8*)(lds + PG8_SB(b, h) + boff + n * 2048 + k * 1024); } while (0)
; #define PG8_MMA(ai, bj, At, Bt) do { __builtin_amdgcn_s_setprio(1); _Pragma("unroll") for (int m = 0; m < 4; ++m) _Pragma("unroll") for (int n = 0; n < 2; ++n) _Pragma("unroll") for (int k = 0; k < 2; ++k) \
;         acc[ai][bj][m][n] = __builtin_amdgcn_mfma_f32_16x16x32_bf16(Bt[n][k], At[m][k], acc[ai][bj][m][n], 0, 0, 0); __builtin_amdgcn_s_setprio(0); } while (0)
; #define PG8_WAIT_V(n) asm volatile("s_waitcnt vmcnt(" #n ")" ::: "memory")
; #define PG8_WAIT_L(n) asm volatile("s_waitcnt lgkmcnt(" #n ")" ::: "memory")
; #define PG8_BAR __builtin_amdgcn_s_barrier()
; template <class Epi, class Sched, bool ALIGN_EPI = false, bool SP2 = false>
; __device__ __forceinline__ void gemm_phase(PG8_LAS unsigned char* lds, const Gemm g, const Sched& S, const Epi& E) {
;     ...
;             const char* a1 = cA + (size_t)(t + 1) * kstep;
;             const char* a2 = last ? nA : cA + (size_t)(t + 2) * kstep; const char* b2 = last ? nB : cB + (size_t)(t + 2) * kstep;
;             const char* a3 = a2 + kstep; const char* b3 = b2 + kstep;
;             if (last && has_next) S.a_ready(nxt);
;             if constexpr (SP2) {
;             PG8_LDB(B0, 0, 0); PG8_LDB(B1, 0, 1); PG8_SCHED; PG8_LDA(At, 0, 0); PG8_STAGE(PG8_SA(1, 1), a1 + hstep, voffA);
;             PG8_WAIT_V(8); PG8_WAIT_L(0); PG8_BAR; PG8_MMA(0, 0, At, B0); PG8_MMA(0, 1, At, B1); PG8_BAR; PG8_SCHED;
;             PG8_LDA(At, 0, 1); PG8_STAGE(PG8_SB(0, 0), b2, voffB); PG8_STAGE(PG8_SB(0, 1), b2 + hstep, voffB); PG8_STAGE(PG8_SA(0, 0), a2, voffA);
;             PG8_WAIT_V(8); PG8_WAIT_L(0); PG8_BAR; PG8_MMA(1, 0, At, B0); PG8_MMA(1, 1, At, B1); PG8_BAR; PG8_SCHED;
.LBB0_371:
	v_add_u32_e32 v148, s54, v201
	v_add_u32_e32 v190, s55, v201
	ds_read_b128 v[136:139], v148
	ds_read_b128 v[140:143], v148 offset:1024
	ds_read_b128 v[144:147], v148 offset:2048
	ds_read_b128 v[148:151], v148 offset:3072
	ds_read_b128 v[152:155], v190
	ds_read_b128 v[182:185], v190 offset:1024
	ds_read_b128 v[186:189], v190 offset:2048
	ds_read_b128 v[190:193], v190 offset:3072
	s_cmp_eq_u32 s48, s12
	v_lshl_add_u64 v[194:195], v[134:135], 0, s[22:23]
	s_cselect_b64 vcc, -1, 0
	s_add_i32 s12, s12, 2
	v_cndmask_b32_e32 v199, v195, v179, vcc
	v_cndmask_b32_e32 v198, v194, v178, vcc
	v_cndmask_b32_e32 v215, v133, v181, vcc
	v_cndmask_b32_e32 v214, v132, v180, vcc
	s_mov_b32 m0, s56
	v_lshl_add_u64 v[236:237], v[134:135], 0, v[174:175]
	ds_read_b128 v[194:197], v203
	ds_read_b128 v[206:209], v203 offset:1024
	ds_read_b128 v[210:213], v203 offset:2048
	ds_read_b128 v[216:219], v203 offset:3072
	ds_read_b128 v[220:223], v203 offset:4096
	ds_read_b128 v[224:227], v203 offset:5120
	ds_read_b128 v[228:231], v203 offset:6144
	ds_read_b128 v[232:235], v203 offset:7168
	global_load_lds_dwordx4 v[236:237], off
	v_lshl_add_u64 v[236:237], v[134:135], 0, v[172:173]
	s_mov_b32 m0, s57
	s_nop 0
	global_load_lds_dwordx4 v[236:237], off
	s_waitcnt vmcnt(8)
	s_waitcnt lgkmcnt(0)
	s_setprio 1
	s_barrier
	v_mfma_f32_16x16x32_bf16 v[124:127], v[136:139], v[194:197], v[124:127]
	v_mfma_f32_16x16x32_bf16 v[128:131], v[144:147], v[194:197], v[128:131]
	v_mfma_f32_16x16x32_bf16 v[112:115], v[136:139], v[210:213], v[112:115]
	v_mfma_f32_16x16x32_bf16 v[108:111], v[144:147], v[210:213], v[108:111]
	v_mfma_f32_16x16x32_bf16 v[96:99], v[136:139], v[220:223], v[96:99]
	v_mfma_f32_16x16x32_bf16 v[92:95], v[144:147], v[220:223], v[92:95]
	v_mfma_f32_16x16x32_bf16 v[80:83], v[136:139], v[228:231], v[80:83]
	v_mfma_f32_16x16x32_bf16 v[76:79], v[144:147], v[228:231], v[76:79]
	v_mfma_f32_16x16x32_bf16 v[124:127], v[140:143], v[206:209], v[124:127]
	v_mfma_f32_16x16x32_bf16 v[128:131], v[148:151], v[206:209], v[128:131]
	v_mfma_f32_16x16x32_bf16 v[112:115], v[140:143], v[216:219], v[112:115]
	v_mfma_f32_16x16x32_bf16 v[108:111], v[148:151], v[216:219], v[108:111]
	v_mfma_f32_16x16x32_bf16 v[96:99], v[140:143], v[224:227], v[96:99]
	v_mfma_f32_16x16x32_bf16 v[92:95], v[148:151], v[224:227], v[92:95]
	v_mfma_f32_16x16x32_bf16 v[80:83], v[140:143], v[232:235], v[80:83]
	v_mfma_f32_16x16x32_bf16 v[76:79], v[148:151], v[232:235], v[76:79]
	v_mfma_f32_16x16x32_bf16 v[120:123], v[152:155], v[194:197], v[120:123]
	v_mfma_f32_16x16x32_bf16 v[116:119], v[186:189], v[194:197], v[116:119]
	v_mfma_f32_16x16x32_bf16 v[104:107], v[152:155], v[210:213], v[104:107]
	v_mfma_f32_16x16x32_bf16 v[100:103], v[186:189], v[210:213], v[100:103]
	v_mfma_f32_16x16x32_bf16 v[88:91], v[152:155], v[220:223], v[88:91]
	v_mfma_f32_16x16x32_bf16 v[84:87], v[186:189], v[220:223], v[84:87]
	v_mfma_f32_16x16x32_bf16 v[72:75], v[152:155], v[228:231], v[72:75]
	v_mfma_f32_16x16x32_bf16 v[68:71], v[186:189], v[228:231], v[68:71]
	v_mfma_f32_16x16x32_bf16 v[120:123], v[182:185], v[206:209], v[120:123]
	v_mfma_f32_16x16x32_bf16 v[116:119], v[190:193], v[206:209], v[116:119]
	v_mfma_f32_16x16x32_bf16 v[104:107], v[182:185], v[216:219], v[104:107]
	v_mfma_f32_16x16x32_bf16 v[100:103], v[190:193], v[216:219], v[100:103]
	v_mfma_f32_16x16x32_bf16 v[88:91], v[182:185], v[224:227], v[88:91]
	v_mfma_f32_16x16x32_bf16 v[84:87], v[190:193], v[224:227], v[84:87]
	v_mfma_f32_16x16x32_bf16 v[72:75], v[182:185], v[232:235], v[72:75]
	v_mfma_f32_16x16x32_bf16 v[68:71], v[190:193], v[232:235], v[68:71]
	s_setprio 0
	s_barrier
	s_mov_b32 m0, s58
	v_lshl_add_u64 v[236:237], v[214:215], 0, v[166:167]
	ds_read_b128 v[194:197], v203 offset:16384
	ds_read_b128 v[206:209], v203 offset:17408
	ds_read_b128 v[210:213], v203 offset:18432
	ds_read_b128 v[216:219], v203 offset:19456
	ds_read_b128 v[220:223], v203 offset:20480
	ds_read_b128 v[224:227], v203 offset:21504
	ds_read_b128 v[228:231], v203 offset:22528
	ds_read_b128 v[232:235], v203 offset:23552
	global_load_lds_dwordx4 v[236:237], off
	v_lshl_add_u64 v[238:239], v[214:215], 0, v[170:171]
	s_mov_b32 m0, s59
	v_lshl_add_u64 v[214:215], v[214:215], 0, s[14:15]
	s_add_i32 s13, s55, s30
	global_load_lds_dwordx4 v[238:239], off
	v_lshl_add_u64 v[240:241], v[214:215], 0, v[166:167]
	s_mov_b32 m0, s13
	v_lshl_add_u64 v[214:215], v[214:215], 0, v[170:171]
	global_load_lds_dwordx4 v[240:241], off
	s_add_i32 m0, s13, 0x2000
	v_lshl_add_u64 v[242:243], v[198:199], 0, v[164:165]
	global_load_lds_dwordx4 v[214:215], off
	s_mov_b32 m0, s31
	v_lshl_add_u64 v[244:245], v[198:199], 0, v[168:169]
	global_load_lds_dwordx4 v[242:243], off
	s_mov_b32 m0, s34
	s_nop 0
	global_load_lds_dwordx4 v[244:245], off
	s_waitcnt vmcnt(8)
	s_waitcnt lgkmcnt(0)
	s_setprio 1
	s_barrier
; #define PG8_STAGE(bufoff, gbase, voff) do { _Pragma("unroll") for (int _i = 0; _i < 2; ++_i) \
;         __builtin_amdgcn_global_load_lds((const unsigned*)((const char*)(gbase) + (voff)[_i]), (PG8_LAS unsigned*)(lds + (bufoff) + ldsw + _i * 8192), 16, 0, 0); } while (0)
; #define PG8_LDA(dst, b, h) do { _Pragma("unroll") for (int m = 0; m < 4; ++m) _Pragma("unroll") for (int k = 0; k < 2; ++k) dst[m][k] = *(const PG8_LAS bf16x8*)(lds + PG8_SA(b, h) + aoff + m * 2048 + k * 1024); } while (0)
; #define PG8_LDB(dst, b, h) do { _Pragma("unroll") for (int n = 0; n < 2; ++n) _Pragma("unroll") for (int k = 0; k < 2; ++k) dst[n][k] = *(const PG8_LAS bf16x8*)(lds + PG8_SB(b, h) + boff + n * 2048 + k * 1024); } while (0)
; #define PG8_MMA(ai, bj, At, Bt) do { __builtin_amdgcn_s_setprio(1); _Pragma("unroll") for (int m = 0; m < 4; ++m) _Pragma("unroll") for (int n = 0; n < 2; ++n) _Pragma("unroll") for (int k = 0; k < 2; ++k) \
;         acc[ai][bj][m][n] = __builtin_amdgcn_mfma_f32_16x16x32_bf16(Bt[n][k], At[m][k], acc[ai][bj][m][n], 0, 0, 0); __builtin_amdgcn_s_setprio(0); } while (0)
; #define PG8_WAIT_V(n) asm volatile("s_waitcnt vmcnt(" #n ")" ::: "memory")
; #define PG8_WAIT_L(n) asm volatile("s_waitcnt lgkmcnt(" #n ")" ::: "memory")
; #define PG8_BAR __builtin_amdgcn_s_barrier()
; #define PG8_SCHED __builtin_amdgcn_sched_barrier(0)
; template <class Epi, class Sched, bool ALIGN_EPI = false, bool SP2 = false>
; __device__ __forceinline__ void gemm_phase(PG8_LAS unsigned char* lds, const Gemm g, const Sched& S, const Epi& E) {
;     ...
;             PG8_WAIT_V(8); PG8_WAIT_L(0); PG8_BAR; PG8_MMA(1, 0, At, B0); PG8_MMA(1, 1, At, B1); PG8_BAR; PG8_SCHED;
;             PG8_LDB(B0, 1, 0); PG8_LDB(B1, 1, 1); PG8_SCHED; PG8_LDA(At, 1, 0); PG8_STAGE(PG8_SA(0, 1), a2 + hstep, voffA);
;             PG8_WAIT_V(8); PG8_WAIT_L(0); PG8_BAR; PG8_MMA(0, 0, At, B0); PG8_MMA(0, 1, At, B1); PG8_BAR; PG8_SCHED;
	v_mfma_f32_16x16x32_bf16 v[64:67], v[136:139], v[194:197], v[64:67]
	v_mfma_f32_16x16x32_bf16 v[60:63], v[144:147], v[194:197], v[60:63]
	v_mfma_f32_16x16x32_bf16 v[48:51], v[136:139], v[210:213], v[48:51]
	v_mfma_f32_16x16x32_bf16 v[44:47], v[144:147], v[210:213], v[44:47]
	v_mfma_f32_16x16x32_bf16 v[32:35], v[136:139], v[220:223], v[32:35]
	v_mfma_f32_16x16x32_bf16 v[28:31], v[144:147], v[220:223], v[28:31]
	v_mfma_f32_16x16x32_bf16 v[16:19], v[136:139], v[228:231], v[16:19]
	v_mfma_f32_16x16x32_bf16 v[12:15], v[144:147], v[228:231], v[12:15]
	v_mfma_f32_16x16x32_bf16 v[64:67], v[140:143], v[206:209], v[64:67]
	v_mfma_f32_16x16x32_bf16 v[60:63], v[148:151], v[206:209], v[60:63]
	v_mfma_f32_16x16x32_bf16 v[48:51], v[140:143], v[216:219], v[48:51]
	v_mfma_f32_16x16x32_bf16 v[44:47], v[148:151], v[216:219], v[44:47]
	v_mfma_f32_16x16x32_bf16 v[32:35], v[140:143], v[224:227], v[32:35]
	v_mfma_f32_16x16x32_bf16 v[28:31], v[148:151], v[224:227], v[28:31]
	v_mfma_f32_16x16x32_bf16 v[16:19], v[140:143], v[232:235], v[16:19]
	v_mfma_f32_16x16x32_bf16 v[12:15], v[148:151], v[232:235], v[12:15]
	v_mfma_f32_16x16x32_bf16 v[56:59], v[152:155], v[194:197], v[56:59]
	v_mfma_f32_16x16x32_bf16 v[52:55], v[186:189], v[194:197], v[52:55]
	v_mfma_f32_16x16x32_bf16 v[40:43], v[152:155], v[210:213], v[40:43]
	v_mfma_f32_16x16x32_bf16 v[36:39], v[186:189], v[210:213], v[36:39]
	v_mfma_f32_16x16x32_bf16 v[24:27], v[152:155], v[220:223], v[24:27]
	v_mfma_f32_16x16x32_bf16 v[20:23], v[186:189], v[220:223], v[20:23]
	v_mfma_f32_16x16x32_bf16 v[8:11], v[152:155], v[228:231], v[8:11]
	v_mfma_f32_16x16x32_bf16 v[4:7], v[186:189], v[228:231], v[4:7]
	v_mfma_f32_16x16x32_bf16 v[56:59], v[182:185], v[206:209], v[56:59]
	v_mfma_f32_16x16x32_bf16 v[52:55], v[190:193], v[206:209], v[52:55]
	v_mfma_f32_16x16x32_bf16 v[40:43], v[182:185], v[216:219], v[40:43]
	v_mfma_f32_16x16x32_bf16 v[36:39], v[190:193], v[216:219], v[36:39]
	v_mfma_f32_16x16x32_bf16 v[24:27], v[182:185], v[224:227], v[24:27]
	v_mfma_f32_16x16x32_bf16 v[20:23], v[190:193], v[224:227], v[20:23]
	v_mfma_f32_16x16x32_bf16 v[8:11], v[182:185], v[232:235], v[8:11]
	v_mfma_f32_16x16x32_bf16 v[4:7], v[190:193], v[232:235], v[4:7]
	s_setprio 0
	s_barrier
	s_add_i32 s13, 0, 0x18000
	s_add_i32 s29, 0, 0x1c000
	v_add_u32_e32 v148, s13, v201
	v_add_u32_e32 v190, s29, v201
	ds_read_b128 v[136:139], v148
	ds_read_b128 v[140:143], v148 offset:1024
	ds_read_b128 v[144:147], v148 offset:2048
	ds_read_b128 v[148:151], v148 offset:3072
	ds_read_b128 v[152:155], v190
	ds_read_b128 v[182:185], v190 offset:1024
	ds_read_b128 v[186:189], v190 offset:2048
	ds_read_b128 v[190:193], v190 offset:3072
	v_lshl_add_u64 v[198:199], v[198:199], 0, s[14:15]
	s_mov_b32 m0, s35
	v_lshl_add_u64 v[246:247], v[198:199], 0, v[164:165]
	ds_read_b128 v[194:197], v203 offset:32768
	ds_read_b128 v[206:209], v203 offset:33792
	ds_read_b128 v[210:213], v203 offset:34816
	ds_read_b128 v[216:219], v203 offset:35840
	ds_read_b128 v[220:223], v203 offset:36864
	ds_read_b128 v[224:227], v203 offset:37888
	ds_read_b128 v[228:231], v203 offset:38912
	ds_read_b128 v[232:235], v203 offset:39936
	global_load_lds_dwordx4 v[246:247], off
	v_lshl_add_u64 v[198:199], v[198:199], 0, v[168:169]
	s_mov_b32 m0, s36
	s_nop 0
	global_load_lds_dwordx4 v[198:199], off
	s_waitcnt vmcnt(8)
	s_waitcnt lgkmcnt(0)
	s_setprio 1
	s_barrier
	v_mfma_f32_16x16x32_bf16 v[124:127], v[136:139], v[194:197], v[124:127]
	v_mfma_f32_16x16x32_bf16 v[128:131], v[144:147], v[194:197], v[128:131]
	v_mfma_f32_16x16x32_bf16 v[112:115], v[136:139], v[210:213], v[112:115]
	v_mfma_f32_16x16x32_bf16 v[108:111], v[144:147], v[210:213], v[108:111]
	v_mfma_f32_16x16x32_bf16 v[96:99], v[136:139], v[220:223], v[96:99]
	v_mfma_f32_16x16x32_bf16 v[92:95], v[144:147], v[220:223], v[92:95]
	v_mfma_f32_16x16x32_bf16 v[80:83], v[136:139], v[228:231], v[80:83]
	v_mfma_f32_16x16x32_bf16 v[76:79], v[144:147], v[228:231], v[76:79]
	v_mfma_f32_16x16x32_bf16 v[124:127], v[140:143], v[206:209], v[124:127]
	v_mfma_f32_16x16x32_bf16 v[128:131], v[148:151], v[206:209], v[128:131]
	v_mfma_f32_16x16x32_bf16 v[112:115], v[140:143], v[216:219], v[112:115]
	v_mfma_f32_16x16x32_bf16 v[108:111], v[148:151], v[216:219], v[108:111]
	v_mfma_f32_16x16x32_bf16 v[96:99], v[140:143], v[224:227], v[96:99]
	v_mfma_f32_16x16x32_bf16 v[92:95], v[148:151], v[224:227], v[92:95]
	v_mfma_f32_16x16x32_bf16 v[80:83], v[140:143], v[232:235], v[80:83]
	v_mfma_f32_16x16x32_bf16 v[76:79], v[148:151], v[232:235], v[76:79]
	v_mfma_f32_16x16x32_bf16 v[120:123], v[152:155], v[194:197], v[120:123]
	v_mfma_f32_16x16x32_bf16 v[116:119], v[186:189], v[194:197], v[116:119]
	v_mfma_f32_16x16x32_bf16 v[104:107], v[152:155], v[210:213], v[104:107]
	v_mfma_f32_16x16x32_bf16 v[100:103], v[186:189], v[210:213], v[100:103]
	v_mfma_f32_16x16x32_bf16 v[88:91], v[152:155], v[220:223], v[88:91]
	v_mfma_f32_16x16x32_bf16 v[84:87], v[186:189], v[220:223], v[84:87]
	v_mfma_f32_16x16x32_bf16 v[72:75], v[152:155], v[228:231], v[72:75]
	v_mfma_f32_16x16x32_bf16 v[68:71], v[186:189], v[228:231], v[68:71]
	v_mfma_f32_16x16x32_bf16 v[120:123], v[182:185], v[206:209], v[120:123]
	v_mfma_f32_16x16x32_bf16 v[116:119], v[190:193], v[206:209], v[116:119]
	v_mfma_f32_16x16x32_bf16 v[104:107], v[182:185], v[216:219], v[104:107]
	v_mfma_f32_16x16x32_bf16 v[100:103], v[190:193], v[216:219], v[100:103]
	v_mfma_f32_16x16x32_bf16 v[88:91], v[182:185], v[224:227], v[88:91]
	v_mfma_f32_16x16x32_bf16 v[84:87], v[190:193], v[224:227], v[84:87]
	v_mfma_f32_16x16x32_bf16 v[72:75], v[182:185], v[232:235], v[72:75]
	v_mfma_f32_16x16x32_bf16 v[68:71], v[190:193], v[232:235], v[68:71]
	s_setprio 0
	s_barrier
; #define PG8_STAGE(bufoff, gbase, voff) do { _Pragma("unroll") for (int _i = 0; _i < 2; ++_i) \
;         __builtin_amdgcn_global_load_lds((const unsigned*)((const char*)(gbase) + (voff)[_i]), (PG8_LAS unsigned*)(lds + (bufoff) + ldsw + _i * 8192), 16, 0, 0); } while (0)
; #define PG8_LDA(dst, b, h) do { _Pragma("unroll") for (int m = 0; m < 4; ++m) _Pragma("unroll") for (int k = 0; k < 2; ++k) dst[m][k] = *(const PG8_LAS bf16x8*)(lds + PG8_SA(b, h) + aoff + m * 2048 + k * 1024); } while (0)
; #define PG8_MMA(ai, bj, At, Bt) do { __builtin_amdgcn_s_setprio(1); _Pragma("unroll") for (int m = 0; m < 4; ++m) _Pragma("unroll") for (int n = 0; n < 2; ++n) _Pragma("unroll") for (int k = 0; k < 2; ++k) \
;         acc[ai][bj][m][n] = __builtin_amdgcn_mfma_f32_16x16x32_bf16(Bt[n][k], At[m][k], acc[ai][bj][m][n], 0, 0, 0); __builtin_amdgcn_s_setprio(0); } while (0)
; #define PG8_WAIT_V(n) asm volatile("s_waitcnt vmcnt(" #n ")" ::: "memory")
; #define PG8_WAIT_L(n) asm volatile("s_waitcnt lgkmcnt(" #n ")" ::: "memory")
; #define PG8_BAR __builtin_amdgcn_s_barrier()
; #define PG8_SCHED __builtin_amdgcn_sched_barrier(0)
; template <class Epi, class Sched, bool ALIGN_EPI = false, bool SP2 = false>
; __device__ __forceinline__ void gemm_phase(PG8_LAS unsigned char* lds, const Gemm g, const Sched& S, const Epi& E) {
;     ...
;             PG8_LDA(At, 1, 1); PG8_STAGE(PG8_SB(1, 0), b3, voffB); PG8_STAGE(PG8_SB(1, 1), b3 + hstep, voffB); PG8_STAGE(PG8_SA(1, 0), a3, voffA);
;             PG8_WAIT_V(8); PG8_WAIT_L(0); PG8_BAR; PG8_MMA(1, 0, At, B0); PG8_MMA(1, 1, At, B1); PG8_BAR; PG8_SCHED;
	s_add_i32 s13, s13, s30
	v_lshl_add_u64 v[198:199], v[236:237], 0, s[22:23]
	s_mov_b32 m0, s13
	ds_read_b128 v[194:197], v203 offset:49152
	ds_read_b128 v[206:209], v203 offset:50176
	ds_read_b128 v[210:213], v203 offset:51200
	ds_read_b128 v[216:219], v203 offset:52224
	ds_read_b128 v[220:223], v203 offset:53248
	ds_read_b128 v[224:227], v203 offset:54272
	ds_read_b128 v[228:231], v203 offset:55296
	ds_read_b128 v[232:235], v203 offset:56320
	global_load_lds_dwordx4 v[198:199], off
	v_lshl_add_u64 v[198:199], v[238:239], 0, s[22:23]
	s_add_i32 m0, s13, 0x2000
	s_add_i32 s13, s29, s30
	global_load_lds_dwordx4 v[198:199], off
	v_lshl_add_u64 v[198:199], v[240:241], 0, s[22:23]
	s_mov_b32 m0, s13
	s_nop 0
	global_load_lds_dwordx4 v[198:199], off
	v_lshl_add_u64 v[198:199], v[214:215], 0, s[22:23]
	s_add_i32 m0, s13, 0x2000
	s_nop 0
	global_load_lds_dwordx4 v[198:199], off
	v_lshl_add_u64 v[198:199], v[242:243], 0, s[22:23]
	s_mov_b32 m0, s37
	s_nop 0
	global_load_lds_dwordx4 v[198:199], off
	v_lshl_add_u64 v[198:199], v[244:245], 0, s[22:23]
	s_mov_b32 m0, s41
	s_nop 0
	global_load_lds_dwordx4 v[198:199], off
	s_waitcnt vmcnt(8)
	s_waitcnt lgkmcnt(0)
	s_setprio 1
	s_barrier
	v_mfma_f32_16x16x32_bf16 v[64:67], v[136:139], v[194:197], v[64:67]
	v_mfma_f32_16x16x32_bf16 v[60:63], v[144:147], v[194:197], v[60:63]
	v_mfma_f32_16x16x32_bf16 v[48:51], v[136:139], v[210:213], v[48:51]
	v_mfma_f32_16x16x32_bf16 v[44:47], v[144:147], v[210:213], v[44:47]
	v_mfma_f32_16x16x32_bf16 v[32:35], v[136:139], v[220:223], v[32:35]
	v_mfma_f32_16x16x32_bf16 v[28:31], v[144:147], v[220:223], v[28:31]
	v_mfma_f32_16x16x32_bf16 v[16:19], v[136:139], v[228:231], v[16:19]
	v_mfma_f32_16x16x32_bf16 v[12:15], v[144:147], v[228:231], v[12:15]
	v_mfma_f32_16x16x32_bf16 v[64:67], v[140:143], v[206:209], v[64:67]
	v_mfma_f32_16x16x32_bf16 v[60:63], v[148:151], v[206:209], v[60:63]
	v_mfma_f32_16x16x32_bf16 v[48:51], v[140:143], v[216:219], v[48:51]
	v_mfma_f32_16x16x32_bf16 v[44:47], v[148:151], v[216:219], v[44:47]
	v_mfma_f32_16x16x32_bf16 v[32:35], v[140:143], v[224:227], v[32:35]
	v_mfma_f32_16x16x32_bf16 v[28:31], v[148:151], v[224:227], v[28:31]
	v_mfma_f32_16x16x32_bf16 v[16:19], v[140:143], v[232:235], v[16:19]
	v_mfma_f32_16x16x32_bf16 v[12:15], v[148:151], v[232:235], v[12:15]
	v_mfma_f32_16x16x32_bf16 v[56:59], v[152:155], v[194:197], v[56:59]
	v_mfma_f32_16x16x32_bf16 v[52:55], v[186:189], v[194:197], v[52:55]
	v_mfma_f32_16x16x32_bf16 v[40:43], v[152:155], v[210:213], v[40:43]
	v_mfma_f32_16x16x32_bf16 v[36:39], v[186:189], v[210:213], v[36:39]
	v_mfma_f32_16x16x32_bf16 v[24:27], v[152:155], v[220:223], v[24:27]
	v_mfma_f32_16x16x32_bf16 v[20:23], v[186:189], v[220:223], v[20:23]
	v_mfma_f32_16x16x32_bf16 v[8:11], v[152:155], v[228:231], v[8:11]
	v_mfma_f32_16x16x32_bf16 v[4:7], v[186:189], v[228:231], v[4:7]
	v_mfma_f32_16x16x32_bf16 v[56:59], v[182:185], v[206:209], v[56:59]
	v_mfma_f32_16x16x32_bf16 v[52:55], v[190:193], v[206:209], v[52:55]
	v_mfma_f32_16x16x32_bf16 v[40:43], v[182:185], v[216:219], v[40:43]
	v_mfma_f32_16x16x32_bf16 v[36:39], v[190:193], v[216:219], v[36:39]
	v_mfma_f32_16x16x32_bf16 v[24:27], v[182:185], v[224:227], v[24:27]
	v_mfma_f32_16x16x32_bf16 v[20:23], v[190:193], v[224:227], v[20:23]
	v_mfma_f32_16x16x32_bf16 v[8:11], v[182:185], v[232:235], v[8:11]
	v_mfma_f32_16x16x32_bf16 v[4:7], v[190:193], v[232:235], v[4:7]
	s_setprio 0
	s_barrier
	v_lshl_add_u64 v[132:133], v[132:133], 0, s[26:27]
	s_cmp_ge_i32 s12, s47
	v_lshl_add_u64 v[134:135], v[134:135], 0, s[26:27]
	s_cbranch_scc0 .LBB0_371

; #define PG8_STAGE(bufoff, gbase, voff) do { _Pragma("unroll") for (int _i = 0; _i < 2; ++_i) \
;         __builtin_amdgcn_global_load_lds((const unsigned*)((const char*)(gbase) + (voff)[_i]), (PG8_LAS unsigned*)(lds + (bufoff) + ldsw + _i * 8192), 16, 0, 0); } while (0)
; #define PG8_LDA(dst, b, h) do { _Pragma("unroll") for (int m = 0; m < 4; ++m) _Pragma("unroll") for (int k = 0; k < 2; ++k) dst[m][k] = *(const PG8_LAS bf16x8*)(lds + PG8_SA(b, h) + aoff + m * 2048 + k * 1024); } while (0)
; #define PG8_LDB(dst, b, h) do { _Pragma("unroll") for (int n = 0; n < 2; ++n) _Pragma("unroll") for (int k = 0; k < 2; ++k) dst[n][k] = *(const PG8_LAS bf16x8*)(lds + PG8_SB(b, h) + boff + n * 2048 + k * 1024); } while (0)
; #define PG8_MMA(ai, bj, At, Bt) do { __builtin_amdgcn_s_setprio(1); _Pragma("unroll") for (int m = 0; m < 4; ++m) _Pragma("unroll") for (int n = 0; n < 2; ++n) _Pragma("unroll") for (int k = 0; k < 2; ++k) \
;         acc[ai][bj][m][n] = __builtin_amdgcn_mfma_f32_16x16x32_bf16(Bt[n][k], At[m][k], acc[ai][bj][m][n], 0, 0, 0); __builtin_amdgcn_s_setprio(0); } while (0)
; #define PG8_WAIT_V(n) asm volatile("s_waitcnt vmcnt(" #n ")" ::: "memory")
; #define PG8_WAIT_L(n) asm volatile("s_waitcnt lgkmcnt(" #n ")" ::: "memory")
; #define PG8_BAR __builtin_amdgcn_s_barrier()
; template <class Epi, class Sched, bool ALIGN_EPI = false, bool SP2 = false>
; __device__ __forceinline__ void gemm_phase(PG8_LAS unsigned char* lds, const Gemm g, const Sched& S, const Epi& E) {
;     ...
;             const char* a1 = cA + (size_t)(t + 1) * kstep;
;             const char* a2 = last ? nA : cA + (size_t)(t + 2) * kstep; const char* b2 = last ? nB : cB + (size_t)(t + 2) * kstep;
;             const char* a3 = a2 + kstep; const char* b3 = b2 + kstep;
;             if (last && has_next) S.a_ready(nxt);
;             if constexpr (SP2) {
;             PG8_LDB(B0, 0, 0); PG8_LDB(B1, 0, 1); PG8_SCHED; PG8_LDA(At, 0, 0); PG8_STAGE(PG8_SA(1, 1), a1 + hstep, voffA);
;             PG8_WAIT_V(8); PG8_WAIT_L(0); PG8_BAR; PG8_MMA(0, 0, At, B0); PG8_MMA(0, 1, At, B1); PG8_BAR; PG8_SCHED;
;             PG8_LDA(At, 0, 1); PG8_STAGE(PG8_SB(0, 0), b2, voffB); PG8_STAGE(PG8_SB(0, 1), b2 + hstep, voffB); PG8_STAGE(PG8_SA(0, 0), a2, voffA);
;             PG8_WAIT_V(8); PG8_WAIT_L(0); PG8_BAR; PG8_MMA(1, 0, At, B0); PG8_MMA(1, 1, At, B1); PG8_BAR; PG8_SCHED;
.LBB0_454:
	v_add_u32_e32 v165, s69, v171
	v_add_u32_e32 v167, s70, v171
	ds_read_b128 v[132:135], v165
	ds_read_b128 v[136:139], v165 offset:1024
	ds_read_b128 v[176:179], v165 offset:2048
	ds_read_b128 v[180:183], v165 offset:3072
	ds_read_b128 v[184:187], v167
	ds_read_b128 v[188:191], v167 offset:1024
	ds_read_b128 v[192:195], v167 offset:2048
	ds_read_b128 v[196:199], v167 offset:3072
	s_cmp_eq_u32 s62, s12
	v_lshl_add_u64 v[200:201], v[130:131], 0, s[24:25]
	s_cselect_b64 vcc, -1, 0
	s_add_i32 s12, s12, 2
	v_cndmask_b32_e32 v209, v201, v173, vcc
	v_cndmask_b32_e32 v208, v200, v172, vcc
	v_cndmask_b32_e32 v213, v129, v175, vcc
	v_cndmask_b32_e32 v212, v128, v174, vcc
	v_lshl_add_u64 v[214:215], v[130:131], 0, v[160:161]
	s_add_i32 m0, s41, 0xc000
	ds_read_b128 v[200:203], v216
	ds_read_b128 v[204:207], v216 offset:1024
	ds_read_b128 v[218:221], v216 offset:2048
	ds_read_b128 v[222:225], v216 offset:3072
	ds_read_b128 v[226:229], v216 offset:4096
	ds_read_b128 v[230:233], v216 offset:5120
	ds_read_b128 v[234:237], v216 offset:6144
	ds_read_b128 v[238:241], v216 offset:7168
	global_load_lds_dwordx4 v[214:215], off
	v_lshl_add_u64 v[214:215], v[130:131], 0, v[158:159]
	s_add_i32 m0, s41, 0xe000
	s_nop 0
	global_load_lds_dwordx4 v[214:215], off
	s_waitcnt vmcnt(8)
	s_waitcnt lgkmcnt(0)
	s_setprio 1
	s_barrier
	v_mfma_f32_16x16x32_bf16 v[124:127], v[132:135], v[200:203], v[124:127]
	v_mfma_f32_16x16x32_bf16 v[120:123], v[176:179], v[200:203], v[120:123]
	v_mfma_f32_16x16x32_bf16 v[108:111], v[132:135], v[218:221], v[108:111]
	v_mfma_f32_16x16x32_bf16 v[104:107], v[176:179], v[218:221], v[104:107]
	v_mfma_f32_16x16x32_bf16 v[92:95], v[132:135], v[226:229], v[92:95]
	v_mfma_f32_16x16x32_bf16 v[88:91], v[176:179], v[226:229], v[88:91]
	v_mfma_f32_16x16x32_bf16 v[76:79], v[132:135], v[234:237], v[76:79]
	v_mfma_f32_16x16x32_bf16 v[72:75], v[176:179], v[234:237], v[72:75]
	v_mfma_f32_16x16x32_bf16 v[124:127], v[136:139], v[204:207], v[124:127]
	v_mfma_f32_16x16x32_bf16 v[120:123], v[180:183], v[204:207], v[120:123]
	v_mfma_f32_16x16x32_bf16 v[108:111], v[136:139], v[222:225], v[108:111]
	v_mfma_f32_16x16x32_bf16 v[104:107], v[180:183], v[222:225], v[104:107]
	v_mfma_f32_16x16x32_bf16 v[92:95], v[136:139], v[230:233], v[92:95]
	v_mfma_f32_16x16x32_bf16 v[88:91], v[180:183], v[230:233], v[88:91]
	v_mfma_f32_16x16x32_bf16 v[76:79], v[136:139], v[238:241], v[76:79]
	v_mfma_f32_16x16x32_bf16 v[72:75], v[180:183], v[238:241], v[72:75]
	v_mfma_f32_16x16x32_bf16 v[116:119], v[184:187], v[200:203], v[116:119]
	v_mfma_f32_16x16x32_bf16 v[112:115], v[192:195], v[200:203], v[112:115]
	v_mfma_f32_16x16x32_bf16 v[100:103], v[184:187], v[218:221], v[100:103]
	v_mfma_f32_16x16x32_bf16 v[96:99], v[192:195], v[218:221], v[96:99]
	v_mfma_f32_16x16x32_bf16 v[84:87], v[184:187], v[226:229], v[84:87]
	v_mfma_f32_16x16x32_bf16 v[80:83], v[192:195], v[226:229], v[80:83]
	v_mfma_f32_16x16x32_bf16 v[68:71], v[184:187], v[234:237], v[68:71]
	v_mfma_f32_16x16x32_bf16 v[64:67], v[192:195], v[234:237], v[64:67]
	v_mfma_f32_16x16x32_bf16 v[116:119], v[188:191], v[204:207], v[116:119]
	v_mfma_f32_16x16x32_bf16 v[112:115], v[196:199], v[204:207], v[112:115]
	v_mfma_f32_16x16x32_bf16 v[100:103], v[188:191], v[222:225], v[100:103]
	v_mfma_f32_16x16x32_bf16 v[96:99], v[196:199], v[222:225], v[96:99]
	v_mfma_f32_16x16x32_bf16 v[84:87], v[188:191], v[230:233], v[84:87]
	v_mfma_f32_16x16x32_bf16 v[80:83], v[196:199], v[230:233], v[80:83]
	v_mfma_f32_16x16x32_bf16 v[68:71], v[188:191], v[238:241], v[68:71]
	v_mfma_f32_16x16x32_bf16 v[64:67], v[196:199], v[238:241], v[64:67]
	s_setprio 0
	s_barrier
	s_add_i32 s13, s69, s37
	v_lshl_add_u64 v[214:215], v[212:213], 0, v[146:147]
	s_mov_b32 m0, s13
	ds_read_b128 v[200:203], v216 offset:16384
	ds_read_b128 v[204:207], v216 offset:17408
	ds_read_b128 v[218:221], v216 offset:18432
	ds_read_b128 v[222:225], v216 offset:19456
	ds_read_b128 v[226:229], v216 offset:20480
	ds_read_b128 v[230:233], v216 offset:21504
	ds_read_b128 v[234:237], v216 offset:22528
	ds_read_b128 v[238:241], v216 offset:23552
	global_load_lds_dwordx4 v[214:215], off
	v_lshl_add_u64 v[242:243], v[212:213], 0, v[150:151]
	s_add_i32 m0, s13, 0x2000
	v_lshl_add_u64 v[212:213], v[212:213], 0, s[16:17]
	s_add_i32 s13, s70, s37
	global_load_lds_dwordx4 v[242:243], off
	v_lshl_add_u64 v[244:245], v[212:213], 0, v[146:147]
	s_mov_b32 m0, s13
	v_lshl_add_u64 v[212:213], v[212:213], 0, v[150:151]
	global_load_lds_dwordx4 v[244:245], off
	s_add_i32 m0, s13, 0x2000
	v_lshl_add_u64 v[246:247], v[208:209], 0, v[144:145]
	global_load_lds_dwordx4 v[212:213], off
	s_mov_b32 m0, s41
	v_lshl_add_u64 v[248:249], v[208:209], 0, v[148:149]
	global_load_lds_dwordx4 v[246:247], off
	s_mov_b32 m0, s50
	s_nop 0
	global_load_lds_dwordx4 v[248:249], off
	s_waitcnt vmcnt(8)
	s_waitcnt lgkmcnt(0)
	s_setprio 1
	s_barrier
; #define PG8_STAGE(bufoff, gbase, voff) do { _Pragma("unroll") for (int _i = 0; _i < 2; ++_i) \
;         __builtin_amdgcn_global_load_lds((const unsigned*)((const char*)(gbase) + (voff)[_i]), (PG8_LAS unsigned*)(lds + (bufoff) + ldsw + _i * 8192), 16, 0, 0); } while (0)
; #define PG8_LDA(dst, b, h) do { _Pragma("unroll") for (int m = 0; m < 4; ++m) _Pragma("unroll") for (int k = 0; k < 2; ++k) dst[m][k] = *(const PG8_LAS bf16x8*)(lds + PG8_SA(b, h) + aoff + m * 2048 + k * 1024); } while (0)
; #define PG8_LDB(dst, b, h) do { _Pragma("unroll") for (int n = 0; n < 2; ++n) _Pragma("unroll") for (int k = 0; k < 2; ++k) dst[n][k] = *(const PG8_LAS bf16x8*)(lds + PG8_SB(b, h) + boff + n * 2048 + k * 1024); } while (0)
; #define PG8_MMA(ai, bj, At, Bt) do { __builtin_amdgcn_s_setprio(1); _Pragma("unroll") for (int m = 0; m < 4; ++m) _Pragma("unroll") for (int n = 0; n < 2; ++n) _Pragma("unroll") for (int k = 0; k < 2; ++k) \
;         acc[ai][bj][m][n] = __builtin_amdgcn_mfma_f32_16x16x32_bf16(Bt[n][k], At[m][k], acc[ai][bj][m][n], 0, 0, 0); __builtin_amdgcn_s_setprio(0); } while (0)
; #define PG8_WAIT_V(n) asm volatile("s_waitcnt vmcnt(" #n ")" ::: "memory")
; #define PG8_WAIT_L(n) asm volatile("s_waitcnt lgkmcnt(" #n ")" ::: "memory")
; #define PG8_BAR __builtin_amdgcn_s_barrier()
; #define PG8_SCHED __builtin_amdgcn_sched_barrier(0)
; template <class Epi, class Sched, bool ALIGN_EPI = false, bool SP2 = false>
; __device__ __forceinline__ void gemm_phase(PG8_LAS unsigned char* lds, const Gemm g, const Sched& S, const Epi& E) {
;     ...
;             PG8_WAIT_V(8); PG8_WAIT_L(0); PG8_BAR; PG8_MMA(1, 0, At, B0); PG8_MMA(1, 1, At, B1); PG8_BAR; PG8_SCHED;
;             PG8_LDB(B0, 1, 0); PG8_LDB(B1, 1, 1); PG8_SCHED; PG8_LDA(At, 1, 0); PG8_STAGE(PG8_SA(0, 1), a2 + hstep, voffA);
;             PG8_WAIT_V(8); PG8_WAIT_L(0); PG8_BAR; PG8_MMA(0, 0, At, B0); PG8_MMA(0, 1, At, B1); PG8_BAR; PG8_SCHED;
	v_mfma_f32_16x16x32_bf16 v[60:63], v[132:135], v[200:203], v[60:63]
	v_mfma_f32_16x16x32_bf16 v[56:59], v[176:179], v[200:203], v[56:59]
	v_mfma_f32_16x16x32_bf16 v[44:47], v[132:135], v[218:221], v[44:47]
	v_mfma_f32_16x16x32_bf16 v[40:43], v[176:179], v[218:221], v[40:43]
	v_mfma_f32_16x16x32_bf16 v[28:31], v[132:135], v[226:229], v[28:31]
	v_mfma_f32_16x16x32_bf16 v[24:27], v[176:179], v[226:229], v[24:27]
	v_mfma_f32_16x16x32_bf16 v[12:15], v[132:135], v[234:237], v[12:15]
	v_mfma_f32_16x16x32_bf16 v[8:11], v[176:179], v[234:237], v[8:11]
	v_mfma_f32_16x16x32_bf16 v[60:63], v[136:139], v[204:207], v[60:63]
	v_mfma_f32_16x16x32_bf16 v[56:59], v[180:183], v[204:207], v[56:59]
	v_mfma_f32_16x16x32_bf16 v[44:47], v[136:139], v[222:225], v[44:47]
	v_mfma_f32_16x16x32_bf16 v[40:43], v[180:183], v[222:225], v[40:43]
	v_mfma_f32_16x16x32_bf16 v[28:31], v[136:139], v[230:233], v[28:31]
	v_mfma_f32_16x16x32_bf16 v[24:27], v[180:183], v[230:233], v[24:27]
	v_mfma_f32_16x16x32_bf16 v[12:15], v[136:139], v[238:241], v[12:15]
	v_mfma_f32_16x16x32_bf16 v[8:11], v[180:183], v[238:241], v[8:11]
	v_mfma_f32_16x16x32_bf16 v[52:55], v[184:187], v[200:203], v[52:55]
	v_mfma_f32_16x16x32_bf16 v[48:51], v[192:195], v[200:203], v[48:51]
	v_mfma_f32_16x16x32_bf16 v[36:39], v[184:187], v[218:221], v[36:39]
	v_mfma_f32_16x16x32_bf16 v[32:35], v[192:195], v[218:221], v[32:35]
	v_mfma_f32_16x16x32_bf16 v[20:23], v[184:187], v[226:229], v[20:23]
	v_mfma_f32_16x16x32_bf16 v[16:19], v[192:195], v[226:229], v[16:19]
	v_mfma_f32_16x16x32_bf16 v[4:7], v[184:187], v[234:237], v[4:7]
	v_mfma_f32_16x16x32_bf16 v[0:3], v[192:195], v[234:237], v[0:3]
	v_mfma_f32_16x16x32_bf16 v[52:55], v[188:191], v[204:207], v[52:55]
	v_mfma_f32_16x16x32_bf16 v[48:51], v[196:199], v[204:207], v[48:51]
	v_mfma_f32_16x16x32_bf16 v[36:39], v[188:191], v[222:225], v[36:39]
	v_mfma_f32_16x16x32_bf16 v[32:35], v[196:199], v[222:225], v[32:35]
	v_mfma_f32_16x16x32_bf16 v[20:23], v[188:191], v[230:233], v[20:23]
	v_mfma_f32_16x16x32_bf16 v[16:19], v[196:199], v[230:233], v[16:19]
	v_mfma_f32_16x16x32_bf16 v[4:7], v[188:191], v[238:241], v[4:7]
	v_mfma_f32_16x16x32_bf16 v[0:3], v[196:199], v[238:241], v[0:3]
	s_setprio 0
	s_barrier
	s_add_i32 s13, 0, 0x18000
	v_add_u32_e32 v165, s13, v171
	s_add_i32 s15, 0, 0x1c000
	ds_read_b128 v[132:135], v165
	ds_read_b128 v[136:139], v165 offset:1024
	ds_read_b128 v[176:179], v165 offset:2048
	ds_read_b128 v[180:183], v165 offset:3072
	v_add_u32_e32 v165, s15, v171
	ds_read_b128 v[184:187], v165
	ds_read_b128 v[188:191], v165 offset:1024
	ds_read_b128 v[192:195], v165 offset:2048
	ds_read_b128 v[196:199], v165 offset:3072
	v_lshl_add_u64 v[208:209], v[208:209], 0, s[16:17]
	s_mov_b32 m0, s52
	v_lshl_add_u64 v[250:251], v[208:209], 0, v[144:145]
	ds_read_b128 v[200:203], v216 offset:32768
	ds_read_b128 v[204:207], v216 offset:33792
	ds_read_b128 v[218:221], v216 offset:34816
	ds_read_b128 v[222:225], v216 offset:35840
	ds_read_b128 v[226:229], v216 offset:36864
	ds_read_b128 v[230:233], v216 offset:37888
	ds_read_b128 v[234:237], v216 offset:38912
	ds_read_b128 v[238:241], v216 offset:39936
	global_load_lds_dwordx4 v[250:251], off
	v_lshl_add_u64 v[208:209], v[208:209], 0, v[148:149]
	s_mov_b32 m0, s53
	s_nop 0
	global_load_lds_dwordx4 v[208:209], off
	s_waitcnt vmcnt(8)
	s_waitcnt lgkmcnt(0)
	s_setprio 1
	s_barrier
	v_mfma_f32_16x16x32_bf16 v[124:127], v[132:135], v[200:203], v[124:127]
	v_mfma_f32_16x16x32_bf16 v[120:123], v[176:179], v[200:203], v[120:123]
	v_mfma_f32_16x16x32_bf16 v[108:111], v[132:135], v[218:221], v[108:111]
	v_mfma_f32_16x16x32_bf16 v[104:107], v[176:179], v[218:221], v[104:107]
	v_mfma_f32_16x16x32_bf16 v[92:95], v[132:135], v[226:229], v[92:95]
	v_mfma_f32_16x16x32_bf16 v[88:91], v[176:179], v[226:229], v[88:91]
	v_mfma_f32_16x16x32_bf16 v[76:79], v[132:135], v[234:237], v[76:79]
	v_mfma_f32_16x16x32_bf16 v[72:75], v[176:179], v[234:237], v[72:75]
	v_mfma_f32_16x16x32_bf16 v[124:127], v[136:139], v[204:207], v[124:127]
	v_mfma_f32_16x16x32_bf16 v[120:123], v[180:183], v[204:207], v[120:123]
	v_mfma_f32_16x16x32_bf16 v[108:111], v[136:139], v[222:225], v[108:111]
	v_mfma_f32_16x16x32_bf16 v[104:107], v[180:183], v[222:225], v[104:107]
	v_mfma_f32_16x16x32_bf16 v[92:95], v[136:139], v[230:233], v[92:95]
	v_mfma_f32_16x16x32_bf16 v[88:91], v[180:183], v[230:233], v[88:91]
	v_mfma_f32_16x16x32_bf16 v[76:79], v[136:139], v[238:241], v[76:79]
	v_mfma_f32_16x16x32_bf16 v[72:75], v[180:183], v[238:241], v[72:75]
	v_mfma_f32_16x16x32_bf16 v[116:119], v[184:187], v[200:203], v[116:119]
	v_mfma_f32_16x16x32_bf16 v[112:115], v[192:195], v[200:203], v[112:115]
	v_mfma_f32_16x16x32_bf16 v[100:103], v[184:187], v[218:221], v[100:103]
	v_mfma_f32_16x16x32_bf16 v[96:99], v[192:195], v[218:221], v[96:99]
	v_mfma_f32_16x16x32_bf16 v[84:87], v[184:187], v[226:229], v[84:87]
	v_mfma_f32_16x16x32_bf16 v[80:83], v[192:195], v[226:229], v[80:83]
	v_mfma_f32_16x16x32_bf16 v[68:71], v[184:187], v[234:237], v[68:71]
	v_mfma_f32_16x16x32_bf16 v[64:67], v[192:195], v[234:237], v[64:67]
	v_mfma_f32_16x16x32_bf16 v[116:119], v[188:191], v[204:207], v[116:119]
	v_mfma_f32_16x16x32_bf16 v[112:115], v[196:199], v[204:207], v[112:115]
	v_mfma_f32_16x16x32_bf16 v[100:103], v[188:191], v[222:225], v[100:103]
	v_mfma_f32_16x16x32_bf16 v[96:99], v[196:199], v[222:225], v[96:99]
	v_mfma_f32_16x16x32_bf16 v[84:87], v[188:191], v[230:233], v[84:87]
	v_mfma_f32_16x16x32_bf16 v[80:83], v[196:199], v[230:233], v[80:83]
	v_mfma_f32_16x16x32_bf16 v[68:71], v[188:191], v[238:241], v[68:71]
	v_mfma_f32_16x16x32_bf16 v[64:67], v[196:199], v[238:241], v[64:67]
	s_setprio 0
	s_barrier
; #define PG8_STAGE(bufoff, gbase, voff) do { _Pragma("unroll") for (int _i = 0; _i < 2; ++_i) \
;         __builtin_amdgcn_global_load_lds((const unsigned*)((const char*)(gbase) + (voff)[_i]), (PG8_LAS unsigned*)(lds + (bufoff) + ldsw + _i * 8192), 16, 0, 0); } while (0)
; #define PG8_LDA(dst, b, h) do { _Pragma("unroll") for (int m = 0; m < 4; ++m) _Pragma("unroll") for (int k = 0; k < 2; ++k) dst[m][k] = *(const PG8_LAS bf16x8*)(lds + PG8_SA(b, h) + aoff + m * 2048 + k * 1024); } while (0)
; #define PG8_MMA(ai, bj, At, Bt) do { __builtin_amdgcn_s_setprio(1); _Pragma("unroll") for (int m = 0; m < 4; ++m) _Pragma("unroll") for (int n = 0; n < 2; ++n) _Pragma("unroll") for (int k = 0; k < 2; ++k) \
;         acc[ai][bj][m][n] = __builtin_amdgcn_mfma_f32_16x16x32_bf16(Bt[n][k], At[m][k], acc[ai][bj][m][n], 0, 0, 0); __builtin_amdgcn_s_setprio(0); } while (0)
; #define PG8_WAIT_V(n) asm volatile("s_waitcnt vmcnt(" #n ")" ::: "memory")
; #define PG8_WAIT_L(n) asm volatile("s_waitcnt lgkmcnt(" #n ")" ::: "memory")
; #define PG8_BAR __builtin_amdgcn_s_barrier()
; #define PG8_SCHED __builtin_amdgcn_sched_barrier(0)
; template <class Epi, class Sched, bool ALIGN_EPI = false, bool SP2 = false>
; __device__ __forceinline__ void gemm_phase(PG8_LAS unsigned char* lds, const Gemm g, const Sched& S, const Epi& E) {
;     ...
;             PG8_LDA(At, 1, 1); PG8_STAGE(PG8_SB(1, 0), b3, voffB); PG8_STAGE(PG8_SB(1, 1), b3 + hstep, voffB); PG8_STAGE(PG8_SA(1, 0), a3, voffA);
;             PG8_WAIT_V(8); PG8_WAIT_L(0); PG8_BAR; PG8_MMA(1, 0, At, B0); PG8_MMA(1, 1, At, B1); PG8_BAR; PG8_SCHED;
	s_add_i32 s13, s13, s37
	v_lshl_add_u64 v[208:209], v[214:215], 0, s[24:25]
	s_mov_b32 m0, s13
	ds_read_b128 v[200:203], v216 offset:49152
	ds_read_b128 v[204:207], v216 offset:50176
	ds_read_b128 v[218:221], v216 offset:51200
	ds_read_b128 v[222:225], v216 offset:52224
	ds_read_b128 v[226:229], v216 offset:53248
	ds_read_b128 v[230:233], v216 offset:54272
	ds_read_b128 v[234:237], v216 offset:55296
	ds_read_b128 v[238:241], v216 offset:56320
	global_load_lds_dwordx4 v[208:209], off
	v_lshl_add_u64 v[208:209], v[242:243], 0, s[24:25]
	s_add_i32 m0, s13, 0x2000
	s_add_i32 s13, s15, s37
	global_load_lds_dwordx4 v[208:209], off
	v_lshl_add_u64 v[208:209], v[244:245], 0, s[24:25]
	s_mov_b32 m0, s13
	s_nop 0
	global_load_lds_dwordx4 v[208:209], off
	v_lshl_add_u64 v[208:209], v[212:213], 0, s[24:25]
	s_add_i32 m0, s13, 0x2000
	s_nop 0
	global_load_lds_dwordx4 v[208:209], off
	v_lshl_add_u64 v[208:209], v[246:247], 0, s[24:25]
	s_mov_b32 m0, s56
	s_nop 0
	global_load_lds_dwordx4 v[208:209], off
	v_lshl_add_u64 v[208:209], v[248:249], 0, s[24:25]
	s_mov_b32 m0, s57
	s_nop 0
	global_load_lds_dwordx4 v[208:209], off
	s_waitcnt vmcnt(8)
	s_waitcnt lgkmcnt(0)
	s_setprio 1
	s_barrier
	v_mfma_f32_16x16x32_bf16 v[60:63], v[132:135], v[200:203], v[60:63]
	v_mfma_f32_16x16x32_bf16 v[56:59], v[176:179], v[200:203], v[56:59]
	v_mfma_f32_16x16x32_bf16 v[44:47], v[132:135], v[218:221], v[44:47]
	v_mfma_f32_16x16x32_bf16 v[40:43], v[176:179], v[218:221], v[40:43]
	v_mfma_f32_16x16x32_bf16 v[28:31], v[132:135], v[226:229], v[28:31]
	v_mfma_f32_16x16x32_bf16 v[24:27], v[176:179], v[226:229], v[24:27]
	v_mfma_f32_16x16x32_bf16 v[12:15], v[132:135], v[234:237], v[12:15]
	v_mfma_f32_16x16x32_bf16 v[8:11], v[176:179], v[234:237], v[8:11]
	v_mfma_f32_16x16x32_bf16 v[60:63], v[136:139], v[204:207], v[60:63]
	v_mfma_f32_16x16x32_bf16 v[56:59], v[180:183], v[204:207], v[56:59]
	v_mfma_f32_16x16x32_bf16 v[44:47], v[136:139], v[222:225], v[44:47]
	v_mfma_f32_16x16x32_bf16 v[40:43], v[180:183], v[222:225], v[40:43]
	v_mfma_f32_16x16x32_bf16 v[28:31], v[136:139], v[230:233], v[28:31]
	v_mfma_f32_16x16x32_bf16 v[24:27], v[180:183], v[230:233], v[24:27]
	v_mfma_f32_16x16x32_bf16 v[12:15], v[136:139], v[238:241], v[12:15]
	v_mfma_f32_16x16x32_bf16 v[8:11], v[180:183], v[238:241], v[8:11]
	v_mfma_f32_16x16x32_bf16 v[52:55], v[184:187], v[200:203], v[52:55]
	v_mfma_f32_16x16x32_bf16 v[48:51], v[192:195], v[200:203], v[48:51]
	v_mfma_f32_16x16x32_bf16 v[36:39], v[184:187], v[218:221], v[36:39]
	v_mfma_f32_16x16x32_bf16 v[32:35], v[192:195], v[218:221], v[32:35]
	v_mfma_f32_16x16x32_bf16 v[20:23], v[184:187], v[226:229], v[20:23]
	v_mfma_f32_16x16x32_bf16 v[16:19], v[192:195], v[226:229], v[16:19]
	v_mfma_f32_16x16x32_bf16 v[4:7], v[184:187], v[234:237], v[4:7]
	v_mfma_f32_16x16x32_bf16 v[0:3], v[192:195], v[234:237], v[0:3]
	v_mfma_f32_16x16x32_bf16 v[52:55], v[188:191], v[204:207], v[52:55]
	v_mfma_f32_16x16x32_bf16 v[48:51], v[196:199], v[204:207], v[48:51]
	v_mfma_f32_16x16x32_bf16 v[36:39], v[188:191], v[222:225], v[36:39]
	v_mfma_f32_16x16x32_bf16 v[32:35], v[196:199], v[222:225], v[32:35]
	v_mfma_f32_16x16x32_bf16 v[20:23], v[188:191], v[230:233], v[20:23]
	v_mfma_f32_16x16x32_bf16 v[16:19], v[196:199], v[230:233], v[16:19]
	v_mfma_f32_16x16x32_bf16 v[4:7], v[188:191], v[238:241], v[4:7]
	v_mfma_f32_16x16x32_bf16 v[0:3], v[196:199], v[238:241], v[0:3]
	s_setprio 0
	s_barrier
	v_lshl_add_u64 v[128:129], v[128:129], 0, s[34:35]
	s_cmp_ge_i32 s12, s58
	v_lshl_add_u64 v[130:131], v[130:131], 0, s[34:35]
	s_cbranch_scc0 .LBB0_454

; #define PG8_STAGE(bufoff, gbase, voff) do { _Pragma("unroll") for (int _i = 0; _i < 2; ++_i) \
;         __builtin_amdgcn_global_load_lds((const unsigned*)((const char*)(gbase) + (voff)[_i]), (PG8_LAS unsigned*)(lds + (bufoff) + ldsw + _i * 8192), 16, 0, 0); } while (0)
; #define PG8_LDA(dst, b, h) do { _Pragma("unroll") for (int m = 0; m < 4; ++m) _Pragma("unroll") for (int k = 0; k < 2; ++k) dst[m][k] = *(const PG8_LAS bf16x8*)(lds + PG8_SA(b, h) + aoff + m * 2048 + k * 1024); } while (0)
; #define PG8_LDB(dst, b, h) do { _Pragma("unroll") for (int n = 0; n < 2; ++n) _Pragma("unroll") for (int k = 0; k < 2; ++k) dst[n][k] = *(const PG8_LAS bf16x8*)(lds + PG8_SB(b, h) + boff + n * 2048 + k * 1024); } while (0)
; #define PG8_MMA(ai, bj, At, Bt) do { __builtin_amdgcn_s_setprio(1); _Pragma("unroll") for (int m = 0; m < 4; ++m) _Pragma("unroll") for (int n = 0; n < 2; ++n) _Pragma("unroll") for (int k = 0; k < 2; ++k) \
;         acc[ai][bj][m][n] = __builtin_amdgcn_mfma_f32_16x16x32_bf16(Bt[n][k], At[m][k], acc[ai][bj][m][n], 0, 0, 0); __builtin_amdgcn_s_setprio(0); } while (0)
; #define PG8_WAIT_V(n) asm volatile("s_waitcnt vmcnt(" #n ")" ::: "memory")
; #define PG8_WAIT_L(n) asm volatile("s_waitcnt lgkmcnt(" #n ")" ::: "memory")
; #define PG8_BAR __builtin_amdgcn_s_barrier()
; template <class Epi, class Sched, bool ALIGN_EPI = false, bool SP2 = false>
; __device__ __forceinline__ void gemm_phase(PG8_LAS unsigned char* lds, const Gemm g, const Sched& S, const Epi& E) {
;     ...
;             const char* a1 = cA + (size_t)(t + 1) * kstep;
;             const char* a2 = last ? nA : cA + (size_t)(t + 2) * kstep; const char* b2 = last ? nB : cB + (size_t)(t + 2) * kstep;
;             const char* a3 = a2 + kstep; const char* b3 = b2 + kstep;
;             if (last && has_next) S.a_ready(nxt);
;             if constexpr (SP2) {
;             PG8_LDB(B0, 0, 0); PG8_LDB(B1, 0, 1); PG8_SCHED; PG8_LDA(At, 0, 0); PG8_STAGE(PG8_SA(1, 1), a1 + hstep, voffA);
;             PG8_WAIT_V(8); PG8_WAIT_L(0); PG8_BAR; PG8_MMA(0, 0, At, B0); PG8_MMA(0, 1, At, B1); PG8_BAR; PG8_SCHED;
;             PG8_LDA(At, 0, 1); PG8_STAGE(PG8_SB(0, 0), b2, voffB); PG8_STAGE(PG8_SB(0, 1), b2 + hstep, voffB); PG8_STAGE(PG8_SA(0, 0), a2, voffA);
;             PG8_WAIT_V(8); PG8_WAIT_L(0); PG8_BAR; PG8_MMA(1, 0, At, B0); PG8_MMA(1, 1, At, B1); PG8_BAR; PG8_SCHED;
.LBB0_635:
	v_add_u32_e32 v144, s64, v209
	v_add_u32_e32 v194, s65, v209
	ds_read_b128 v[92:95], v144
	ds_read_b128 v[128:131], v144 offset:1024
	ds_read_b128 v[132:135], v144 offset:2048
	ds_read_b128 v[144:147], v144 offset:3072
	ds_read_b128 v[148:151], v194
	ds_read_b128 v[152:155], v194 offset:1024
	ds_read_b128 v[190:193], v194 offset:2048
	ds_read_b128 v[194:197], v194 offset:3072
	s_cmp_eq_u32 s58, s10
	v_lshl_add_u64 v[198:199], v[90:91], 0, s[24:25]
	s_cselect_b64 vcc, -1, 0
	s_add_i32 s10, s10, 2
	v_cndmask_b32_e32 v207, v199, v187, vcc
	v_cndmask_b32_e32 v206, v198, v186, vcc
	v_cndmask_b32_e32 v215, v89, v189, vcc
	v_cndmask_b32_e32 v214, v88, v188, vcc
	v_lshl_add_u64 v[238:239], v[90:91], 0, v[180:181]
	s_add_i32 m0, s41, 0xc000
	ds_read_b128 v[198:201], v216
	ds_read_b128 v[202:205], v216 offset:1024
	ds_read_b128 v[210:213], v216 offset:2048
	ds_read_b128 v[218:221], v216 offset:3072
	ds_read_b128 v[222:225], v216 offset:4096
	ds_read_b128 v[226:229], v216 offset:5120
	ds_read_b128 v[230:233], v216 offset:6144
	ds_read_b128 v[234:237], v216 offset:7168
	global_load_lds_dwordx4 v[238:239], off
	v_lshl_add_u64 v[238:239], v[90:91], 0, v[178:179]
	s_add_i32 m0, s41, 0xe000
	s_nop 0
	global_load_lds_dwordx4 v[238:239], off
	s_waitcnt vmcnt(8)
	s_waitcnt lgkmcnt(0)
	s_setprio 1
	s_barrier
	v_mfma_f32_16x16x32_bf16 v[140:143], v[92:95], v[198:201], v[140:143]
	v_mfma_f32_16x16x32_bf16 v[136:139], v[132:135], v[198:201], v[136:139]
	v_mfma_f32_16x16x32_bf16 v[116:119], v[92:95], v[210:213], v[116:119]
	v_mfma_f32_16x16x32_bf16 v[112:115], v[132:135], v[210:213], v[112:115]
	v_mfma_f32_16x16x32_bf16 v[100:103], v[92:95], v[222:225], v[100:103]
	v_mfma_f32_16x16x32_bf16 v[96:99], v[132:135], v[222:225], v[96:99]
	v_mfma_f32_16x16x32_bf16 v[76:79], v[92:95], v[230:233], v[76:79]
	v_mfma_f32_16x16x32_bf16 v[72:75], v[132:135], v[230:233], v[72:75]
	v_mfma_f32_16x16x32_bf16 v[140:143], v[128:131], v[202:205], v[140:143]
	v_mfma_f32_16x16x32_bf16 v[136:139], v[144:147], v[202:205], v[136:139]
	v_mfma_f32_16x16x32_bf16 v[116:119], v[128:131], v[218:221], v[116:119]
	v_mfma_f32_16x16x32_bf16 v[112:115], v[144:147], v[218:221], v[112:115]
	v_mfma_f32_16x16x32_bf16 v[100:103], v[128:131], v[226:229], v[100:103]
	v_mfma_f32_16x16x32_bf16 v[96:99], v[144:147], v[226:229], v[96:99]
	v_mfma_f32_16x16x32_bf16 v[76:79], v[128:131], v[234:237], v[76:79]
	v_mfma_f32_16x16x32_bf16 v[72:75], v[144:147], v[234:237], v[72:75]
	v_mfma_f32_16x16x32_bf16 v[124:127], v[148:151], v[198:201], v[124:127]
	v_mfma_f32_16x16x32_bf16 v[120:123], v[190:193], v[198:201], v[120:123]
	v_mfma_f32_16x16x32_bf16 v[108:111], v[148:151], v[210:213], v[108:111]
	v_mfma_f32_16x16x32_bf16 v[104:107], v[190:193], v[210:213], v[104:107]
	v_mfma_f32_16x16x32_bf16 v[84:87], v[148:151], v[222:225], v[84:87]
	v_mfma_f32_16x16x32_bf16 v[80:83], v[190:193], v[222:225], v[80:83]
	v_mfma_f32_16x16x32_bf16 v[68:71], v[148:151], v[230:233], v[68:71]
	v_mfma_f32_16x16x32_bf16 v[64:67], v[190:193], v[230:233], v[64:67]
	v_mfma_f32_16x16x32_bf16 v[124:127], v[152:155], v[202:205], v[124:127]
	v_mfma_f32_16x16x32_bf16 v[120:123], v[194:197], v[202:205], v[120:123]
	v_mfma_f32_16x16x32_bf16 v[108:111], v[152:155], v[218:221], v[108:111]
	v_mfma_f32_16x16x32_bf16 v[104:107], v[194:197], v[218:221], v[104:107]
	v_mfma_f32_16x16x32_bf16 v[84:87], v[152:155], v[226:229], v[84:87]
	v_mfma_f32_16x16x32_bf16 v[80:83], v[194:197], v[226:229], v[80:83]
	v_mfma_f32_16x16x32_bf16 v[68:71], v[152:155], v[234:237], v[68:71]
	v_mfma_f32_16x16x32_bf16 v[64:67], v[194:197], v[234:237], v[64:67]
	s_setprio 0
	s_barrier
	s_add_i32 s11, s64, s35
	v_lshl_add_u64 v[238:239], v[214:215], 0, v[168:169]
	s_mov_b32 m0, s11
	ds_read_b128 v[198:201], v216 offset:16384
	ds_read_b128 v[202:205], v216 offset:17408
	ds_read_b128 v[210:213], v216 offset:18432
	ds_read_b128 v[218:221], v216 offset:19456
	ds_read_b128 v[222:225], v216 offset:20480
	ds_read_b128 v[226:229], v216 offset:21504
	ds_read_b128 v[230:233], v216 offset:22528
	ds_read_b128 v[234:237], v216 offset:23552
	global_load_lds_dwordx4 v[238:239], off
	v_lshl_add_u64 v[240:241], v[214:215], 0, v[172:173]
	s_add_i32 m0, s11, 0x2000
	v_lshl_add_u64 v[214:215], v[214:215], 0, s[18:19]
	s_add_i32 s11, s65, s35
	global_load_lds_dwordx4 v[240:241], off
	v_lshl_add_u64 v[242:243], v[214:215], 0, v[168:169]
	s_mov_b32 m0, s11
	v_lshl_add_u64 v[214:215], v[214:215], 0, v[172:173]
	global_load_lds_dwordx4 v[242:243], off
	s_add_i32 m0, s11, 0x2000
	v_lshl_add_u64 v[244:245], v[206:207], 0, v[166:167]
	global_load_lds_dwordx4 v[214:215], off
	s_mov_b32 m0, s41
	v_lshl_add_u64 v[246:247], v[206:207], 0, v[170:171]
	global_load_lds_dwordx4 v[244:245], off
	s_mov_b32 m0, s50
	s_nop 0
	global_load_lds_dwordx4 v[246:247], off
	s_waitcnt vmcnt(8)
	s_waitcnt lgkmcnt(0)
	s_setprio 1
	s_barrier
; #define PG8_STAGE(bufoff, gbase, voff) do { _Pragma("unroll") for (int _i = 0; _i < 2; ++_i) \
;         __builtin_amdgcn_global_load_lds((const unsigned*)((const char*)(gbase) + (voff)[_i]), (PG8_LAS unsigned*)(lds + (bufoff) + ldsw + _i * 8192), 16, 0, 0); } while (0)
; #define PG8_LDA(dst, b, h) do { _Pragma("unroll") for (int m = 0; m < 4; ++m) _Pragma("unroll") for (int k = 0; k < 2; ++k) dst[m][k] = *(const PG8_LAS bf16x8*)(lds + PG8_SA(b, h) + aoff + m * 2048 + k * 1024); } while (0)
; #define PG8_LDB(dst, b, h) do { _Pragma("unroll") for (int n = 0; n < 2; ++n) _Pragma("unroll") for (int k = 0; k < 2; ++k) dst[n][k] = *(const PG8_LAS bf16x8*)(lds + PG8_SB(b, h) + boff + n * 2048 + k * 1024); } while (0)
; #define PG8_MMA(ai, bj, At, Bt) do { __builtin_amdgcn_s_setprio(1); _Pragma("unroll") for (int m = 0; m < 4; ++m) _Pragma("unroll") for (int n = 0; n < 2; ++n) _Pragma("unroll") for (int k = 0; k < 2; ++k) \
;         acc[ai][bj][m][n] = __builtin_amdgcn_mfma_f32_16x16x32_bf16(Bt[n][k], At[m][k], acc[ai][bj][m][n], 0, 0, 0); __builtin_amdgcn_s_setprio(0); } while (0)
; #define PG8_WAIT_V(n) asm volatile("s_waitcnt vmcnt(" #n ")" ::: "memory")
; #define PG8_WAIT_L(n) asm volatile("s_waitcnt lgkmcnt(" #n ")" ::: "memory")
; #define PG8_BAR __builtin_amdgcn_s_barrier()
; #define PG8_SCHED __builtin_amdgcn_sched_barrier(0)
; template <class Epi, class Sched, bool ALIGN_EPI = false, bool SP2 = false>
; __device__ __forceinline__ void gemm_phase(PG8_LAS unsigned char* lds, const Gemm g, const Sched& S, const Epi& E) {
;     ...
;             PG8_WAIT_V(8); PG8_WAIT_L(0); PG8_BAR; PG8_MMA(1, 0, At, B0); PG8_MMA(1, 1, At, B1); PG8_BAR; PG8_SCHED;
;             PG8_LDB(B0, 1, 0); PG8_LDB(B1, 1, 1); PG8_SCHED; PG8_LDA(At, 1, 0); PG8_STAGE(PG8_SA(0, 1), a2 + hstep, voffA);
;             PG8_WAIT_V(8); PG8_WAIT_L(0); PG8_BAR; PG8_MMA(0, 0, At, B0); PG8_MMA(0, 1, At, B1); PG8_BAR; PG8_SCHED;
	v_mfma_f32_16x16x32_bf16 v[60:63], v[92:95], v[198:201], v[60:63]
	v_mfma_f32_16x16x32_bf16 v[56:59], v[132:135], v[198:201], v[56:59]
	v_mfma_f32_16x16x32_bf16 v[44:47], v[92:95], v[210:213], v[44:47]
	v_mfma_f32_16x16x32_bf16 v[40:43], v[132:135], v[210:213], v[40:43]
	v_mfma_f32_16x16x32_bf16 v[28:31], v[92:95], v[222:225], v[28:31]
	v_mfma_f32_16x16x32_bf16 v[24:27], v[132:135], v[222:225], v[24:27]
	v_mfma_f32_16x16x32_bf16 v[12:15], v[92:95], v[230:233], v[12:15]
	v_mfma_f32_16x16x32_bf16 v[8:11], v[132:135], v[230:233], v[8:11]
	v_mfma_f32_16x16x32_bf16 v[60:63], v[128:131], v[202:205], v[60:63]
	v_mfma_f32_16x16x32_bf16 v[56:59], v[144:147], v[202:205], v[56:59]
	v_mfma_f32_16x16x32_bf16 v[44:47], v[128:131], v[218:221], v[44:47]
	v_mfma_f32_16x16x32_bf16 v[40:43], v[144:147], v[218:221], v[40:43]
	v_mfma_f32_16x16x32_bf16 v[28:31], v[128:131], v[226:229], v[28:31]
	v_mfma_f32_16x16x32_bf16 v[24:27], v[144:147], v[226:229], v[24:27]
	v_mfma_f32_16x16x32_bf16 v[12:15], v[128:131], v[234:237], v[12:15]
	v_mfma_f32_16x16x32_bf16 v[8:11], v[144:147], v[234:237], v[8:11]
	v_mfma_f32_16x16x32_bf16 v[52:55], v[148:151], v[198:201], v[52:55]
	v_mfma_f32_16x16x32_bf16 v[48:51], v[190:193], v[198:201], v[48:51]
	v_mfma_f32_16x16x32_bf16 v[36:39], v[148:151], v[210:213], v[36:39]
	v_mfma_f32_16x16x32_bf16 v[32:35], v[190:193], v[210:213], v[32:35]
	v_mfma_f32_16x16x32_bf16 v[20:23], v[148:151], v[222:225], v[20:23]
	v_mfma_f32_16x16x32_bf16 v[16:19], v[190:193], v[222:225], v[16:19]
	v_mfma_f32_16x16x32_bf16 v[4:7], v[148:151], v[230:233], v[4:7]
	v_mfma_f32_16x16x32_bf16 v[0:3], v[190:193], v[230:233], v[0:3]
	v_mfma_f32_16x16x32_bf16 v[52:55], v[152:155], v[202:205], v[52:55]
	v_mfma_f32_16x16x32_bf16 v[48:51], v[194:197], v[202:205], v[48:51]
	v_mfma_f32_16x16x32_bf16 v[36:39], v[152:155], v[218:221], v[36:39]
	v_mfma_f32_16x16x32_bf16 v[32:35], v[194:197], v[218:221], v[32:35]
	v_mfma_f32_16x16x32_bf16 v[20:23], v[152:155], v[226:229], v[20:23]
	v_mfma_f32_16x16x32_bf16 v[16:19], v[194:197], v[226:229], v[16:19]
	v_mfma_f32_16x16x32_bf16 v[4:7], v[152:155], v[234:237], v[4:7]
	v_mfma_f32_16x16x32_bf16 v[0:3], v[194:197], v[234:237], v[0:3]
	s_setprio 0
	s_barrier
	s_add_i32 s11, 0, 0x18000
	s_add_i32 s14, 0, 0x1c000
	v_add_u32_e32 v144, s11, v209
	v_add_u32_e32 v194, s14, v209
	ds_read_b128 v[92:95], v144
	ds_read_b128 v[128:131], v144 offset:1024
	ds_read_b128 v[132:135], v144 offset:2048
	ds_read_b128 v[144:147], v144 offset:3072
	ds_read_b128 v[148:151], v194
	ds_read_b128 v[152:155], v194 offset:1024
	ds_read_b128 v[190:193], v194 offset:2048
	ds_read_b128 v[194:197], v194 offset:3072
	v_lshl_add_u64 v[206:207], v[206:207], 0, s[18:19]
	s_mov_b32 m0, s51
	v_lshl_add_u64 v[248:249], v[206:207], 0, v[166:167]
	ds_read_b128 v[198:201], v216 offset:32768
	ds_read_b128 v[202:205], v216 offset:33792
	ds_read_b128 v[210:213], v216 offset:34816
	ds_read_b128 v[218:221], v216 offset:35840
	ds_read_b128 v[222:225], v216 offset:36864
	ds_read_b128 v[226:229], v216 offset:37888
	ds_read_b128 v[230:233], v216 offset:38912
	ds_read_b128 v[234:237], v216 offset:39936
	global_load_lds_dwordx4 v[248:249], off
	v_lshl_add_u64 v[206:207], v[206:207], 0, v[170:171]
	s_mov_b32 m0, s52
	s_nop 0
	global_load_lds_dwordx4 v[206:207], off
	s_waitcnt vmcnt(8)
	s_waitcnt lgkmcnt(0)
	s_setprio 1
	s_barrier
	v_mfma_f32_16x16x32_bf16 v[140:143], v[92:95], v[198:201], v[140:143]
	v_mfma_f32_16x16x32_bf16 v[136:139], v[132:135], v[198:201], v[136:139]
	v_mfma_f32_16x16x32_bf16 v[116:119], v[92:95], v[210:213], v[116:119]
	v_mfma_f32_16x16x32_bf16 v[112:115], v[132:135], v[210:213], v[112:115]
	v_mfma_f32_16x16x32_bf16 v[100:103], v[92:95], v[222:225], v[100:103]
	v_mfma_f32_16x16x32_bf16 v[96:99], v[132:135], v[222:225], v[96:99]
	v_mfma_f32_16x16x32_bf16 v[76:79], v[92:95], v[230:233], v[76:79]
	v_mfma_f32_16x16x32_bf16 v[72:75], v[132:135], v[230:233], v[72:75]
	v_mfma_f32_16x16x32_bf16 v[140:143], v[128:131], v[202:205], v[140:143]
	v_mfma_f32_16x16x32_bf16 v[136:139], v[144:147], v[202:205], v[136:139]
	v_mfma_f32_16x16x32_bf16 v[116:119], v[128:131], v[218:221], v[116:119]
	v_mfma_f32_16x16x32_bf16 v[112:115], v[144:147], v[218:221], v[112:115]
	v_mfma_f32_16x16x32_bf16 v[100:103], v[128:131], v[226:229], v[100:103]
	v_mfma_f32_16x16x32_bf16 v[96:99], v[144:147], v[226:229], v[96:99]
	v_mfma_f32_16x16x32_bf16 v[76:79], v[128:131], v[234:237], v[76:79]
	v_mfma_f32_16x16x32_bf16 v[72:75], v[144:147], v[234:237], v[72:75]
	v_mfma_f32_16x16x32_bf16 v[124:127], v[148:151], v[198:201], v[124:127]
	v_mfma_f32_16x16x32_bf16 v[120:123], v[190:193], v[198:201], v[120:123]
	v_mfma_f32_16x16x32_bf16 v[108:111], v[148:151], v[210:213], v[108:111]
	v_mfma_f32_16x16x32_bf16 v[104:107], v[190:193], v[210:213], v[104:107]
	v_mfma_f32_16x16x32_bf16 v[84:87], v[148:151], v[222:225], v[84:87]
	v_mfma_f32_16x16x32_bf16 v[80:83], v[190:193], v[222:225], v[80:83]
	v_mfma_f32_16x16x32_bf16 v[68:71], v[148:151], v[230:233], v[68:71]
	v_mfma_f32_16x16x32_bf16 v[64:67], v[190:193], v[230:233], v[64:67]
	v_mfma_f32_16x16x32_bf16 v[124:127], v[152:155], v[202:205], v[124:127]
	v_mfma_f32_16x16x32_bf16 v[120:123], v[194:197], v[202:205], v[120:123]
	v_mfma_f32_16x16x32_bf16 v[108:111], v[152:155], v[218:221], v[108:111]
	v_mfma_f32_16x16x32_bf16 v[104:107], v[194:197], v[218:221], v[104:107]
	v_mfma_f32_16x16x32_bf16 v[84:87], v[152:155], v[226:229], v[84:87]
	v_mfma_f32_16x16x32_bf16 v[80:83], v[194:197], v[226:229], v[80:83]
	v_mfma_f32_16x16x32_bf16 v[68:71], v[152:155], v[234:237], v[68:71]
	v_mfma_f32_16x16x32_bf16 v[64:67], v[194:197], v[234:237], v[64:67]
	s_setprio 0
	s_barrier
; #define PG8_STAGE(bufoff, gbase, voff) do { _Pragma("unroll") for (int _i = 0; _i < 2; ++_i) \
;         __builtin_amdgcn_global_load_lds((const unsigned*)((const char*)(gbase) + (voff)[_i]), (PG8_LAS unsigned*)(lds + (bufoff) + ldsw + _i * 8192), 16, 0, 0); } while (0)
; #define PG8_LDA(dst, b, h) do { _Pragma("unroll") for (int m = 0; m < 4; ++m) _Pragma("unroll") for (int k = 0; k < 2; ++k) dst[m][k] = *(const PG8_LAS bf16x8*)(lds + PG8_SA(b, h) + aoff + m * 2048 + k * 1024); } while (0)
; #define PG8_MMA(ai, bj, At, Bt) do { __builtin_amdgcn_s_setprio(1); _Pragma("unroll") for (int m = 0; m < 4; ++m) _Pragma("unroll") for (int n = 0; n < 2; ++n) _Pragma("unroll") for (int k = 0; k < 2; ++k) \
;         acc[ai][bj][m][n] = __builtin_amdgcn_mfma_f32_16x16x32_bf16(Bt[n][k], At[m][k], acc[ai][bj][m][n], 0, 0, 0); __builtin_amdgcn_s_setprio(0); } while (0)
; #define PG8_WAIT_V(n) asm volatile("s_waitcnt vmcnt(" #n ")" ::: "memory")
; #define PG8_WAIT_L(n) asm volatile("s_waitcnt lgkmcnt(" #n ")" ::: "memory")
; #define PG8_BAR __builtin_amdgcn_s_barrier()
; #define PG8_SCHED __builtin_amdgcn_sched_barrier(0)
; template <class Epi, class Sched, bool ALIGN_EPI = false, bool SP2 = false>
; __device__ __forceinline__ void gemm_phase(PG8_LAS unsigned char* lds, const Gemm g, const Sched& S, const Epi& E) {
;     ...
;             PG8_LDA(At, 1, 1); PG8_STAGE(PG8_SB(1, 0), b3, voffB); PG8_STAGE(PG8_SB(1, 1), b3 + hstep, voffB); PG8_STAGE(PG8_SA(1, 0), a3, voffA);
;             PG8_WAIT_V(8); PG8_WAIT_L(0); PG8_BAR; PG8_MMA(1, 0, At, B0); PG8_MMA(1, 1, At, B1); PG8_BAR; PG8_SCHED;
	s_add_i32 s11, s11, s35
	v_lshl_add_u64 v[206:207], v[238:239], 0, s[24:25]
	s_mov_b32 m0, s11
	ds_read_b128 v[198:201], v216 offset:49152
	ds_read_b128 v[202:205], v216 offset:50176
	ds_read_b128 v[210:213], v216 offset:51200
	ds_read_b128 v[218:221], v216 offset:52224
	ds_read_b128 v[222:225], v216 offset:53248
	ds_read_b128 v[226:229], v216 offset:54272
	ds_read_b128 v[230:233], v216 offset:55296
	ds_read_b128 v[234:237], v216 offset:56320
	global_load_lds_dwordx4 v[206:207], off
	v_lshl_add_u64 v[206:207], v[240:241], 0, s[24:25]
	s_add_i32 m0, s11, 0x2000
	s_add_i32 s11, s14, s35
	global_load_lds_dwordx4 v[206:207], off
	v_lshl_add_u64 v[206:207], v[242:243], 0, s[24:25]
	s_mov_b32 m0, s11
	s_nop 0
	global_load_lds_dwordx4 v[206:207], off
	v_lshl_add_u64 v[206:207], v[214:215], 0, s[24:25]
	s_add_i32 m0, s11, 0x2000
	s_nop 0
	global_load_lds_dwordx4 v[206:207], off
	v_lshl_add_u64 v[206:207], v[244:245], 0, s[24:25]
	s_mov_b32 m0, s54
	s_nop 0
	global_load_lds_dwordx4 v[206:207], off
	v_lshl_add_u64 v[206:207], v[246:247], 0, s[24:25]
	s_mov_b32 m0, s55
	s_nop 0
	global_load_lds_dwordx4 v[206:207], off
	s_waitcnt vmcnt(8)
	s_waitcnt lgkmcnt(0)
	s_setprio 1
	s_barrier
	v_mfma_f32_16x16x32_bf16 v[60:63], v[92:95], v[198:201], v[60:63]
	v_mfma_f32_16x16x32_bf16 v[56:59], v[132:135], v[198:201], v[56:59]
	v_mfma_f32_16x16x32_bf16 v[44:47], v[92:95], v[210:213], v[44:47]
	v_mfma_f32_16x16x32_bf16 v[40:43], v[132:135], v[210:213], v[40:43]
	v_mfma_f32_16x16x32_bf16 v[28:31], v[92:95], v[222:225], v[28:31]
	v_mfma_f32_16x16x32_bf16 v[24:27], v[132:135], v[222:225], v[24:27]
	v_mfma_f32_16x16x32_bf16 v[12:15], v[92:95], v[230:233], v[12:15]
	v_mfma_f32_16x16x32_bf16 v[8:11], v[132:135], v[230:233], v[8:11]
	v_mfma_f32_16x16x32_bf16 v[60:63], v[128:131], v[202:205], v[60:63]
	v_mfma_f32_16x16x32_bf16 v[56:59], v[144:147], v[202:205], v[56:59]
	v_mfma_f32_16x16x32_bf16 v[44:47], v[128:131], v[218:221], v[44:47]
	v_mfma_f32_16x16x32_bf16 v[40:43], v[144:147], v[218:221], v[40:43]
	v_mfma_f32_16x16x32_bf16 v[28:31], v[128:131], v[226:229], v[28:31]
	v_mfma_f32_16x16x32_bf16 v[24:27], v[144:147], v[226:229], v[24:27]
	v_mfma_f32_16x16x32_bf16 v[12:15], v[128:131], v[234:237], v[12:15]
	v_mfma_f32_16x16x32_bf16 v[8:11], v[144:147], v[234:237], v[8:11]
	v_mfma_f32_16x16x32_bf16 v[52:55], v[148:151], v[198:201], v[52:55]
	v_mfma_f32_16x16x32_bf16 v[48:51], v[190:193], v[198:201], v[48:51]
	v_mfma_f32_16x16x32_bf16 v[36:39], v[148:151], v[210:213], v[36:39]
	v_mfma_f32_16x16x32_bf16 v[32:35], v[190:193], v[210:213], v[32:35]
	v_mfma_f32_16x16x32_bf16 v[20:23], v[148:151], v[222:225], v[20:23]
	v_mfma_f32_16x16x32_bf16 v[16:19], v[190:193], v[222:225], v[16:19]
	v_mfma_f32_16x16x32_bf16 v[4:7], v[148:151], v[230:233], v[4:7]
	v_mfma_f32_16x16x32_bf16 v[0:3], v[190:193], v[230:233], v[0:3]
	v_mfma_f32_16x16x32_bf16 v[52:55], v[152:155], v[202:205], v[52:55]
	v_mfma_f32_16x16x32_bf16 v[48:51], v[194:197], v[202:205], v[48:51]
	v_mfma_f32_16x16x32_bf16 v[36:39], v[152:155], v[218:221], v[36:39]
	v_mfma_f32_16x16x32_bf16 v[32:35], v[194:197], v[218:221], v[32:35]
	v_mfma_f32_16x16x32_bf16 v[20:23], v[152:155], v[226:229], v[20:23]
	v_mfma_f32_16x16x32_bf16 v[16:19], v[194:197], v[226:229], v[16:19]
	v_mfma_f32_16x16x32_bf16 v[4:7], v[152:155], v[234:237], v[4:7]
	v_mfma_f32_16x16x32_bf16 v[0:3], v[194:197], v[234:237], v[0:3]
	s_setprio 0
	s_barrier
	v_lshl_add_u64 v[88:89], v[88:89], 0, s[30:31]
	s_cmp_ge_i32 s10, s57
	v_lshl_add_u64 v[90:91], v[90:91], 0, s[30:31]
	s_cbranch_scc0 .LBB0_635

; #define PG8_STAGE(bufoff, gbase, voff) do { _Pragma("unroll") for (int _i = 0; _i < 2; ++_i) \
;         __builtin_amdgcn_global_load_lds((const unsigned*)((const char*)(gbase) + (voff)[_i]), (PG8_LAS unsigned*)(lds + (bufoff) + ldsw + _i * 8192), 16, 0, 0); } while (0)
; #define PG8_LDA(dst, b, h) do { _Pragma("unroll") for (int m = 0; m < 4; ++m) _Pragma("unroll") for (int k = 0; k < 2; ++k) dst[m][k] = *(const PG8_LAS bf16x8*)(lds + PG8_SA(b, h) + aoff + m * 2048 + k * 1024); } while (0)
; #define PG8_LDB(dst, b, h) do { _Pragma("unroll") for (int n = 0; n < 2; ++n) _Pragma("unroll") for (int k = 0; k < 2; ++k) dst[n][k] = *(const PG8_LAS bf16x8*)(lds + PG8_SB(b, h) + boff + n * 2048 + k * 1024); } while (0)
; #define PG8_MMA(ai, bj, At, Bt) do { __builtin_amdgcn_s_setprio(1); _Pragma("unroll") for (int m = 0; m < 4; ++m) _Pragma("unroll") for (int n = 0; n < 2; ++n) _Pragma("unroll") for (int k = 0; k < 2; ++k) \
;         acc[ai][bj][m][n] = __builtin_amdgcn_mfma_f32_16x16x32_bf16(Bt[n][k], At[m][k], acc[ai][bj][m][n], 0, 0, 0); __builtin_amdgcn_s_setprio(0); } while (0)
; #define PG8_WAIT_V(n) asm volatile("s_waitcnt vmcnt(" #n ")" ::: "memory")
; #define PG8_WAIT_L(n) asm volatile("s_waitcnt lgkmcnt(" #n ")" ::: "memory")
; #define PG8_BAR __builtin_amdgcn_s_barrier()
; template <class Epi, class Sched, bool ALIGN_EPI = false, bool SP2 = false>
; __device__ __forceinline__ void gemm_phase(PG8_LAS unsigned char* lds, const Gemm g, const Sched& S, const Epi& E) {
;     ...
;             const char* a1 = cA + (size_t)(t + 1) * kstep;
;             const char* a2 = last ? nA : cA + (size_t)(t + 2) * kstep; const char* b2 = last ? nB : cB + (size_t)(t + 2) * kstep;
;             const char* a3 = a2 + kstep; const char* b3 = b2 + kstep;
;             if (last && has_next) S.a_ready(nxt);
;             if constexpr (SP2) {
;             PG8_LDB(B0, 0, 0); PG8_LDB(B1, 0, 1); PG8_SCHED; PG8_LDA(At, 0, 0); PG8_STAGE(PG8_SA(1, 1), a1 + hstep, voffA);
;             PG8_WAIT_V(8); PG8_WAIT_L(0); PG8_BAR; PG8_MMA(0, 0, At, B0); PG8_MMA(0, 1, At, B1); PG8_BAR; PG8_SCHED;
;             PG8_LDA(At, 0, 1); PG8_STAGE(PG8_SB(0, 0), b2, voffB); PG8_STAGE(PG8_SB(0, 1), b2 + hstep, voffB); PG8_STAGE(PG8_SA(0, 0), a2, voffA);
;             PG8_WAIT_V(8); PG8_WAIT_L(0); PG8_BAR; PG8_MMA(1, 0, At, B0); PG8_MMA(1, 1, At, B1); PG8_BAR; PG8_SCHED;
.LBB0_722:
	v_add_u32_e32 v144, s59, v183
	v_add_u32_e32 v170, s60, v183
	ds_read_b128 v[116:119], v144
	ds_read_b128 v[136:139], v144 offset:1024
	ds_read_b128 v[140:143], v144 offset:2048
	ds_read_b128 v[144:147], v144 offset:3072
	ds_read_b128 v[148:151], v170
	ds_read_b128 v[188:191], v170 offset:1024
	ds_read_b128 v[192:195], v170 offset:2048
	ds_read_b128 v[198:201], v170 offset:3072
	s_cmp_eq_u32 s53, s8
	v_lshl_add_u64 v[204:205], v[114:115], 0, s[18:19]
	s_cselect_b64 vcc, -1, 0
	s_add_i32 s8, s8, 2
	v_cndmask_b32_e32 v213, v205, v185, vcc
	v_cndmask_b32_e32 v212, v204, v184, vcc
	v_cndmask_b32_e32 v215, v113, v187, vcc
	v_cndmask_b32_e32 v214, v112, v186, vcc
	v_lshl_add_u64 v[240:241], v[114:115], 0, v[178:179]
	s_add_i32 m0, s34, 0xc000
	ds_read_b128 v[204:207], v202
	ds_read_b128 v[208:211], v202 offset:1024
	ds_read_b128 v[216:219], v202 offset:2048
	ds_read_b128 v[220:223], v202 offset:3072
	ds_read_b128 v[224:227], v202 offset:4096
	ds_read_b128 v[228:231], v202 offset:5120
	ds_read_b128 v[232:235], v202 offset:6144
	ds_read_b128 v[236:239], v202 offset:7168
	global_load_lds_dwordx4 v[240:241], off
	v_lshl_add_u64 v[240:241], v[114:115], 0, v[176:177]
	s_add_i32 m0, s34, 0xe000
	s_nop 0
	global_load_lds_dwordx4 v[240:241], off
	s_waitcnt vmcnt(8)
	s_waitcnt lgkmcnt(0)
	s_setprio 1
	s_barrier
	v_mfma_f32_16x16x32_bf16 v[132:135], v[116:119], v[204:207], v[132:135]
	v_mfma_f32_16x16x32_bf16 v[128:131], v[140:143], v[204:207], v[128:131]
	v_mfma_f32_16x16x32_bf16 v[108:111], v[116:119], v[216:219], v[108:111]
	v_mfma_f32_16x16x32_bf16 v[104:107], v[140:143], v[216:219], v[104:107]
	v_mfma_f32_16x16x32_bf16 v[92:95], v[116:119], v[224:227], v[92:95]
	v_mfma_f32_16x16x32_bf16 v[88:91], v[140:143], v[224:227], v[88:91]
	v_mfma_f32_16x16x32_bf16 v[76:79], v[116:119], v[232:235], v[76:79]
	v_mfma_f32_16x16x32_bf16 v[72:75], v[140:143], v[232:235], v[72:75]
	v_mfma_f32_16x16x32_bf16 v[132:135], v[136:139], v[208:211], v[132:135]
	v_mfma_f32_16x16x32_bf16 v[128:131], v[144:147], v[208:211], v[128:131]
	v_mfma_f32_16x16x32_bf16 v[108:111], v[136:139], v[220:223], v[108:111]
	v_mfma_f32_16x16x32_bf16 v[104:107], v[144:147], v[220:223], v[104:107]
	v_mfma_f32_16x16x32_bf16 v[92:95], v[136:139], v[228:231], v[92:95]
	v_mfma_f32_16x16x32_bf16 v[88:91], v[144:147], v[228:231], v[88:91]
	v_mfma_f32_16x16x32_bf16 v[76:79], v[136:139], v[236:239], v[76:79]
	v_mfma_f32_16x16x32_bf16 v[72:75], v[144:147], v[236:239], v[72:75]
	v_mfma_f32_16x16x32_bf16 v[124:127], v[148:151], v[204:207], v[124:127]
	v_mfma_f32_16x16x32_bf16 v[120:123], v[192:195], v[204:207], v[120:123]
	v_mfma_f32_16x16x32_bf16 v[100:103], v[148:151], v[216:219], v[100:103]
	v_mfma_f32_16x16x32_bf16 v[96:99], v[192:195], v[216:219], v[96:99]
	v_mfma_f32_16x16x32_bf16 v[84:87], v[148:151], v[224:227], v[84:87]
	v_mfma_f32_16x16x32_bf16 v[80:83], v[192:195], v[224:227], v[80:83]
	v_mfma_f32_16x16x32_bf16 v[68:71], v[148:151], v[232:235], v[68:71]
	v_mfma_f32_16x16x32_bf16 v[64:67], v[192:195], v[232:235], v[64:67]
	v_mfma_f32_16x16x32_bf16 v[124:127], v[188:191], v[208:211], v[124:127]
	v_mfma_f32_16x16x32_bf16 v[120:123], v[198:201], v[208:211], v[120:123]
	v_mfma_f32_16x16x32_bf16 v[100:103], v[188:191], v[220:223], v[100:103]
	v_mfma_f32_16x16x32_bf16 v[96:99], v[198:201], v[220:223], v[96:99]
	v_mfma_f32_16x16x32_bf16 v[84:87], v[188:191], v[228:231], v[84:87]
	v_mfma_f32_16x16x32_bf16 v[80:83], v[198:201], v[228:231], v[80:83]
	v_mfma_f32_16x16x32_bf16 v[68:71], v[188:191], v[236:239], v[68:71]
	v_mfma_f32_16x16x32_bf16 v[64:67], v[198:201], v[236:239], v[64:67]
	s_setprio 0
	s_barrier
	s_add_i32 s9, s59, s29
	v_lshl_add_u64 v[240:241], v[214:215], 0, v[164:165]
	s_mov_b32 m0, s9
	ds_read_b128 v[204:207], v202 offset:16384
	ds_read_b128 v[208:211], v202 offset:17408
	ds_read_b128 v[216:219], v202 offset:18432
	ds_read_b128 v[220:223], v202 offset:19456
	ds_read_b128 v[224:227], v202 offset:20480
	ds_read_b128 v[228:231], v202 offset:21504
	ds_read_b128 v[232:235], v202 offset:22528
	ds_read_b128 v[236:239], v202 offset:23552
	global_load_lds_dwordx4 v[240:241], off
	v_lshl_add_u64 v[242:243], v[214:215], 0, v[168:169]
	s_add_i32 m0, s9, 0x2000
	v_lshl_add_u64 v[214:215], v[214:215], 0, s[12:13]
	s_add_i32 s9, s60, s29
	global_load_lds_dwordx4 v[242:243], off
	v_lshl_add_u64 v[244:245], v[214:215], 0, v[164:165]
	s_mov_b32 m0, s9
	v_lshl_add_u64 v[214:215], v[214:215], 0, v[168:169]
	global_load_lds_dwordx4 v[244:245], off
	s_add_i32 m0, s9, 0x2000
	v_lshl_add_u64 v[246:247], v[212:213], 0, v[162:163]
	global_load_lds_dwordx4 v[214:215], off
	s_mov_b32 m0, s34
	v_lshl_add_u64 v[248:249], v[212:213], 0, v[166:167]
	global_load_lds_dwordx4 v[246:247], off
	s_mov_b32 m0, s36
	s_nop 0
	global_load_lds_dwordx4 v[248:249], off
	s_waitcnt vmcnt(8)
	s_waitcnt lgkmcnt(0)
	s_setprio 1
	s_barrier
; #define PG8_STAGE(bufoff, gbase, voff) do { _Pragma("unroll") for (int _i = 0; _i < 2; ++_i) \
;         __builtin_amdgcn_global_load_lds((const unsigned*)((const char*)(gbase) + (voff)[_i]), (PG8_LAS unsigned*)(lds + (bufoff) + ldsw + _i * 8192), 16, 0, 0); } while (0)
; #define PG8_LDA(dst, b, h) do { _Pragma("unroll") for (int m = 0; m < 4; ++m) _Pragma("unroll") for (int k = 0; k < 2; ++k) dst[m][k] = *(const PG8_LAS bf16x8*)(lds + PG8_SA(b, h) + aoff + m * 2048 + k * 1024); } while (0)
; #define PG8_LDB(dst, b, h) do { _Pragma("unroll") for (int n = 0; n < 2; ++n) _Pragma("unroll") for (int k = 0; k < 2; ++k) dst[n][k] = *(const PG8_LAS bf16x8*)(lds + PG8_SB(b, h) + boff + n * 2048 + k * 1024); } while (0)
; #define PG8_MMA(ai, bj, At, Bt) do { __builtin_amdgcn_s_setprio(1); _Pragma("unroll") for (int m = 0; m < 4; ++m) _Pragma("unroll") for (int n = 0; n < 2; ++n) _Pragma("unroll") for (int k = 0; k < 2; ++k) \
;         acc[ai][bj][m][n] = __builtin_amdgcn_mfma_f32_16x16x32_bf16(Bt[n][k], At[m][k], acc[ai][bj][m][n], 0, 0, 0); __builtin_amdgcn_s_setprio(0); } while (0)
; #define PG8_WAIT_V(n) asm volatile("s_waitcnt vmcnt(" #n ")" ::: "memory")
; #define PG8_WAIT_L(n) asm volatile("s_waitcnt lgkmcnt(" #n ")" ::: "memory")
; #define PG8_BAR __builtin_amdgcn_s_barrier()
; #define PG8_SCHED __builtin_amdgcn_sched_barrier(0)
; template <class Epi, class Sched, bool ALIGN_EPI = false, bool SP2 = false>
; __device__ __forceinline__ void gemm_phase(PG8_LAS unsigned char* lds, const Gemm g, const Sched& S, const Epi& E) {
;     ...
;             PG8_WAIT_V(8); PG8_WAIT_L(0); PG8_BAR; PG8_MMA(1, 0, At, B0); PG8_MMA(1, 1, At, B1); PG8_BAR; PG8_SCHED;
;             PG8_LDB(B0, 1, 0); PG8_LDB(B1, 1, 1); PG8_SCHED; PG8_LDA(At, 1, 0); PG8_STAGE(PG8_SA(0, 1), a2 + hstep, voffA);
;             PG8_WAIT_V(8); PG8_WAIT_L(0); PG8_BAR; PG8_MMA(0, 0, At, B0); PG8_MMA(0, 1, At, B1); PG8_BAR; PG8_SCHED;
	v_mfma_f32_16x16x32_bf16 v[60:63], v[116:119], v[204:207], v[60:63]
	v_mfma_f32_16x16x32_bf16 v[56:59], v[140:143], v[204:207], v[56:59]
	v_mfma_f32_16x16x32_bf16 v[44:47], v[116:119], v[216:219], v[44:47]
	v_mfma_f32_16x16x32_bf16 v[40:43], v[140:143], v[216:219], v[40:43]
	v_mfma_f32_16x16x32_bf16 v[28:31], v[116:119], v[224:227], v[28:31]
	v_mfma_f32_16x16x32_bf16 v[24:27], v[140:143], v[224:227], v[24:27]
	v_mfma_f32_16x16x32_bf16 v[12:15], v[116:119], v[232:235], v[12:15]
	v_mfma_f32_16x16x32_bf16 v[8:11], v[140:143], v[232:235], v[8:11]
	v_mfma_f32_16x16x32_bf16 v[60:63], v[136:139], v[208:211], v[60:63]
	v_mfma_f32_16x16x32_bf16 v[56:59], v[144:147], v[208:211], v[56:59]
	v_mfma_f32_16x16x32_bf16 v[44:47], v[136:139], v[220:223], v[44:47]
	v_mfma_f32_16x16x32_bf16 v[40:43], v[144:147], v[220:223], v[40:43]
	v_mfma_f32_16x16x32_bf16 v[28:31], v[136:139], v[228:231], v[28:31]
	v_mfma_f32_16x16x32_bf16 v[24:27], v[144:147], v[228:231], v[24:27]
	v_mfma_f32_16x16x32_bf16 v[12:15], v[136:139], v[236:239], v[12:15]
	v_mfma_f32_16x16x32_bf16 v[8:11], v[144:147], v[236:239], v[8:11]
	v_mfma_f32_16x16x32_bf16 v[52:55], v[148:151], v[204:207], v[52:55]
	v_mfma_f32_16x16x32_bf16 v[48:51], v[192:195], v[204:207], v[48:51]
	v_mfma_f32_16x16x32_bf16 v[36:39], v[148:151], v[216:219], v[36:39]
	v_mfma_f32_16x16x32_bf16 v[32:35], v[192:195], v[216:219], v[32:35]
	v_mfma_f32_16x16x32_bf16 v[20:23], v[148:151], v[224:227], v[20:23]
	v_mfma_f32_16x16x32_bf16 v[16:19], v[192:195], v[224:227], v[16:19]
	v_mfma_f32_16x16x32_bf16 v[4:7], v[148:151], v[232:235], v[4:7]
	v_mfma_f32_16x16x32_bf16 v[0:3], v[192:195], v[232:235], v[0:3]
	v_mfma_f32_16x16x32_bf16 v[52:55], v[188:191], v[208:211], v[52:55]
	v_mfma_f32_16x16x32_bf16 v[48:51], v[198:201], v[208:211], v[48:51]
	v_mfma_f32_16x16x32_bf16 v[36:39], v[188:191], v[220:223], v[36:39]
	v_mfma_f32_16x16x32_bf16 v[32:35], v[198:201], v[220:223], v[32:35]
	v_mfma_f32_16x16x32_bf16 v[20:23], v[188:191], v[228:231], v[20:23]
	v_mfma_f32_16x16x32_bf16 v[16:19], v[198:201], v[228:231], v[16:19]
	v_mfma_f32_16x16x32_bf16 v[4:7], v[188:191], v[236:239], v[4:7]
	v_mfma_f32_16x16x32_bf16 v[0:3], v[198:201], v[236:239], v[0:3]
	s_setprio 0
	s_barrier
	s_add_i32 s9, 0, 0x18000
	s_add_i32 s10, 0, 0x1c000
	v_add_u32_e32 v144, s9, v183
	v_add_u32_e32 v170, s10, v183
	ds_read_b128 v[116:119], v144
	ds_read_b128 v[136:139], v144 offset:1024
	ds_read_b128 v[140:143], v144 offset:2048
	ds_read_b128 v[144:147], v144 offset:3072
	ds_read_b128 v[148:151], v170
	ds_read_b128 v[188:191], v170 offset:1024
	ds_read_b128 v[192:195], v170 offset:2048
	ds_read_b128 v[198:201], v170 offset:3072
	v_lshl_add_u64 v[212:213], v[212:213], 0, s[12:13]
	s_mov_b32 m0, s37
	v_lshl_add_u64 v[250:251], v[212:213], 0, v[162:163]
	ds_read_b128 v[204:207], v202 offset:32768
	ds_read_b128 v[208:211], v202 offset:33792
	ds_read_b128 v[216:219], v202 offset:34816
	ds_read_b128 v[220:223], v202 offset:35840
	ds_read_b128 v[224:227], v202 offset:36864
	ds_read_b128 v[228:231], v202 offset:37888
	ds_read_b128 v[232:235], v202 offset:38912
	ds_read_b128 v[236:239], v202 offset:39936
	global_load_lds_dwordx4 v[250:251], off
	v_lshl_add_u64 v[212:213], v[212:213], 0, v[166:167]
	s_mov_b32 m0, s41
	s_nop 0
	global_load_lds_dwordx4 v[212:213], off
	s_waitcnt vmcnt(8)
	s_waitcnt lgkmcnt(0)
	s_setprio 1
	s_barrier
	v_mfma_f32_16x16x32_bf16 v[132:135], v[116:119], v[204:207], v[132:135]
	v_mfma_f32_16x16x32_bf16 v[128:131], v[140:143], v[204:207], v[128:131]
	v_mfma_f32_16x16x32_bf16 v[108:111], v[116:119], v[216:219], v[108:111]
	v_mfma_f32_16x16x32_bf16 v[104:107], v[140:143], v[216:219], v[104:107]
	v_mfma_f32_16x16x32_bf16 v[92:95], v[116:119], v[224:227], v[92:95]
	v_mfma_f32_16x16x32_bf16 v[88:91], v[140:143], v[224:227], v[88:91]
	v_mfma_f32_16x16x32_bf16 v[76:79], v[116:119], v[232:235], v[76:79]
	v_mfma_f32_16x16x32_bf16 v[72:75], v[140:143], v[232:235], v[72:75]
	v_mfma_f32_16x16x32_bf16 v[132:135], v[136:139], v[208:211], v[132:135]
	v_mfma_f32_16x16x32_bf16 v[128:131], v[144:147], v[208:211], v[128:131]
	v_mfma_f32_16x16x32_bf16 v[108:111], v[136:139], v[220:223], v[108:111]
	v_mfma_f32_16x16x32_bf16 v[104:107], v[144:147], v[220:223], v[104:107]
	v_mfma_f32_16x16x32_bf16 v[92:95], v[136:139], v[228:231], v[92:95]
	v_mfma_f32_16x16x32_bf16 v[88:91], v[144:147], v[228:231], v[88:91]
	v_mfma_f32_16x16x32_bf16 v[76:79], v[136:139], v[236:239], v[76:79]
	v_mfma_f32_16x16x32_bf16 v[72:75], v[144:147], v[236:239], v[72:75]
	v_mfma_f32_16x16x32_bf16 v[124:127], v[148:151], v[204:207], v[124:127]
	v_mfma_f32_16x16x32_bf16 v[120:123], v[192:195], v[204:207], v[120:123]
	v_mfma_f32_16x16x32_bf16 v[100:103], v[148:151], v[216:219], v[100:103]
	v_mfma_f32_16x16x32_bf16 v[96:99], v[192:195], v[216:219], v[96:99]
	v_mfma_f32_16x16x32_bf16 v[84:87], v[148:151], v[224:227], v[84:87]
	v_mfma_f32_16x16x32_bf16 v[80:83], v[192:195], v[224:227], v[80:83]
	v_mfma_f32_16x16x32_bf16 v[68:71], v[148:151], v[232:235], v[68:71]
	v_mfma_f32_16x16x32_bf16 v[64:67], v[192:195], v[232:235], v[64:67]
	v_mfma_f32_16x16x32_bf16 v[124:127], v[188:191], v[208:211], v[124:127]
	v_mfma_f32_16x16x32_bf16 v[120:123], v[198:201], v[208:211], v[120:123]
	v_mfma_f32_16x16x32_bf16 v[100:103], v[188:191], v[220:223], v[100:103]
	v_mfma_f32_16x16x32_bf16 v[96:99], v[198:201], v[220:223], v[96:99]
	v_mfma_f32_16x16x32_bf16 v[84:87], v[188:191], v[228:231], v[84:87]
	v_mfma_f32_16x16x32_bf16 v[80:83], v[198:201], v[228:231], v[80:83]
	v_mfma_f32_16x16x32_bf16 v[68:71], v[188:191], v[236:239], v[68:71]
	v_mfma_f32_16x16x32_bf16 v[64:67], v[198:201], v[236:239], v[64:67]
	s_setprio 0
	s_barrier
; #define PG8_STAGE(bufoff, gbase, voff) do { _Pragma("unroll") for (int _i = 0; _i < 2; ++_i) \
;         __builtin_amdgcn_global_load_lds((const unsigned*)((const char*)(gbase) + (voff)[_i]), (PG8_LAS unsigned*)(lds + (bufoff) + ldsw + _i * 8192), 16, 0, 0); } while (0)
; #define PG8_LDA(dst, b, h) do { _Pragma("unroll") for (int m = 0; m < 4; ++m) _Pragma("unroll") for (int k = 0; k < 2; ++k) dst[m][k] = *(const PG8_LAS bf16x8*)(lds + PG8_SA(b, h) + aoff + m * 2048 + k * 1024); } while (0)
; #define PG8_MMA(ai, bj, At, Bt) do { __builtin_amdgcn_s_setprio(1); _Pragma("unroll") for (int m = 0; m < 4; ++m) _Pragma("unroll") for (int n = 0; n < 2; ++n) _Pragma("unroll") for (int k = 0; k < 2; ++k) \
;         acc[ai][bj][m][n] = __builtin_amdgcn_mfma_f32_16x16x32_bf16(Bt[n][k], At[m][k], acc[ai][bj][m][n], 0, 0, 0); __builtin_amdgcn_s_setprio(0); } while (0)
; #define PG8_WAIT_V(n) asm volatile("s_waitcnt vmcnt(" #n ")" ::: "memory")
; #define PG8_WAIT_L(n) asm volatile("s_waitcnt lgkmcnt(" #n ")" ::: "memory")
; #define PG8_BAR __builtin_amdgcn_s_barrier()
; #define PG8_SCHED __builtin_amdgcn_sched_barrier(0)
; template <class Epi, class Sched, bool ALIGN_EPI = false, bool SP2 = false>
; __device__ __forceinline__ void gemm_phase(PG8_LAS unsigned char* lds, const Gemm g, const Sched& S, const Epi& E) {
;     ...
;             PG8_LDA(At, 1, 1); PG8_STAGE(PG8_SB(1, 0), b3, voffB); PG8_STAGE(PG8_SB(1, 1), b3 + hstep, voffB); PG8_STAGE(PG8_SA(1, 0), a3, voffA);
;             PG8_WAIT_V(8); PG8_WAIT_L(0); PG8_BAR; PG8_MMA(1, 0, At, B0); PG8_MMA(1, 1, At, B1); PG8_BAR; PG8_SCHED;
	s_add_i32 s9, s9, s29
	v_lshl_add_u64 v[212:213], v[240:241], 0, s[18:19]
	s_mov_b32 m0, s9
	ds_read_b128 v[204:207], v202 offset:49152
	ds_read_b128 v[208:211], v202 offset:50176
	ds_read_b128 v[216:219], v202 offset:51200
	ds_read_b128 v[220:223], v202 offset:52224
	ds_read_b128 v[224:227], v202 offset:53248
	ds_read_b128 v[228:231], v202 offset:54272
	ds_read_b128 v[232:235], v202 offset:55296
	ds_read_b128 v[236:239], v202 offset:56320
	global_load_lds_dwordx4 v[212:213], off
	v_lshl_add_u64 v[212:213], v[242:243], 0, s[18:19]
	s_add_i32 m0, s9, 0x2000
	s_add_i32 s9, s10, s29
	global_load_lds_dwordx4 v[212:213], off
	v_lshl_add_u64 v[212:213], v[244:245], 0, s[18:19]
	s_mov_b32 m0, s9
	s_nop 0
	global_load_lds_dwordx4 v[212:213], off
	v_lshl_add_u64 v[212:213], v[214:215], 0, s[18:19]
	s_add_i32 m0, s9, 0x2000
	s_nop 0
	global_load_lds_dwordx4 v[212:213], off
	v_lshl_add_u64 v[212:213], v[246:247], 0, s[18:19]
	s_mov_b32 m0, s49
	s_nop 0
	global_load_lds_dwordx4 v[212:213], off
	v_lshl_add_u64 v[212:213], v[248:249], 0, s[18:19]
	s_mov_b32 m0, s50
	s_nop 0
	global_load_lds_dwordx4 v[212:213], off
	s_waitcnt vmcnt(8)
	s_waitcnt lgkmcnt(0)
	s_setprio 1
	s_barrier
	v_mfma_f32_16x16x32_bf16 v[60:63], v[116:119], v[204:207], v[60:63]
	v_mfma_f32_16x16x32_bf16 v[56:59], v[140:143], v[204:207], v[56:59]
	v_mfma_f32_16x16x32_bf16 v[44:47], v[116:119], v[216:219], v[44:47]
	v_mfma_f32_16x16x32_bf16 v[40:43], v[140:143], v[216:219], v[40:43]
	v_mfma_f32_16x16x32_bf16 v[28:31], v[116:119], v[224:227], v[28:31]
	v_mfma_f32_16x16x32_bf16 v[24:27], v[140:143], v[224:227], v[24:27]
	v_mfma_f32_16x16x32_bf16 v[12:15], v[116:119], v[232:235], v[12:15]
	v_mfma_f32_16x16x32_bf16 v[8:11], v[140:143], v[232:235], v[8:11]
	v_mfma_f32_16x16x32_bf16 v[60:63], v[136:139], v[208:211], v[60:63]
	v_mfma_f32_16x16x32_bf16 v[56:59], v[144:147], v[208:211], v[56:59]
	v_mfma_f32_16x16x32_bf16 v[44:47], v[136:139], v[220:223], v[44:47]
	v_mfma_f32_16x16x32_bf16 v[40:43], v[144:147], v[220:223], v[40:43]
	v_mfma_f32_16x16x32_bf16 v[28:31], v[136:139], v[228:231], v[28:31]
	v_mfma_f32_16x16x32_bf16 v[24:27], v[144:147], v[228:231], v[24:27]
	v_mfma_f32_16x16x32_bf16 v[12:15], v[136:139], v[236:239], v[12:15]
	v_mfma_f32_16x16x32_bf16 v[8:11], v[144:147], v[236:239], v[8:11]
	v_mfma_f32_16x16x32_bf16 v[52:55], v[148:151], v[204:207], v[52:55]
	v_mfma_f32_16x16x32_bf16 v[48:51], v[192:195], v[204:207], v[48:51]
	v_mfma_f32_16x16x32_bf16 v[36:39], v[148:151], v[216:219], v[36:39]
	v_mfma_f32_16x16x32_bf16 v[32:35], v[192:195], v[216:219], v[32:35]
	v_mfma_f32_16x16x32_bf16 v[20:23], v[148:151], v[224:227], v[20:23]
	v_mfma_f32_16x16x32_bf16 v[16:19], v[192:195], v[224:227], v[16:19]
	v_mfma_f32_16x16x32_bf16 v[4:7], v[148:151], v[232:235], v[4:7]
	v_mfma_f32_16x16x32_bf16 v[0:3], v[192:195], v[232:235], v[0:3]
	v_mfma_f32_16x16x32_bf16 v[52:55], v[188:191], v[208:211], v[52:55]
	v_mfma_f32_16x16x32_bf16 v[48:51], v[198:201], v[208:211], v[48:51]
	v_mfma_f32_16x16x32_bf16 v[36:39], v[188:191], v[220:223], v[36:39]
	v_mfma_f32_16x16x32_bf16 v[32:35], v[198:201], v[220:223], v[32:35]
	v_mfma_f32_16x16x32_bf16 v[20:23], v[188:191], v[228:231], v[20:23]
	v_mfma_f32_16x16x32_bf16 v[16:19], v[198:201], v[228:231], v[16:19]
	v_mfma_f32_16x16x32_bf16 v[4:7], v[188:191], v[236:239], v[4:7]
	v_mfma_f32_16x16x32_bf16 v[0:3], v[198:201], v[236:239], v[0:3]
	s_setprio 0
	s_barrier
	v_lshl_add_u64 v[112:113], v[112:113], 0, s[26:27]
	s_cmp_ge_i32 s8, s51
	v_lshl_add_u64 v[114:115], v[114:115], 0, s[26:27]
	s_cbranch_scc0 .LBB0_722

; #define PG8_STAGE(bufoff, gbase, voff) do { _Pragma("unroll") for (int _i = 0; _i < 2; ++_i) \
;         __builtin_amdgcn_global_load_lds((const unsigned*)((const char*)(gbase) + (voff)[_i]), (PG8_LAS unsigned*)(lds + (bufoff) + ldsw + _i * 8192), 16, 0, 0); } while (0)
; #define PG8_LDA(dst, b, h) do { _Pragma("unroll") for (int m = 0; m < 4; ++m) _Pragma("unroll") for (int k = 0; k < 2; ++k) dst[m][k] = *(const PG8_LAS bf16x8*)(lds + PG8_SA(b, h) + aoff + m * 2048 + k * 1024); } while (0)
; #define PG8_LDB(dst, b, h) do { _Pragma("unroll") for (int n = 0; n < 2; ++n) _Pragma("unroll") for (int k = 0; k < 2; ++k) dst[n][k] = *(const PG8_LAS bf16x8*)(lds + PG8_SB(b, h) + boff + n * 2048 + k * 1024); } while (0)
; #define PG8_MMA(ai, bj, At, Bt) do { __builtin_amdgcn_s_setprio(1); _Pragma("unroll") for (int m = 0; m < 4; ++m) _Pragma("unroll") for (int n = 0; n < 2; ++n) _Pragma("unroll") for (int k = 0; k < 2; ++k) \
;         acc[ai][bj][m][n] = __builtin_amdgcn_mfma_f32_16x16x32_bf16(Bt[n][k], At[m][k], acc[ai][bj][m][n], 0, 0, 0); __builtin_amdgcn_s_setprio(0); } while (0)
; #define PG8_WAIT_V(n) asm volatile("s_waitcnt vmcnt(" #n ")" ::: "memory")
; #define PG8_WAIT_L(n) asm volatile("s_waitcnt lgkmcnt(" #n ")" ::: "memory")
; #define PG8_BAR __builtin_amdgcn_s_barrier()
; template <class Epi, class Sched, bool ALIGN_EPI = false, bool SP2 = false>
; __device__ __forceinline__ void gemm_phase(PG8_LAS unsigned char* lds, const Gemm g, const Sched& S, const Epi& E) {
;     ...
;             const char* a1 = cA + (size_t)(t + 1) * kstep;
;             const char* a2 = last ? nA : cA + (size_t)(t + 2) * kstep; const char* b2 = last ? nB : cB + (size_t)(t + 2) * kstep;
;             const char* a3 = a2 + kstep; const char* b3 = b2 + kstep;
;             if (last && has_next) S.a_ready(nxt);
;             if constexpr (SP2) {
;             PG8_LDB(B0, 0, 0); PG8_LDB(B1, 0, 1); PG8_SCHED; PG8_LDA(At, 0, 0); PG8_STAGE(PG8_SA(1, 1), a1 + hstep, voffA);
;             PG8_WAIT_V(8); PG8_WAIT_L(0); PG8_BAR; PG8_MMA(0, 0, At, B0); PG8_MMA(0, 1, At, B1); PG8_BAR; PG8_SCHED;
;             PG8_LDA(At, 0, 1); PG8_STAGE(PG8_SB(0, 0), b2, voffB); PG8_STAGE(PG8_SB(0, 1), b2 + hstep, voffB); PG8_STAGE(PG8_SA(0, 0), a2, voffA);
;             PG8_WAIT_V(8); PG8_WAIT_L(0); PG8_BAR; PG8_MMA(1, 0, At, B0); PG8_MMA(1, 1, At, B1); PG8_BAR; PG8_SCHED;
.LBB0_940:
	v_add_u32_e32 v188, s55, v199
	ds_read_b128 v[132:135], v201
	ds_read_b128 v[136:139], v201 offset:1024
	ds_read_b128 v[140:143], v201 offset:2048
	ds_read_b128 v[144:147], v201 offset:3072
	ds_read_b128 v[148:151], v188
	ds_read_b128 v[180:183], v188 offset:1024
	ds_read_b128 v[184:187], v188 offset:2048
	ds_read_b128 v[188:191], v188 offset:3072
	s_cmp_eq_u32 s48, s12
	v_lshl_add_u64 v[192:193], v[130:131], 0, s[22:23]
	s_cselect_b64 vcc, -1, 0
	s_add_i32 s12, s12, 2
	v_cndmask_b32_e32 v197, v193, v177, vcc
	v_cndmask_b32_e32 v196, v192, v176, vcc
	v_cndmask_b32_e32 v213, v129, v179, vcc
	v_cndmask_b32_e32 v212, v128, v178, vcc
	s_mov_b32 m0, s56
	v_lshl_add_u64 v[214:215], v[130:131], 0, v[172:173]
	ds_read_b128 v[192:195], v202
	ds_read_b128 v[204:207], v202 offset:1024
	ds_read_b128 v[208:211], v202 offset:2048
	ds_read_b128 v[216:219], v202 offset:3072
	ds_read_b128 v[220:223], v202 offset:4096
	ds_read_b128 v[224:227], v202 offset:5120
	ds_read_b128 v[228:231], v202 offset:6144
	ds_read_b128 v[232:235], v202 offset:7168
	global_load_lds_dwordx4 v[214:215], off
	v_lshl_add_u64 v[214:215], v[130:131], 0, v[170:171]
	s_mov_b32 m0, s57
	s_nop 0
	global_load_lds_dwordx4 v[214:215], off
	s_waitcnt vmcnt(8)
	s_waitcnt lgkmcnt(0)
	s_setprio 1
	s_barrier
	v_mfma_f32_16x16x32_bf16 v[120:123], v[132:135], v[192:195], v[120:123]
	v_mfma_f32_16x16x32_bf16 v[124:127], v[140:143], v[192:195], v[124:127]
	v_mfma_f32_16x16x32_bf16 v[108:111], v[132:135], v[208:211], v[108:111]
	v_mfma_f32_16x16x32_bf16 v[104:107], v[140:143], v[208:211], v[104:107]
	v_mfma_f32_16x16x32_bf16 v[92:95], v[132:135], v[220:223], v[92:95]
	v_mfma_f32_16x16x32_bf16 v[88:91], v[140:143], v[220:223], v[88:91]
	v_mfma_f32_16x16x32_bf16 v[76:79], v[132:135], v[228:231], v[76:79]
	v_mfma_f32_16x16x32_bf16 v[72:75], v[140:143], v[228:231], v[72:75]
	v_mfma_f32_16x16x32_bf16 v[120:123], v[136:139], v[204:207], v[120:123]
	v_mfma_f32_16x16x32_bf16 v[124:127], v[144:147], v[204:207], v[124:127]
	v_mfma_f32_16x16x32_bf16 v[108:111], v[136:139], v[216:219], v[108:111]
	v_mfma_f32_16x16x32_bf16 v[104:107], v[144:147], v[216:219], v[104:107]
	v_mfma_f32_16x16x32_bf16 v[92:95], v[136:139], v[224:227], v[92:95]
	v_mfma_f32_16x16x32_bf16 v[88:91], v[144:147], v[224:227], v[88:91]
	v_mfma_f32_16x16x32_bf16 v[76:79], v[136:139], v[232:235], v[76:79]
	v_mfma_f32_16x16x32_bf16 v[72:75], v[144:147], v[232:235], v[72:75]
	v_mfma_f32_16x16x32_bf16 v[116:119], v[148:151], v[192:195], v[116:119]
	v_mfma_f32_16x16x32_bf16 v[112:115], v[184:187], v[192:195], v[112:115]
	v_mfma_f32_16x16x32_bf16 v[100:103], v[148:151], v[208:211], v[100:103]
	v_mfma_f32_16x16x32_bf16 v[96:99], v[184:187], v[208:211], v[96:99]
	v_mfma_f32_16x16x32_bf16 v[84:87], v[148:151], v[220:223], v[84:87]
	v_mfma_f32_16x16x32_bf16 v[80:83], v[184:187], v[220:223], v[80:83]
	v_mfma_f32_16x16x32_bf16 v[68:71], v[148:151], v[228:231], v[68:71]
	v_mfma_f32_16x16x32_bf16 v[64:67], v[184:187], v[228:231], v[64:67]
	v_mfma_f32_16x16x32_bf16 v[116:119], v[180:183], v[204:207], v[116:119]
	v_mfma_f32_16x16x32_bf16 v[112:115], v[188:191], v[204:207], v[112:115]
	v_mfma_f32_16x16x32_bf16 v[100:103], v[180:183], v[216:219], v[100:103]
	v_mfma_f32_16x16x32_bf16 v[96:99], v[188:191], v[216:219], v[96:99]
	v_mfma_f32_16x16x32_bf16 v[84:87], v[180:183], v[224:227], v[84:87]
	v_mfma_f32_16x16x32_bf16 v[80:83], v[188:191], v[224:227], v[80:83]
	v_mfma_f32_16x16x32_bf16 v[68:71], v[180:183], v[232:235], v[68:71]
	v_mfma_f32_16x16x32_bf16 v[64:67], v[188:191], v[232:235], v[64:67]
	s_setprio 0
	s_barrier
	s_mov_b32 m0, s58
	v_lshl_add_u64 v[214:215], v[212:213], 0, v[164:165]
	ds_read_b128 v[192:195], v202 offset:16384
	ds_read_b128 v[204:207], v202 offset:17408
	ds_read_b128 v[208:211], v202 offset:18432
	ds_read_b128 v[216:219], v202 offset:19456
	ds_read_b128 v[220:223], v202 offset:20480
	ds_read_b128 v[224:227], v202 offset:21504
	ds_read_b128 v[228:231], v202 offset:22528
	ds_read_b128 v[232:235], v202 offset:23552
	global_load_lds_dwordx4 v[214:215], off
	v_lshl_add_u64 v[236:237], v[212:213], 0, v[168:169]
	s_mov_b32 m0, s59
	v_lshl_add_u64 v[212:213], v[212:213], 0, s[14:15]
	s_add_i32 s13, s55, s30
	global_load_lds_dwordx4 v[236:237], off
	v_lshl_add_u64 v[238:239], v[212:213], 0, v[164:165]
	s_mov_b32 m0, s13
	v_lshl_add_u64 v[212:213], v[212:213], 0, v[168:169]
	global_load_lds_dwordx4 v[238:239], off
	s_add_i32 m0, s13, 0x2000
	v_lshl_add_u64 v[240:241], v[196:197], 0, v[162:163]
	global_load_lds_dwordx4 v[212:213], off
	s_mov_b32 m0, s31
	v_lshl_add_u64 v[242:243], v[196:197], 0, v[166:167]
	global_load_lds_dwordx4 v[240:241], off
	s_mov_b32 m0, s34
	s_nop 0
	global_load_lds_dwordx4 v[242:243], off
	s_waitcnt vmcnt(8)
	s_waitcnt lgkmcnt(0)
	s_setprio 1
	s_barrier
; #define PG8_STAGE(bufoff, gbase, voff) do { _Pragma("unroll") for (int _i = 0; _i < 2; ++_i) \
;         __builtin_amdgcn_global_load_lds((const unsigned*)((const char*)(gbase) + (voff)[_i]), (PG8_LAS unsigned*)(lds + (bufoff) + ldsw + _i * 8192), 16, 0, 0); } while (0)
; #define PG8_LDA(dst, b, h) do { _Pragma("unroll") for (int m = 0; m < 4; ++m) _Pragma("unroll") for (int k = 0; k < 2; ++k) dst[m][k] = *(const PG8_LAS bf16x8*)(lds + PG8_SA(b, h) + aoff + m * 2048 + k * 1024); } while (0)
; #define PG8_LDB(dst, b, h) do { _Pragma("unroll") for (int n = 0; n < 2; ++n) _Pragma("unroll") for (int k = 0; k < 2; ++k) dst[n][k] = *(const PG8_LAS bf16x8*)(lds + PG8_SB(b, h) + boff + n * 2048 + k * 1024); } while (0)
; #define PG8_MMA(ai, bj, At, Bt) do { __builtin_amdgcn_s_setprio(1); _Pragma("unroll") for (int m = 0; m < 4; ++m) _Pragma("unroll") for (int n = 0; n < 2; ++n) _Pragma("unroll") for (int k = 0; k < 2; ++k) \
;         acc[ai][bj][m][n] = __builtin_amdgcn_mfma_f32_16x16x32_bf16(Bt[n][k], At[m][k], acc[ai][bj][m][n], 0, 0, 0); __builtin_amdgcn_s_setprio(0); } while (0)
; #define PG8_WAIT_V(n) asm volatile("s_waitcnt vmcnt(" #n ")" ::: "memory")
; #define PG8_WAIT_L(n) asm volatile("s_waitcnt lgkmcnt(" #n ")" ::: "memory")
; #define PG8_BAR __builtin_amdgcn_s_barrier()
; #define PG8_SCHED __builtin_amdgcn_sched_barrier(0)
; template <class Epi, class Sched, bool ALIGN_EPI = false, bool SP2 = false>
; __device__ __forceinline__ void gemm_phase(PG8_LAS unsigned char* lds, const Gemm g, const Sched& S, const Epi& E) {
;     ...
;             PG8_WAIT_V(8); PG8_WAIT_L(0); PG8_BAR; PG8_MMA(1, 0, At, B0); PG8_MMA(1, 1, At, B1); PG8_BAR; PG8_SCHED;
;             PG8_LDB(B0, 1, 0); PG8_LDB(B1, 1, 1); PG8_SCHED; PG8_LDA(At, 1, 0); PG8_STAGE(PG8_SA(0, 1), a2 + hstep, voffA);
;             PG8_WAIT_V(8); PG8_WAIT_L(0); PG8_BAR; PG8_MMA(0, 0, At, B0); PG8_MMA(0, 1, At, B1); PG8_BAR; PG8_SCHED;
	v_mfma_f32_16x16x32_bf16 v[60:63], v[132:135], v[192:195], v[60:63]
	v_mfma_f32_16x16x32_bf16 v[56:59], v[140:143], v[192:195], v[56:59]
	v_mfma_f32_16x16x32_bf16 v[44:47], v[132:135], v[208:211], v[44:47]
	v_mfma_f32_16x16x32_bf16 v[40:43], v[140:143], v[208:211], v[40:43]
	v_mfma_f32_16x16x32_bf16 v[28:31], v[132:135], v[220:223], v[28:31]
	v_mfma_f32_16x16x32_bf16 v[24:27], v[140:143], v[220:223], v[24:27]
	v_mfma_f32_16x16x32_bf16 v[12:15], v[132:135], v[228:231], v[12:15]
	v_mfma_f32_16x16x32_bf16 v[8:11], v[140:143], v[228:231], v[8:11]
	v_mfma_f32_16x16x32_bf16 v[60:63], v[136:139], v[204:207], v[60:63]
	v_mfma_f32_16x16x32_bf16 v[56:59], v[144:147], v[204:207], v[56:59]
	v_mfma_f32_16x16x32_bf16 v[44:47], v[136:139], v[216:219], v[44:47]
	v_mfma_f32_16x16x32_bf16 v[40:43], v[144:147], v[216:219], v[40:43]
	v_mfma_f32_16x16x32_bf16 v[28:31], v[136:139], v[224:227], v[28:31]
	v_mfma_f32_16x16x32_bf16 v[24:27], v[144:147], v[224:227], v[24:27]
	v_mfma_f32_16x16x32_bf16 v[12:15], v[136:139], v[232:235], v[12:15]
	v_mfma_f32_16x16x32_bf16 v[8:11], v[144:147], v[232:235], v[8:11]
	v_mfma_f32_16x16x32_bf16 v[52:55], v[148:151], v[192:195], v[52:55]
	v_mfma_f32_16x16x32_bf16 v[48:51], v[184:187], v[192:195], v[48:51]
	v_mfma_f32_16x16x32_bf16 v[36:39], v[148:151], v[208:211], v[36:39]
	v_mfma_f32_16x16x32_bf16 v[32:35], v[184:187], v[208:211], v[32:35]
	v_mfma_f32_16x16x32_bf16 v[20:23], v[148:151], v[220:223], v[20:23]
	v_mfma_f32_16x16x32_bf16 v[16:19], v[184:187], v[220:223], v[16:19]
	v_mfma_f32_16x16x32_bf16 v[4:7], v[148:151], v[228:231], v[4:7]
	v_mfma_f32_16x16x32_bf16 v[0:3], v[184:187], v[228:231], v[0:3]
	v_mfma_f32_16x16x32_bf16 v[52:55], v[180:183], v[204:207], v[52:55]
	v_mfma_f32_16x16x32_bf16 v[48:51], v[188:191], v[204:207], v[48:51]
	v_mfma_f32_16x16x32_bf16 v[36:39], v[180:183], v[216:219], v[36:39]
	v_mfma_f32_16x16x32_bf16 v[32:35], v[188:191], v[216:219], v[32:35]
	v_mfma_f32_16x16x32_bf16 v[20:23], v[180:183], v[224:227], v[20:23]
	v_mfma_f32_16x16x32_bf16 v[16:19], v[188:191], v[224:227], v[16:19]
	v_mfma_f32_16x16x32_bf16 v[4:7], v[180:183], v[232:235], v[4:7]
	v_mfma_f32_16x16x32_bf16 v[0:3], v[188:191], v[232:235], v[0:3]
	s_setprio 0
	s_barrier
	s_add_i32 s13, 0, 0x18000
	s_add_i32 s29, 0, 0x1c000
	v_add_u32_e32 v144, s13, v199
	v_add_u32_e32 v188, s29, v199
	ds_read_b128 v[132:135], v144
	ds_read_b128 v[136:139], v144 offset:1024
	ds_read_b128 v[140:143], v144 offset:2048
	ds_read_b128 v[144:147], v144 offset:3072
	ds_read_b128 v[148:151], v188
	ds_read_b128 v[180:183], v188 offset:1024
	ds_read_b128 v[184:187], v188 offset:2048
	ds_read_b128 v[188:191], v188 offset:3072
	v_lshl_add_u64 v[196:197], v[196:197], 0, s[14:15]
	s_mov_b32 m0, s35
	v_lshl_add_u64 v[244:245], v[196:197], 0, v[162:163]
	ds_read_b128 v[192:195], v202 offset:32768
	ds_read_b128 v[204:207], v202 offset:33792
	ds_read_b128 v[208:211], v202 offset:34816
	ds_read_b128 v[216:219], v202 offset:35840
	ds_read_b128 v[220:223], v202 offset:36864
	ds_read_b128 v[224:227], v202 offset:37888
	ds_read_b128 v[228:231], v202 offset:38912
	ds_read_b128 v[232:235], v202 offset:39936
	global_load_lds_dwordx4 v[244:245], off
	v_lshl_add_u64 v[196:197], v[196:197], 0, v[166:167]
	s_mov_b32 m0, s36
	s_nop 0
	global_load_lds_dwordx4 v[196:197], off
	s_waitcnt vmcnt(8)
	s_waitcnt lgkmcnt(0)
	s_setprio 1
	s_barrier
	v_mfma_f32_16x16x32_bf16 v[120:123], v[132:135], v[192:195], v[120:123]
	v_mfma_f32_16x16x32_bf16 v[124:127], v[140:143], v[192:195], v[124:127]
	v_mfma_f32_16x16x32_bf16 v[108:111], v[132:135], v[208:211], v[108:111]
	v_mfma_f32_16x16x32_bf16 v[104:107], v[140:143], v[208:211], v[104:107]
	v_mfma_f32_16x16x32_bf16 v[92:95], v[132:135], v[220:223], v[92:95]
	v_mfma_f32_16x16x32_bf16 v[88:91], v[140:143], v[220:223], v[88:91]
	v_mfma_f32_16x16x32_bf16 v[76:79], v[132:135], v[228:231], v[76:79]
	v_mfma_f32_16x16x32_bf16 v[72:75], v[140:143], v[228:231], v[72:75]
	v_mfma_f32_16x16x32_bf16 v[120:123], v[136:139], v[204:207], v[120:123]
	v_mfma_f32_16x16x32_bf16 v[124:127], v[144:147], v[204:207], v[124:127]
	v_mfma_f32_16x16x32_bf16 v[108:111], v[136:139], v[216:219], v[108:111]
	v_mfma_f32_16x16x32_bf16 v[104:107], v[144:147], v[216:219], v[104:107]
	v_mfma_f32_16x16x32_bf16 v[92:95], v[136:139], v[224:227], v[92:95]
	v_mfma_f32_16x16x32_bf16 v[88:91], v[144:147], v[224:227], v[88:91]
	v_mfma_f32_16x16x32_bf16 v[76:79], v[136:139], v[232:235], v[76:79]
	v_mfma_f32_16x16x32_bf16 v[72:75], v[144:147], v[232:235], v[72:75]
	v_mfma_f32_16x16x32_bf16 v[116:119], v[148:151], v[192:195], v[116:119]
	v_mfma_f32_16x16x32_bf16 v[112:115], v[184:187], v[192:195], v[112:115]
	v_mfma_f32_16x16x32_bf16 v[100:103], v[148:151], v[208:211], v[100:103]
	v_mfma_f32_16x16x32_bf16 v[96:99], v[184:187], v[208:211], v[96:99]
	v_mfma_f32_16x16x32_bf16 v[84:87], v[148:151], v[220:223], v[84:87]
	v_mfma_f32_16x16x32_bf16 v[80:83], v[184:187], v[220:223], v[80:83]
	v_mfma_f32_16x16x32_bf16 v[68:71], v[148:151], v[228:231], v[68:71]
	v_mfma_f32_16x16x32_bf16 v[64:67], v[184:187], v[228:231], v[64:67]
	v_mfma_f32_16x16x32_bf16 v[116:119], v[180:183], v[204:207], v[116:119]
	v_mfma_f32_16x16x32_bf16 v[112:115], v[188:191], v[204:207], v[112:115]
	v_mfma_f32_16x16x32_bf16 v[100:103], v[180:183], v[216:219], v[100:103]
	v_mfma_f32_16x16x32_bf16 v[96:99], v[188:191], v[216:219], v[96:99]
	v_mfma_f32_16x16x32_bf16 v[84:87], v[180:183], v[224:227], v[84:87]
	v_mfma_f32_16x16x32_bf16 v[80:83], v[188:191], v[224:227], v[80:83]
	v_mfma_f32_16x16x32_bf16 v[68:71], v[180:183], v[232:235], v[68:71]
	v_mfma_f32_16x16x32_bf16 v[64:67], v[188:191], v[232:235], v[64:67]
	s_setprio 0
	s_barrier
; #define PG8_STAGE(bufoff, gbase, voff) do { _Pragma("unroll") for (int _i = 0; _i < 2; ++_i) \
;         __builtin_amdgcn_global_load_lds((const unsigned*)((const char*)(gbase) + (voff)[_i]), (PG8_LAS unsigned*)(lds + (bufoff) + ldsw + _i * 8192), 16, 0, 0); } while (0)
; #define PG8_LDA(dst, b, h) do { _Pragma("unroll") for (int m = 0; m < 4; ++m) _Pragma("unroll") for (int k = 0; k < 2; ++k) dst[m][k] = *(const PG8_LAS bf16x8*)(lds + PG8_SA(b, h) + aoff + m * 2048 + k * 1024); } while (0)
; #define PG8_MMA(ai, bj, At, Bt) do { __builtin_amdgcn_s_setprio(1); _Pragma("unroll") for (int m = 0; m < 4; ++m) _Pragma("unroll") for (int n = 0; n < 2; ++n) _Pragma("unroll") for (int k = 0; k < 2; ++k) \
;         acc[ai][bj][m][n] = __builtin_amdgcn_mfma_f32_16x16x32_bf16(Bt[n][k], At[m][k], acc[ai][bj][m][n], 0, 0, 0); __builtin_amdgcn_s_setprio(0); } while (0)
; #define PG8_WAIT_V(n) asm volatile("s_waitcnt vmcnt(" #n ")" ::: "memory")
; #define PG8_WAIT_L(n) asm volatile("s_waitcnt lgkmcnt(" #n ")" ::: "memory")
; #define PG8_BAR __builtin_amdgcn_s_barrier()
; #define PG8_SCHED __builtin_amdgcn_sched_barrier(0)
; template <class Epi, class Sched, bool ALIGN_EPI = false, bool SP2 = false>
; __device__ __forceinline__ void gemm_phase(PG8_LAS unsigned char* lds, const Gemm g, const Sched& S, const Epi& E) {
;     ...
;             PG8_LDA(At, 1, 1); PG8_STAGE(PG8_SB(1, 0), b3, voffB); PG8_STAGE(PG8_SB(1, 1), b3 + hstep, voffB); PG8_STAGE(PG8_SA(1, 0), a3, voffA);
;             PG8_WAIT_V(8); PG8_WAIT_L(0); PG8_BAR; PG8_MMA(1, 0, At, B0); PG8_MMA(1, 1, At, B1); PG8_BAR; PG8_SCHED;
	s_add_i32 s13, s13, s30
	v_lshl_add_u64 v[196:197], v[214:215], 0, s[22:23]
	s_mov_b32 m0, s13
	ds_read_b128 v[192:195], v202 offset:49152
	ds_read_b128 v[204:207], v202 offset:50176
	ds_read_b128 v[208:211], v202 offset:51200
	ds_read_b128 v[216:219], v202 offset:52224
	ds_read_b128 v[220:223], v202 offset:53248
	ds_read_b128 v[224:227], v202 offset:54272
	ds_read_b128 v[228:231], v202 offset:55296
	ds_read_b128 v[232:235], v202 offset:56320
	global_load_lds_dwordx4 v[196:197], off
	v_lshl_add_u64 v[196:197], v[236:237], 0, s[22:23]
	s_add_i32 m0, s13, 0x2000
	s_add_i32 s13, s29, s30
	global_load_lds_dwordx4 v[196:197], off
	v_lshl_add_u64 v[196:197], v[238:239], 0, s[22:23]
	s_mov_b32 m0, s13
	s_nop 0
	global_load_lds_dwordx4 v[196:197], off
	v_lshl_add_u64 v[196:197], v[212:213], 0, s[22:23]
	s_add_i32 m0, s13, 0x2000
	s_nop 0
	global_load_lds_dwordx4 v[196:197], off
	v_lshl_add_u64 v[196:197], v[240:241], 0, s[22:23]
	s_mov_b32 m0, s37
	s_nop 0
	global_load_lds_dwordx4 v[196:197], off
	v_lshl_add_u64 v[196:197], v[242:243], 0, s[22:23]
	s_mov_b32 m0, s41
	s_nop 0
	global_load_lds_dwordx4 v[196:197], off
	s_waitcnt vmcnt(8)
	s_waitcnt lgkmcnt(0)
	s_setprio 1
	s_barrier
	v_mfma_f32_16x16x32_bf16 v[60:63], v[132:135], v[192:195], v[60:63]
	v_mfma_f32_16x16x32_bf16 v[56:59], v[140:143], v[192:195], v[56:59]
	v_mfma_f32_16x16x32_bf16 v[44:47], v[132:135], v[208:211], v[44:47]
	v_mfma_f32_16x16x32_bf16 v[40:43], v[140:143], v[208:211], v[40:43]
	v_mfma_f32_16x16x32_bf16 v[28:31], v[132:135], v[220:223], v[28:31]
	v_mfma_f32_16x16x32_bf16 v[24:27], v[140:143], v[220:223], v[24:27]
	v_mfma_f32_16x16x32_bf16 v[12:15], v[132:135], v[228:231], v[12:15]
	v_mfma_f32_16x16x32_bf16 v[8:11], v[140:143], v[228:231], v[8:11]
	v_mfma_f32_16x16x32_bf16 v[60:63], v[136:139], v[204:207], v[60:63]
	v_mfma_f32_16x16x32_bf16 v[56:59], v[144:147], v[204:207], v[56:59]
	v_mfma_f32_16x16x32_bf16 v[44:47], v[136:139], v[216:219], v[44:47]
	v_mfma_f32_16x16x32_bf16 v[40:43], v[144:147], v[216:219], v[40:43]
	v_mfma_f32_16x16x32_bf16 v[28:31], v[136:139], v[224:227], v[28:31]
	v_mfma_f32_16x16x32_bf16 v[24:27], v[144:147], v[224:227], v[24:27]
	v_mfma_f32_16x16x32_bf16 v[12:15], v[136:139], v[232:235], v[12:15]
	v_mfma_f32_16x16x32_bf16 v[8:11], v[144:147], v[232:235], v[8:11]
	v_mfma_f32_16x16x32_bf16 v[52:55], v[148:151], v[192:195], v[52:55]
	v_mfma_f32_16x16x32_bf16 v[48:51], v[184:187], v[192:195], v[48:51]
	v_mfma_f32_16x16x32_bf16 v[36:39], v[148:151], v[208:211], v[36:39]
	v_mfma_f32_16x16x32_bf16 v[32:35], v[184:187], v[208:211], v[32:35]
	v_mfma_f32_16x16x32_bf16 v[20:23], v[148:151], v[220:223], v[20:23]
	v_mfma_f32_16x16x32_bf16 v[16:19], v[184:187], v[220:223], v[16:19]
	v_mfma_f32_16x16x32_bf16 v[4:7], v[148:151], v[228:231], v[4:7]
	v_mfma_f32_16x16x32_bf16 v[0:3], v[184:187], v[228:231], v[0:3]
	v_mfma_f32_16x16x32_bf16 v[52:55], v[180:183], v[204:207], v[52:55]
	v_mfma_f32_16x16x32_bf16 v[48:51], v[188:191], v[204:207], v[48:51]
	v_mfma_f32_16x16x32_bf16 v[36:39], v[180:183], v[216:219], v[36:39]
	v_mfma_f32_16x16x32_bf16 v[32:35], v[188:191], v[216:219], v[32:35]
	v_mfma_f32_16x16x32_bf16 v[20:23], v[180:183], v[224:227], v[20:23]
	v_mfma_f32_16x16x32_bf16 v[16:19], v[188:191], v[224:227], v[16:19]
	v_mfma_f32_16x16x32_bf16 v[4:7], v[180:183], v[232:235], v[4:7]
	v_mfma_f32_16x16x32_bf16 v[0:3], v[188:191], v[232:235], v[0:3]
	s_setprio 0
	s_barrier
	v_lshl_add_u64 v[128:129], v[128:129], 0, s[26:27]
	s_cmp_ge_i32 s12, s47
	v_lshl_add_u64 v[130:131], v[130:131], 0, s[26:27]
	s_cbranch_scc0 .LBB0_940

; #define PG8_STAGE(bufoff, gbase, voff) do { _Pragma("unroll") for (int _i = 0; _i < 2; ++_i) \
;         __builtin_amdgcn_global_load_lds((const unsigned*)((const char*)(gbase) + (voff)[_i]), (PG8_LAS unsigned*)(lds + (bufoff) + ldsw + _i * 8192), 16, 0, 0); } while (0)
; #define PG8_LDA(dst, b, h) do { _Pragma("unroll") for (int m = 0; m < 4; ++m) _Pragma("unroll") for (int k = 0; k < 2; ++k) dst[m][k] = *(const PG8_LAS bf16x8*)(lds + PG8_SA(b, h) + aoff + m * 2048 + k * 1024); } while (0)
; #define PG8_LDB(dst, b, h) do { _Pragma("unroll") for (int n = 0; n < 2; ++n) _Pragma("unroll") for (int k = 0; k < 2; ++k) dst[n][k] = *(const PG8_LAS bf16x8*)(lds + PG8_SB(b, h) + boff + n * 2048 + k * 1024); } while (0)
; #define PG8_MMA(ai, bj, At, Bt) do { __builtin_amdgcn_s_setprio(1); _Pragma("unroll") for (int m = 0; m < 4; ++m) _Pragma("unroll") for (int n = 0; n < 2; ++n) _Pragma("unroll") for (int k = 0; k < 2; ++k) \
;         acc[ai][bj][m][n] = __builtin_amdgcn_mfma_f32_16x16x32_bf16(Bt[n][k], At[m][k], acc[ai][bj][m][n], 0, 0, 0); __builtin_amdgcn_s_setprio(0); } while (0)
; #define PG8_WAIT_V(n) asm volatile("s_waitcnt vmcnt(" #n ")" ::: "memory")
; #define PG8_WAIT_L(n) asm volatile("s_waitcnt lgkmcnt(" #n ")" ::: "memory")
; #define PG8_BAR __builtin_amdgcn_s_barrier()
; template <class Epi, class Sched, bool ALIGN_EPI = false, bool SP2 = false>
; __device__ __forceinline__ void gemm_phase(PG8_LAS unsigned char* lds, const Gemm g, const Sched& S, const Epi& E) {
;     ...
;             const char* a1 = cA + (size_t)(t + 1) * kstep;
;             const char* a2 = last ? nA : cA + (size_t)(t + 2) * kstep; const char* b2 = last ? nB : cB + (size_t)(t + 2) * kstep;
;             const char* a3 = a2 + kstep; const char* b3 = b2 + kstep;
;             if (last && has_next) S.a_ready(nxt);
;             if constexpr (SP2) {
;             PG8_LDB(B0, 0, 0); PG8_LDB(B1, 0, 1); PG8_SCHED; PG8_LDA(At, 0, 0); PG8_STAGE(PG8_SA(1, 1), a1 + hstep, voffA);
;             PG8_WAIT_V(8); PG8_WAIT_L(0); PG8_BAR; PG8_MMA(0, 0, At, B0); PG8_MMA(0, 1, At, B1); PG8_BAR; PG8_SCHED;
;             PG8_LDA(At, 0, 1); PG8_STAGE(PG8_SB(0, 0), b2, voffB); PG8_STAGE(PG8_SB(0, 1), b2 + hstep, voffB); PG8_STAGE(PG8_SA(0, 0), a2, voffA);
;             PG8_WAIT_V(8); PG8_WAIT_L(0); PG8_BAR; PG8_MMA(1, 0, At, B0); PG8_MMA(1, 1, At, B1); PG8_BAR; PG8_SCHED;
.LBB0_1021:
	v_add_u32_e32 v166, s55, v169
	v_add_u32_e32 v168, s56, v169
	ds_read_b128 v[162:165], v166
	ds_read_b128 v[182:185], v166 offset:1024
	ds_read_b128 v[186:189], v166 offset:2048
	ds_read_b128 v[190:193], v166 offset:3072
	ds_read_b128 v[194:197], v168
	ds_read_b128 v[198:201], v168 offset:1024
	ds_read_b128 v[202:205], v168 offset:2048
	ds_read_b128 v[206:209], v168 offset:3072
	s_cmp_eq_u32 s54, s10
	v_lshl_add_u64 v[172:173], v[160:161], 0, s[22:23]
	s_cselect_b64 vcc, -1, 0
	s_add_i32 s10, s10, 2
	v_cndmask_b32_e32 v173, v173, v153, vcc
	v_cndmask_b32_e32 v172, v172, v152, vcc
	v_cndmask_b32_e32 v215, v159, v155, vcc
	v_cndmask_b32_e32 v214, v158, v154, vcc
	s_mov_b32 m0, s57
	v_lshl_add_u64 v[244:245], v[160:161], 0, v[148:149]
	ds_read_b128 v[210:213], v179
	ds_read_b128 v[216:219], v179 offset:1024
	ds_read_b128 v[220:223], v179 offset:2048
	ds_read_b128 v[224:227], v179 offset:3072
	ds_read_b128 v[228:231], v179 offset:4096
	ds_read_b128 v[232:235], v179 offset:5120
	ds_read_b128 v[236:239], v179 offset:6144
	ds_read_b128 v[240:243], v179 offset:7168
	global_load_lds_dwordx4 v[244:245], off
	v_lshl_add_u64 v[244:245], v[160:161], 0, v[146:147]
	s_mov_b32 m0, s58
	s_nop 0
	global_load_lds_dwordx4 v[244:245], off
	s_waitcnt vmcnt(8)
	s_waitcnt lgkmcnt(0)
	s_setprio 1
	s_barrier
	v_mfma_f32_16x16x32_bf16 v[124:127], v[162:165], v[210:213], v[124:127]
	v_mfma_f32_16x16x32_bf16 v[116:119], v[186:189], v[210:213], v[116:119]
	v_mfma_f32_16x16x32_bf16 v[108:111], v[162:165], v[220:223], v[108:111]
	v_mfma_f32_16x16x32_bf16 v[100:103], v[186:189], v[220:223], v[100:103]
	v_mfma_f32_16x16x32_bf16 v[92:95], v[162:165], v[228:231], v[92:95]
	v_mfma_f32_16x16x32_bf16 v[84:87], v[186:189], v[228:231], v[84:87]
	v_mfma_f32_16x16x32_bf16 v[76:79], v[162:165], v[236:239], v[76:79]
	v_mfma_f32_16x16x32_bf16 v[68:71], v[186:189], v[236:239], v[68:71]
	v_mfma_f32_16x16x32_bf16 v[124:127], v[182:185], v[216:219], v[124:127]
	v_mfma_f32_16x16x32_bf16 v[116:119], v[190:193], v[216:219], v[116:119]
	v_mfma_f32_16x16x32_bf16 v[108:111], v[182:185], v[224:227], v[108:111]
	v_mfma_f32_16x16x32_bf16 v[100:103], v[190:193], v[224:227], v[100:103]
	v_mfma_f32_16x16x32_bf16 v[92:95], v[182:185], v[232:235], v[92:95]
	v_mfma_f32_16x16x32_bf16 v[84:87], v[190:193], v[232:235], v[84:87]
	v_mfma_f32_16x16x32_bf16 v[76:79], v[182:185], v[240:243], v[76:79]
	v_mfma_f32_16x16x32_bf16 v[68:71], v[190:193], v[240:243], v[68:71]
	v_mfma_f32_16x16x32_bf16 v[120:123], v[194:197], v[210:213], v[120:123]
	v_mfma_f32_16x16x32_bf16 v[112:115], v[202:205], v[210:213], v[112:115]
	v_mfma_f32_16x16x32_bf16 v[104:107], v[194:197], v[220:223], v[104:107]
	v_mfma_f32_16x16x32_bf16 v[96:99], v[202:205], v[220:223], v[96:99]
	v_mfma_f32_16x16x32_bf16 v[88:91], v[194:197], v[228:231], v[88:91]
	v_mfma_f32_16x16x32_bf16 v[80:83], v[202:205], v[228:231], v[80:83]
	v_mfma_f32_16x16x32_bf16 v[72:75], v[194:197], v[236:239], v[72:75]
	v_mfma_f32_16x16x32_bf16 v[64:67], v[202:205], v[236:239], v[64:67]
	v_mfma_f32_16x16x32_bf16 v[120:123], v[198:201], v[216:219], v[120:123]
	v_mfma_f32_16x16x32_bf16 v[112:115], v[206:209], v[216:219], v[112:115]
	v_mfma_f32_16x16x32_bf16 v[104:107], v[198:201], v[224:227], v[104:107]
	v_mfma_f32_16x16x32_bf16 v[96:99], v[206:209], v[224:227], v[96:99]
	v_mfma_f32_16x16x32_bf16 v[88:91], v[198:201], v[232:235], v[88:91]
	v_mfma_f32_16x16x32_bf16 v[80:83], v[206:209], v[232:235], v[80:83]
	v_mfma_f32_16x16x32_bf16 v[72:75], v[198:201], v[240:243], v[72:75]
	v_mfma_f32_16x16x32_bf16 v[64:67], v[206:209], v[240:243], v[64:67]
	s_setprio 0
	s_barrier
	s_mov_b32 m0, s61
	v_lshl_add_u64 v[244:245], v[214:215], 0, v[138:139]
	ds_read_b128 v[210:213], v179 offset:16384
	ds_read_b128 v[216:219], v179 offset:17408
	ds_read_b128 v[220:223], v179 offset:18432
	ds_read_b128 v[224:227], v179 offset:19456
	ds_read_b128 v[228:231], v179 offset:20480
	ds_read_b128 v[232:235], v179 offset:21504
	ds_read_b128 v[236:239], v179 offset:22528
	ds_read_b128 v[240:243], v179 offset:23552
	global_load_lds_dwordx4 v[244:245], off
	v_lshl_add_u64 v[246:247], v[214:215], 0, v[134:135]
	s_mov_b32 m0, s62
	v_lshl_add_u64 v[214:215], v[214:215], 0, s[14:15]
	global_load_lds_dwordx4 v[246:247], off
	v_lshl_add_u64 v[248:249], v[214:215], 0, v[138:139]
	s_mov_b32 m0, s63
	v_lshl_add_u64 v[214:215], v[214:215], 0, v[134:135]
	global_load_lds_dwordx4 v[248:249], off
	s_add_i32 m0, s63, 0x2000
	v_lshl_add_u64 v[250:251], v[172:173], 0, v[140:141]
	global_load_lds_dwordx4 v[214:215], off
	s_mov_b32 m0, s46
	v_lshl_add_u64 v[252:253], v[172:173], 0, v[136:137]
	global_load_lds_dwordx4 v[250:251], off
	s_mov_b32 m0, s47
	s_nop 0
	global_load_lds_dwordx4 v[252:253], off
	s_waitcnt vmcnt(8)
	s_waitcnt lgkmcnt(0)
	s_setprio 1
	s_barrier
; #define PG8_STAGE(bufoff, gbase, voff) do { _Pragma("unroll") for (int _i = 0; _i < 2; ++_i) \
;         __builtin_amdgcn_global_load_lds((const unsigned*)((const char*)(gbase) + (voff)[_i]), (PG8_LAS unsigned*)(lds + (bufoff) + ldsw + _i * 8192), 16, 0, 0); } while (0)
; #define PG8_LDA(dst, b, h) do { _Pragma("unroll") for (int m = 0; m < 4; ++m) _Pragma("unroll") for (int k = 0; k < 2; ++k) dst[m][k] = *(const PG8_LAS bf16x8*)(lds + PG8_SA(b, h) + aoff + m * 2048 + k * 1024); } while (0)
; #define PG8_LDB(dst, b, h) do { _Pragma("unroll") for (int n = 0; n < 2; ++n) _Pragma("unroll") for (int k = 0; k < 2; ++k) dst[n][k] = *(const PG8_LAS bf16x8*)(lds + PG8_SB(b, h) + boff + n * 2048 + k * 1024); } while (0)
; #define PG8_MMA(ai, bj, At, Bt) do { __builtin_amdgcn_s_setprio(1); _Pragma("unroll") for (int m = 0; m < 4; ++m) _Pragma("unroll") for (int n = 0; n < 2; ++n) _Pragma("unroll") for (int k = 0; k < 2; ++k) \
;         acc[ai][bj][m][n] = __builtin_amdgcn_mfma_f32_16x16x32_bf16(Bt[n][k], At[m][k], acc[ai][bj][m][n], 0, 0, 0); __builtin_amdgcn_s_setprio(0); } while (0)
; #define PG8_WAIT_V(n) asm volatile("s_waitcnt vmcnt(" #n ")" ::: "memory")
; #define PG8_WAIT_L(n) asm volatile("s_waitcnt lgkmcnt(" #n ")" ::: "memory")
; #define PG8_BAR __builtin_amdgcn_s_barrier()
; #define PG8_SCHED __builtin_amdgcn_sched_barrier(0)
; template <class Epi, class Sched, bool ALIGN_EPI = false, bool SP2 = false>
; __device__ __forceinline__ void gemm_phase(PG8_LAS unsigned char* lds, const Gemm g, const Sched& S, const Epi& E) {
;     ...
;             PG8_WAIT_V(8); PG8_WAIT_L(0); PG8_BAR; PG8_MMA(1, 0, At, B0); PG8_MMA(1, 1, At, B1); PG8_BAR; PG8_SCHED;
;             PG8_LDB(B0, 1, 0); PG8_LDB(B1, 1, 1); PG8_SCHED; PG8_LDA(At, 1, 0); PG8_STAGE(PG8_SA(0, 1), a2 + hstep, voffA);
;             PG8_WAIT_V(8); PG8_WAIT_L(0); PG8_BAR; PG8_MMA(0, 0, At, B0); PG8_MMA(0, 1, At, B1); PG8_BAR; PG8_SCHED;
	v_mfma_f32_16x16x32_bf16 v[60:63], v[162:165], v[210:213], v[60:63]
	v_mfma_f32_16x16x32_bf16 v[52:55], v[186:189], v[210:213], v[52:55]
	v_mfma_f32_16x16x32_bf16 v[44:47], v[162:165], v[220:223], v[44:47]
	v_mfma_f32_16x16x32_bf16 v[36:39], v[186:189], v[220:223], v[36:39]
	v_mfma_f32_16x16x32_bf16 v[28:31], v[162:165], v[228:231], v[28:31]
	v_mfma_f32_16x16x32_bf16 v[20:23], v[186:189], v[228:231], v[20:23]
	v_mfma_f32_16x16x32_bf16 v[12:15], v[162:165], v[236:239], v[12:15]
	v_mfma_f32_16x16x32_bf16 v[4:7], v[186:189], v[236:239], v[4:7]
	v_mfma_f32_16x16x32_bf16 v[60:63], v[182:185], v[216:219], v[60:63]
	v_mfma_f32_16x16x32_bf16 v[52:55], v[190:193], v[216:219], v[52:55]
	v_mfma_f32_16x16x32_bf16 v[44:47], v[182:185], v[224:227], v[44:47]
	v_mfma_f32_16x16x32_bf16 v[36:39], v[190:193], v[224:227], v[36:39]
	v_mfma_f32_16x16x32_bf16 v[28:31], v[182:185], v[232:235], v[28:31]
	v_mfma_f32_16x16x32_bf16 v[20:23], v[190:193], v[232:235], v[20:23]
	v_mfma_f32_16x16x32_bf16 v[12:15], v[182:185], v[240:243], v[12:15]
	v_mfma_f32_16x16x32_bf16 v[4:7], v[190:193], v[240:243], v[4:7]
	v_mfma_f32_16x16x32_bf16 v[56:59], v[194:197], v[210:213], v[56:59]
	v_mfma_f32_16x16x32_bf16 v[48:51], v[202:205], v[210:213], v[48:51]
	v_mfma_f32_16x16x32_bf16 v[40:43], v[194:197], v[220:223], v[40:43]
	v_mfma_f32_16x16x32_bf16 v[32:35], v[202:205], v[220:223], v[32:35]
	v_mfma_f32_16x16x32_bf16 v[24:27], v[194:197], v[228:231], v[24:27]
	v_mfma_f32_16x16x32_bf16 v[16:19], v[202:205], v[228:231], v[16:19]
	v_mfma_f32_16x16x32_bf16 v[8:11], v[194:197], v[236:239], v[8:11]
	v_mfma_f32_16x16x32_bf16 v[0:3], v[202:205], v[236:239], v[0:3]
	v_mfma_f32_16x16x32_bf16 v[56:59], v[198:201], v[216:219], v[56:59]
	v_mfma_f32_16x16x32_bf16 v[48:51], v[206:209], v[216:219], v[48:51]
	v_mfma_f32_16x16x32_bf16 v[40:43], v[198:201], v[224:227], v[40:43]
	v_mfma_f32_16x16x32_bf16 v[32:35], v[206:209], v[224:227], v[32:35]
	v_mfma_f32_16x16x32_bf16 v[24:27], v[198:201], v[232:235], v[24:27]
	v_mfma_f32_16x16x32_bf16 v[16:19], v[206:209], v[232:235], v[16:19]
	v_mfma_f32_16x16x32_bf16 v[8:11], v[198:201], v[240:243], v[8:11]
	v_mfma_f32_16x16x32_bf16 v[0:3], v[206:209], v[240:243], v[0:3]
	s_setprio 0
	s_barrier
	s_add_i32 s11, 0, 0x18000
	v_add_u32_e32 v166, s11, v169
	s_add_i32 s13, 0, 0x1c000
	ds_read_b128 v[162:165], v166
	ds_read_b128 v[182:185], v166 offset:1024
	ds_read_b128 v[186:189], v166 offset:2048
	ds_read_b128 v[190:193], v166 offset:3072
	v_add_u32_e32 v166, s13, v169
	ds_read_b128 v[194:197], v166
	ds_read_b128 v[198:201], v166 offset:1024
	ds_read_b128 v[202:205], v166 offset:2048
	ds_read_b128 v[206:209], v166 offset:3072
	v_lshl_add_u64 v[172:173], v[172:173], 0, s[14:15]
	s_mov_b32 m0, s48
	v_lshl_add_u64 v[170:171], v[172:173], 0, v[140:141]
	ds_read_b128 v[210:213], v179 offset:32768
	ds_read_b128 v[216:219], v179 offset:33792
	ds_read_b128 v[220:223], v179 offset:34816
	ds_read_b128 v[224:227], v179 offset:35840
	ds_read_b128 v[228:231], v179 offset:36864
	ds_read_b128 v[232:235], v179 offset:37888
	ds_read_b128 v[236:239], v179 offset:38912
	ds_read_b128 v[240:243], v179 offset:39936
	global_load_lds_dwordx4 v[170:171], off
	v_lshl_add_u64 v[170:171], v[172:173], 0, v[136:137]
	s_mov_b32 m0, s49
	s_nop 0
	global_load_lds_dwordx4 v[170:171], off
	s_waitcnt vmcnt(8)
	s_waitcnt lgkmcnt(0)
	s_setprio 1
	s_barrier
	v_mfma_f32_16x16x32_bf16 v[124:127], v[162:165], v[210:213], v[124:127]
	v_mfma_f32_16x16x32_bf16 v[116:119], v[186:189], v[210:213], v[116:119]
	v_mfma_f32_16x16x32_bf16 v[108:111], v[162:165], v[220:223], v[108:111]
	v_mfma_f32_16x16x32_bf16 v[100:103], v[186:189], v[220:223], v[100:103]
	v_mfma_f32_16x16x32_bf16 v[92:95], v[162:165], v[228:231], v[92:95]
	v_mfma_f32_16x16x32_bf16 v[84:87], v[186:189], v[228:231], v[84:87]
	v_mfma_f32_16x16x32_bf16 v[76:79], v[162:165], v[236:239], v[76:79]
	v_mfma_f32_16x16x32_bf16 v[68:71], v[186:189], v[236:239], v[68:71]
	v_mfma_f32_16x16x32_bf16 v[124:127], v[182:185], v[216:219], v[124:127]
	v_mfma_f32_16x16x32_bf16 v[116:119], v[190:193], v[216:219], v[116:119]
	v_mfma_f32_16x16x32_bf16 v[108:111], v[182:185], v[224:227], v[108:111]
	v_mfma_f32_16x16x32_bf16 v[100:103], v[190:193], v[224:227], v[100:103]
	v_mfma_f32_16x16x32_bf16 v[92:95], v[182:185], v[232:235], v[92:95]
	v_mfma_f32_16x16x32_bf16 v[84:87], v[190:193], v[232:235], v[84:87]
	v_mfma_f32_16x16x32_bf16 v[76:79], v[182:185], v[240:243], v[76:79]
	v_mfma_f32_16x16x32_bf16 v[68:71], v[190:193], v[240:243], v[68:71]
	v_mfma_f32_16x16x32_bf16 v[120:123], v[194:197], v[210:213], v[120:123]
	v_mfma_f32_16x16x32_bf16 v[112:115], v[202:205], v[210:213], v[112:115]
	v_mfma_f32_16x16x32_bf16 v[104:107], v[194:197], v[220:223], v[104:107]
	v_mfma_f32_16x16x32_bf16 v[96:99], v[202:205], v[220:223], v[96:99]
	v_mfma_f32_16x16x32_bf16 v[88:91], v[194:197], v[228:231], v[88:91]
	v_mfma_f32_16x16x32_bf16 v[80:83], v[202:205], v[228:231], v[80:83]
	v_mfma_f32_16x16x32_bf16 v[72:75], v[194:197], v[236:239], v[72:75]
	v_mfma_f32_16x16x32_bf16 v[64:67], v[202:205], v[236:239], v[64:67]
	v_mfma_f32_16x16x32_bf16 v[120:123], v[198:201], v[216:219], v[120:123]
	v_mfma_f32_16x16x32_bf16 v[112:115], v[206:209], v[216:219], v[112:115]
	v_mfma_f32_16x16x32_bf16 v[104:107], v[198:201], v[224:227], v[104:107]
	v_mfma_f32_16x16x32_bf16 v[96:99], v[206:209], v[224:227], v[96:99]
	v_mfma_f32_16x16x32_bf16 v[88:91], v[198:201], v[232:235], v[88:91]
	v_mfma_f32_16x16x32_bf16 v[80:83], v[206:209], v[232:235], v[80:83]
	v_mfma_f32_16x16x32_bf16 v[72:75], v[198:201], v[240:243], v[72:75]
	v_mfma_f32_16x16x32_bf16 v[64:67], v[206:209], v[240:243], v[64:67]
	s_setprio 0
	s_barrier
; #define PG8_STAGE(bufoff, gbase, voff) do { _Pragma("unroll") for (int _i = 0; _i < 2; ++_i) \
;         __builtin_amdgcn_global_load_lds((const unsigned*)((const char*)(gbase) + (voff)[_i]), (PG8_LAS unsigned*)(lds + (bufoff) + ldsw + _i * 8192), 16, 0, 0); } while (0)
; #define PG8_LDA(dst, b, h) do { _Pragma("unroll") for (int m = 0; m < 4; ++m) _Pragma("unroll") for (int k = 0; k < 2; ++k) dst[m][k] = *(const PG8_LAS bf16x8*)(lds + PG8_SA(b, h) + aoff + m * 2048 + k * 1024); } while (0)
; #define PG8_MMA(ai, bj, At, Bt) do { __builtin_amdgcn_s_setprio(1); _Pragma("unroll") for (int m = 0; m < 4; ++m) _Pragma("unroll") for (int n = 0; n < 2; ++n) _Pragma("unroll") for (int k = 0; k < 2; ++k) \
;         acc[ai][bj][m][n] = __builtin_amdgcn_mfma_f32_16x16x32_bf16(Bt[n][k], At[m][k], acc[ai][bj][m][n], 0, 0, 0); __builtin_amdgcn_s_setprio(0); } while (0)
; #define PG8_WAIT_V(n) asm volatile("s_waitcnt vmcnt(" #n ")" ::: "memory")
; #define PG8_WAIT_L(n) asm volatile("s_waitcnt lgkmcnt(" #n ")" ::: "memory")
; #define PG8_BAR __builtin_amdgcn_s_barrier()
; #define PG8_SCHED __builtin_amdgcn_sched_barrier(0)
; template <class Epi, class Sched, bool ALIGN_EPI = false, bool SP2 = false>
; __device__ __forceinline__ void gemm_phase(PG8_LAS unsigned char* lds, const Gemm g, const Sched& S, const Epi& E) {
;     ...
;             PG8_LDA(At, 1, 1); PG8_STAGE(PG8_SB(1, 0), b3, voffB); PG8_STAGE(PG8_SB(1, 1), b3 + hstep, voffB); PG8_STAGE(PG8_SA(1, 0), a3, voffA);
;             PG8_WAIT_V(8); PG8_WAIT_L(0); PG8_BAR; PG8_MMA(1, 0, At, B0); PG8_MMA(1, 1, At, B1); PG8_BAR; PG8_SCHED;
	s_add_i32 s11, s11, s29
	v_lshl_add_u64 v[170:171], v[244:245], 0, s[22:23]
	s_mov_b32 m0, s11
	ds_read_b128 v[210:213], v179 offset:49152
	ds_read_b128 v[216:219], v179 offset:50176
	ds_read_b128 v[220:223], v179 offset:51200
	ds_read_b128 v[224:227], v179 offset:52224
	ds_read_b128 v[228:231], v179 offset:53248
	ds_read_b128 v[232:235], v179 offset:54272
	ds_read_b128 v[236:239], v179 offset:55296
	ds_read_b128 v[240:243], v179 offset:56320
	global_load_lds_dwordx4 v[170:171], off
	v_lshl_add_u64 v[170:171], v[246:247], 0, s[22:23]
	s_add_i32 m0, s11, 0x2000
	s_add_i32 s11, s13, s29
	global_load_lds_dwordx4 v[170:171], off
	v_lshl_add_u64 v[170:171], v[248:249], 0, s[22:23]
	s_mov_b32 m0, s11
	s_nop 0
	global_load_lds_dwordx4 v[170:171], off
	v_lshl_add_u64 v[170:171], v[214:215], 0, s[22:23]
	s_add_i32 m0, s11, 0x2000
	s_nop 0
	global_load_lds_dwordx4 v[170:171], off
	v_lshl_add_u64 v[170:171], v[250:251], 0, s[22:23]
	s_mov_b32 m0, s50
	s_nop 0
	global_load_lds_dwordx4 v[170:171], off
	v_lshl_add_u64 v[170:171], v[252:253], 0, s[22:23]
	s_mov_b32 m0, s51
	s_nop 0
	global_load_lds_dwordx4 v[170:171], off
	s_waitcnt vmcnt(8)
	s_waitcnt lgkmcnt(0)
	s_setprio 1
	s_barrier
	v_mfma_f32_16x16x32_bf16 v[60:63], v[162:165], v[210:213], v[60:63]
	v_mfma_f32_16x16x32_bf16 v[52:55], v[186:189], v[210:213], v[52:55]
	v_mfma_f32_16x16x32_bf16 v[44:47], v[162:165], v[220:223], v[44:47]
	v_mfma_f32_16x16x32_bf16 v[36:39], v[186:189], v[220:223], v[36:39]
	v_mfma_f32_16x16x32_bf16 v[28:31], v[162:165], v[228:231], v[28:31]
	v_mfma_f32_16x16x32_bf16 v[20:23], v[186:189], v[228:231], v[20:23]
	v_mfma_f32_16x16x32_bf16 v[12:15], v[162:165], v[236:239], v[12:15]
	v_mfma_f32_16x16x32_bf16 v[4:7], v[186:189], v[236:239], v[4:7]
	v_mfma_f32_16x16x32_bf16 v[60:63], v[182:185], v[216:219], v[60:63]
	v_mfma_f32_16x16x32_bf16 v[52:55], v[190:193], v[216:219], v[52:55]
	v_mfma_f32_16x16x32_bf16 v[44:47], v[182:185], v[224:227], v[44:47]
	v_mfma_f32_16x16x32_bf16 v[36:39], v[190:193], v[224:227], v[36:39]
	v_mfma_f32_16x16x32_bf16 v[28:31], v[182:185], v[232:235], v[28:31]
	v_mfma_f32_16x16x32_bf16 v[20:23], v[190:193], v[232:235], v[20:23]
	v_mfma_f32_16x16x32_bf16 v[12:15], v[182:185], v[240:243], v[12:15]
	v_mfma_f32_16x16x32_bf16 v[4:7], v[190:193], v[240:243], v[4:7]
	v_mfma_f32_16x16x32_bf16 v[56:59], v[194:197], v[210:213], v[56:59]
	v_mfma_f32_16x16x32_bf16 v[48:51], v[202:205], v[210:213], v[48:51]
	v_mfma_f32_16x16x32_bf16 v[40:43], v[194:197], v[220:223], v[40:43]
	v_mfma_f32_16x16x32_bf16 v[32:35], v[202:205], v[220:223], v[32:35]
	v_mfma_f32_16x16x32_bf16 v[24:27], v[194:197], v[228:231], v[24:27]
	v_mfma_f32_16x16x32_bf16 v[16:19], v[202:205], v[228:231], v[16:19]
	v_mfma_f32_16x16x32_bf16 v[8:11], v[194:197], v[236:239], v[8:11]
	v_mfma_f32_16x16x32_bf16 v[0:3], v[202:205], v[236:239], v[0:3]
	v_mfma_f32_16x16x32_bf16 v[56:59], v[198:201], v[216:219], v[56:59]
	v_mfma_f32_16x16x32_bf16 v[48:51], v[206:209], v[216:219], v[48:51]
	v_mfma_f32_16x16x32_bf16 v[40:43], v[198:201], v[224:227], v[40:43]
	v_mfma_f32_16x16x32_bf16 v[32:35], v[206:209], v[224:227], v[32:35]
	v_mfma_f32_16x16x32_bf16 v[24:27], v[198:201], v[232:235], v[24:27]
	v_mfma_f32_16x16x32_bf16 v[16:19], v[206:209], v[232:235], v[16:19]
	v_mfma_f32_16x16x32_bf16 v[8:11], v[198:201], v[240:243], v[8:11]
	v_mfma_f32_16x16x32_bf16 v[0:3], v[206:209], v[240:243], v[0:3]
	s_setprio 0
	s_barrier
	v_lshl_add_u64 v[158:159], v[158:159], 0, s[26:27]
	s_cmp_ge_i32 s10, s52
	v_lshl_add_u64 v[160:161], v[160:161], 0, s[26:27]
	s_cbranch_scc0 .LBB0_1021

; #define PG8_STAGE(bufoff, gbase, voff) do { _Pragma("unroll") for (int _i = 0; _i < 2; ++_i) \
;         __builtin_amdgcn_global_load_lds((const unsigned*)((const char*)(gbase) + (voff)[_i]), (PG8_LAS unsigned*)(lds + (bufoff) + ldsw + _i * 8192), 16, 0, 0); } while (0)
; #define PG8_LDA(dst, b, h) do { _Pragma("unroll") for (int m = 0; m < 4; ++m) _Pragma("unroll") for (int k = 0; k < 2; ++k) dst[m][k] = *(const PG8_LAS bf16x8*)(lds + PG8_SA(b, h) + aoff + m * 2048 + k * 1024); } while (0)
; #define PG8_LDB(dst, b, h) do { _Pragma("unroll") for (int n = 0; n < 2; ++n) _Pragma("unroll") for (int k = 0; k < 2; ++k) dst[n][k] = *(const PG8_LAS bf16x8*)(lds + PG8_SB(b, h) + boff + n * 2048 + k * 1024); } while (0)
; #define PG8_MMA(ai, bj, At, Bt) do { __builtin_amdgcn_s_setprio(1); _Pragma("unroll") for (int m = 0; m < 4; ++m) _Pragma("unroll") for (int n = 0; n < 2; ++n) _Pragma("unroll") for (int k = 0; k < 2; ++k) \
;         acc[ai][bj][m][n] = __builtin_amdgcn_mfma_f32_16x16x32_bf16(Bt[n][k], At[m][k], acc[ai][bj][m][n], 0, 0, 0); __builtin_amdgcn_s_setprio(0); } while (0)
; #define PG8_WAIT_V(n) asm volatile("s_waitcnt vmcnt(" #n ")" ::: "memory")
; #define PG8_WAIT_L(n) asm volatile("s_waitcnt lgkmcnt(" #n ")" ::: "memory")
; #define PG8_BAR __builtin_amdgcn_s_barrier()
; template <class Epi, class Sched, bool ALIGN_EPI = false, bool SP2 = false>
; __device__ __forceinline__ void gemm_phase(PG8_LAS unsigned char* lds, const Gemm g, const Sched& S, const Epi& E) {
;     ...
;             const char* a1 = cA + (size_t)(t + 1) * kstep;
;             const char* a2 = last ? nA : cA + (size_t)(t + 2) * kstep; const char* b2 = last ? nB : cB + (size_t)(t + 2) * kstep;
;             const char* a3 = a2 + kstep; const char* b3 = b2 + kstep;
;             if (last && has_next) S.a_ready(nxt);
;             if constexpr (SP2) {
;             PG8_LDB(B0, 0, 0); PG8_LDB(B1, 0, 1); PG8_SCHED; PG8_LDA(At, 0, 0); PG8_STAGE(PG8_SA(1, 1), a1 + hstep, voffA);
;             PG8_WAIT_V(8); PG8_WAIT_L(0); PG8_BAR; PG8_MMA(0, 0, At, B0); PG8_MMA(0, 1, At, B1); PG8_BAR; PG8_SCHED;
;             PG8_LDA(At, 0, 1); PG8_STAGE(PG8_SB(0, 0), b2, voffB); PG8_STAGE(PG8_SB(0, 1), b2 + hstep, voffB); PG8_STAGE(PG8_SA(0, 0), a2, voffA);
;             PG8_WAIT_V(8); PG8_WAIT_L(0); PG8_BAR; PG8_MMA(1, 0, At, B0); PG8_MMA(1, 1, At, B1); PG8_BAR; PG8_SCHED;
.LBB0_1169:
	v_add_u32_e32 v192, s52, v161
	ds_read_b128 v[164:167], v162
	ds_read_b128 v[168:171], v162 offset:1024
	ds_read_b128 v[172:175], v162 offset:2048
	ds_read_b128 v[176:179], v162 offset:3072
	ds_read_b128 v[180:183], v192
	ds_read_b128 v[184:187], v192 offset:1024
	ds_read_b128 v[188:191], v192 offset:2048
	ds_read_b128 v[192:195], v192 offset:3072
	s_cmp_eq_u32 s51, s10
	v_lshl_add_u64 v[196:197], v[158:159], 0, s[24:25]
	s_cselect_b64 vcc, -1, 0
	s_add_i32 s10, s10, 2
	v_cndmask_b32_e32 v213, v197, v151, vcc
	v_cndmask_b32_e32 v212, v196, v150, vcc
	v_cndmask_b32_e32 v215, v155, v153, vcc
	v_cndmask_b32_e32 v214, v154, v152, vcc
	s_mov_b32 m0, s54
	v_lshl_add_u64 v[232:233], v[158:159], 0, v[146:147]
	ds_read_b128 v[196:199], v163
	ds_read_b128 v[200:203], v163 offset:1024
	ds_read_b128 v[204:207], v163 offset:2048
	ds_read_b128 v[208:211], v163 offset:3072
	ds_read_b128 v[216:219], v163 offset:4096
	ds_read_b128 v[220:223], v163 offset:5120
	ds_read_b128 v[224:227], v163 offset:6144
	ds_read_b128 v[228:231], v163 offset:7168
	global_load_lds_dwordx4 v[232:233], off
	v_lshl_add_u64 v[232:233], v[158:159], 0, v[144:145]
	s_mov_b32 m0, s55
	s_nop 0
	global_load_lds_dwordx4 v[232:233], off
	s_waitcnt vmcnt(8)
	s_waitcnt lgkmcnt(0)
	s_setprio 1
	s_barrier
	v_mfma_f32_16x16x32_bf16 v[124:127], v[164:167], v[196:199], v[124:127]
	v_mfma_f32_16x16x32_bf16 v[120:123], v[172:175], v[196:199], v[120:123]
	v_mfma_f32_16x16x32_bf16 v[108:111], v[164:167], v[204:207], v[108:111]
	v_mfma_f32_16x16x32_bf16 v[104:107], v[172:175], v[204:207], v[104:107]
	v_mfma_f32_16x16x32_bf16 v[92:95], v[164:167], v[216:219], v[92:95]
	v_mfma_f32_16x16x32_bf16 v[88:91], v[172:175], v[216:219], v[88:91]
	v_mfma_f32_16x16x32_bf16 v[76:79], v[164:167], v[224:227], v[76:79]
	v_mfma_f32_16x16x32_bf16 v[72:75], v[172:175], v[224:227], v[72:75]
	v_mfma_f32_16x16x32_bf16 v[124:127], v[168:171], v[200:203], v[124:127]
	v_mfma_f32_16x16x32_bf16 v[120:123], v[176:179], v[200:203], v[120:123]
	v_mfma_f32_16x16x32_bf16 v[108:111], v[168:171], v[208:211], v[108:111]
	v_mfma_f32_16x16x32_bf16 v[104:107], v[176:179], v[208:211], v[104:107]
	v_mfma_f32_16x16x32_bf16 v[92:95], v[168:171], v[220:223], v[92:95]
	v_mfma_f32_16x16x32_bf16 v[88:91], v[176:179], v[220:223], v[88:91]
	v_mfma_f32_16x16x32_bf16 v[76:79], v[168:171], v[228:231], v[76:79]
	v_mfma_f32_16x16x32_bf16 v[72:75], v[176:179], v[228:231], v[72:75]
	v_mfma_f32_16x16x32_bf16 v[116:119], v[180:183], v[196:199], v[116:119]
	v_mfma_f32_16x16x32_bf16 v[112:115], v[188:191], v[196:199], v[112:115]
	v_mfma_f32_16x16x32_bf16 v[100:103], v[180:183], v[204:207], v[100:103]
	v_mfma_f32_16x16x32_bf16 v[96:99], v[188:191], v[204:207], v[96:99]
	v_mfma_f32_16x16x32_bf16 v[84:87], v[180:183], v[216:219], v[84:87]
	v_mfma_f32_16x16x32_bf16 v[80:83], v[188:191], v[216:219], v[80:83]
	v_mfma_f32_16x16x32_bf16 v[68:71], v[180:183], v[224:227], v[68:71]
	v_mfma_f32_16x16x32_bf16 v[64:67], v[188:191], v[224:227], v[64:67]
	v_mfma_f32_16x16x32_bf16 v[116:119], v[184:187], v[200:203], v[116:119]
	v_mfma_f32_16x16x32_bf16 v[112:115], v[192:195], v[200:203], v[112:115]
	v_mfma_f32_16x16x32_bf16 v[100:103], v[184:187], v[208:211], v[100:103]
	v_mfma_f32_16x16x32_bf16 v[96:99], v[192:195], v[208:211], v[96:99]
	v_mfma_f32_16x16x32_bf16 v[84:87], v[184:187], v[220:223], v[84:87]
	v_mfma_f32_16x16x32_bf16 v[80:83], v[192:195], v[220:223], v[80:83]
	v_mfma_f32_16x16x32_bf16 v[68:71], v[184:187], v[228:231], v[68:71]
	v_mfma_f32_16x16x32_bf16 v[64:67], v[192:195], v[228:231], v[64:67]
	s_setprio 0
	s_barrier
	s_mov_b32 m0, s56
	v_lshl_add_u64 v[232:233], v[214:215], 0, v[138:139]
	ds_read_b128 v[196:199], v163 offset:16384
	ds_read_b128 v[200:203], v163 offset:17408
	ds_read_b128 v[204:207], v163 offset:18432
	ds_read_b128 v[208:211], v163 offset:19456
	ds_read_b128 v[216:219], v163 offset:20480
	ds_read_b128 v[220:223], v163 offset:21504
	ds_read_b128 v[224:227], v163 offset:22528
	ds_read_b128 v[228:231], v163 offset:23552
	global_load_lds_dwordx4 v[232:233], off
	v_lshl_add_u64 v[234:235], v[214:215], 0, v[134:135]
	s_mov_b32 m0, s57
	v_lshl_add_u64 v[214:215], v[214:215], 0, s[14:15]
	global_load_lds_dwordx4 v[234:235], off
	v_lshl_add_u64 v[236:237], v[214:215], 0, v[138:139]
	s_mov_b32 m0, s58
	v_lshl_add_u64 v[214:215], v[214:215], 0, v[134:135]
	global_load_lds_dwordx4 v[236:237], off
	s_mov_b32 m0, s59
	v_lshl_add_u64 v[238:239], v[212:213], 0, v[140:141]
	global_load_lds_dwordx4 v[214:215], off
	s_mov_b32 m0, s37
	v_lshl_add_u64 v[240:241], v[212:213], 0, v[136:137]
	global_load_lds_dwordx4 v[238:239], off
	s_mov_b32 m0, s41
	s_nop 0
	global_load_lds_dwordx4 v[240:241], off
	s_waitcnt vmcnt(8)
	s_waitcnt lgkmcnt(0)
	s_setprio 1
	s_barrier
; #define PG8_STAGE(bufoff, gbase, voff) do { _Pragma("unroll") for (int _i = 0; _i < 2; ++_i) \
;         __builtin_amdgcn_global_load_lds((const unsigned*)((const char*)(gbase) + (voff)[_i]), (PG8_LAS unsigned*)(lds + (bufoff) + ldsw + _i * 8192), 16, 0, 0); } while (0)
; #define PG8_LDA(dst, b, h) do { _Pragma("unroll") for (int m = 0; m < 4; ++m) _Pragma("unroll") for (int k = 0; k < 2; ++k) dst[m][k] = *(const PG8_LAS bf16x8*)(lds + PG8_SA(b, h) + aoff + m * 2048 + k * 1024); } while (0)
; #define PG8_LDB(dst, b, h) do { _Pragma("unroll") for (int n = 0; n < 2; ++n) _Pragma("unroll") for (int k = 0; k < 2; ++k) dst[n][k] = *(const PG8_LAS bf16x8*)(lds + PG8_SB(b, h) + boff + n * 2048 + k * 1024); } while (0)
; #define PG8_MMA(ai, bj, At, Bt) do { __builtin_amdgcn_s_setprio(1); _Pragma("unroll") for (int m = 0; m < 4; ++m) _Pragma("unroll") for (int n = 0; n < 2; ++n) _Pragma("unroll") for (int k = 0; k < 2; ++k) \
;         acc[ai][bj][m][n] = __builtin_amdgcn_mfma_f32_16x16x32_bf16(Bt[n][k], At[m][k], acc[ai][bj][m][n], 0, 0, 0); __builtin_amdgcn_s_setprio(0); } while (0)
; #define PG8_WAIT_V(n) asm volatile("s_waitcnt vmcnt(" #n ")" ::: "memory")
; #define PG8_WAIT_L(n) asm volatile("s_waitcnt lgkmcnt(" #n ")" ::: "memory")
; #define PG8_BAR __builtin_amdgcn_s_barrier()
; #define PG8_SCHED __builtin_amdgcn_sched_barrier(0)
; template <class Epi, class Sched, bool ALIGN_EPI = false, bool SP2 = false>
; __device__ __forceinline__ void gemm_phase(PG8_LAS unsigned char* lds, const Gemm g, const Sched& S, const Epi& E) {
;     ...
;             PG8_WAIT_V(8); PG8_WAIT_L(0); PG8_BAR; PG8_MMA(1, 0, At, B0); PG8_MMA(1, 1, At, B1); PG8_BAR; PG8_SCHED;
;             PG8_LDB(B0, 1, 0); PG8_LDB(B1, 1, 1); PG8_SCHED; PG8_LDA(At, 1, 0); PG8_STAGE(PG8_SA(0, 1), a2 + hstep, voffA);
;             PG8_WAIT_V(8); PG8_WAIT_L(0); PG8_BAR; PG8_MMA(0, 0, At, B0); PG8_MMA(0, 1, At, B1); PG8_BAR; PG8_SCHED;
	v_mfma_f32_16x16x32_bf16 v[60:63], v[164:167], v[196:199], v[60:63]
	v_mfma_f32_16x16x32_bf16 v[56:59], v[172:175], v[196:199], v[56:59]
	v_mfma_f32_16x16x32_bf16 v[44:47], v[164:167], v[204:207], v[44:47]
	v_mfma_f32_16x16x32_bf16 v[40:43], v[172:175], v[204:207], v[40:43]
	v_mfma_f32_16x16x32_bf16 v[28:31], v[164:167], v[216:219], v[28:31]
	v_mfma_f32_16x16x32_bf16 v[24:27], v[172:175], v[216:219], v[24:27]
	v_mfma_f32_16x16x32_bf16 v[12:15], v[164:167], v[224:227], v[12:15]
	v_mfma_f32_16x16x32_bf16 v[8:11], v[172:175], v[224:227], v[8:11]
	v_mfma_f32_16x16x32_bf16 v[60:63], v[168:171], v[200:203], v[60:63]
	v_mfma_f32_16x16x32_bf16 v[56:59], v[176:179], v[200:203], v[56:59]
	v_mfma_f32_16x16x32_bf16 v[44:47], v[168:171], v[208:211], v[44:47]
	v_mfma_f32_16x16x32_bf16 v[40:43], v[176:179], v[208:211], v[40:43]
	v_mfma_f32_16x16x32_bf16 v[28:31], v[168:171], v[220:223], v[28:31]
	v_mfma_f32_16x16x32_bf16 v[24:27], v[176:179], v[220:223], v[24:27]
	v_mfma_f32_16x16x32_bf16 v[12:15], v[168:171], v[228:231], v[12:15]
	v_mfma_f32_16x16x32_bf16 v[8:11], v[176:179], v[228:231], v[8:11]
	v_mfma_f32_16x16x32_bf16 v[52:55], v[180:183], v[196:199], v[52:55]
	v_mfma_f32_16x16x32_bf16 v[48:51], v[188:191], v[196:199], v[48:51]
	v_mfma_f32_16x16x32_bf16 v[36:39], v[180:183], v[204:207], v[36:39]
	v_mfma_f32_16x16x32_bf16 v[32:35], v[188:191], v[204:207], v[32:35]
	v_mfma_f32_16x16x32_bf16 v[20:23], v[180:183], v[216:219], v[20:23]
	v_mfma_f32_16x16x32_bf16 v[16:19], v[188:191], v[216:219], v[16:19]
	v_mfma_f32_16x16x32_bf16 v[4:7], v[180:183], v[224:227], v[4:7]
	v_mfma_f32_16x16x32_bf16 v[0:3], v[188:191], v[224:227], v[0:3]
	v_mfma_f32_16x16x32_bf16 v[52:55], v[184:187], v[200:203], v[52:55]
	v_mfma_f32_16x16x32_bf16 v[48:51], v[192:195], v[200:203], v[48:51]
	v_mfma_f32_16x16x32_bf16 v[36:39], v[184:187], v[208:211], v[36:39]
	v_mfma_f32_16x16x32_bf16 v[32:35], v[192:195], v[208:211], v[32:35]
	v_mfma_f32_16x16x32_bf16 v[20:23], v[184:187], v[220:223], v[20:23]
	v_mfma_f32_16x16x32_bf16 v[16:19], v[192:195], v[220:223], v[16:19]
	v_mfma_f32_16x16x32_bf16 v[4:7], v[184:187], v[228:231], v[4:7]
	v_mfma_f32_16x16x32_bf16 v[0:3], v[192:195], v[228:231], v[0:3]
	s_setprio 0
	s_barrier
	v_add_u32_e32 v176, s60, v161
	v_add_u32_e32 v192, s61, v161
	ds_read_b128 v[164:167], v176
	ds_read_b128 v[168:171], v176 offset:1024
	ds_read_b128 v[172:175], v176 offset:2048
	ds_read_b128 v[176:179], v176 offset:3072
	ds_read_b128 v[180:183], v192
	ds_read_b128 v[184:187], v192 offset:1024
	ds_read_b128 v[188:191], v192 offset:2048
	ds_read_b128 v[192:195], v192 offset:3072
	v_lshl_add_u64 v[212:213], v[212:213], 0, s[14:15]
	s_mov_b32 m0, s46
	v_lshl_add_u64 v[242:243], v[212:213], 0, v[140:141]
	ds_read_b128 v[196:199], v163 offset:32768
	ds_read_b128 v[200:203], v163 offset:33792
	ds_read_b128 v[204:207], v163 offset:34816
	ds_read_b128 v[208:211], v163 offset:35840
	ds_read_b128 v[216:219], v163 offset:36864
	ds_read_b128 v[220:223], v163 offset:37888
	ds_read_b128 v[224:227], v163 offset:38912
	ds_read_b128 v[228:231], v163 offset:39936
	global_load_lds_dwordx4 v[242:243], off
	v_lshl_add_u64 v[212:213], v[212:213], 0, v[136:137]
	s_mov_b32 m0, s47
	s_nop 0
	global_load_lds_dwordx4 v[212:213], off
	s_waitcnt vmcnt(8)
	s_waitcnt lgkmcnt(0)
	s_setprio 1
	s_barrier
	v_mfma_f32_16x16x32_bf16 v[124:127], v[164:167], v[196:199], v[124:127]
	v_mfma_f32_16x16x32_bf16 v[120:123], v[172:175], v[196:199], v[120:123]
	v_mfma_f32_16x16x32_bf16 v[108:111], v[164:167], v[204:207], v[108:111]
	v_mfma_f32_16x16x32_bf16 v[104:107], v[172:175], v[204:207], v[104:107]
	v_mfma_f32_16x16x32_bf16 v[92:95], v[164:167], v[216:219], v[92:95]
	v_mfma_f32_16x16x32_bf16 v[88:91], v[172:175], v[216:219], v[88:91]
	v_mfma_f32_16x16x32_bf16 v[76:79], v[164:167], v[224:227], v[76:79]
	v_mfma_f32_16x16x32_bf16 v[72:75], v[172:175], v[224:227], v[72:75]
	v_mfma_f32_16x16x32_bf16 v[124:127], v[168:171], v[200:203], v[124:127]
	v_mfma_f32_16x16x32_bf16 v[120:123], v[176:179], v[200:203], v[120:123]
	v_mfma_f32_16x16x32_bf16 v[108:111], v[168:171], v[208:211], v[108:111]
	v_mfma_f32_16x16x32_bf16 v[104:107], v[176:179], v[208:211], v[104:107]
	v_mfma_f32_16x16x32_bf16 v[92:95], v[168:171], v[220:223], v[92:95]
	v_mfma_f32_16x16x32_bf16 v[88:91], v[176:179], v[220:223], v[88:91]
	v_mfma_f32_16x16x32_bf16 v[76:79], v[168:171], v[228:231], v[76:79]
	v_mfma_f32_16x16x32_bf16 v[72:75], v[176:179], v[228:231], v[72:75]
	v_mfma_f32_16x16x32_bf16 v[116:119], v[180:183], v[196:199], v[116:119]
	v_mfma_f32_16x16x32_bf16 v[112:115], v[188:191], v[196:199], v[112:115]
	v_mfma_f32_16x16x32_bf16 v[100:103], v[180:183], v[204:207], v[100:103]
	v_mfma_f32_16x16x32_bf16 v[96:99], v[188:191], v[204:207], v[96:99]
	v_mfma_f32_16x16x32_bf16 v[84:87], v[180:183], v[216:219], v[84:87]
	v_mfma_f32_16x16x32_bf16 v[80:83], v[188:191], v[216:219], v[80:83]
	v_mfma_f32_16x16x32_bf16 v[68:71], v[180:183], v[224:227], v[68:71]
	v_mfma_f32_16x16x32_bf16 v[64:67], v[188:191], v[224:227], v[64:67]
	v_mfma_f32_16x16x32_bf16 v[116:119], v[184:187], v[200:203], v[116:119]
	v_mfma_f32_16x16x32_bf16 v[112:115], v[192:195], v[200:203], v[112:115]
	v_mfma_f32_16x16x32_bf16 v[100:103], v[184:187], v[208:211], v[100:103]
	v_mfma_f32_16x16x32_bf16 v[96:99], v[192:195], v[208:211], v[96:99]
	v_mfma_f32_16x16x32_bf16 v[84:87], v[184:187], v[220:223], v[84:87]
	v_mfma_f32_16x16x32_bf16 v[80:83], v[192:195], v[220:223], v[80:83]
	v_mfma_f32_16x16x32_bf16 v[68:71], v[184:187], v[228:231], v[68:71]
	v_mfma_f32_16x16x32_bf16 v[64:67], v[192:195], v[228:231], v[64:67]
	s_setprio 0
	s_barrier
; #define PG8_STAGE(bufoff, gbase, voff) do { _Pragma("unroll") for (int _i = 0; _i < 2; ++_i) \
;         __builtin_amdgcn_global_load_lds((const unsigned*)((const char*)(gbase) + (voff)[_i]), (PG8_LAS unsigned*)(lds + (bufoff) + ldsw + _i * 8192), 16, 0, 0); } while (0)
; #define PG8_LDA(dst, b, h) do { _Pragma("unroll") for (int m = 0; m < 4; ++m) _Pragma("unroll") for (int k = 0; k < 2; ++k) dst[m][k] = *(const PG8_LAS bf16x8*)(lds + PG8_SA(b, h) + aoff + m * 2048 + k * 1024); } while (0)
; #define PG8_MMA(ai, bj, At, Bt) do { __builtin_amdgcn_s_setprio(1); _Pragma("unroll") for (int m = 0; m < 4; ++m) _Pragma("unroll") for (int n = 0; n < 2; ++n) _Pragma("unroll") for (int k = 0; k < 2; ++k) \
;         acc[ai][bj][m][n] = __builtin_amdgcn_mfma_f32_16x16x32_bf16(Bt[n][k], At[m][k], acc[ai][bj][m][n], 0, 0, 0); __builtin_amdgcn_s_setprio(0); } while (0)
; #define PG8_WAIT_V(n) asm volatile("s_waitcnt vmcnt(" #n ")" ::: "memory")
; #define PG8_WAIT_L(n) asm volatile("s_waitcnt lgkmcnt(" #n ")" ::: "memory")
; #define PG8_BAR __builtin_amdgcn_s_barrier()
; #define PG8_SCHED __builtin_amdgcn_sched_barrier(0)
; template <class Epi, class Sched, bool ALIGN_EPI = false, bool SP2 = false>
; __device__ __forceinline__ void gemm_phase(PG8_LAS unsigned char* lds, const Gemm g, const Sched& S, const Epi& E) {
;     ...
;             PG8_LDA(At, 1, 1); PG8_STAGE(PG8_SB(1, 0), b3, voffB); PG8_STAGE(PG8_SB(1, 1), b3 + hstep, voffB); PG8_STAGE(PG8_SA(1, 0), a3, voffA);
;             PG8_WAIT_V(8); PG8_WAIT_L(0); PG8_BAR; PG8_MMA(1, 0, At, B0); PG8_MMA(1, 1, At, B1); PG8_BAR; PG8_SCHED;
	s_mov_b32 m0, s62
	v_lshl_add_u64 v[212:213], v[232:233], 0, s[24:25]
	ds_read_b128 v[196:199], v163 offset:49152
	ds_read_b128 v[200:203], v163 offset:50176
	ds_read_b128 v[204:207], v163 offset:51200
	ds_read_b128 v[208:211], v163 offset:52224
	ds_read_b128 v[216:219], v163 offset:53248
	ds_read_b128 v[220:223], v163 offset:54272
	ds_read_b128 v[224:227], v163 offset:55296
	ds_read_b128 v[228:231], v163 offset:56320
	global_load_lds_dwordx4 v[212:213], off
	v_lshl_add_u64 v[212:213], v[234:235], 0, s[24:25]
	s_mov_b32 m0, s63
	s_nop 0
	global_load_lds_dwordx4 v[212:213], off
	v_lshl_add_u64 v[212:213], v[236:237], 0, s[24:25]
	s_mov_b32 m0, s64
	s_nop 0
	global_load_lds_dwordx4 v[212:213], off
	v_lshl_add_u64 v[212:213], v[214:215], 0, s[24:25]
	s_mov_b32 m0, s65
	s_nop 0
	global_load_lds_dwordx4 v[212:213], off
	v_lshl_add_u64 v[212:213], v[238:239], 0, s[24:25]
	s_mov_b32 m0, s48
	s_nop 0
	global_load_lds_dwordx4 v[212:213], off
	v_lshl_add_u64 v[212:213], v[240:241], 0, s[24:25]
	s_mov_b32 m0, s49
	s_nop 0
	global_load_lds_dwordx4 v[212:213], off
	s_waitcnt vmcnt(8)
	s_waitcnt lgkmcnt(0)
	s_setprio 1
	s_barrier
	v_mfma_f32_16x16x32_bf16 v[60:63], v[164:167], v[196:199], v[60:63]
	v_mfma_f32_16x16x32_bf16 v[56:59], v[172:175], v[196:199], v[56:59]
	v_mfma_f32_16x16x32_bf16 v[44:47], v[164:167], v[204:207], v[44:47]
	v_mfma_f32_16x16x32_bf16 v[40:43], v[172:175], v[204:207], v[40:43]
	v_mfma_f32_16x16x32_bf16 v[28:31], v[164:167], v[216:219], v[28:31]
	v_mfma_f32_16x16x32_bf16 v[24:27], v[172:175], v[216:219], v[24:27]
	v_mfma_f32_16x16x32_bf16 v[12:15], v[164:167], v[224:227], v[12:15]
	v_mfma_f32_16x16x32_bf16 v[8:11], v[172:175], v[224:227], v[8:11]
	v_mfma_f32_16x16x32_bf16 v[60:63], v[168:171], v[200:203], v[60:63]
	v_mfma_f32_16x16x32_bf16 v[56:59], v[176:179], v[200:203], v[56:59]
	v_mfma_f32_16x16x32_bf16 v[44:47], v[168:171], v[208:211], v[44:47]
	v_mfma_f32_16x16x32_bf16 v[40:43], v[176:179], v[208:211], v[40:43]
	v_mfma_f32_16x16x32_bf16 v[28:31], v[168:171], v[220:223], v[28:31]
	v_mfma_f32_16x16x32_bf16 v[24:27], v[176:179], v[220:223], v[24:27]
	v_mfma_f32_16x16x32_bf16 v[12:15], v[168:171], v[228:231], v[12:15]
	v_mfma_f32_16x16x32_bf16 v[8:11], v[176:179], v[228:231], v[8:11]
	v_mfma_f32_16x16x32_bf16 v[52:55], v[180:183], v[196:199], v[52:55]
	v_mfma_f32_16x16x32_bf16 v[48:51], v[188:191], v[196:199], v[48:51]
	v_mfma_f32_16x16x32_bf16 v[36:39], v[180:183], v[204:207], v[36:39]
	v_mfma_f32_16x16x32_bf16 v[32:35], v[188:191], v[204:207], v[32:35]
	v_mfma_f32_16x16x32_bf16 v[20:23], v[180:183], v[216:219], v[20:23]
	v_mfma_f32_16x16x32_bf16 v[16:19], v[188:191], v[216:219], v[16:19]
	v_mfma_f32_16x16x32_bf16 v[4:7], v[180:183], v[224:227], v[4:7]
	v_mfma_f32_16x16x32_bf16 v[0:3], v[188:191], v[224:227], v[0:3]
	v_mfma_f32_16x16x32_bf16 v[52:55], v[184:187], v[200:203], v[52:55]
	v_mfma_f32_16x16x32_bf16 v[48:51], v[192:195], v[200:203], v[48:51]
	v_mfma_f32_16x16x32_bf16 v[36:39], v[184:187], v[208:211], v[36:39]
	v_mfma_f32_16x16x32_bf16 v[32:35], v[192:195], v[208:211], v[32:35]
	v_mfma_f32_16x16x32_bf16 v[20:23], v[184:187], v[220:223], v[20:23]
	v_mfma_f32_16x16x32_bf16 v[16:19], v[192:195], v[220:223], v[16:19]
	v_mfma_f32_16x16x32_bf16 v[4:7], v[184:187], v[228:231], v[4:7]
	v_mfma_f32_16x16x32_bf16 v[0:3], v[192:195], v[228:231], v[0:3]
	s_setprio 0
	s_barrier
	v_lshl_add_u64 v[154:155], v[154:155], 0, s[28:29]
	s_cmp_ge_i32 s10, s50
	v_lshl_add_u64 v[158:159], v[158:159], 0, s[28:29]
	s_cbranch_scc0 .LBB0_1169

; #define PG8_STAGE(bufoff, gbase, voff) do { _Pragma("unroll") for (int _i = 0; _i < 2; ++_i) \
;         __builtin_amdgcn_global_load_lds((const unsigned*)((const char*)(gbase) + (voff)[_i]), (PG8_LAS unsigned*)(lds + (bufoff) + ldsw + _i * 8192), 16, 0, 0); } while (0)
; #define PG8_LDA(dst, b, h) do { _Pragma("unroll") for (int m = 0; m < 4; ++m) _Pragma("unroll") for (int k = 0; k < 2; ++k) dst[m][k] = *(const PG8_LAS bf16x8*)(lds + PG8_SA(b, h) + aoff + m * 2048 + k * 1024); } while (0)
; #define PG8_LDB(dst, b, h) do { _Pragma("unroll") for (int n = 0; n < 2; ++n) _Pragma("unroll") for (int k = 0; k < 2; ++k) dst[n][k] = *(const PG8_LAS bf16x8*)(lds + PG8_SB(b, h) + boff + n * 2048 + k * 1024); } while (0)
; #define PG8_MMA(ai, bj, At, Bt) do { __builtin_amdgcn_s_setprio(1); _Pragma("unroll") for (int m = 0; m < 4; ++m) _Pragma("unroll") for (int n = 0; n < 2; ++n) _Pragma("unroll") for (int k = 0; k < 2; ++k) \
;         acc[ai][bj][m][n] = __builtin_amdgcn_mfma_f32_16x16x32_bf16(Bt[n][k], At[m][k], acc[ai][bj][m][n], 0, 0, 0); __builtin_amdgcn_s_setprio(0); } while (0)
; #define PG8_WAIT_V(n) asm volatile("s_waitcnt vmcnt(" #n ")" ::: "memory")
; #define PG8_WAIT_L(n) asm volatile("s_waitcnt lgkmcnt(" #n ")" ::: "memory")
; #define PG8_BAR __builtin_amdgcn_s_barrier()
; template <class Epi, class Sched, bool ALIGN_EPI = false, bool SP2 = false>
; __device__ __forceinline__ void gemm_phase(PG8_LAS unsigned char* lds, const Gemm g, const Sched& S, const Epi& E) {
;     ...
;             const char* a1 = cA + (size_t)(t + 1) * kstep;
;             const char* a2 = last ? nA : cA + (size_t)(t + 2) * kstep; const char* b2 = last ? nB : cB + (size_t)(t + 2) * kstep;
;             const char* a3 = a2 + kstep; const char* b3 = b2 + kstep;
;             if (last && has_next) S.a_ready(nxt);
;             if constexpr (SP2) {
;             PG8_LDB(B0, 0, 0); PG8_LDB(B1, 0, 1); PG8_SCHED; PG8_LDA(At, 0, 0); PG8_STAGE(PG8_SA(1, 1), a1 + hstep, voffA);
;             PG8_WAIT_V(8); PG8_WAIT_L(0); PG8_BAR; PG8_MMA(0, 0, At, B0); PG8_MMA(0, 1, At, B1); PG8_BAR; PG8_SCHED;
;             PG8_LDA(At, 0, 1); PG8_STAGE(PG8_SB(0, 0), b2, voffB); PG8_STAGE(PG8_SB(0, 1), b2 + hstep, voffB); PG8_STAGE(PG8_SA(0, 0), a2, voffA);
;             PG8_WAIT_V(8); PG8_WAIT_L(0); PG8_BAR; PG8_MMA(1, 0, At, B0); PG8_MMA(1, 1, At, B1); PG8_BAR; PG8_SCHED;
.LBB0_1192:
	v_add_u32_e32 v178, s56, v216
	v_add_u32_e32 v194, s57, v216
	ds_read_b128 v[138:141], v178
	ds_read_b128 v[142:145], v178 offset:1024
	ds_read_b128 v[146:149], v178 offset:2048
	ds_read_b128 v[178:181], v178 offset:3072
	ds_read_b128 v[182:185], v194
	ds_read_b128 v[186:189], v194 offset:1024
	ds_read_b128 v[190:193], v194 offset:2048
	ds_read_b128 v[194:197], v194 offset:3072
	s_cmp_eq_u32 s49, s10
	v_lshl_add_u64 v[198:199], v[136:137], 0, s[20:21]
	s_cselect_b64 vcc, -1, 0
	s_add_i32 s10, s10, 2
	v_cndmask_b32_e32 v215, v199, v175, vcc
	v_cndmask_b32_e32 v214, v198, v174, vcc
	v_cndmask_b32_e32 v237, v135, v177, vcc
	v_cndmask_b32_e32 v236, v134, v176, vcc
	v_lshl_add_u64 v[238:239], v[136:137], 0, v[168:169]
	s_add_i32 m0, s34, 0xc000
	ds_read_b128 v[198:201], v218
	ds_read_b128 v[202:205], v218 offset:1024
	ds_read_b128 v[206:209], v218 offset:2048
	ds_read_b128 v[210:213], v218 offset:3072
	ds_read_b128 v[220:223], v218 offset:4096
	ds_read_b128 v[224:227], v218 offset:5120
	ds_read_b128 v[228:231], v218 offset:6144
	ds_read_b128 v[232:235], v218 offset:7168
	global_load_lds_dwordx4 v[238:239], off
	v_lshl_add_u64 v[238:239], v[136:137], 0, v[166:167]
	s_add_i32 m0, s34, 0xe000
	s_nop 0
	global_load_lds_dwordx4 v[238:239], off
	s_waitcnt vmcnt(8)
	s_waitcnt lgkmcnt(0)
	s_setprio 1
	s_barrier
	v_mfma_f32_16x16x32_bf16 v[130:133], v[138:141], v[198:201], v[130:133]
	v_mfma_f32_16x16x32_bf16 v[126:129], v[146:149], v[198:201], v[126:129]
	v_mfma_f32_16x16x32_bf16 v[114:117], v[138:141], v[206:209], v[114:117]
	v_mfma_f32_16x16x32_bf16 v[110:113], v[146:149], v[206:209], v[110:113]
	v_mfma_f32_16x16x32_bf16 v[98:101], v[138:141], v[220:223], v[98:101]
	v_mfma_f32_16x16x32_bf16 v[94:97], v[146:149], v[220:223], v[94:97]
	v_mfma_f32_16x16x32_bf16 v[82:85], v[138:141], v[228:231], v[82:85]
	v_mfma_f32_16x16x32_bf16 v[78:81], v[146:149], v[228:231], v[78:81]
	v_mfma_f32_16x16x32_bf16 v[130:133], v[142:145], v[202:205], v[130:133]
	v_mfma_f32_16x16x32_bf16 v[126:129], v[178:181], v[202:205], v[126:129]
	v_mfma_f32_16x16x32_bf16 v[114:117], v[142:145], v[210:213], v[114:117]
	v_mfma_f32_16x16x32_bf16 v[110:113], v[178:181], v[210:213], v[110:113]
	v_mfma_f32_16x16x32_bf16 v[98:101], v[142:145], v[224:227], v[98:101]
	v_mfma_f32_16x16x32_bf16 v[94:97], v[178:181], v[224:227], v[94:97]
	v_mfma_f32_16x16x32_bf16 v[82:85], v[142:145], v[232:235], v[82:85]
	v_mfma_f32_16x16x32_bf16 v[78:81], v[178:181], v[232:235], v[78:81]
	v_mfma_f32_16x16x32_bf16 v[122:125], v[182:185], v[198:201], v[122:125]
	v_mfma_f32_16x16x32_bf16 v[118:121], v[190:193], v[198:201], v[118:121]
	v_mfma_f32_16x16x32_bf16 v[106:109], v[182:185], v[206:209], v[106:109]
	v_mfma_f32_16x16x32_bf16 v[102:105], v[190:193], v[206:209], v[102:105]
	v_mfma_f32_16x16x32_bf16 v[90:93], v[182:185], v[220:223], v[90:93]
	v_mfma_f32_16x16x32_bf16 v[86:89], v[190:193], v[220:223], v[86:89]
	v_mfma_f32_16x16x32_bf16 v[74:77], v[182:185], v[228:231], v[74:77]
	v_mfma_f32_16x16x32_bf16 v[70:73], v[190:193], v[228:231], v[70:73]
	v_mfma_f32_16x16x32_bf16 v[122:125], v[186:189], v[202:205], v[122:125]
	v_mfma_f32_16x16x32_bf16 v[118:121], v[194:197], v[202:205], v[118:121]
	v_mfma_f32_16x16x32_bf16 v[106:109], v[186:189], v[210:213], v[106:109]
	v_mfma_f32_16x16x32_bf16 v[102:105], v[194:197], v[210:213], v[102:105]
	v_mfma_f32_16x16x32_bf16 v[90:93], v[186:189], v[224:227], v[90:93]
	v_mfma_f32_16x16x32_bf16 v[86:89], v[194:197], v[224:227], v[86:89]
	v_mfma_f32_16x16x32_bf16 v[74:77], v[186:189], v[232:235], v[74:77]
	v_mfma_f32_16x16x32_bf16 v[70:73], v[194:197], v[232:235], v[70:73]
	s_setprio 0
	s_barrier
	s_add_i32 s11, s56, s29
	v_lshl_add_u64 v[238:239], v[236:237], 0, v[158:159]
	s_mov_b32 m0, s11
	ds_read_b128 v[198:201], v218 offset:16384
	ds_read_b128 v[202:205], v218 offset:17408
	ds_read_b128 v[206:209], v218 offset:18432
	ds_read_b128 v[210:213], v218 offset:19456
	ds_read_b128 v[220:223], v218 offset:20480
	ds_read_b128 v[224:227], v218 offset:21504
	ds_read_b128 v[228:231], v218 offset:22528
	ds_read_b128 v[232:235], v218 offset:23552
	global_load_lds_dwordx4 v[238:239], off
	v_lshl_add_u64 v[240:241], v[236:237], 0, v[162:163]
	s_add_i32 m0, s11, 0x2000
	v_lshl_add_u64 v[236:237], v[236:237], 0, s[12:13]
	s_add_i32 s11, s57, s29
	global_load_lds_dwordx4 v[240:241], off
	v_lshl_add_u64 v[242:243], v[236:237], 0, v[158:159]
	s_mov_b32 m0, s11
	v_lshl_add_u64 v[236:237], v[236:237], 0, v[162:163]
	global_load_lds_dwordx4 v[242:243], off
	s_add_i32 m0, s11, 0x2000
	v_lshl_add_u64 v[244:245], v[214:215], 0, v[154:155]
	global_load_lds_dwordx4 v[236:237], off
	s_mov_b32 m0, s34
	v_lshl_add_u64 v[246:247], v[214:215], 0, v[160:161]
	global_load_lds_dwordx4 v[244:245], off
	s_mov_b32 m0, s35
	s_nop 0
	global_load_lds_dwordx4 v[246:247], off
	s_waitcnt vmcnt(8)
	s_waitcnt lgkmcnt(0)
	s_setprio 1
	s_barrier
; #define PG8_STAGE(bufoff, gbase, voff) do { _Pragma("unroll") for (int _i = 0; _i < 2; ++_i) \
;         __builtin_amdgcn_global_load_lds((const unsigned*)((const char*)(gbase) + (voff)[_i]), (PG8_LAS unsigned*)(lds + (bufoff) + ldsw + _i * 8192), 16, 0, 0); } while (0)
; #define PG8_LDA(dst, b, h) do { _Pragma("unroll") for (int m = 0; m < 4; ++m) _Pragma("unroll") for (int k = 0; k < 2; ++k) dst[m][k] = *(const PG8_LAS bf16x8*)(lds + PG8_SA(b, h) + aoff + m * 2048 + k * 1024); } while (0)
; #define PG8_LDB(dst, b, h) do { _Pragma("unroll") for (int n = 0; n < 2; ++n) _Pragma("unroll") for (int k = 0; k < 2; ++k) dst[n][k] = *(const PG8_LAS bf16x8*)(lds + PG8_SB(b, h) + boff + n * 2048 + k * 1024); } while (0)
; #define PG8_MMA(ai, bj, At, Bt) do { __builtin_amdgcn_s_setprio(1); _Pragma("unroll") for (int m = 0; m < 4; ++m) _Pragma("unroll") for (int n = 0; n < 2; ++n) _Pragma("unroll") for (int k = 0; k < 2; ++k) \
;         acc[ai][bj][m][n] = __builtin_amdgcn_mfma_f32_16x16x32_bf16(Bt[n][k], At[m][k], acc[ai][bj][m][n], 0, 0, 0); __builtin_amdgcn_s_setprio(0); } while (0)
; #define PG8_WAIT_V(n) asm volatile("s_waitcnt vmcnt(" #n ")" ::: "memory")
; #define PG8_WAIT_L(n) asm volatile("s_waitcnt lgkmcnt(" #n ")" ::: "memory")
; #define PG8_BAR __builtin_amdgcn_s_barrier()
; #define PG8_SCHED __builtin_amdgcn_sched_barrier(0)
; template <class Epi, class Sched, bool ALIGN_EPI = false, bool SP2 = false>
; __device__ __forceinline__ void gemm_phase(PG8_LAS unsigned char* lds, const Gemm g, const Sched& S, const Epi& E) {
;     ...
;             PG8_WAIT_V(8); PG8_WAIT_L(0); PG8_BAR; PG8_MMA(1, 0, At, B0); PG8_MMA(1, 1, At, B1); PG8_BAR; PG8_SCHED;
;             PG8_LDB(B0, 1, 0); PG8_LDB(B1, 1, 1); PG8_SCHED; PG8_LDA(At, 1, 0); PG8_STAGE(PG8_SA(0, 1), a2 + hstep, voffA);
;             PG8_WAIT_V(8); PG8_WAIT_L(0); PG8_BAR; PG8_MMA(0, 0, At, B0); PG8_MMA(0, 1, At, B1); PG8_BAR; PG8_SCHED;
	v_mfma_f32_16x16x32_bf16 v[66:69], v[138:141], v[198:201], v[66:69]
	v_mfma_f32_16x16x32_bf16 v[62:65], v[146:149], v[198:201], v[62:65]
	v_mfma_f32_16x16x32_bf16 v[50:53], v[138:141], v[206:209], v[50:53]
	v_mfma_f32_16x16x32_bf16 v[46:49], v[146:149], v[206:209], v[46:49]
	v_mfma_f32_16x16x32_bf16 v[34:37], v[138:141], v[220:223], v[34:37]
	v_mfma_f32_16x16x32_bf16 v[30:33], v[146:149], v[220:223], v[30:33]
	v_mfma_f32_16x16x32_bf16 v[18:21], v[138:141], v[228:231], v[18:21]
	v_mfma_f32_16x16x32_bf16 v[14:17], v[146:149], v[228:231], v[14:17]
	v_mfma_f32_16x16x32_bf16 v[66:69], v[142:145], v[202:205], v[66:69]
	v_mfma_f32_16x16x32_bf16 v[62:65], v[178:181], v[202:205], v[62:65]
	v_mfma_f32_16x16x32_bf16 v[50:53], v[142:145], v[210:213], v[50:53]
	v_mfma_f32_16x16x32_bf16 v[46:49], v[178:181], v[210:213], v[46:49]
	v_mfma_f32_16x16x32_bf16 v[34:37], v[142:145], v[224:227], v[34:37]
	v_mfma_f32_16x16x32_bf16 v[30:33], v[178:181], v[224:227], v[30:33]
	v_mfma_f32_16x16x32_bf16 v[18:21], v[142:145], v[232:235], v[18:21]
	v_mfma_f32_16x16x32_bf16 v[14:17], v[178:181], v[232:235], v[14:17]
	v_mfma_f32_16x16x32_bf16 v[58:61], v[182:185], v[198:201], v[58:61]
	v_mfma_f32_16x16x32_bf16 v[54:57], v[190:193], v[198:201], v[54:57]
	v_mfma_f32_16x16x32_bf16 v[42:45], v[182:185], v[206:209], v[42:45]
	v_mfma_f32_16x16x32_bf16 v[38:41], v[190:193], v[206:209], v[38:41]
	v_mfma_f32_16x16x32_bf16 v[26:29], v[182:185], v[220:223], v[26:29]
	v_mfma_f32_16x16x32_bf16 v[22:25], v[190:193], v[220:223], v[22:25]
	v_mfma_f32_16x16x32_bf16 v[10:13], v[182:185], v[228:231], v[10:13]
	v_mfma_f32_16x16x32_bf16 v[6:9], v[190:193], v[228:231], v[6:9]
	v_mfma_f32_16x16x32_bf16 v[58:61], v[186:189], v[202:205], v[58:61]
	v_mfma_f32_16x16x32_bf16 v[54:57], v[194:197], v[202:205], v[54:57]
	v_mfma_f32_16x16x32_bf16 v[42:45], v[186:189], v[210:213], v[42:45]
	v_mfma_f32_16x16x32_bf16 v[38:41], v[194:197], v[210:213], v[38:41]
	v_mfma_f32_16x16x32_bf16 v[26:29], v[186:189], v[224:227], v[26:29]
	v_mfma_f32_16x16x32_bf16 v[22:25], v[194:197], v[224:227], v[22:25]
	v_mfma_f32_16x16x32_bf16 v[10:13], v[186:189], v[232:235], v[10:13]
	v_mfma_f32_16x16x32_bf16 v[6:9], v[194:197], v[232:235], v[6:9]
	s_setprio 0
	s_barrier
	s_add_i32 s11, 0, 0x18000
	s_add_i32 s31, 0, 0x1c000
	v_add_u32_e32 v178, s11, v216
	v_add_u32_e32 v194, s31, v216
	ds_read_b128 v[138:141], v178
	ds_read_b128 v[142:145], v178 offset:1024
	ds_read_b128 v[146:149], v178 offset:2048
	ds_read_b128 v[178:181], v178 offset:3072
	ds_read_b128 v[182:185], v194
	ds_read_b128 v[186:189], v194 offset:1024
	ds_read_b128 v[190:193], v194 offset:2048
	ds_read_b128 v[194:197], v194 offset:3072
	v_lshl_add_u64 v[214:215], v[214:215], 0, s[12:13]
	s_mov_b32 m0, s36
	v_lshl_add_u64 v[248:249], v[214:215], 0, v[154:155]
	ds_read_b128 v[198:201], v218 offset:32768
	ds_read_b128 v[202:205], v218 offset:33792
	ds_read_b128 v[206:209], v218 offset:34816
	ds_read_b128 v[210:213], v218 offset:35840
	ds_read_b128 v[220:223], v218 offset:36864
	ds_read_b128 v[224:227], v218 offset:37888
	ds_read_b128 v[228:231], v218 offset:38912
	ds_read_b128 v[232:235], v218 offset:39936
	global_load_lds_dwordx4 v[248:249], off
	v_lshl_add_u64 v[214:215], v[214:215], 0, v[160:161]
	s_mov_b32 m0, s37
	s_nop 0
	global_load_lds_dwordx4 v[214:215], off
	s_waitcnt vmcnt(8)
	s_waitcnt lgkmcnt(0)
	s_setprio 1
	s_barrier
	v_mfma_f32_16x16x32_bf16 v[130:133], v[138:141], v[198:201], v[130:133]
	v_mfma_f32_16x16x32_bf16 v[126:129], v[146:149], v[198:201], v[126:129]
	v_mfma_f32_16x16x32_bf16 v[114:117], v[138:141], v[206:209], v[114:117]
	v_mfma_f32_16x16x32_bf16 v[110:113], v[146:149], v[206:209], v[110:113]
	v_mfma_f32_16x16x32_bf16 v[98:101], v[138:141], v[220:223], v[98:101]
	v_mfma_f32_16x16x32_bf16 v[94:97], v[146:149], v[220:223], v[94:97]
	v_mfma_f32_16x16x32_bf16 v[82:85], v[138:141], v[228:231], v[82:85]
	v_mfma_f32_16x16x32_bf16 v[78:81], v[146:149], v[228:231], v[78:81]
	v_mfma_f32_16x16x32_bf16 v[130:133], v[142:145], v[202:205], v[130:133]
	v_mfma_f32_16x16x32_bf16 v[126:129], v[178:181], v[202:205], v[126:129]
	v_mfma_f32_16x16x32_bf16 v[114:117], v[142:145], v[210:213], v[114:117]
	v_mfma_f32_16x16x32_bf16 v[110:113], v[178:181], v[210:213], v[110:113]
	v_mfma_f32_16x16x32_bf16 v[98:101], v[142:145], v[224:227], v[98:101]
	v_mfma_f32_16x16x32_bf16 v[94:97], v[178:181], v[224:227], v[94:97]
	v_mfma_f32_16x16x32_bf16 v[82:85], v[142:145], v[232:235], v[82:85]
	v_mfma_f32_16x16x32_bf16 v[78:81], v[178:181], v[232:235], v[78:81]
	v_mfma_f32_16x16x32_bf16 v[122:125], v[182:185], v[198:201], v[122:125]
	v_mfma_f32_16x16x32_bf16 v[118:121], v[190:193], v[198:201], v[118:121]
	v_mfma_f32_16x16x32_bf16 v[106:109], v[182:185], v[206:209], v[106:109]
	v_mfma_f32_16x16x32_bf16 v[102:105], v[190:193], v[206:209], v[102:105]
	v_mfma_f32_16x16x32_bf16 v[90:93], v[182:185], v[220:223], v[90:93]
	v_mfma_f32_16x16x32_bf16 v[86:89], v[190:193], v[220:223], v[86:89]
	v_mfma_f32_16x16x32_bf16 v[74:77], v[182:185], v[228:231], v[74:77]
	v_mfma_f32_16x16x32_bf16 v[70:73], v[190:193], v[228:231], v[70:73]
	v_mfma_f32_16x16x32_bf16 v[122:125], v[186:189], v[202:205], v[122:125]
	v_mfma_f32_16x16x32_bf16 v[118:121], v[194:197], v[202:205], v[118:121]
	v_mfma_f32_16x16x32_bf16 v[106:109], v[186:189], v[210:213], v[106:109]
	v_mfma_f32_16x16x32_bf16 v[102:105], v[194:197], v[210:213], v[102:105]
	v_mfma_f32_16x16x32_bf16 v[90:93], v[186:189], v[224:227], v[90:93]
	v_mfma_f32_16x16x32_bf16 v[86:89], v[194:197], v[224:227], v[86:89]
	v_mfma_f32_16x16x32_bf16 v[74:77], v[186:189], v[232:235], v[74:77]
	v_mfma_f32_16x16x32_bf16 v[70:73], v[194:197], v[232:235], v[70:73]
	s_setprio 0
	s_barrier
; #define PG8_STAGE(bufoff, gbase, voff) do { _Pragma("unroll") for (int _i = 0; _i < 2; ++_i) \
;         __builtin_amdgcn_global_load_lds((const unsigned*)((const char*)(gbase) + (voff)[_i]), (PG8_LAS unsigned*)(lds + (bufoff) + ldsw + _i * 8192), 16, 0, 0); } while (0)
; #define PG8_LDA(dst, b, h) do { _Pragma("unroll") for (int m = 0; m < 4; ++m) _Pragma("unroll") for (int k = 0; k < 2; ++k) dst[m][k] = *(const PG8_LAS bf16x8*)(lds + PG8_SA(b, h) + aoff + m * 2048 + k * 1024); } while (0)
; #define PG8_MMA(ai, bj, At, Bt) do { __builtin_amdgcn_s_setprio(1); _Pragma("unroll") for (int m = 0; m < 4; ++m) _Pragma("unroll") for (int n = 0; n < 2; ++n) _Pragma("unroll") for (int k = 0; k < 2; ++k) \
;         acc[ai][bj][m][n] = __builtin_amdgcn_mfma_f32_16x16x32_bf16(Bt[n][k], At[m][k], acc[ai][bj][m][n], 0, 0, 0); __builtin_amdgcn_s_setprio(0); } while (0)
; #define PG8_WAIT_V(n) asm volatile("s_waitcnt vmcnt(" #n ")" ::: "memory")
; #define PG8_WAIT_L(n) asm volatile("s_waitcnt lgkmcnt(" #n ")" ::: "memory")
; #define PG8_BAR __builtin_amdgcn_s_barrier()
; #define PG8_SCHED __builtin_amdgcn_sched_barrier(0)
; template <class Epi, class Sched, bool ALIGN_EPI = false, bool SP2 = false>
; __device__ __forceinline__ void gemm_phase(PG8_LAS unsigned char* lds, const Gemm g, const Sched& S, const Epi& E) {
;     ...
;             PG8_LDA(At, 1, 1); PG8_STAGE(PG8_SB(1, 0), b3, voffB); PG8_STAGE(PG8_SB(1, 1), b3 + hstep, voffB); PG8_STAGE(PG8_SA(1, 0), a3, voffA);
;             PG8_WAIT_V(8); PG8_WAIT_L(0); PG8_BAR; PG8_MMA(1, 0, At, B0); PG8_MMA(1, 1, At, B1); PG8_BAR; PG8_SCHED;
	s_add_i32 s11, s11, s29
	v_lshl_add_u64 v[214:215], v[238:239], 0, s[20:21]
	s_mov_b32 m0, s11
	ds_read_b128 v[198:201], v218 offset:49152
	ds_read_b128 v[202:205], v218 offset:50176
	ds_read_b128 v[206:209], v218 offset:51200
	ds_read_b128 v[210:213], v218 offset:52224
	ds_read_b128 v[220:223], v218 offset:53248
	ds_read_b128 v[224:227], v218 offset:54272
	ds_read_b128 v[228:231], v218 offset:55296
	ds_read_b128 v[232:235], v218 offset:56320
	global_load_lds_dwordx4 v[214:215], off
	v_lshl_add_u64 v[214:215], v[240:241], 0, s[20:21]
	s_add_i32 m0, s11, 0x2000
	s_add_i32 s11, s31, s29
	global_load_lds_dwordx4 v[214:215], off
	v_lshl_add_u64 v[214:215], v[242:243], 0, s[20:21]
	s_mov_b32 m0, s11
	s_nop 0
	global_load_lds_dwordx4 v[214:215], off
	v_lshl_add_u64 v[214:215], v[236:237], 0, s[20:21]
	s_add_i32 m0, s11, 0x2000
	s_nop 0
	global_load_lds_dwordx4 v[214:215], off
	v_lshl_add_u64 v[214:215], v[244:245], 0, s[20:21]
	s_mov_b32 m0, s41
	s_nop 0
	global_load_lds_dwordx4 v[214:215], off
	v_lshl_add_u64 v[214:215], v[246:247], 0, s[20:21]
	s_mov_b32 m0, s46
	s_nop 0
	global_load_lds_dwordx4 v[214:215], off
	s_waitcnt vmcnt(8)
	s_waitcnt lgkmcnt(0)
	s_setprio 1
	s_barrier
	v_mfma_f32_16x16x32_bf16 v[66:69], v[138:141], v[198:201], v[66:69]
	v_mfma_f32_16x16x32_bf16 v[62:65], v[146:149], v[198:201], v[62:65]
	v_mfma_f32_16x16x32_bf16 v[50:53], v[138:141], v[206:209], v[50:53]
	v_mfma_f32_16x16x32_bf16 v[46:49], v[146:149], v[206:209], v[46:49]
	v_mfma_f32_16x16x32_bf16 v[34:37], v[138:141], v[220:223], v[34:37]
	v_mfma_f32_16x16x32_bf16 v[30:33], v[146:149], v[220:223], v[30:33]
	v_mfma_f32_16x16x32_bf16 v[18:21], v[138:141], v[228:231], v[18:21]
	v_mfma_f32_16x16x32_bf16 v[14:17], v[146:149], v[228:231], v[14:17]
	v_mfma_f32_16x16x32_bf16 v[66:69], v[142:145], v[202:205], v[66:69]
	v_mfma_f32_16x16x32_bf16 v[62:65], v[178:181], v[202:205], v[62:65]
	v_mfma_f32_16x16x32_bf16 v[50:53], v[142:145], v[210:213], v[50:53]
	v_mfma_f32_16x16x32_bf16 v[46:49], v[178:181], v[210:213], v[46:49]
	v_mfma_f32_16x16x32_bf16 v[34:37], v[142:145], v[224:227], v[34:37]
	v_mfma_f32_16x16x32_bf16 v[30:33], v[178:181], v[224:227], v[30:33]
	v_mfma_f32_16x16x32_bf16 v[18:21], v[142:145], v[232:235], v[18:21]
	v_mfma_f32_16x16x32_bf16 v[14:17], v[178:181], v[232:235], v[14:17]
	v_mfma_f32_16x16x32_bf16 v[58:61], v[182:185], v[198:201], v[58:61]
	v_mfma_f32_16x16x32_bf16 v[54:57], v[190:193], v[198:201], v[54:57]
	v_mfma_f32_16x16x32_bf16 v[42:45], v[182:185], v[206:209], v[42:45]
	v_mfma_f32_16x16x32_bf16 v[38:41], v[190:193], v[206:209], v[38:41]
	v_mfma_f32_16x16x32_bf16 v[26:29], v[182:185], v[220:223], v[26:29]
	v_mfma_f32_16x16x32_bf16 v[22:25], v[190:193], v[220:223], v[22:25]
	v_mfma_f32_16x16x32_bf16 v[10:13], v[182:185], v[228:231], v[10:13]
	v_mfma_f32_16x16x32_bf16 v[6:9], v[190:193], v[228:231], v[6:9]
	v_mfma_f32_16x16x32_bf16 v[58:61], v[186:189], v[202:205], v[58:61]
	v_mfma_f32_16x16x32_bf16 v[54:57], v[194:197], v[202:205], v[54:57]
	v_mfma_f32_16x16x32_bf16 v[42:45], v[186:189], v[210:213], v[42:45]
	v_mfma_f32_16x16x32_bf16 v[38:41], v[194:197], v[210:213], v[38:41]
	v_mfma_f32_16x16x32_bf16 v[26:29], v[186:189], v[224:227], v[26:29]
	v_mfma_f32_16x16x32_bf16 v[22:25], v[194:197], v[224:227], v[22:25]
	v_mfma_f32_16x16x32_bf16 v[10:13], v[186:189], v[232:235], v[10:13]
	v_mfma_f32_16x16x32_bf16 v[6:9], v[194:197], v[232:235], v[6:9]
	s_setprio 0
	s_barrier
	v_lshl_add_u64 v[134:135], v[134:135], 0, s[26:27]
	s_cmp_ge_i32 s10, s48
	v_lshl_add_u64 v[136:137], v[136:137], 0, s[26:27]
	s_cbranch_scc0 .LBB0_1192

; #define PG8_STAGE(bufoff, gbase, voff) do { _Pragma("unroll") for (int _i = 0; _i < 2; ++_i) \
;         __builtin_amdgcn_global_load_lds((const unsigned*)((const char*)(gbase) + (voff)[_i]), (PG8_LAS unsigned*)(lds + (bufoff) + ldsw + _i * 8192), 16, 0, 0); } while (0)
; #define PG8_LDA(dst, b, h) do { _Pragma("unroll") for (int m = 0; m < 4; ++m) _Pragma("unroll") for (int k = 0; k < 2; ++k) dst[m][k] = *(const PG8_LAS bf16x8*)(lds + PG8_SA(b, h) + aoff + m * 2048 + k * 1024); } while (0)
; #define PG8_LDB(dst, b, h) do { _Pragma("unroll") for (int n = 0; n < 2; ++n) _Pragma("unroll") for (int k = 0; k < 2; ++k) dst[n][k] = *(const PG8_LAS bf16x8*)(lds + PG8_SB(b, h) + boff + n * 2048 + k * 1024); } while (0)
; #define PG8_MMA(ai, bj, At, Bt) do { __builtin_amdgcn_s_setprio(1); _Pragma("unroll") for (int m = 0; m < 4; ++m) _Pragma("unroll") for (int n = 0; n < 2; ++n) _Pragma("unroll") for (int k = 0; k < 2; ++k) \
;         acc[ai][bj][m][n] = __builtin_amdgcn_mfma_f32_16x16x32_bf16(Bt[n][k], At[m][k], acc[ai][bj][m][n], 0, 0, 0); __builtin_amdgcn_s_setprio(0); } while (0)
; #define PG8_WAIT_V(n) asm volatile("s_waitcnt vmcnt(" #n ")" ::: "memory")
; #define PG8_WAIT_L(n) asm volatile("s_waitcnt lgkmcnt(" #n ")" ::: "memory")
; #define PG8_BAR __builtin_amdgcn_s_barrier()
; template <class Epi, class Sched, bool ALIGN_EPI = false, bool SP2 = false>
; __device__ __forceinline__ void gemm_phase(PG8_LAS unsigned char* lds, const Gemm g, const Sched& S, const Epi& E) {
;     ...
;             const char* a1 = cA + (size_t)(t + 1) * kstep;
;             const char* a2 = last ? nA : cA + (size_t)(t + 2) * kstep; const char* b2 = last ? nB : cB + (size_t)(t + 2) * kstep;
;             const char* a3 = a2 + kstep; const char* b3 = b2 + kstep;
;             if (last && has_next) S.a_ready(nxt);
;             if constexpr (SP2) {
;             PG8_LDB(B0, 0, 0); PG8_LDB(B1, 0, 1); PG8_SCHED; PG8_LDA(At, 0, 0); PG8_STAGE(PG8_SA(1, 1), a1 + hstep, voffA);
;             PG8_WAIT_V(8); PG8_WAIT_L(0); PG8_BAR; PG8_MMA(0, 0, At, B0); PG8_MMA(0, 1, At, B1); PG8_BAR; PG8_SCHED;
;             PG8_LDA(At, 0, 1); PG8_STAGE(PG8_SB(0, 0), b2, voffB); PG8_STAGE(PG8_SB(0, 1), b2 + hstep, voffB); PG8_STAGE(PG8_SA(0, 0), a2, voffA);
;             PG8_WAIT_V(8); PG8_WAIT_L(0); PG8_BAR; PG8_MMA(1, 0, At, B0); PG8_MMA(1, 1, At, B1); PG8_BAR; PG8_SCHED;
.LBB0_1340:
	v_add_u32_e32 v148, s55, v201
	v_add_u32_e32 v190, s56, v201
	ds_read_b128 v[136:139], v148
	ds_read_b128 v[140:143], v148 offset:1024
	ds_read_b128 v[144:147], v148 offset:2048
	ds_read_b128 v[148:151], v148 offset:3072
	ds_read_b128 v[152:155], v190
	ds_read_b128 v[182:185], v190 offset:1024
	ds_read_b128 v[186:189], v190 offset:2048
	ds_read_b128 v[190:193], v190 offset:3072
	s_cmp_eq_u32 s48, s12
	v_lshl_add_u64 v[194:195], v[134:135], 0, s[22:23]
	s_cselect_b64 vcc, -1, 0
	s_add_i32 s12, s12, 2
	v_cndmask_b32_e32 v199, v195, v179, vcc
	v_cndmask_b32_e32 v198, v194, v178, vcc
	v_cndmask_b32_e32 v215, v133, v181, vcc
	v_cndmask_b32_e32 v214, v132, v180, vcc
	s_mov_b32 m0, s57
	v_lshl_add_u64 v[236:237], v[134:135], 0, v[174:175]
	ds_read_b128 v[194:197], v203
	ds_read_b128 v[206:209], v203 offset:1024
	ds_read_b128 v[210:213], v203 offset:2048
	ds_read_b128 v[216:219], v203 offset:3072
	ds_read_b128 v[220:223], v203 offset:4096
	ds_read_b128 v[224:227], v203 offset:5120
	ds_read_b128 v[228:231], v203 offset:6144
	ds_read_b128 v[232:235], v203 offset:7168
	global_load_lds_dwordx4 v[236:237], off
	v_lshl_add_u64 v[236:237], v[134:135], 0, v[172:173]
	s_mov_b32 m0, s58
	s_nop 0
	global_load_lds_dwordx4 v[236:237], off
	s_waitcnt vmcnt(8)
	s_waitcnt lgkmcnt(0)
	s_setprio 1
	s_barrier
	v_mfma_f32_16x16x32_bf16 v[124:127], v[136:139], v[194:197], v[124:127]
	v_mfma_f32_16x16x32_bf16 v[128:131], v[144:147], v[194:197], v[128:131]
	v_mfma_f32_16x16x32_bf16 v[112:115], v[136:139], v[210:213], v[112:115]
	v_mfma_f32_16x16x32_bf16 v[108:111], v[144:147], v[210:213], v[108:111]
	v_mfma_f32_16x16x32_bf16 v[96:99], v[136:139], v[220:223], v[96:99]
	v_mfma_f32_16x16x32_bf16 v[92:95], v[144:147], v[220:223], v[92:95]
	v_mfma_f32_16x16x32_bf16 v[80:83], v[136:139], v[228:231], v[80:83]
	v_mfma_f32_16x16x32_bf16 v[76:79], v[144:147], v[228:231], v[76:79]
	v_mfma_f32_16x16x32_bf16 v[124:127], v[140:143], v[206:209], v[124:127]
	v_mfma_f32_16x16x32_bf16 v[128:131], v[148:151], v[206:209], v[128:131]
	v_mfma_f32_16x16x32_bf16 v[112:115], v[140:143], v[216:219], v[112:115]
	v_mfma_f32_16x16x32_bf16 v[108:111], v[148:151], v[216:219], v[108:111]
	v_mfma_f32_16x16x32_bf16 v[96:99], v[140:143], v[224:227], v[96:99]
	v_mfma_f32_16x16x32_bf16 v[92:95], v[148:151], v[224:227], v[92:95]
	v_mfma_f32_16x16x32_bf16 v[80:83], v[140:143], v[232:235], v[80:83]
	v_mfma_f32_16x16x32_bf16 v[76:79], v[148:151], v[232:235], v[76:79]
	v_mfma_f32_16x16x32_bf16 v[120:123], v[152:155], v[194:197], v[120:123]
	v_mfma_f32_16x16x32_bf16 v[116:119], v[186:189], v[194:197], v[116:119]
	v_mfma_f32_16x16x32_bf16 v[104:107], v[152:155], v[210:213], v[104:107]
	v_mfma_f32_16x16x32_bf16 v[100:103], v[186:189], v[210:213], v[100:103]
	v_mfma_f32_16x16x32_bf16 v[88:91], v[152:155], v[220:223], v[88:91]
	v_mfma_f32_16x16x32_bf16 v[84:87], v[186:189], v[220:223], v[84:87]
	v_mfma_f32_16x16x32_bf16 v[72:75], v[152:155], v[228:231], v[72:75]
	v_mfma_f32_16x16x32_bf16 v[68:71], v[186:189], v[228:231], v[68:71]
	v_mfma_f32_16x16x32_bf16 v[120:123], v[182:185], v[206:209], v[120:123]
	v_mfma_f32_16x16x32_bf16 v[116:119], v[190:193], v[206:209], v[116:119]
	v_mfma_f32_16x16x32_bf16 v[104:107], v[182:185], v[216:219], v[104:107]
	v_mfma_f32_16x16x32_bf16 v[100:103], v[190:193], v[216:219], v[100:103]
	v_mfma_f32_16x16x32_bf16 v[88:91], v[182:185], v[224:227], v[88:91]
	v_mfma_f32_16x16x32_bf16 v[84:87], v[190:193], v[224:227], v[84:87]
	v_mfma_f32_16x16x32_bf16 v[72:75], v[182:185], v[232:235], v[72:75]
	v_mfma_f32_16x16x32_bf16 v[68:71], v[190:193], v[232:235], v[68:71]
	s_setprio 0
	s_barrier
	s_mov_b32 m0, s59
	v_lshl_add_u64 v[236:237], v[214:215], 0, v[166:167]
	ds_read_b128 v[194:197], v203 offset:16384
	ds_read_b128 v[206:209], v203 offset:17408
	ds_read_b128 v[210:213], v203 offset:18432
	ds_read_b128 v[216:219], v203 offset:19456
	ds_read_b128 v[220:223], v203 offset:20480
	ds_read_b128 v[224:227], v203 offset:21504
	ds_read_b128 v[228:231], v203 offset:22528
	ds_read_b128 v[232:235], v203 offset:23552
	global_load_lds_dwordx4 v[236:237], off
	v_lshl_add_u64 v[238:239], v[214:215], 0, v[170:171]
	s_mov_b32 m0, s60
	v_lshl_add_u64 v[214:215], v[214:215], 0, s[14:15]
	s_add_i32 s13, s56, s30
	global_load_lds_dwordx4 v[238:239], off
	v_lshl_add_u64 v[240:241], v[214:215], 0, v[166:167]
	s_mov_b32 m0, s13
	v_lshl_add_u64 v[214:215], v[214:215], 0, v[170:171]
	global_load_lds_dwordx4 v[240:241], off
	s_add_i32 m0, s13, 0x2000
	v_lshl_add_u64 v[242:243], v[198:199], 0, v[164:165]
	global_load_lds_dwordx4 v[214:215], off
	s_mov_b32 m0, s31
	v_lshl_add_u64 v[244:245], v[198:199], 0, v[168:169]
	global_load_lds_dwordx4 v[242:243], off
	s_mov_b32 m0, s34
	s_nop 0
	global_load_lds_dwordx4 v[244:245], off
	s_waitcnt vmcnt(8)
	s_waitcnt lgkmcnt(0)
	s_setprio 1
	s_barrier
; #define PG8_STAGE(bufoff, gbase, voff) do { _Pragma("unroll") for (int _i = 0; _i < 2; ++_i) \
;         __builtin_amdgcn_global_load_lds((const unsigned*)((const char*)(gbase) + (voff)[_i]), (PG8_LAS unsigned*)(lds + (bufoff) + ldsw + _i * 8192), 16, 0, 0); } while (0)
; #define PG8_LDA(dst, b, h) do { _Pragma("unroll") for (int m = 0; m < 4; ++m) _Pragma("unroll") for (int k = 0; k < 2; ++k) dst[m][k] = *(const PG8_LAS bf16x8*)(lds + PG8_SA(b, h) + aoff + m * 2048 + k * 1024); } while (0)
; #define PG8_LDB(dst, b, h) do { _Pragma("unroll") for (int n = 0; n < 2; ++n) _Pragma("unroll") for (int k = 0; k < 2; ++k) dst[n][k] = *(const PG8_LAS bf16x8*)(lds + PG8_SB(b, h) + boff + n * 2048 + k * 1024); } while (0)
; #define PG8_MMA(ai, bj, At, Bt) do { __builtin_amdgcn_s_setprio(1); _Pragma("unroll") for (int m = 0; m < 4; ++m) _Pragma("unroll") for (int n = 0; n < 2; ++n) _Pragma("unroll") for (int k = 0; k < 2; ++k) \
;         acc[ai][bj][m][n] = __builtin_amdgcn_mfma_f32_16x16x32_bf16(Bt[n][k], At[m][k], acc[ai][bj][m][n], 0, 0, 0); __builtin_amdgcn_s_setprio(0); } while (0)
; #define PG8_WAIT_V(n) asm volatile("s_waitcnt vmcnt(" #n ")" ::: "memory")
; #define PG8_WAIT_L(n) asm volatile("s_waitcnt lgkmcnt(" #n ")" ::: "memory")
; #define PG8_BAR __builtin_amdgcn_s_barrier()
; #define PG8_SCHED __builtin_amdgcn_sched_barrier(0)
; template <class Epi, class Sched, bool ALIGN_EPI = false, bool SP2 = false>
; __device__ __forceinline__ void gemm_phase(PG8_LAS unsigned char* lds, const Gemm g, const Sched& S, const Epi& E) {
;     ...
;             PG8_WAIT_V(8); PG8_WAIT_L(0); PG8_BAR; PG8_MMA(1, 0, At, B0); PG8_MMA(1, 1, At, B1); PG8_BAR; PG8_SCHED;
;             PG8_LDB(B0, 1, 0); PG8_LDB(B1, 1, 1); PG8_SCHED; PG8_LDA(At, 1, 0); PG8_STAGE(PG8_SA(0, 1), a2 + hstep, voffA);
;             PG8_WAIT_V(8); PG8_WAIT_L(0); PG8_BAR; PG8_MMA(0, 0, At, B0); PG8_MMA(0, 1, At, B1); PG8_BAR; PG8_SCHED;
	v_mfma_f32_16x16x32_bf16 v[64:67], v[136:139], v[194:197], v[64:67]
	v_mfma_f32_16x16x32_bf16 v[60:63], v[144:147], v[194:197], v[60:63]
	v_mfma_f32_16x16x32_bf16 v[48:51], v[136:139], v[210:213], v[48:51]
	v_mfma_f32_16x16x32_bf16 v[44:47], v[144:147], v[210:213], v[44:47]
	v_mfma_f32_16x16x32_bf16 v[32:35], v[136:139], v[220:223], v[32:35]
	v_mfma_f32_16x16x32_bf16 v[28:31], v[144:147], v[220:223], v[28:31]
	v_mfma_f32_16x16x32_bf16 v[16:19], v[136:139], v[228:231], v[16:19]
	v_mfma_f32_16x16x32_bf16 v[12:15], v[144:147], v[228:231], v[12:15]
	v_mfma_f32_16x16x32_bf16 v[64:67], v[140:143], v[206:209], v[64:67]
	v_mfma_f32_16x16x32_bf16 v[60:63], v[148:151], v[206:209], v[60:63]
	v_mfma_f32_16x16x32_bf16 v[48:51], v[140:143], v[216:219], v[48:51]
	v_mfma_f32_16x16x32_bf16 v[44:47], v[148:151], v[216:219], v[44:47]
	v_mfma_f32_16x16x32_bf16 v[32:35], v[140:143], v[224:227], v[32:35]
	v_mfma_f32_16x16x32_bf16 v[28:31], v[148:151], v[224:227], v[28:31]
	v_mfma_f32_16x16x32_bf16 v[16:19], v[140:143], v[232:235], v[16:19]
	v_mfma_f32_16x16x32_bf16 v[12:15], v[148:151], v[232:235], v[12:15]
	v_mfma_f32_16x16x32_bf16 v[56:59], v[152:155], v[194:197], v[56:59]
	v_mfma_f32_16x16x32_bf16 v[52:55], v[186:189], v[194:197], v[52:55]
	v_mfma_f32_16x16x32_bf16 v[40:43], v[152:155], v[210:213], v[40:43]
	v_mfma_f32_16x16x32_bf16 v[36:39], v[186:189], v[210:213], v[36:39]
	v_mfma_f32_16x16x32_bf16 v[24:27], v[152:155], v[220:223], v[24:27]
	v_mfma_f32_16x16x32_bf16 v[20:23], v[186:189], v[220:223], v[20:23]
	v_mfma_f32_16x16x32_bf16 v[8:11], v[152:155], v[228:231], v[8:11]
	v_mfma_f32_16x16x32_bf16 v[4:7], v[186:189], v[228:231], v[4:7]
	v_mfma_f32_16x16x32_bf16 v[56:59], v[182:185], v[206:209], v[56:59]
	v_mfma_f32_16x16x32_bf16 v[52:55], v[190:193], v[206:209], v[52:55]
	v_mfma_f32_16x16x32_bf16 v[40:43], v[182:185], v[216:219], v[40:43]
	v_mfma_f32_16x16x32_bf16 v[36:39], v[190:193], v[216:219], v[36:39]
	v_mfma_f32_16x16x32_bf16 v[24:27], v[182:185], v[224:227], v[24:27]
	v_mfma_f32_16x16x32_bf16 v[20:23], v[190:193], v[224:227], v[20:23]
	v_mfma_f32_16x16x32_bf16 v[8:11], v[182:185], v[232:235], v[8:11]
	v_mfma_f32_16x16x32_bf16 v[4:7], v[190:193], v[232:235], v[4:7]
	s_setprio 0
	s_barrier
	s_add_i32 s13, 0, 0x18000
	s_add_i32 s29, 0, 0x1c000
	v_add_u32_e32 v148, s13, v201
	v_add_u32_e32 v190, s29, v201
	ds_read_b128 v[136:139], v148
	ds_read_b128 v[140:143], v148 offset:1024
	ds_read_b128 v[144:147], v148 offset:2048
	ds_read_b128 v[148:151], v148 offset:3072
	ds_read_b128 v[152:155], v190
	ds_read_b128 v[182:185], v190 offset:1024
	ds_read_b128 v[186:189], v190 offset:2048
	ds_read_b128 v[190:193], v190 offset:3072
	v_lshl_add_u64 v[198:199], v[198:199], 0, s[14:15]
	s_mov_b32 m0, s35
	v_lshl_add_u64 v[246:247], v[198:199], 0, v[164:165]
	ds_read_b128 v[194:197], v203 offset:32768
	ds_read_b128 v[206:209], v203 offset:33792
	ds_read_b128 v[210:213], v203 offset:34816
	ds_read_b128 v[216:219], v203 offset:35840
	ds_read_b128 v[220:223], v203 offset:36864
	ds_read_b128 v[224:227], v203 offset:37888
	ds_read_b128 v[228:231], v203 offset:38912
	ds_read_b128 v[232:235], v203 offset:39936
	global_load_lds_dwordx4 v[246:247], off
	v_lshl_add_u64 v[198:199], v[198:199], 0, v[168:169]
	s_mov_b32 m0, s36
	s_nop 0
	global_load_lds_dwordx4 v[198:199], off
	s_waitcnt vmcnt(8)
	s_waitcnt lgkmcnt(0)
	s_setprio 1
	s_barrier
	v_mfma_f32_16x16x32_bf16 v[124:127], v[136:139], v[194:197], v[124:127]
	v_mfma_f32_16x16x32_bf16 v[128:131], v[144:147], v[194:197], v[128:131]
	v_mfma_f32_16x16x32_bf16 v[112:115], v[136:139], v[210:213], v[112:115]
	v_mfma_f32_16x16x32_bf16 v[108:111], v[144:147], v[210:213], v[108:111]
	v_mfma_f32_16x16x32_bf16 v[96:99], v[136:139], v[220:223], v[96:99]
	v_mfma_f32_16x16x32_bf16 v[92:95], v[144:147], v[220:223], v[92:95]
	v_mfma_f32_16x16x32_bf16 v[80:83], v[136:139], v[228:231], v[80:83]
	v_mfma_f32_16x16x32_bf16 v[76:79], v[144:147], v[228:231], v[76:79]
	v_mfma_f32_16x16x32_bf16 v[124:127], v[140:143], v[206:209], v[124:127]
	v_mfma_f32_16x16x32_bf16 v[128:131], v[148:151], v[206:209], v[128:131]
	v_mfma_f32_16x16x32_bf16 v[112:115], v[140:143], v[216:219], v[112:115]
	v_mfma_f32_16x16x32_bf16 v[108:111], v[148:151], v[216:219], v[108:111]
	v_mfma_f32_16x16x32_bf16 v[96:99], v[140:143], v[224:227], v[96:99]
	v_mfma_f32_16x16x32_bf16 v[92:95], v[148:151], v[224:227], v[92:95]
	v_mfma_f32_16x16x32_bf16 v[80:83], v[140:143], v[232:235], v[80:83]
	v_mfma_f32_16x16x32_bf16 v[76:79], v[148:151], v[232:235], v[76:79]
	v_mfma_f32_16x16x32_bf16 v[120:123], v[152:155], v[194:197], v[120:123]
	v_mfma_f32_16x16x32_bf16 v[116:119], v[186:189], v[194:197], v[116:119]
	v_mfma_f32_16x16x32_bf16 v[104:107], v[152:155], v[210:213], v[104:107]
	v_mfma_f32_16x16x32_bf16 v[100:103], v[186:189], v[210:213], v[100:103]
	v_mfma_f32_16x16x32_bf16 v[88:91], v[152:155], v[220:223], v[88:91]
	v_mfma_f32_16x16x32_bf16 v[84:87], v[186:189], v[220:223], v[84:87]
	v_mfma_f32_16x16x32_bf16 v[72:75], v[152:155], v[228:231], v[72:75]
	v_mfma_f32_16x16x32_bf16 v[68:71], v[186:189], v[228:231], v[68:71]
	v_mfma_f32_16x16x32_bf16 v[120:123], v[182:185], v[206:209], v[120:123]
	v_mfma_f32_16x16x32_bf16 v[116:119], v[190:193], v[206:209], v[116:119]
	v_mfma_f32_16x16x32_bf16 v[104:107], v[182:185], v[216:219], v[104:107]
	v_mfma_f32_16x16x32_bf16 v[100:103], v[190:193], v[216:219], v[100:103]
	v_mfma_f32_16x16x32_bf16 v[88:91], v[182:185], v[224:227], v[88:91]
	v_mfma_f32_16x16x32_bf16 v[84:87], v[190:193], v[224:227], v[84:87]
	v_mfma_f32_16x16x32_bf16 v[72:75], v[182:185], v[232:235], v[72:75]
	v_mfma_f32_16x16x32_bf16 v[68:71], v[190:193], v[232:235], v[68:71]
	s_setprio 0
	s_barrier
; #define PG8_STAGE(bufoff, gbase, voff) do { _Pragma("unroll") for (int _i = 0; _i < 2; ++_i) \
;         __builtin_amdgcn_global_load_lds((const unsigned*)((const char*)(gbase) + (voff)[_i]), (PG8_LAS unsigned*)(lds + (bufoff) + ldsw + _i * 8192), 16, 0, 0); } while (0)
; #define PG8_LDA(dst, b, h) do { _Pragma("unroll") for (int m = 0; m < 4; ++m) _Pragma("unroll") for (int k = 0; k < 2; ++k) dst[m][k] = *(const PG8_LAS bf16x8*)(lds + PG8_SA(b, h) + aoff + m * 2048 + k * 1024); } while (0)
; #define PG8_MMA(ai, bj, At, Bt) do { __builtin_amdgcn_s_setprio(1); _Pragma("unroll") for (int m = 0; m < 4; ++m) _Pragma("unroll") for (int n = 0; n < 2; ++n) _Pragma("unroll") for (int k = 0; k < 2; ++k) \
;         acc[ai][bj][m][n] = __builtin_amdgcn_mfma_f32_16x16x32_bf16(Bt[n][k], At[m][k], acc[ai][bj][m][n], 0, 0, 0); __builtin_amdgcn_s_setprio(0); } while (0)
; #define PG8_WAIT_V(n) asm volatile("s_waitcnt vmcnt(" #n ")" ::: "memory")
; #define PG8_WAIT_L(n) asm volatile("s_waitcnt lgkmcnt(" #n ")" ::: "memory")
; #define PG8_BAR __builtin_amdgcn_s_barrier()
; #define PG8_SCHED __builtin_amdgcn_sched_barrier(0)
; template <class Epi, class Sched, bool ALIGN_EPI = false, bool SP2 = false>
; __device__ __forceinline__ void gemm_phase(PG8_LAS unsigned char* lds, const Gemm g, const Sched& S, const Epi& E) {
;     ...
;             PG8_LDA(At, 1, 1); PG8_STAGE(PG8_SB(1, 0), b3, voffB); PG8_STAGE(PG8_SB(1, 1), b3 + hstep, voffB); PG8_STAGE(PG8_SA(1, 0), a3, voffA);
;             PG8_WAIT_V(8); PG8_WAIT_L(0); PG8_BAR; PG8_MMA(1, 0, At, B0); PG8_MMA(1, 1, At, B1); PG8_BAR; PG8_SCHED;
	s_add_i32 s13, s13, s30
	v_lshl_add_u64 v[198:199], v[236:237], 0, s[22:23]
	s_mov_b32 m0, s13
	ds_read_b128 v[194:197], v203 offset:49152
	ds_read_b128 v[206:209], v203 offset:50176
	ds_read_b128 v[210:213], v203 offset:51200
	ds_read_b128 v[216:219], v203 offset:52224
	ds_read_b128 v[220:223], v203 offset:53248
	ds_read_b128 v[224:227], v203 offset:54272
	ds_read_b128 v[228:231], v203 offset:55296
	ds_read_b128 v[232:235], v203 offset:56320
	global_load_lds_dwordx4 v[198:199], off
	v_lshl_add_u64 v[198:199], v[238:239], 0, s[22:23]
	s_add_i32 m0, s13, 0x2000
	s_add_i32 s13, s29, s30
	global_load_lds_dwordx4 v[198:199], off
	v_lshl_add_u64 v[198:199], v[240:241], 0, s[22:23]
	s_mov_b32 m0, s13
	s_nop 0
	global_load_lds_dwordx4 v[198:199], off
	v_lshl_add_u64 v[198:199], v[214:215], 0, s[22:23]
	s_add_i32 m0, s13, 0x2000
	s_nop 0
	global_load_lds_dwordx4 v[198:199], off
	v_lshl_add_u64 v[198:199], v[242:243], 0, s[22:23]
	s_mov_b32 m0, s37
	s_nop 0
	global_load_lds_dwordx4 v[198:199], off
	v_lshl_add_u64 v[198:199], v[244:245], 0, s[22:23]
	s_mov_b32 m0, s41
	s_nop 0
	global_load_lds_dwordx4 v[198:199], off
	s_waitcnt vmcnt(8)
	s_waitcnt lgkmcnt(0)
	s_setprio 1
	s_barrier
	v_mfma_f32_16x16x32_bf16 v[64:67], v[136:139], v[194:197], v[64:67]
	v_mfma_f32_16x16x32_bf16 v[60:63], v[144:147], v[194:197], v[60:63]
	v_mfma_f32_16x16x32_bf16 v[48:51], v[136:139], v[210:213], v[48:51]
	v_mfma_f32_16x16x32_bf16 v[44:47], v[144:147], v[210:213], v[44:47]
	v_mfma_f32_16x16x32_bf16 v[32:35], v[136:139], v[220:223], v[32:35]
	v_mfma_f32_16x16x32_bf16 v[28:31], v[144:147], v[220:223], v[28:31]
	v_mfma_f32_16x16x32_bf16 v[16:19], v[136:139], v[228:231], v[16:19]
	v_mfma_f32_16x16x32_bf16 v[12:15], v[144:147], v[228:231], v[12:15]
	v_mfma_f32_16x16x32_bf16 v[64:67], v[140:143], v[206:209], v[64:67]
	v_mfma_f32_16x16x32_bf16 v[60:63], v[148:151], v[206:209], v[60:63]
	v_mfma_f32_16x16x32_bf16 v[48:51], v[140:143], v[216:219], v[48:51]
	v_mfma_f32_16x16x32_bf16 v[44:47], v[148:151], v[216:219], v[44:47]
	v_mfma_f32_16x16x32_bf16 v[32:35], v[140:143], v[224:227], v[32:35]
	v_mfma_f32_16x16x32_bf16 v[28:31], v[148:151], v[224:227], v[28:31]
	v_mfma_f32_16x16x32_bf16 v[16:19], v[140:143], v[232:235], v[16:19]
	v_mfma_f32_16x16x32_bf16 v[12:15], v[148:151], v[232:235], v[12:15]
	v_mfma_f32_16x16x32_bf16 v[56:59], v[152:155], v[194:197], v[56:59]
	v_mfma_f32_16x16x32_bf16 v[52:55], v[186:189], v[194:197], v[52:55]
	v_mfma_f32_16x16x32_bf16 v[40:43], v[152:155], v[210:213], v[40:43]
	v_mfma_f32_16x16x32_bf16 v[36:39], v[186:189], v[210:213], v[36:39]
	v_mfma_f32_16x16x32_bf16 v[24:27], v[152:155], v[220:223], v[24:27]
	v_mfma_f32_16x16x32_bf16 v[20:23], v[186:189], v[220:223], v[20:23]
	v_mfma_f32_16x16x32_bf16 v[8:11], v[152:155], v[228:231], v[8:11]
	v_mfma_f32_16x16x32_bf16 v[4:7], v[186:189], v[228:231], v[4:7]
	v_mfma_f32_16x16x32_bf16 v[56:59], v[182:185], v[206:209], v[56:59]
	v_mfma_f32_16x16x32_bf16 v[52:55], v[190:193], v[206:209], v[52:55]
	v_mfma_f32_16x16x32_bf16 v[40:43], v[182:185], v[216:219], v[40:43]
	v_mfma_f32_16x16x32_bf16 v[36:39], v[190:193], v[216:219], v[36:39]
	v_mfma_f32_16x16x32_bf16 v[24:27], v[182:185], v[224:227], v[24:27]
	v_mfma_f32_16x16x32_bf16 v[20:23], v[190:193], v[224:227], v[20:23]
	v_mfma_f32_16x16x32_bf16 v[8:11], v[182:185], v[232:235], v[8:11]
	v_mfma_f32_16x16x32_bf16 v[4:7], v[190:193], v[232:235], v[4:7]
	s_setprio 0
	s_barrier
	v_lshl_add_u64 v[132:133], v[132:133], 0, s[26:27]
	s_cmp_ge_i32 s12, s47
	v_lshl_add_u64 v[134:135], v[134:135], 0, s[26:27]
	s_cbranch_scc0 .LBB0_1340

; #define PG8_STAGE(bufoff, gbase, voff) do { _Pragma("unroll") for (int _i = 0; _i < 2; ++_i) \
;         __builtin_amdgcn_global_load_lds((const unsigned*)((const char*)(gbase) + (voff)[_i]), (PG8_LAS unsigned*)(lds + (bufoff) + ldsw + _i * 8192), 16, 0, 0); } while (0)
; #define PG8_LDA(dst, b, h) do { _Pragma("unroll") for (int m = 0; m < 4; ++m) _Pragma("unroll") for (int k = 0; k < 2; ++k) dst[m][k] = *(const PG8_LAS bf16x8*)(lds + PG8_SA(b, h) + aoff + m * 2048 + k * 1024); } while (0)
; #define PG8_LDB(dst, b, h) do { _Pragma("unroll") for (int n = 0; n < 2; ++n) _Pragma("unroll") for (int k = 0; k < 2; ++k) dst[n][k] = *(const PG8_LAS bf16x8*)(lds + PG8_SB(b, h) + boff + n * 2048 + k * 1024); } while (0)
; #define PG8_MMA(ai, bj, At, Bt) do { __builtin_amdgcn_s_setprio(1); _Pragma("unroll") for (int m = 0; m < 4; ++m) _Pragma("unroll") for (int n = 0; n < 2; ++n) _Pragma("unroll") for (int k = 0; k < 2; ++k) \
;         acc[ai][bj][m][n] = __builtin_amdgcn_mfma_f32_16x16x32_bf16(Bt[n][k], At[m][k], acc[ai][bj][m][n], 0, 0, 0); __builtin_amdgcn_s_setprio(0); } while (0)
; #define PG8_WAIT_V(n) asm volatile("s_waitcnt vmcnt(" #n ")" ::: "memory")
; #define PG8_WAIT_L(n) asm volatile("s_waitcnt lgkmcnt(" #n ")" ::: "memory")
; #define PG8_BAR __builtin_amdgcn_s_barrier()
; #define PG8_SCHED __builtin_amdgcn_sched_barrier(0)
; template <class Epi, class Sched, bool ALIGN_EPI = false, bool SP2 = false>
; __device__ __forceinline__ void gemm_phase(PG8_LAS unsigned char* lds, const Gemm g, const Sched& S, const Epi& E) {
;     ...
;             const bool last = (t == nt - 2);
;             const char* a1 = cA + (size_t)(t + 1) * kstep;
;             const char* a2 = last ? nA : cA + (size_t)(t + 2) * kstep; const char* b2 = last ? nB : cB + (size_t)(t + 2) * kstep;
;             const char* a3 = a2 + kstep; const char* b3 = b2 + kstep;
;             if (last && has_next) S.a_ready(nxt);
;             if constexpr (SP2) {
;             PG8_LDB(B0, 0, 0); PG8_LDB(B1, 0, 1); PG8_SCHED; PG8_LDA(At, 0, 0); PG8_STAGE(PG8_SA(1, 1), a1 + hstep, voffA);
;             PG8_WAIT_V(8); PG8_WAIT_L(0); PG8_BAR; PG8_MMA(0, 0, At, B0); PG8_MMA(0, 1, At, B1); PG8_BAR; PG8_SCHED;
;             PG8_LDA(At, 0, 1); PG8_STAGE(PG8_SB(0, 0), b2, voffB); PG8_STAGE(PG8_SB(0, 1), b2 + hstep, voffB); PG8_STAGE(PG8_SA(0, 0), a2, voffA);
.LBB0_1423:
	v_add_u32_e32 v152, s81, v169
	v_add_u32_e32 v165, s82, v169
	ds_read_b128 v[132:135], v152
	ds_read_b128 v[136:139], v152 offset:1024
	ds_read_b128 v[174:177], v152 offset:2048
	ds_read_b128 v[178:181], v152 offset:3072
	ds_read_b128 v[182:185], v165
	ds_read_b128 v[186:189], v165 offset:1024
	ds_read_b128 v[190:193], v165 offset:2048
	ds_read_b128 v[194:197], v165 offset:3072
	s_cmp_eq_u32 s74, s10
	v_lshl_add_u64 v[198:199], v[130:131], 0, s[26:27]
	s_cselect_b64 vcc, -1, 0
	s_add_i32 s10, s10, 2
	v_cndmask_b32_e32 v211, v199, v171, vcc
	v_cndmask_b32_e32 v210, v198, v170, vcc
	v_cndmask_b32_e32 v215, v129, v173, vcc
	v_cndmask_b32_e32 v214, v128, v172, vcc
	v_lshl_add_u64 v[240:241], v[130:131], 0, v[160:161]
	s_add_i32 m0, s47, 0xc000
	ds_read_b128 v[198:201], v213
	ds_read_b128 v[202:205], v213 offset:1024
	ds_read_b128 v[206:209], v213 offset:2048
	ds_read_b128 v[220:223], v213 offset:3072
	ds_read_b128 v[224:227], v213 offset:4096
	ds_read_b128 v[228:231], v213 offset:5120
	ds_read_b128 v[232:235], v213 offset:6144
	ds_read_b128 v[236:239], v213 offset:7168
	global_load_lds_dwordx4 v[240:241], off
	v_lshl_add_u64 v[240:241], v[130:131], 0, v[158:159]
	s_add_i32 m0, s47, 0xe000
	s_nop 0
	global_load_lds_dwordx4 v[240:241], off
	s_waitcnt vmcnt(8)
	s_waitcnt lgkmcnt(0)
	s_setprio 1
	s_barrier
	v_mfma_f32_16x16x32_bf16 v[124:127], v[132:135], v[198:201], v[124:127]
	v_mfma_f32_16x16x32_bf16 v[120:123], v[174:177], v[198:201], v[120:123]
	v_mfma_f32_16x16x32_bf16 v[108:111], v[132:135], v[206:209], v[108:111]
	v_mfma_f32_16x16x32_bf16 v[104:107], v[174:177], v[206:209], v[104:107]
	v_mfma_f32_16x16x32_bf16 v[92:95], v[132:135], v[224:227], v[92:95]
	v_mfma_f32_16x16x32_bf16 v[88:91], v[174:177], v[224:227], v[88:91]
	v_mfma_f32_16x16x32_bf16 v[76:79], v[132:135], v[232:235], v[76:79]
	v_mfma_f32_16x16x32_bf16 v[72:75], v[174:177], v[232:235], v[72:75]
	v_mfma_f32_16x16x32_bf16 v[124:127], v[136:139], v[202:205], v[124:127]
	v_mfma_f32_16x16x32_bf16 v[120:123], v[178:181], v[202:205], v[120:123]
	v_mfma_f32_16x16x32_bf16 v[108:111], v[136:139], v[220:223], v[108:111]
	v_mfma_f32_16x16x32_bf16 v[104:107], v[178:181], v[220:223], v[104:107]
	v_mfma_f32_16x16x32_bf16 v[92:95], v[136:139], v[228:231], v[92:95]
	v_mfma_f32_16x16x32_bf16 v[88:91], v[178:181], v[228:231], v[88:91]
	v_mfma_f32_16x16x32_bf16 v[76:79], v[136:139], v[236:239], v[76:79]
	v_mfma_f32_16x16x32_bf16 v[72:75], v[178:181], v[236:239], v[72:75]
	v_mfma_f32_16x16x32_bf16 v[116:119], v[182:185], v[198:201], v[116:119]
	v_mfma_f32_16x16x32_bf16 v[112:115], v[190:193], v[198:201], v[112:115]
	v_mfma_f32_16x16x32_bf16 v[100:103], v[182:185], v[206:209], v[100:103]
	v_mfma_f32_16x16x32_bf16 v[96:99], v[190:193], v[206:209], v[96:99]
	v_mfma_f32_16x16x32_bf16 v[84:87], v[182:185], v[224:227], v[84:87]
	v_mfma_f32_16x16x32_bf16 v[80:83], v[190:193], v[224:227], v[80:83]
	v_mfma_f32_16x16x32_bf16 v[68:71], v[182:185], v[232:235], v[68:71]
	v_mfma_f32_16x16x32_bf16 v[64:67], v[190:193], v[232:235], v[64:67]
	v_mfma_f32_16x16x32_bf16 v[116:119], v[186:189], v[202:205], v[116:119]
	v_mfma_f32_16x16x32_bf16 v[112:115], v[194:197], v[202:205], v[112:115]
	v_mfma_f32_16x16x32_bf16 v[100:103], v[186:189], v[220:223], v[100:103]
	v_mfma_f32_16x16x32_bf16 v[96:99], v[194:197], v[220:223], v[96:99]
	v_mfma_f32_16x16x32_bf16 v[84:87], v[186:189], v[228:231], v[84:87]
	v_mfma_f32_16x16x32_bf16 v[80:83], v[194:197], v[228:231], v[80:83]
	v_mfma_f32_16x16x32_bf16 v[68:71], v[186:189], v[236:239], v[68:71]
	v_mfma_f32_16x16x32_bf16 v[64:67], v[194:197], v[236:239], v[64:67]
	s_setprio 0
	s_barrier
	s_add_i32 s11, s81, s41
	v_lshl_add_u64 v[240:241], v[214:215], 0, v[146:147]
	s_mov_b32 m0, s11
	ds_read_b128 v[198:201], v213 offset:16384
	ds_read_b128 v[202:205], v213 offset:17408
	ds_read_b128 v[206:209], v213 offset:18432
	ds_read_b128 v[220:223], v213 offset:19456
	ds_read_b128 v[224:227], v213 offset:20480
	ds_read_b128 v[228:231], v213 offset:21504
	ds_read_b128 v[232:235], v213 offset:22528
	ds_read_b128 v[236:239], v213 offset:23552
	global_load_lds_dwordx4 v[240:241], off
	v_lshl_add_u64 v[242:243], v[214:215], 0, v[150:151]
	s_add_i32 m0, s11, 0x2000
	v_lshl_add_u64 v[214:215], v[214:215], 0, s[18:19]
	s_add_i32 s11, s82, s41
	global_load_lds_dwordx4 v[242:243], off
	v_lshl_add_u64 v[244:245], v[214:215], 0, v[146:147]
	s_mov_b32 m0, s11
	v_lshl_add_u64 v[214:215], v[214:215], 0, v[150:151]
	global_load_lds_dwordx4 v[244:245], off
	s_add_i32 m0, s11, 0x2000
	v_lshl_add_u64 v[246:247], v[210:211], 0, v[144:145]
	global_load_lds_dwordx4 v[214:215], off
	s_mov_b32 m0, s47
	v_lshl_add_u64 v[248:249], v[210:211], 0, v[148:149]
	global_load_lds_dwordx4 v[246:247], off
	s_mov_b32 m0, s55
	s_nop 0
	global_load_lds_dwordx4 v[248:249], off
	s_waitcnt vmcnt(8)
	s_waitcnt lgkmcnt(0)
	s_setprio 1
	s_barrier
; #define PG8_STAGE(bufoff, gbase, voff) do { _Pragma("unroll") for (int _i = 0; _i < 2; ++_i) \
;         __builtin_amdgcn_global_load_lds((const unsigned*)((const char*)(gbase) + (voff)[_i]), (PG8_LAS unsigned*)(lds + (bufoff) + ldsw + _i * 8192), 16, 0, 0); } while (0)
; #define PG8_LDA(dst, b, h) do { _Pragma("unroll") for (int m = 0; m < 4; ++m) _Pragma("unroll") for (int k = 0; k < 2; ++k) dst[m][k] = *(const PG8_LAS bf16x8*)(lds + PG8_SA(b, h) + aoff + m * 2048 + k * 1024); } while (0)
; #define PG8_LDB(dst, b, h) do { _Pragma("unroll") for (int n = 0; n < 2; ++n) _Pragma("unroll") for (int k = 0; k < 2; ++k) dst[n][k] = *(const PG8_LAS bf16x8*)(lds + PG8_SB(b, h) + boff + n * 2048 + k * 1024); } while (0)
; #define PG8_MMA(ai, bj, At, Bt) do { __builtin_amdgcn_s_setprio(1); _Pragma("unroll") for (int m = 0; m < 4; ++m) _Pragma("unroll") for (int n = 0; n < 2; ++n) _Pragma("unroll") for (int k = 0; k < 2; ++k) \
;         acc[ai][bj][m][n] = __builtin_amdgcn_mfma_f32_16x16x32_bf16(Bt[n][k], At[m][k], acc[ai][bj][m][n], 0, 0, 0); __builtin_amdgcn_s_setprio(0); } while (0)
; #define PG8_WAIT_V(n) asm volatile("s_waitcnt vmcnt(" #n ")" ::: "memory")
; #define PG8_WAIT_L(n) asm volatile("s_waitcnt lgkmcnt(" #n ")" ::: "memory")
; #define PG8_BAR __builtin_amdgcn_s_barrier()
; #define PG8_SCHED __builtin_amdgcn_sched_barrier(0)
; template <class Epi, class Sched, bool ALIGN_EPI = false, bool SP2 = false>
; __device__ __forceinline__ void gemm_phase(PG8_LAS unsigned char* lds, const Gemm g, const Sched& S, const Epi& E) {
;     ...
;             PG8_WAIT_V(8); PG8_WAIT_L(0); PG8_BAR; PG8_MMA(1, 0, At, B0); PG8_MMA(1, 1, At, B1); PG8_BAR; PG8_SCHED;
;             PG8_LDB(B0, 1, 0); PG8_LDB(B1, 1, 1); PG8_SCHED; PG8_LDA(At, 1, 0); PG8_STAGE(PG8_SA(0, 1), a2 + hstep, voffA);
;             PG8_WAIT_V(8); PG8_WAIT_L(0); PG8_BAR; PG8_MMA(0, 0, At, B0); PG8_MMA(0, 1, At, B1); PG8_BAR; PG8_SCHED;
	v_mfma_f32_16x16x32_bf16 v[60:63], v[132:135], v[198:201], v[60:63]
	v_mfma_f32_16x16x32_bf16 v[56:59], v[174:177], v[198:201], v[56:59]
	v_mfma_f32_16x16x32_bf16 v[44:47], v[132:135], v[206:209], v[44:47]
	v_mfma_f32_16x16x32_bf16 v[40:43], v[174:177], v[206:209], v[40:43]
	v_mfma_f32_16x16x32_bf16 v[28:31], v[132:135], v[224:227], v[28:31]
	v_mfma_f32_16x16x32_bf16 v[24:27], v[174:177], v[224:227], v[24:27]
	v_mfma_f32_16x16x32_bf16 v[12:15], v[132:135], v[232:235], v[12:15]
	v_mfma_f32_16x16x32_bf16 v[8:11], v[174:177], v[232:235], v[8:11]
	v_mfma_f32_16x16x32_bf16 v[60:63], v[136:139], v[202:205], v[60:63]
	v_mfma_f32_16x16x32_bf16 v[56:59], v[178:181], v[202:205], v[56:59]
	v_mfma_f32_16x16x32_bf16 v[44:47], v[136:139], v[220:223], v[44:47]
	v_mfma_f32_16x16x32_bf16 v[40:43], v[178:181], v[220:223], v[40:43]
	v_mfma_f32_16x16x32_bf16 v[28:31], v[136:139], v[228:231], v[28:31]
	v_mfma_f32_16x16x32_bf16 v[24:27], v[178:181], v[228:231], v[24:27]
	v_mfma_f32_16x16x32_bf16 v[12:15], v[136:139], v[236:239], v[12:15]
	v_mfma_f32_16x16x32_bf16 v[8:11], v[178:181], v[236:239], v[8:11]
	v_mfma_f32_16x16x32_bf16 v[52:55], v[182:185], v[198:201], v[52:55]
	v_mfma_f32_16x16x32_bf16 v[48:51], v[190:193], v[198:201], v[48:51]
	v_mfma_f32_16x16x32_bf16 v[36:39], v[182:185], v[206:209], v[36:39]
	v_mfma_f32_16x16x32_bf16 v[32:35], v[190:193], v[206:209], v[32:35]
	v_mfma_f32_16x16x32_bf16 v[20:23], v[182:185], v[224:227], v[20:23]
	v_mfma_f32_16x16x32_bf16 v[16:19], v[190:193], v[224:227], v[16:19]
	v_mfma_f32_16x16x32_bf16 v[4:7], v[182:185], v[232:235], v[4:7]
	v_mfma_f32_16x16x32_bf16 v[0:3], v[190:193], v[232:235], v[0:3]
	v_mfma_f32_16x16x32_bf16 v[52:55], v[186:189], v[202:205], v[52:55]
	v_mfma_f32_16x16x32_bf16 v[48:51], v[194:197], v[202:205], v[48:51]
	v_mfma_f32_16x16x32_bf16 v[36:39], v[186:189], v[220:223], v[36:39]
	v_mfma_f32_16x16x32_bf16 v[32:35], v[194:197], v[220:223], v[32:35]
	v_mfma_f32_16x16x32_bf16 v[20:23], v[186:189], v[228:231], v[20:23]
	v_mfma_f32_16x16x32_bf16 v[16:19], v[194:197], v[228:231], v[16:19]
	v_mfma_f32_16x16x32_bf16 v[4:7], v[186:189], v[236:239], v[4:7]
	v_mfma_f32_16x16x32_bf16 v[0:3], v[194:197], v[236:239], v[0:3]
	s_setprio 0
	s_barrier
	s_add_i32 s11, 0, 0x18000
	v_add_u32_e32 v152, s11, v169
	s_add_i32 s13, 0, 0x1c000
	ds_read_b128 v[132:135], v152
	ds_read_b128 v[136:139], v152 offset:1024
	ds_read_b128 v[174:177], v152 offset:2048
	ds_read_b128 v[178:181], v152 offset:3072
	v_add_u32_e32 v152, s13, v169
	ds_read_b128 v[182:185], v152
	ds_read_b128 v[186:189], v152 offset:1024
	ds_read_b128 v[190:193], v152 offset:2048
	ds_read_b128 v[194:197], v152 offset:3072
	v_lshl_add_u64 v[210:211], v[210:211], 0, s[18:19]
	s_mov_b32 m0, s57
	v_lshl_add_u64 v[250:251], v[210:211], 0, v[144:145]
	ds_read_b128 v[198:201], v213 offset:32768
	ds_read_b128 v[202:205], v213 offset:33792
	ds_read_b128 v[206:209], v213 offset:34816
	ds_read_b128 v[220:223], v213 offset:35840
	ds_read_b128 v[224:227], v213 offset:36864
	ds_read_b128 v[228:231], v213 offset:37888
	ds_read_b128 v[232:235], v213 offset:38912
	ds_read_b128 v[236:239], v213 offset:39936
	global_load_lds_dwordx4 v[250:251], off
	v_lshl_add_u64 v[210:211], v[210:211], 0, v[148:149]
	s_mov_b32 m0, s59
	s_nop 0
	global_load_lds_dwordx4 v[210:211], off
	s_waitcnt vmcnt(8)
	s_waitcnt lgkmcnt(0)
	s_setprio 1
	s_barrier
	v_mfma_f32_16x16x32_bf16 v[124:127], v[132:135], v[198:201], v[124:127]
	v_mfma_f32_16x16x32_bf16 v[120:123], v[174:177], v[198:201], v[120:123]
	v_mfma_f32_16x16x32_bf16 v[108:111], v[132:135], v[206:209], v[108:111]
	v_mfma_f32_16x16x32_bf16 v[104:107], v[174:177], v[206:209], v[104:107]
	v_mfma_f32_16x16x32_bf16 v[92:95], v[132:135], v[224:227], v[92:95]
	v_mfma_f32_16x16x32_bf16 v[88:91], v[174:177], v[224:227], v[88:91]
	v_mfma_f32_16x16x32_bf16 v[76:79], v[132:135], v[232:235], v[76:79]
	v_mfma_f32_16x16x32_bf16 v[72:75], v[174:177], v[232:235], v[72:75]
	v_mfma_f32_16x16x32_bf16 v[124:127], v[136:139], v[202:205], v[124:127]
	v_mfma_f32_16x16x32_bf16 v[120:123], v[178:181], v[202:205], v[120:123]
	v_mfma_f32_16x16x32_bf16 v[108:111], v[136:139], v[220:223], v[108:111]
	v_mfma_f32_16x16x32_bf16 v[104:107], v[178:181], v[220:223], v[104:107]
	v_mfma_f32_16x16x32_bf16 v[92:95], v[136:139], v[228:231], v[92:95]
	v_mfma_f32_16x16x32_bf16 v[88:91], v[178:181], v[228:231], v[88:91]
	v_mfma_f32_16x16x32_bf16 v[76:79], v[136:139], v[236:239], v[76:79]
	v_mfma_f32_16x16x32_bf16 v[72:75], v[178:181], v[236:239], v[72:75]
	v_mfma_f32_16x16x32_bf16 v[116:119], v[182:185], v[198:201], v[116:119]
	v_mfma_f32_16x16x32_bf16 v[112:115], v[190:193], v[198:201], v[112:115]
	v_mfma_f32_16x16x32_bf16 v[100:103], v[182:185], v[206:209], v[100:103]
	v_mfma_f32_16x16x32_bf16 v[96:99], v[190:193], v[206:209], v[96:99]
	v_mfma_f32_16x16x32_bf16 v[84:87], v[182:185], v[224:227], v[84:87]
	v_mfma_f32_16x16x32_bf16 v[80:83], v[190:193], v[224:227], v[80:83]
	v_mfma_f32_16x16x32_bf16 v[68:71], v[182:185], v[232:235], v[68:71]
	v_mfma_f32_16x16x32_bf16 v[64:67], v[190:193], v[232:235], v[64:67]
	v_mfma_f32_16x16x32_bf16 v[116:119], v[186:189], v[202:205], v[116:119]
	v_mfma_f32_16x16x32_bf16 v[112:115], v[194:197], v[202:205], v[112:115]
	v_mfma_f32_16x16x32_bf16 v[100:103], v[186:189], v[220:223], v[100:103]
	v_mfma_f32_16x16x32_bf16 v[96:99], v[194:197], v[220:223], v[96:99]
	v_mfma_f32_16x16x32_bf16 v[84:87], v[186:189], v[228:231], v[84:87]
	v_mfma_f32_16x16x32_bf16 v[80:83], v[194:197], v[228:231], v[80:83]
	v_mfma_f32_16x16x32_bf16 v[68:71], v[186:189], v[236:239], v[68:71]
	v_mfma_f32_16x16x32_bf16 v[64:67], v[194:197], v[236:239], v[64:67]
	s_setprio 0
	s_barrier
; #define PG8_STAGE(bufoff, gbase, voff) do { _Pragma("unroll") for (int _i = 0; _i < 2; ++_i) \
;         __builtin_amdgcn_global_load_lds((const unsigned*)((const char*)(gbase) + (voff)[_i]), (PG8_LAS unsigned*)(lds + (bufoff) + ldsw + _i * 8192), 16, 0, 0); } while (0)
; #define PG8_LDA(dst, b, h) do { _Pragma("unroll") for (int m = 0; m < 4; ++m) _Pragma("unroll") for (int k = 0; k < 2; ++k) dst[m][k] = *(const PG8_LAS bf16x8*)(lds + PG8_SA(b, h) + aoff + m * 2048 + k * 1024); } while (0)
; #define PG8_MMA(ai, bj, At, Bt) do { __builtin_amdgcn_s_setprio(1); _Pragma("unroll") for (int m = 0; m < 4; ++m) _Pragma("unroll") for (int n = 0; n < 2; ++n) _Pragma("unroll") for (int k = 0; k < 2; ++k) \
;         acc[ai][bj][m][n] = __builtin_amdgcn_mfma_f32_16x16x32_bf16(Bt[n][k], At[m][k], acc[ai][bj][m][n], 0, 0, 0); __builtin_amdgcn_s_setprio(0); } while (0)
; #define PG8_WAIT_V(n) asm volatile("s_waitcnt vmcnt(" #n ")" ::: "memory")
; #define PG8_WAIT_L(n) asm volatile("s_waitcnt lgkmcnt(" #n ")" ::: "memory")
; #define PG8_BAR __builtin_amdgcn_s_barrier()
; #define PG8_SCHED __builtin_amdgcn_sched_barrier(0)
; template <class Epi, class Sched, bool ALIGN_EPI = false, bool SP2 = false>
; __device__ __forceinline__ void gemm_phase(PG8_LAS unsigned char* lds, const Gemm g, const Sched& S, const Epi& E) {
;     ...
;             PG8_LDA(At, 1, 1); PG8_STAGE(PG8_SB(1, 0), b3, voffB); PG8_STAGE(PG8_SB(1, 1), b3 + hstep, voffB); PG8_STAGE(PG8_SA(1, 0), a3, voffA);
;             PG8_WAIT_V(8); PG8_WAIT_L(0); PG8_BAR; PG8_MMA(1, 0, At, B0); PG8_MMA(1, 1, At, B1); PG8_BAR; PG8_SCHED;
	s_add_i32 s11, s11, s41
	v_lshl_add_u64 v[210:211], v[240:241], 0, s[26:27]
	s_mov_b32 m0, s11
	ds_read_b128 v[198:201], v213 offset:49152
	ds_read_b128 v[202:205], v213 offset:50176
	ds_read_b128 v[206:209], v213 offset:51200
	ds_read_b128 v[220:223], v213 offset:52224
	ds_read_b128 v[224:227], v213 offset:53248
	ds_read_b128 v[228:231], v213 offset:54272
	ds_read_b128 v[232:235], v213 offset:55296
	ds_read_b128 v[236:239], v213 offset:56320
	global_load_lds_dwordx4 v[210:211], off
	v_lshl_add_u64 v[210:211], v[242:243], 0, s[26:27]
	s_add_i32 m0, s11, 0x2000
	s_add_i32 s11, s13, s41
	global_load_lds_dwordx4 v[210:211], off
	v_lshl_add_u64 v[210:211], v[244:245], 0, s[26:27]
	s_mov_b32 m0, s11
	s_nop 0
	global_load_lds_dwordx4 v[210:211], off
	v_lshl_add_u64 v[210:211], v[214:215], 0, s[26:27]
	s_add_i32 m0, s11, 0x2000
	s_nop 0
	global_load_lds_dwordx4 v[210:211], off
	v_lshl_add_u64 v[210:211], v[246:247], 0, s[26:27]
	s_mov_b32 m0, s69
	s_nop 0
	global_load_lds_dwordx4 v[210:211], off
	v_lshl_add_u64 v[210:211], v[248:249], 0, s[26:27]
	s_mov_b32 m0, s70
	s_nop 0
	global_load_lds_dwordx4 v[210:211], off
	s_waitcnt vmcnt(8)
	s_waitcnt lgkmcnt(0)
	s_setprio 1
	s_barrier
	v_mfma_f32_16x16x32_bf16 v[60:63], v[132:135], v[198:201], v[60:63]
	v_mfma_f32_16x16x32_bf16 v[56:59], v[174:177], v[198:201], v[56:59]
	v_mfma_f32_16x16x32_bf16 v[44:47], v[132:135], v[206:209], v[44:47]
	v_mfma_f32_16x16x32_bf16 v[40:43], v[174:177], v[206:209], v[40:43]
	v_mfma_f32_16x16x32_bf16 v[28:31], v[132:135], v[224:227], v[28:31]
	v_mfma_f32_16x16x32_bf16 v[24:27], v[174:177], v[224:227], v[24:27]
	v_mfma_f32_16x16x32_bf16 v[12:15], v[132:135], v[232:235], v[12:15]
	v_mfma_f32_16x16x32_bf16 v[8:11], v[174:177], v[232:235], v[8:11]
	v_mfma_f32_16x16x32_bf16 v[60:63], v[136:139], v[202:205], v[60:63]
	v_mfma_f32_16x16x32_bf16 v[56:59], v[178:181], v[202:205], v[56:59]
	v_mfma_f32_16x16x32_bf16 v[44:47], v[136:139], v[220:223], v[44:47]
	v_mfma_f32_16x16x32_bf16 v[40:43], v[178:181], v[220:223], v[40:43]
	v_mfma_f32_16x16x32_bf16 v[28:31], v[136:139], v[228:231], v[28:31]
	v_mfma_f32_16x16x32_bf16 v[24:27], v[178:181], v[228:231], v[24:27]
	v_mfma_f32_16x16x32_bf16 v[12:15], v[136:139], v[236:239], v[12:15]
	v_mfma_f32_16x16x32_bf16 v[8:11], v[178:181], v[236:239], v[8:11]
	v_mfma_f32_16x16x32_bf16 v[52:55], v[182:185], v[198:201], v[52:55]
	v_mfma_f32_16x16x32_bf16 v[48:51], v[190:193], v[198:201], v[48:51]
	v_mfma_f32_16x16x32_bf16 v[36:39], v[182:185], v[206:209], v[36:39]
	v_mfma_f32_16x16x32_bf16 v[32:35], v[190:193], v[206:209], v[32:35]
	v_mfma_f32_16x16x32_bf16 v[20:23], v[182:185], v[224:227], v[20:23]
	v_mfma_f32_16x16x32_bf16 v[16:19], v[190:193], v[224:227], v[16:19]
	v_mfma_f32_16x16x32_bf16 v[4:7], v[182:185], v[232:235], v[4:7]
	v_mfma_f32_16x16x32_bf16 v[0:3], v[190:193], v[232:235], v[0:3]
	v_mfma_f32_16x16x32_bf16 v[52:55], v[186:189], v[202:205], v[52:55]
	v_mfma_f32_16x16x32_bf16 v[48:51], v[194:197], v[202:205], v[48:51]
	v_mfma_f32_16x16x32_bf16 v[36:39], v[186:189], v[220:223], v[36:39]
	v_mfma_f32_16x16x32_bf16 v[32:35], v[194:197], v[220:223], v[32:35]
	v_mfma_f32_16x16x32_bf16 v[20:23], v[186:189], v[228:231], v[20:23]
	v_mfma_f32_16x16x32_bf16 v[16:19], v[194:197], v[228:231], v[16:19]
	v_mfma_f32_16x16x32_bf16 v[4:7], v[186:189], v[236:239], v[4:7]
	v_mfma_f32_16x16x32_bf16 v[0:3], v[194:197], v[236:239], v[0:3]
	s_setprio 0
	s_barrier
	v_lshl_add_u64 v[128:129], v[128:129], 0, s[36:37]
	s_cmp_ge_i32 s10, s67
	v_lshl_add_u64 v[130:131], v[130:131], 0, s[36:37]
	s_cbranch_scc0 .LBB0_1423

; #define PG8_STAGE(bufoff, gbase, voff) do { _Pragma("unroll") for (int _i = 0; _i < 2; ++_i) \
;         __builtin_amdgcn_global_load_lds((const unsigned*)((const char*)(gbase) + (voff)[_i]), (PG8_LAS unsigned*)(lds + (bufoff) + ldsw + _i * 8192), 16, 0, 0); } while (0)
; #define PG8_LDA(dst, b, h) do { _Pragma("unroll") for (int m = 0; m < 4; ++m) _Pragma("unroll") for (int k = 0; k < 2; ++k) dst[m][k] = *(const PG8_LAS bf16x8*)(lds + PG8_SA(b, h) + aoff + m * 2048 + k * 1024); } while (0)
; #define PG8_LDB(dst, b, h) do { _Pragma("unroll") for (int n = 0; n < 2; ++n) _Pragma("unroll") for (int k = 0; k < 2; ++k) dst[n][k] = *(const PG8_LAS bf16x8*)(lds + PG8_SB(b, h) + boff + n * 2048 + k * 1024); } while (0)
; #define PG8_MMA(ai, bj, At, Bt) do { __builtin_amdgcn_s_setprio(1); _Pragma("unroll") for (int m = 0; m < 4; ++m) _Pragma("unroll") for (int n = 0; n < 2; ++n) _Pragma("unroll") for (int k = 0; k < 2; ++k) \
;         acc[ai][bj][m][n] = __builtin_amdgcn_mfma_f32_16x16x32_bf16(Bt[n][k], At[m][k], acc[ai][bj][m][n], 0, 0, 0); __builtin_amdgcn_s_setprio(0); } while (0)
; #define PG8_WAIT_V(n) asm volatile("s_waitcnt vmcnt(" #n ")" ::: "memory")
; #define PG8_WAIT_L(n) asm volatile("s_waitcnt lgkmcnt(" #n ")" ::: "memory")
; #define PG8_BAR __builtin_amdgcn_s_barrier()
; #define PG8_SCHED __builtin_amdgcn_sched_barrier(0)
; template <class Epi, class Sched, bool ALIGN_EPI = false, bool SP2 = false>
; __device__ __forceinline__ void gemm_phase(PG8_LAS unsigned char* lds, const Gemm g, const Sched& S, const Epi& E) {
;     ...
;             const bool last = (t == nt - 2);
;             const char* a1 = cA + (size_t)(t + 1) * kstep;
;             const char* a2 = last ? nA : cA + (size_t)(t + 2) * kstep; const char* b2 = last ? nB : cB + (size_t)(t + 2) * kstep;
;             const char* a3 = a2 + kstep; const char* b3 = b2 + kstep;
;             if (last && has_next) S.a_ready(nxt);
;             if constexpr (SP2) {
;             PG8_LDB(B0, 0, 0); PG8_LDB(B1, 0, 1); PG8_SCHED; PG8_LDA(At, 0, 0); PG8_STAGE(PG8_SA(1, 1), a1 + hstep, voffA);
;             PG8_WAIT_V(8); PG8_WAIT_L(0); PG8_BAR; PG8_MMA(0, 0, At, B0); PG8_MMA(0, 1, At, B1); PG8_BAR; PG8_SCHED;
;             PG8_LDA(At, 0, 1); PG8_STAGE(PG8_SB(0, 0), b2, voffB); PG8_STAGE(PG8_SB(0, 1), b2 + hstep, voffB); PG8_STAGE(PG8_SA(0, 0), a2, voffA);
.LBB0_1695:
	v_add_u32_e32 v188, s54, v199
	ds_read_b128 v[132:135], v201
	ds_read_b128 v[136:139], v201 offset:1024
	ds_read_b128 v[140:143], v201 offset:2048
	ds_read_b128 v[144:147], v201 offset:3072
	ds_read_b128 v[148:151], v188
	ds_read_b128 v[180:183], v188 offset:1024
	ds_read_b128 v[184:187], v188 offset:2048
	ds_read_b128 v[188:191], v188 offset:3072
	s_cmp_eq_u32 s48, s12
	v_lshl_add_u64 v[192:193], v[130:131], 0, s[22:23]
	s_cselect_b64 vcc, -1, 0
	s_add_i32 s12, s12, 2
	v_cndmask_b32_e32 v197, v193, v177, vcc
	v_cndmask_b32_e32 v196, v192, v176, vcc
	v_cndmask_b32_e32 v213, v129, v179, vcc
	v_cndmask_b32_e32 v212, v128, v178, vcc
	s_mov_b32 m0, s55
	v_lshl_add_u64 v[214:215], v[130:131], 0, v[172:173]
	ds_read_b128 v[192:195], v202
	ds_read_b128 v[204:207], v202 offset:1024
	ds_read_b128 v[208:211], v202 offset:2048
	ds_read_b128 v[216:219], v202 offset:3072
	ds_read_b128 v[220:223], v202 offset:4096
	ds_read_b128 v[224:227], v202 offset:5120
	ds_read_b128 v[228:231], v202 offset:6144
	ds_read_b128 v[232:235], v202 offset:7168
	global_load_lds_dwordx4 v[214:215], off
	v_lshl_add_u64 v[214:215], v[130:131], 0, v[170:171]
	s_mov_b32 m0, s56
	s_nop 0
	global_load_lds_dwordx4 v[214:215], off
	s_waitcnt vmcnt(8)
	s_waitcnt lgkmcnt(0)
	s_setprio 1
	s_barrier
	v_mfma_f32_16x16x32_bf16 v[120:123], v[132:135], v[192:195], v[120:123]
	v_mfma_f32_16x16x32_bf16 v[124:127], v[140:143], v[192:195], v[124:127]
	v_mfma_f32_16x16x32_bf16 v[108:111], v[132:135], v[208:211], v[108:111]
	v_mfma_f32_16x16x32_bf16 v[104:107], v[140:143], v[208:211], v[104:107]
	v_mfma_f32_16x16x32_bf16 v[92:95], v[132:135], v[220:223], v[92:95]
	v_mfma_f32_16x16x32_bf16 v[88:91], v[140:143], v[220:223], v[88:91]
	v_mfma_f32_16x16x32_bf16 v[76:79], v[132:135], v[228:231], v[76:79]
	v_mfma_f32_16x16x32_bf16 v[72:75], v[140:143], v[228:231], v[72:75]
	v_mfma_f32_16x16x32_bf16 v[120:123], v[136:139], v[204:207], v[120:123]
	v_mfma_f32_16x16x32_bf16 v[124:127], v[144:147], v[204:207], v[124:127]
	v_mfma_f32_16x16x32_bf16 v[108:111], v[136:139], v[216:219], v[108:111]
	v_mfma_f32_16x16x32_bf16 v[104:107], v[144:147], v[216:219], v[104:107]
	v_mfma_f32_16x16x32_bf16 v[92:95], v[136:139], v[224:227], v[92:95]
	v_mfma_f32_16x16x32_bf16 v[88:91], v[144:147], v[224:227], v[88:91]
	v_mfma_f32_16x16x32_bf16 v[76:79], v[136:139], v[232:235], v[76:79]
	v_mfma_f32_16x16x32_bf16 v[72:75], v[144:147], v[232:235], v[72:75]
	v_mfma_f32_16x16x32_bf16 v[116:119], v[148:151], v[192:195], v[116:119]
	v_mfma_f32_16x16x32_bf16 v[112:115], v[184:187], v[192:195], v[112:115]
	v_mfma_f32_16x16x32_bf16 v[100:103], v[148:151], v[208:211], v[100:103]
	v_mfma_f32_16x16x32_bf16 v[96:99], v[184:187], v[208:211], v[96:99]
	v_mfma_f32_16x16x32_bf16 v[84:87], v[148:151], v[220:223], v[84:87]
	v_mfma_f32_16x16x32_bf16 v[80:83], v[184:187], v[220:223], v[80:83]
	v_mfma_f32_16x16x32_bf16 v[68:71], v[148:151], v[228:231], v[68:71]
	v_mfma_f32_16x16x32_bf16 v[64:67], v[184:187], v[228:231], v[64:67]
	v_mfma_f32_16x16x32_bf16 v[116:119], v[180:183], v[204:207], v[116:119]
	v_mfma_f32_16x16x32_bf16 v[112:115], v[188:191], v[204:207], v[112:115]
	v_mfma_f32_16x16x32_bf16 v[100:103], v[180:183], v[216:219], v[100:103]
	v_mfma_f32_16x16x32_bf16 v[96:99], v[188:191], v[216:219], v[96:99]
	v_mfma_f32_16x16x32_bf16 v[84:87], v[180:183], v[224:227], v[84:87]
	v_mfma_f32_16x16x32_bf16 v[80:83], v[188:191], v[224:227], v[80:83]
	v_mfma_f32_16x16x32_bf16 v[68:71], v[180:183], v[232:235], v[68:71]
	v_mfma_f32_16x16x32_bf16 v[64:67], v[188:191], v[232:235], v[64:67]
	s_setprio 0
	s_barrier
	s_mov_b32 m0, s57
	v_lshl_add_u64 v[214:215], v[212:213], 0, v[164:165]
	ds_read_b128 v[192:195], v202 offset:16384
	ds_read_b128 v[204:207], v202 offset:17408
	ds_read_b128 v[208:211], v202 offset:18432
	ds_read_b128 v[216:219], v202 offset:19456
	ds_read_b128 v[220:223], v202 offset:20480
	ds_read_b128 v[224:227], v202 offset:21504
	ds_read_b128 v[228:231], v202 offset:22528
	ds_read_b128 v[232:235], v202 offset:23552
	global_load_lds_dwordx4 v[214:215], off
	v_lshl_add_u64 v[236:237], v[212:213], 0, v[168:169]
	s_mov_b32 m0, s58
	v_lshl_add_u64 v[212:213], v[212:213], 0, s[14:15]
	s_add_i32 s13, s54, s30
	global_load_lds_dwordx4 v[236:237], off
	v_lshl_add_u64 v[238:239], v[212:213], 0, v[164:165]
	s_mov_b32 m0, s13
	v_lshl_add_u64 v[212:213], v[212:213], 0, v[168:169]
	global_load_lds_dwordx4 v[238:239], off
	s_add_i32 m0, s13, 0x2000
	v_lshl_add_u64 v[240:241], v[196:197], 0, v[162:163]
	global_load_lds_dwordx4 v[212:213], off
	s_mov_b32 m0, s31
	v_lshl_add_u64 v[242:243], v[196:197], 0, v[166:167]
	global_load_lds_dwordx4 v[240:241], off
	s_mov_b32 m0, s34
	s_nop 0
	global_load_lds_dwordx4 v[242:243], off
	s_waitcnt vmcnt(8)
	s_waitcnt lgkmcnt(0)
	s_setprio 1
	s_barrier
; #define PG8_STAGE(bufoff, gbase, voff) do { _Pragma("unroll") for (int _i = 0; _i < 2; ++_i) \
;         __builtin_amdgcn_global_load_lds((const unsigned*)((const char*)(gbase) + (voff)[_i]), (PG8_LAS unsigned*)(lds + (bufoff) + ldsw + _i * 8192), 16, 0, 0); } while (0)
; #define PG8_LDA(dst, b, h) do { _Pragma("unroll") for (int m = 0; m < 4; ++m) _Pragma("unroll") for (int k = 0; k < 2; ++k) dst[m][k] = *(const PG8_LAS bf16x8*)(lds + PG8_SA(b, h) + aoff + m * 2048 + k * 1024); } while (0)
; #define PG8_LDB(dst, b, h) do { _Pragma("unroll") for (int n = 0; n < 2; ++n) _Pragma("unroll") for (int k = 0; k < 2; ++k) dst[n][k] = *(const PG8_LAS bf16x8*)(lds + PG8_SB(b, h) + boff + n * 2048 + k * 1024); } while (0)
; #define PG8_MMA(ai, bj, At, Bt) do { __builtin_amdgcn_s_setprio(1); _Pragma("unroll") for (int m = 0; m < 4; ++m) _Pragma("unroll") for (int n = 0; n < 2; ++n) _Pragma("unroll") for (int k = 0; k < 2; ++k) \
;         acc[ai][bj][m][n] = __builtin_amdgcn_mfma_f32_16x16x32_bf16(Bt[n][k], At[m][k], acc[ai][bj][m][n], 0, 0, 0); __builtin_amdgcn_s_setprio(0); } while (0)
; #define PG8_WAIT_V(n) asm volatile("s_waitcnt vmcnt(" #n ")" ::: "memory")
; #define PG8_WAIT_L(n) asm volatile("s_waitcnt lgkmcnt(" #n ")" ::: "memory")
; #define PG8_BAR __builtin_amdgcn_s_barrier()
; #define PG8_SCHED __builtin_amdgcn_sched_barrier(0)
; template <class Epi, class Sched, bool ALIGN_EPI = false, bool SP2 = false>
; __device__ __forceinline__ void gemm_phase(PG8_LAS unsigned char* lds, const Gemm g, const Sched& S, const Epi& E) {
;     ...
;             PG8_WAIT_V(8); PG8_WAIT_L(0); PG8_BAR; PG8_MMA(1, 0, At, B0); PG8_MMA(1, 1, At, B1); PG8_BAR; PG8_SCHED;
;             PG8_LDB(B0, 1, 0); PG8_LDB(B1, 1, 1); PG8_SCHED; PG8_LDA(At, 1, 0); PG8_STAGE(PG8_SA(0, 1), a2 + hstep, voffA);
;             PG8_WAIT_V(8); PG8_WAIT_L(0); PG8_BAR; PG8_MMA(0, 0, At, B0); PG8_MMA(0, 1, At, B1); PG8_BAR; PG8_SCHED;
	v_mfma_f32_16x16x32_bf16 v[60:63], v[132:135], v[192:195], v[60:63]
	v_mfma_f32_16x16x32_bf16 v[56:59], v[140:143], v[192:195], v[56:59]
	v_mfma_f32_16x16x32_bf16 v[44:47], v[132:135], v[208:211], v[44:47]
	v_mfma_f32_16x16x32_bf16 v[40:43], v[140:143], v[208:211], v[40:43]
	v_mfma_f32_16x16x32_bf16 v[28:31], v[132:135], v[220:223], v[28:31]
	v_mfma_f32_16x16x32_bf16 v[24:27], v[140:143], v[220:223], v[24:27]
	v_mfma_f32_16x16x32_bf16 v[12:15], v[132:135], v[228:231], v[12:15]
	v_mfma_f32_16x16x32_bf16 v[8:11], v[140:143], v[228:231], v[8:11]
	v_mfma_f32_16x16x32_bf16 v[60:63], v[136:139], v[204:207], v[60:63]
	v_mfma_f32_16x16x32_bf16 v[56:59], v[144:147], v[204:207], v[56:59]
	v_mfma_f32_16x16x32_bf16 v[44:47], v[136:139], v[216:219], v[44:47]
	v_mfma_f32_16x16x32_bf16 v[40:43], v[144:147], v[216:219], v[40:43]
	v_mfma_f32_16x16x32_bf16 v[28:31], v[136:139], v[224:227], v[28:31]
	v_mfma_f32_16x16x32_bf16 v[24:27], v[144:147], v[224:227], v[24:27]
	v_mfma_f32_16x16x32_bf16 v[12:15], v[136:139], v[232:235], v[12:15]
	v_mfma_f32_16x16x32_bf16 v[8:11], v[144:147], v[232:235], v[8:11]
	v_mfma_f32_16x16x32_bf16 v[52:55], v[148:151], v[192:195], v[52:55]
	v_mfma_f32_16x16x32_bf16 v[48:51], v[184:187], v[192:195], v[48:51]
	v_mfma_f32_16x16x32_bf16 v[36:39], v[148:151], v[208:211], v[36:39]
	v_mfma_f32_16x16x32_bf16 v[32:35], v[184:187], v[208:211], v[32:35]
	v_mfma_f32_16x16x32_bf16 v[20:23], v[148:151], v[220:223], v[20:23]
	v_mfma_f32_16x16x32_bf16 v[16:19], v[184:187], v[220:223], v[16:19]
	v_mfma_f32_16x16x32_bf16 v[4:7], v[148:151], v[228:231], v[4:7]
	v_mfma_f32_16x16x32_bf16 v[0:3], v[184:187], v[228:231], v[0:3]
	v_mfma_f32_16x16x32_bf16 v[52:55], v[180:183], v[204:207], v[52:55]
	v_mfma_f32_16x16x32_bf16 v[48:51], v[188:191], v[204:207], v[48:51]
	v_mfma_f32_16x16x32_bf16 v[36:39], v[180:183], v[216:219], v[36:39]
	v_mfma_f32_16x16x32_bf16 v[32:35], v[188:191], v[216:219], v[32:35]
	v_mfma_f32_16x16x32_bf16 v[20:23], v[180:183], v[224:227], v[20:23]
	v_mfma_f32_16x16x32_bf16 v[16:19], v[188:191], v[224:227], v[16:19]
	v_mfma_f32_16x16x32_bf16 v[4:7], v[180:183], v[232:235], v[4:7]
	v_mfma_f32_16x16x32_bf16 v[0:3], v[188:191], v[232:235], v[0:3]
	s_setprio 0
	s_barrier
	s_add_i32 s13, 0, 0x18000
	s_add_i32 s29, 0, 0x1c000
	v_add_u32_e32 v144, s13, v199
	v_add_u32_e32 v188, s29, v199
	ds_read_b128 v[132:135], v144
	ds_read_b128 v[136:139], v144 offset:1024
	ds_read_b128 v[140:143], v144 offset:2048
	ds_read_b128 v[144:147], v144 offset:3072
	ds_read_b128 v[148:151], v188
	ds_read_b128 v[180:183], v188 offset:1024
	ds_read_b128 v[184:187], v188 offset:2048
	ds_read_b128 v[188:191], v188 offset:3072
	v_lshl_add_u64 v[196:197], v[196:197], 0, s[14:15]
	s_mov_b32 m0, s35
	v_lshl_add_u64 v[244:245], v[196:197], 0, v[162:163]
	ds_read_b128 v[192:195], v202 offset:32768
	ds_read_b128 v[204:207], v202 offset:33792
	ds_read_b128 v[208:211], v202 offset:34816
	ds_read_b128 v[216:219], v202 offset:35840
	ds_read_b128 v[220:223], v202 offset:36864
	ds_read_b128 v[224:227], v202 offset:37888
	ds_read_b128 v[228:231], v202 offset:38912
	ds_read_b128 v[232:235], v202 offset:39936
	global_load_lds_dwordx4 v[244:245], off
	v_lshl_add_u64 v[196:197], v[196:197], 0, v[166:167]
	s_mov_b32 m0, s36
	s_nop 0
	global_load_lds_dwordx4 v[196:197], off
	s_waitcnt vmcnt(8)
	s_waitcnt lgkmcnt(0)
	s_setprio 1
	s_barrier
	v_mfma_f32_16x16x32_bf16 v[120:123], v[132:135], v[192:195], v[120:123]
	v_mfma_f32_16x16x32_bf16 v[124:127], v[140:143], v[192:195], v[124:127]
	v_mfma_f32_16x16x32_bf16 v[108:111], v[132:135], v[208:211], v[108:111]
	v_mfma_f32_16x16x32_bf16 v[104:107], v[140:143], v[208:211], v[104:107]
	v_mfma_f32_16x16x32_bf16 v[92:95], v[132:135], v[220:223], v[92:95]
	v_mfma_f32_16x16x32_bf16 v[88:91], v[140:143], v[220:223], v[88:91]
	v_mfma_f32_16x16x32_bf16 v[76:79], v[132:135], v[228:231], v[76:79]
	v_mfma_f32_16x16x32_bf16 v[72:75], v[140:143], v[228:231], v[72:75]
	v_mfma_f32_16x16x32_bf16 v[120:123], v[136:139], v[204:207], v[120:123]
	v_mfma_f32_16x16x32_bf16 v[124:127], v[144:147], v[204:207], v[124:127]
	v_mfma_f32_16x16x32_bf16 v[108:111], v[136:139], v[216:219], v[108:111]
	v_mfma_f32_16x16x32_bf16 v[104:107], v[144:147], v[216:219], v[104:107]
	v_mfma_f32_16x16x32_bf16 v[92:95], v[136:139], v[224:227], v[92:95]
	v_mfma_f32_16x16x32_bf16 v[88:91], v[144:147], v[224:227], v[88:91]
	v_mfma_f32_16x16x32_bf16 v[76:79], v[136:139], v[232:235], v[76:79]
	v_mfma_f32_16x16x32_bf16 v[72:75], v[144:147], v[232:235], v[72:75]
	v_mfma_f32_16x16x32_bf16 v[116:119], v[148:151], v[192:195], v[116:119]
	v_mfma_f32_16x16x32_bf16 v[112:115], v[184:187], v[192:195], v[112:115]
	v_mfma_f32_16x16x32_bf16 v[100:103], v[148:151], v[208:211], v[100:103]
	v_mfma_f32_16x16x32_bf16 v[96:99], v[184:187], v[208:211], v[96:99]
	v_mfma_f32_16x16x32_bf16 v[84:87], v[148:151], v[220:223], v[84:87]
	v_mfma_f32_16x16x32_bf16 v[80:83], v[184:187], v[220:223], v[80:83]
	v_mfma_f32_16x16x32_bf16 v[68:71], v[148:151], v[228:231], v[68:71]
	v_mfma_f32_16x16x32_bf16 v[64:67], v[184:187], v[228:231], v[64:67]
	v_mfma_f32_16x16x32_bf16 v[116:119], v[180:183], v[204:207], v[116:119]
	v_mfma_f32_16x16x32_bf16 v[112:115], v[188:191], v[204:207], v[112:115]
	v_mfma_f32_16x16x32_bf16 v[100:103], v[180:183], v[216:219], v[100:103]
	v_mfma_f32_16x16x32_bf16 v[96:99], v[188:191], v[216:219], v[96:99]
	v_mfma_f32_16x16x32_bf16 v[84:87], v[180:183], v[224:227], v[84:87]
	v_mfma_f32_16x16x32_bf16 v[80:83], v[188:191], v[224:227], v[80:83]
	v_mfma_f32_16x16x32_bf16 v[68:71], v[180:183], v[232:235], v[68:71]
	v_mfma_f32_16x16x32_bf16 v[64:67], v[188:191], v[232:235], v[64:67]
	s_setprio 0
	s_barrier
; #define PG8_STAGE(bufoff, gbase, voff) do { _Pragma("unroll") for (int _i = 0; _i < 2; ++_i) \
;         __builtin_amdgcn_global_load_lds((const unsigned*)((const char*)(gbase) + (voff)[_i]), (PG8_LAS unsigned*)(lds + (bufoff) + ldsw + _i * 8192), 16, 0, 0); } while (0)
; #define PG8_LDA(dst, b, h) do { _Pragma("unroll") for (int m = 0; m < 4; ++m) _Pragma("unroll") for (int k = 0; k < 2; ++k) dst[m][k] = *(const PG8_LAS bf16x8*)(lds + PG8_SA(b, h) + aoff + m * 2048 + k * 1024); } while (0)
; #define PG8_MMA(ai, bj, At, Bt) do { __builtin_amdgcn_s_setprio(1); _Pragma("unroll") for (int m = 0; m < 4; ++m) _Pragma("unroll") for (int n = 0; n < 2; ++n) _Pragma("unroll") for (int k = 0; k < 2; ++k) \
;         acc[ai][bj][m][n] = __builtin_amdgcn_mfma_f32_16x16x32_bf16(Bt[n][k], At[m][k], acc[ai][bj][m][n], 0, 0, 0); __builtin_amdgcn_s_setprio(0); } while (0)
; #define PG8_WAIT_V(n) asm volatile("s_waitcnt vmcnt(" #n ")" ::: "memory")
; #define PG8_WAIT_L(n) asm volatile("s_waitcnt lgkmcnt(" #n ")" ::: "memory")
; #define PG8_BAR __builtin_amdgcn_s_barrier()
; #define PG8_SCHED __builtin_amdgcn_sched_barrier(0)
; template <class Epi, class Sched, bool ALIGN_EPI = false, bool SP2 = false>
; __device__ __forceinline__ void gemm_phase(PG8_LAS unsigned char* lds, const Gemm g, const Sched& S, const Epi& E) {
;     ...
;             PG8_LDA(At, 1, 1); PG8_STAGE(PG8_SB(1, 0), b3, voffB); PG8_STAGE(PG8_SB(1, 1), b3 + hstep, voffB); PG8_STAGE(PG8_SA(1, 0), a3, voffA);
;             PG8_WAIT_V(8); PG8_WAIT_L(0); PG8_BAR; PG8_MMA(1, 0, At, B0); PG8_MMA(1, 1, At, B1); PG8_BAR; PG8_SCHED;
	s_add_i32 s13, s13, s30
	v_lshl_add_u64 v[196:197], v[214:215], 0, s[22:23]
	s_mov_b32 m0, s13
	ds_read_b128 v[192:195], v202 offset:49152
	ds_read_b128 v[204:207], v202 offset:50176
	ds_read_b128 v[208:211], v202 offset:51200
	ds_read_b128 v[216:219], v202 offset:52224
	ds_read_b128 v[220:223], v202 offset:53248
	ds_read_b128 v[224:227], v202 offset:54272
	ds_read_b128 v[228:231], v202 offset:55296
	ds_read_b128 v[232:235], v202 offset:56320
	global_load_lds_dwordx4 v[196:197], off
	v_lshl_add_u64 v[196:197], v[236:237], 0, s[22:23]
	s_add_i32 m0, s13, 0x2000
	s_add_i32 s13, s29, s30
	global_load_lds_dwordx4 v[196:197], off
	v_lshl_add_u64 v[196:197], v[238:239], 0, s[22:23]
	s_mov_b32 m0, s13
	s_nop 0
	global_load_lds_dwordx4 v[196:197], off
	v_lshl_add_u64 v[196:197], v[212:213], 0, s[22:23]
	s_add_i32 m0, s13, 0x2000
	s_nop 0
	global_load_lds_dwordx4 v[196:197], off
	v_lshl_add_u64 v[196:197], v[240:241], 0, s[22:23]
	s_mov_b32 m0, s37
	s_nop 0
	global_load_lds_dwordx4 v[196:197], off
	v_lshl_add_u64 v[196:197], v[242:243], 0, s[22:23]
	s_mov_b32 m0, s41
	s_nop 0
	global_load_lds_dwordx4 v[196:197], off
	s_waitcnt vmcnt(8)
	s_waitcnt lgkmcnt(0)
	s_setprio 1
	s_barrier
	v_mfma_f32_16x16x32_bf16 v[60:63], v[132:135], v[192:195], v[60:63]
	v_mfma_f32_16x16x32_bf16 v[56:59], v[140:143], v[192:195], v[56:59]
	v_mfma_f32_16x16x32_bf16 v[44:47], v[132:135], v[208:211], v[44:47]
	v_mfma_f32_16x16x32_bf16 v[40:43], v[140:143], v[208:211], v[40:43]
	v_mfma_f32_16x16x32_bf16 v[28:31], v[132:135], v[220:223], v[28:31]
	v_mfma_f32_16x16x32_bf16 v[24:27], v[140:143], v[220:223], v[24:27]
	v_mfma_f32_16x16x32_bf16 v[12:15], v[132:135], v[228:231], v[12:15]
	v_mfma_f32_16x16x32_bf16 v[8:11], v[140:143], v[228:231], v[8:11]
	v_mfma_f32_16x16x32_bf16 v[60:63], v[136:139], v[204:207], v[60:63]
	v_mfma_f32_16x16x32_bf16 v[56:59], v[144:147], v[204:207], v[56:59]
	v_mfma_f32_16x16x32_bf16 v[44:47], v[136:139], v[216:219], v[44:47]
	v_mfma_f32_16x16x32_bf16 v[40:43], v[144:147], v[216:219], v[40:43]
	v_mfma_f32_16x16x32_bf16 v[28:31], v[136:139], v[224:227], v[28:31]
	v_mfma_f32_16x16x32_bf16 v[24:27], v[144:147], v[224:227], v[24:27]
	v_mfma_f32_16x16x32_bf16 v[12:15], v[136:139], v[232:235], v[12:15]
	v_mfma_f32_16x16x32_bf16 v[8:11], v[144:147], v[232:235], v[8:11]
	v_mfma_f32_16x16x32_bf16 v[52:55], v[148:151], v[192:195], v[52:55]
	v_mfma_f32_16x16x32_bf16 v[48:51], v[184:187], v[192:195], v[48:51]
	v_mfma_f32_16x16x32_bf16 v[36:39], v[148:151], v[208:211], v[36:39]
	v_mfma_f32_16x16x32_bf16 v[32:35], v[184:187], v[208:211], v[32:35]
	v_mfma_f32_16x16x32_bf16 v[20:23], v[148:151], v[220:223], v[20:23]
	v_mfma_f32_16x16x32_bf16 v[16:19], v[184:187], v[220:223], v[16:19]
	v_mfma_f32_16x16x32_bf16 v[4:7], v[148:151], v[228:231], v[4:7]
	v_mfma_f32_16x16x32_bf16 v[0:3], v[184:187], v[228:231], v[0:3]
	v_mfma_f32_16x16x32_bf16 v[52:55], v[180:183], v[204:207], v[52:55]
	v_mfma_f32_16x16x32_bf16 v[48:51], v[188:191], v[204:207], v[48:51]
	v_mfma_f32_16x16x32_bf16 v[36:39], v[180:183], v[216:219], v[36:39]
	v_mfma_f32_16x16x32_bf16 v[32:35], v[188:191], v[216:219], v[32:35]
	v_mfma_f32_16x16x32_bf16 v[20:23], v[180:183], v[224:227], v[20:23]
	v_mfma_f32_16x16x32_bf16 v[16:19], v[188:191], v[224:227], v[16:19]
	v_mfma_f32_16x16x32_bf16 v[4:7], v[180:183], v[232:235], v[4:7]
	v_mfma_f32_16x16x32_bf16 v[0:3], v[188:191], v[232:235], v[0:3]
	s_setprio 0
	s_barrier
	v_lshl_add_u64 v[128:129], v[128:129], 0, s[26:27]
	s_cmp_ge_i32 s12, s47
	v_lshl_add_u64 v[130:131], v[130:131], 0, s[26:27]
	s_cbranch_scc0 .LBB0_1695

; #define PG8_STAGE(bufoff, gbase, voff) do { _Pragma("unroll") for (int _i = 0; _i < 2; ++_i) \
;         __builtin_amdgcn_global_load_lds((const unsigned*)((const char*)(gbase) + (voff)[_i]), (PG8_LAS unsigned*)(lds + (bufoff) + ldsw + _i * 8192), 16, 0, 0); } while (0)
; #define PG8_LDA(dst, b, h) do { _Pragma("unroll") for (int m = 0; m < 4; ++m) _Pragma("unroll") for (int k = 0; k < 2; ++k) dst[m][k] = *(const PG8_LAS bf16x8*)(lds + PG8_SA(b, h) + aoff + m * 2048 + k * 1024); } while (0)
; #define PG8_LDB(dst, b, h) do { _Pragma("unroll") for (int n = 0; n < 2; ++n) _Pragma("unroll") for (int k = 0; k < 2; ++k) dst[n][k] = *(const PG8_LAS bf16x8*)(lds + PG8_SB(b, h) + boff + n * 2048 + k * 1024); } while (0)
; #define PG8_MMA(ai, bj, At, Bt) do { __builtin_amdgcn_s_setprio(1); _Pragma("unroll") for (int m = 0; m < 4; ++m) _Pragma("unroll") for (int n = 0; n < 2; ++n) _Pragma("unroll") for (int k = 0; k < 2; ++k) \
;         acc[ai][bj][m][n] = __builtin_amdgcn_mfma_f32_16x16x32_bf16(Bt[n][k], At[m][k], acc[ai][bj][m][n], 0, 0, 0); __builtin_amdgcn_s_setprio(0); } while (0)
; #define PG8_WAIT_V(n) asm volatile("s_waitcnt vmcnt(" #n ")" ::: "memory")
; #define PG8_WAIT_L(n) asm volatile("s_waitcnt lgkmcnt(" #n ")" ::: "memory")
; #define PG8_BAR __builtin_amdgcn_s_barrier()
; #define PG8_SCHED __builtin_amdgcn_sched_barrier(0)
; template <class Epi, class Sched, bool ALIGN_EPI = false, bool SP2 = false>
; __device__ __forceinline__ void gemm_phase(PG8_LAS unsigned char* lds, const Gemm g, const Sched& S, const Epi& E) {
;     ...
;             const bool last = (t == nt - 2);
;             const char* a1 = cA + (size_t)(t + 1) * kstep;
;             const char* a2 = last ? nA : cA + (size_t)(t + 2) * kstep; const char* b2 = last ? nB : cB + (size_t)(t + 2) * kstep;
;             const char* a3 = a2 + kstep; const char* b3 = b2 + kstep;
;             if (last && has_next) S.a_ready(nxt);
;             if constexpr (SP2) {
;             PG8_LDB(B0, 0, 0); PG8_LDB(B1, 0, 1); PG8_SCHED; PG8_LDA(At, 0, 0); PG8_STAGE(PG8_SA(1, 1), a1 + hstep, voffA);
;             PG8_WAIT_V(8); PG8_WAIT_L(0); PG8_BAR; PG8_MMA(0, 0, At, B0); PG8_MMA(0, 1, At, B1); PG8_BAR; PG8_SCHED;
;             PG8_LDA(At, 0, 1); PG8_STAGE(PG8_SB(0, 0), b2, voffB); PG8_STAGE(PG8_SB(0, 1), b2 + hstep, voffB); PG8_STAGE(PG8_SA(0, 0), a2, voffA);
.LBB0_1776:
	v_add_u32_e32 v166, s54, v169
	v_add_u32_e32 v168, s55, v169
	ds_read_b128 v[162:165], v166
	ds_read_b128 v[182:185], v166 offset:1024
	ds_read_b128 v[186:189], v166 offset:2048
	ds_read_b128 v[190:193], v166 offset:3072
	ds_read_b128 v[194:197], v168
	ds_read_b128 v[198:201], v168 offset:1024
	ds_read_b128 v[202:205], v168 offset:2048
	ds_read_b128 v[206:209], v168 offset:3072
	s_cmp_eq_u32 s53, s10
	v_lshl_add_u64 v[172:173], v[160:161], 0, s[22:23]
	s_cselect_b64 vcc, -1, 0
	s_add_i32 s10, s10, 2
	v_cndmask_b32_e32 v173, v173, v153, vcc
	v_cndmask_b32_e32 v172, v172, v152, vcc
	v_cndmask_b32_e32 v215, v159, v155, vcc
	v_cndmask_b32_e32 v214, v158, v154, vcc
	s_mov_b32 m0, s56
	v_lshl_add_u64 v[244:245], v[160:161], 0, v[148:149]
	ds_read_b128 v[210:213], v179
	ds_read_b128 v[216:219], v179 offset:1024
	ds_read_b128 v[220:223], v179 offset:2048
	ds_read_b128 v[224:227], v179 offset:3072
	ds_read_b128 v[228:231], v179 offset:4096
	ds_read_b128 v[232:235], v179 offset:5120
	ds_read_b128 v[236:239], v179 offset:6144
	ds_read_b128 v[240:243], v179 offset:7168
	global_load_lds_dwordx4 v[244:245], off
	v_lshl_add_u64 v[244:245], v[160:161], 0, v[146:147]
	s_mov_b32 m0, s57
	s_nop 0
	global_load_lds_dwordx4 v[244:245], off
	s_waitcnt vmcnt(8)
	s_waitcnt lgkmcnt(0)
	s_setprio 1
	s_barrier
	v_mfma_f32_16x16x32_bf16 v[124:127], v[162:165], v[210:213], v[124:127]
	v_mfma_f32_16x16x32_bf16 v[116:119], v[186:189], v[210:213], v[116:119]
	v_mfma_f32_16x16x32_bf16 v[108:111], v[162:165], v[220:223], v[108:111]
	v_mfma_f32_16x16x32_bf16 v[100:103], v[186:189], v[220:223], v[100:103]
	v_mfma_f32_16x16x32_bf16 v[92:95], v[162:165], v[228:231], v[92:95]
	v_mfma_f32_16x16x32_bf16 v[84:87], v[186:189], v[228:231], v[84:87]
	v_mfma_f32_16x16x32_bf16 v[76:79], v[162:165], v[236:239], v[76:79]
	v_mfma_f32_16x16x32_bf16 v[68:71], v[186:189], v[236:239], v[68:71]
	v_mfma_f32_16x16x32_bf16 v[124:127], v[182:185], v[216:219], v[124:127]
	v_mfma_f32_16x16x32_bf16 v[116:119], v[190:193], v[216:219], v[116:119]
	v_mfma_f32_16x16x32_bf16 v[108:111], v[182:185], v[224:227], v[108:111]
	v_mfma_f32_16x16x32_bf16 v[100:103], v[190:193], v[224:227], v[100:103]
	v_mfma_f32_16x16x32_bf16 v[92:95], v[182:185], v[232:235], v[92:95]
	v_mfma_f32_16x16x32_bf16 v[84:87], v[190:193], v[232:235], v[84:87]
	v_mfma_f32_16x16x32_bf16 v[76:79], v[182:185], v[240:243], v[76:79]
	v_mfma_f32_16x16x32_bf16 v[68:71], v[190:193], v[240:243], v[68:71]
	v_mfma_f32_16x16x32_bf16 v[120:123], v[194:197], v[210:213], v[120:123]
	v_mfma_f32_16x16x32_bf16 v[112:115], v[202:205], v[210:213], v[112:115]
	v_mfma_f32_16x16x32_bf16 v[104:107], v[194:197], v[220:223], v[104:107]
	v_mfma_f32_16x16x32_bf16 v[96:99], v[202:205], v[220:223], v[96:99]
	v_mfma_f32_16x16x32_bf16 v[88:91], v[194:197], v[228:231], v[88:91]
	v_mfma_f32_16x16x32_bf16 v[80:83], v[202:205], v[228:231], v[80:83]
	v_mfma_f32_16x16x32_bf16 v[72:75], v[194:197], v[236:239], v[72:75]
	v_mfma_f32_16x16x32_bf16 v[64:67], v[202:205], v[236:239], v[64:67]
	v_mfma_f32_16x16x32_bf16 v[120:123], v[198:201], v[216:219], v[120:123]
	v_mfma_f32_16x16x32_bf16 v[112:115], v[206:209], v[216:219], v[112:115]
	v_mfma_f32_16x16x32_bf16 v[104:107], v[198:201], v[224:227], v[104:107]
	v_mfma_f32_16x16x32_bf16 v[96:99], v[206:209], v[224:227], v[96:99]
	v_mfma_f32_16x16x32_bf16 v[88:91], v[198:201], v[232:235], v[88:91]
	v_mfma_f32_16x16x32_bf16 v[80:83], v[206:209], v[232:235], v[80:83]
	v_mfma_f32_16x16x32_bf16 v[72:75], v[198:201], v[240:243], v[72:75]
	v_mfma_f32_16x16x32_bf16 v[64:67], v[206:209], v[240:243], v[64:67]
	s_setprio 0
	s_barrier
	s_mov_b32 m0, s60
	v_lshl_add_u64 v[244:245], v[214:215], 0, v[138:139]
	ds_read_b128 v[210:213], v179 offset:16384
	ds_read_b128 v[216:219], v179 offset:17408
	ds_read_b128 v[220:223], v179 offset:18432
	ds_read_b128 v[224:227], v179 offset:19456
	ds_read_b128 v[228:231], v179 offset:20480
	ds_read_b128 v[232:235], v179 offset:21504
	ds_read_b128 v[236:239], v179 offset:22528
	ds_read_b128 v[240:243], v179 offset:23552
	global_load_lds_dwordx4 v[244:245], off
	v_lshl_add_u64 v[246:247], v[214:215], 0, v[134:135]
	s_mov_b32 m0, s61
	v_lshl_add_u64 v[214:215], v[214:215], 0, s[14:15]
	global_load_lds_dwordx4 v[246:247], off
	v_lshl_add_u64 v[248:249], v[214:215], 0, v[138:139]
	s_mov_b32 m0, s62
	v_lshl_add_u64 v[214:215], v[214:215], 0, v[134:135]
	global_load_lds_dwordx4 v[248:249], off
	s_add_i32 m0, s62, 0x2000
	v_lshl_add_u64 v[250:251], v[172:173], 0, v[140:141]
	global_load_lds_dwordx4 v[214:215], off
	s_mov_b32 m0, s46
	v_lshl_add_u64 v[252:253], v[172:173], 0, v[136:137]
	global_load_lds_dwordx4 v[250:251], off
	s_mov_b32 m0, s47
	s_nop 0
	global_load_lds_dwordx4 v[252:253], off
	s_waitcnt vmcnt(8)
	s_waitcnt lgkmcnt(0)
	s_setprio 1
	s_barrier
; #define PG8_STAGE(bufoff, gbase, voff) do { _Pragma("unroll") for (int _i = 0; _i < 2; ++_i) \
;         __builtin_amdgcn_global_load_lds((const unsigned*)((const char*)(gbase) + (voff)[_i]), (PG8_LAS unsigned*)(lds + (bufoff) + ldsw + _i * 8192), 16, 0, 0); } while (0)
; #define PG8_LDA(dst, b, h) do { _Pragma("unroll") for (int m = 0; m < 4; ++m) _Pragma("unroll") for (int k = 0; k < 2; ++k) dst[m][k] = *(const PG8_LAS bf16x8*)(lds + PG8_SA(b, h) + aoff + m * 2048 + k * 1024); } while (0)
; #define PG8_LDB(dst, b, h) do { _Pragma("unroll") for (int n = 0; n < 2; ++n) _Pragma("unroll") for (int k = 0; k < 2; ++k) dst[n][k] = *(const PG8_LAS bf16x8*)(lds + PG8_SB(b, h) + boff + n * 2048 + k * 1024); } while (0)
; #define PG8_MMA(ai, bj, At, Bt) do { __builtin_amdgcn_s_setprio(1); _Pragma("unroll") for (int m = 0; m < 4; ++m) _Pragma("unroll") for (int n = 0; n < 2; ++n) _Pragma("unroll") for (int k = 0; k < 2; ++k) \
;         acc[ai][bj][m][n] = __builtin_amdgcn_mfma_f32_16x16x32_bf16(Bt[n][k], At[m][k], acc[ai][bj][m][n], 0, 0, 0); __builtin_amdgcn_s_setprio(0); } while (0)
; #define PG8_WAIT_V(n) asm volatile("s_waitcnt vmcnt(" #n ")" ::: "memory")
; #define PG8_WAIT_L(n) asm volatile("s_waitcnt lgkmcnt(" #n ")" ::: "memory")
; #define PG8_BAR __builtin_amdgcn_s_barrier()
; #define PG8_SCHED __builtin_amdgcn_sched_barrier(0)
; template <class Epi, class Sched, bool ALIGN_EPI = false, bool SP2 = false>
; __device__ __forceinline__ void gemm_phase(PG8_LAS unsigned char* lds, const Gemm g, const Sched& S, const Epi& E) {
;     ...
;             PG8_WAIT_V(8); PG8_WAIT_L(0); PG8_BAR; PG8_MMA(1, 0, At, B0); PG8_MMA(1, 1, At, B1); PG8_BAR; PG8_SCHED;
;             PG8_LDB(B0, 1, 0); PG8_LDB(B1, 1, 1); PG8_SCHED; PG8_LDA(At, 1, 0); PG8_STAGE(PG8_SA(0, 1), a2 + hstep, voffA);
;             PG8_WAIT_V(8); PG8_WAIT_L(0); PG8_BAR; PG8_MMA(0, 0, At, B0); PG8_MMA(0, 1, At, B1); PG8_BAR; PG8_SCHED;
	v_mfma_f32_16x16x32_bf16 v[60:63], v[162:165], v[210:213], v[60:63]
	v_mfma_f32_16x16x32_bf16 v[52:55], v[186:189], v[210:213], v[52:55]
	v_mfma_f32_16x16x32_bf16 v[44:47], v[162:165], v[220:223], v[44:47]
	v_mfma_f32_16x16x32_bf16 v[36:39], v[186:189], v[220:223], v[36:39]
	v_mfma_f32_16x16x32_bf16 v[28:31], v[162:165], v[228:231], v[28:31]
	v_mfma_f32_16x16x32_bf16 v[20:23], v[186:189], v[228:231], v[20:23]
	v_mfma_f32_16x16x32_bf16 v[12:15], v[162:165], v[236:239], v[12:15]
	v_mfma_f32_16x16x32_bf16 v[4:7], v[186:189], v[236:239], v[4:7]
	v_mfma_f32_16x16x32_bf16 v[60:63], v[182:185], v[216:219], v[60:63]
	v_mfma_f32_16x16x32_bf16 v[52:55], v[190:193], v[216:219], v[52:55]
	v_mfma_f32_16x16x32_bf16 v[44:47], v[182:185], v[224:227], v[44:47]
	v_mfma_f32_16x16x32_bf16 v[36:39], v[190:193], v[224:227], v[36:39]
	v_mfma_f32_16x16x32_bf16 v[28:31], v[182:185], v[232:235], v[28:31]
	v_mfma_f32_16x16x32_bf16 v[20:23], v[190:193], v[232:235], v[20:23]
	v_mfma_f32_16x16x32_bf16 v[12:15], v[182:185], v[240:243], v[12:15]
	v_mfma_f32_16x16x32_bf16 v[4:7], v[190:193], v[240:243], v[4:7]
	v_mfma_f32_16x16x32_bf16 v[56:59], v[194:197], v[210:213], v[56:59]
	v_mfma_f32_16x16x32_bf16 v[48:51], v[202:205], v[210:213], v[48:51]
	v_mfma_f32_16x16x32_bf16 v[40:43], v[194:197], v[220:223], v[40:43]
	v_mfma_f32_16x16x32_bf16 v[32:35], v[202:205], v[220:223], v[32:35]
	v_mfma_f32_16x16x32_bf16 v[24:27], v[194:197], v[228:231], v[24:27]
	v_mfma_f32_16x16x32_bf16 v[16:19], v[202:205], v[228:231], v[16:19]
	v_mfma_f32_16x16x32_bf16 v[8:11], v[194:197], v[236:239], v[8:11]
	v_mfma_f32_16x16x32_bf16 v[0:3], v[202:205], v[236:239], v[0:3]
	v_mfma_f32_16x16x32_bf16 v[56:59], v[198:201], v[216:219], v[56:59]
	v_mfma_f32_16x16x32_bf16 v[48:51], v[206:209], v[216:219], v[48:51]
	v_mfma_f32_16x16x32_bf16 v[40:43], v[198:201], v[224:227], v[40:43]
	v_mfma_f32_16x16x32_bf16 v[32:35], v[206:209], v[224:227], v[32:35]
	v_mfma_f32_16x16x32_bf16 v[24:27], v[198:201], v[232:235], v[24:27]
	v_mfma_f32_16x16x32_bf16 v[16:19], v[206:209], v[232:235], v[16:19]
	v_mfma_f32_16x16x32_bf16 v[8:11], v[198:201], v[240:243], v[8:11]
	v_mfma_f32_16x16x32_bf16 v[0:3], v[206:209], v[240:243], v[0:3]
	s_setprio 0
	s_barrier
	s_add_i32 s11, 0, 0x18000
	v_add_u32_e32 v166, s11, v169
	s_add_i32 s13, 0, 0x1c000
	ds_read_b128 v[162:165], v166
	ds_read_b128 v[182:185], v166 offset:1024
	ds_read_b128 v[186:189], v166 offset:2048
	ds_read_b128 v[190:193], v166 offset:3072
	v_add_u32_e32 v166, s13, v169
	ds_read_b128 v[194:197], v166
	ds_read_b128 v[198:201], v166 offset:1024
	ds_read_b128 v[202:205], v166 offset:2048
	ds_read_b128 v[206:209], v166 offset:3072
	v_lshl_add_u64 v[172:173], v[172:173], 0, s[14:15]
	s_mov_b32 m0, s48
	v_lshl_add_u64 v[170:171], v[172:173], 0, v[140:141]
	ds_read_b128 v[210:213], v179 offset:32768
	ds_read_b128 v[216:219], v179 offset:33792
	ds_read_b128 v[220:223], v179 offset:34816
	ds_read_b128 v[224:227], v179 offset:35840
	ds_read_b128 v[228:231], v179 offset:36864
	ds_read_b128 v[232:235], v179 offset:37888
	ds_read_b128 v[236:239], v179 offset:38912
	ds_read_b128 v[240:243], v179 offset:39936
	global_load_lds_dwordx4 v[170:171], off
	v_lshl_add_u64 v[170:171], v[172:173], 0, v[136:137]
	s_mov_b32 m0, s49
	s_nop 0
	global_load_lds_dwordx4 v[170:171], off
	s_waitcnt vmcnt(8)
	s_waitcnt lgkmcnt(0)
	s_setprio 1
	s_barrier
	v_mfma_f32_16x16x32_bf16 v[124:127], v[162:165], v[210:213], v[124:127]
	v_mfma_f32_16x16x32_bf16 v[116:119], v[186:189], v[210:213], v[116:119]
	v_mfma_f32_16x16x32_bf16 v[108:111], v[162:165], v[220:223], v[108:111]
	v_mfma_f32_16x16x32_bf16 v[100:103], v[186:189], v[220:223], v[100:103]
	v_mfma_f32_16x16x32_bf16 v[92:95], v[162:165], v[228:231], v[92:95]
	v_mfma_f32_16x16x32_bf16 v[84:87], v[186:189], v[228:231], v[84:87]
	v_mfma_f32_16x16x32_bf16 v[76:79], v[162:165], v[236:239], v[76:79]
	v_mfma_f32_16x16x32_bf16 v[68:71], v[186:189], v[236:239], v[68:71]
	v_mfma_f32_16x16x32_bf16 v[124:127], v[182:185], v[216:219], v[124:127]
	v_mfma_f32_16x16x32_bf16 v[116:119], v[190:193], v[216:219], v[116:119]
	v_mfma_f32_16x16x32_bf16 v[108:111], v[182:185], v[224:227], v[108:111]
	v_mfma_f32_16x16x32_bf16 v[100:103], v[190:193], v[224:227], v[100:103]
	v_mfma_f32_16x16x32_bf16 v[92:95], v[182:185], v[232:235], v[92:95]
	v_mfma_f32_16x16x32_bf16 v[84:87], v[190:193], v[232:235], v[84:87]
	v_mfma_f32_16x16x32_bf16 v[76:79], v[182:185], v[240:243], v[76:79]
	v_mfma_f32_16x16x32_bf16 v[68:71], v[190:193], v[240:243], v[68:71]
	v_mfma_f32_16x16x32_bf16 v[120:123], v[194:197], v[210:213], v[120:123]
	v_mfma_f32_16x16x32_bf16 v[112:115], v[202:205], v[210:213], v[112:115]
	v_mfma_f32_16x16x32_bf16 v[104:107], v[194:197], v[220:223], v[104:107]
	v_mfma_f32_16x16x32_bf16 v[96:99], v[202:205], v[220:223], v[96:99]
	v_mfma_f32_16x16x32_bf16 v[88:91], v[194:197], v[228:231], v[88:91]
	v_mfma_f32_16x16x32_bf16 v[80:83], v[202:205], v[228:231], v[80:83]
	v_mfma_f32_16x16x32_bf16 v[72:75], v[194:197], v[236:239], v[72:75]
	v_mfma_f32_16x16x32_bf16 v[64:67], v[202:205], v[236:239], v[64:67]
	v_mfma_f32_16x16x32_bf16 v[120:123], v[198:201], v[216:219], v[120:123]
	v_mfma_f32_16x16x32_bf16 v[112:115], v[206:209], v[216:219], v[112:115]
	v_mfma_f32_16x16x32_bf16 v[104:107], v[198:201], v[224:227], v[104:107]
	v_mfma_f32_16x16x32_bf16 v[96:99], v[206:209], v[224:227], v[96:99]
	v_mfma_f32_16x16x32_bf16 v[88:91], v[198:201], v[232:235], v[88:91]
	v_mfma_f32_16x16x32_bf16 v[80:83], v[206:209], v[232:235], v[80:83]
	v_mfma_f32_16x16x32_bf16 v[72:75], v[198:201], v[240:243], v[72:75]
	v_mfma_f32_16x16x32_bf16 v[64:67], v[206:209], v[240:243], v[64:67]
	s_setprio 0
	s_barrier
; #define PG8_STAGE(bufoff, gbase, voff) do { _Pragma("unroll") for (int _i = 0; _i < 2; ++_i) \
;         __builtin_amdgcn_global_load_lds((const unsigned*)((const char*)(gbase) + (voff)[_i]), (PG8_LAS unsigned*)(lds + (bufoff) + ldsw + _i * 8192), 16, 0, 0); } while (0)
; #define PG8_LDA(dst, b, h) do { _Pragma("unroll") for (int m = 0; m < 4; ++m) _Pragma("unroll") for (int k = 0; k < 2; ++k) dst[m][k] = *(const PG8_LAS bf16x8*)(lds + PG8_SA(b, h) + aoff + m * 2048 + k * 1024); } while (0)
; #define PG8_MMA(ai, bj, At, Bt) do { __builtin_amdgcn_s_setprio(1); _Pragma("unroll") for (int m = 0; m < 4; ++m) _Pragma("unroll") for (int n = 0; n < 2; ++n) _Pragma("unroll") for (int k = 0; k < 2; ++k) \
;         acc[ai][bj][m][n] = __builtin_amdgcn_mfma_f32_16x16x32_bf16(Bt[n][k], At[m][k], acc[ai][bj][m][n], 0, 0, 0); __builtin_amdgcn_s_setprio(0); } while (0)
; #define PG8_WAIT_V(n) asm volatile("s_waitcnt vmcnt(" #n ")" ::: "memory")
; #define PG8_WAIT_L(n) asm volatile("s_waitcnt lgkmcnt(" #n ")" ::: "memory")
; #define PG8_BAR __builtin_amdgcn_s_barrier()
; #define PG8_SCHED __builtin_amdgcn_sched_barrier(0)
; template <class Epi, class Sched, bool ALIGN_EPI = false, bool SP2 = false>
; __device__ __forceinline__ void gemm_phase(PG8_LAS unsigned char* lds, const Gemm g, const Sched& S, const Epi& E) {
;     ...
;             PG8_LDA(At, 1, 1); PG8_STAGE(PG8_SB(1, 0), b3, voffB); PG8_STAGE(PG8_SB(1, 1), b3 + hstep, voffB); PG8_STAGE(PG8_SA(1, 0), a3, voffA);
;             PG8_WAIT_V(8); PG8_WAIT_L(0); PG8_BAR; PG8_MMA(1, 0, At, B0); PG8_MMA(1, 1, At, B1); PG8_BAR; PG8_SCHED;
	s_add_i32 s11, s11, s29
	v_lshl_add_u64 v[170:171], v[244:245], 0, s[22:23]
	s_mov_b32 m0, s11
	ds_read_b128 v[210:213], v179 offset:49152
	ds_read_b128 v[216:219], v179 offset:50176
	ds_read_b128 v[220:223], v179 offset:51200
	ds_read_b128 v[224:227], v179 offset:52224
	ds_read_b128 v[228:231], v179 offset:53248
	ds_read_b128 v[232:235], v179 offset:54272
	ds_read_b128 v[236:239], v179 offset:55296
	ds_read_b128 v[240:243], v179 offset:56320
	global_load_lds_dwordx4 v[170:171], off
	v_lshl_add_u64 v[170:171], v[246:247], 0, s[22:23]
	s_add_i32 m0, s11, 0x2000
	s_add_i32 s11, s13, s29
	global_load_lds_dwordx4 v[170:171], off
	v_lshl_add_u64 v[170:171], v[248:249], 0, s[22:23]
	s_mov_b32 m0, s11
	s_nop 0
	global_load_lds_dwordx4 v[170:171], off
	v_lshl_add_u64 v[170:171], v[214:215], 0, s[22:23]
	s_add_i32 m0, s11, 0x2000
	s_nop 0
	global_load_lds_dwordx4 v[170:171], off
	v_lshl_add_u64 v[170:171], v[250:251], 0, s[22:23]
	s_mov_b32 m0, s50
	s_nop 0
	global_load_lds_dwordx4 v[170:171], off
	v_lshl_add_u64 v[170:171], v[252:253], 0, s[22:23]
	s_mov_b32 m0, s51
	s_nop 0
	global_load_lds_dwordx4 v[170:171], off
	s_waitcnt vmcnt(8)
	s_waitcnt lgkmcnt(0)
	s_setprio 1
	s_barrier
	v_mfma_f32_16x16x32_bf16 v[60:63], v[162:165], v[210:213], v[60:63]
	v_mfma_f32_16x16x32_bf16 v[52:55], v[186:189], v[210:213], v[52:55]
	v_mfma_f32_16x16x32_bf16 v[44:47], v[162:165], v[220:223], v[44:47]
	v_mfma_f32_16x16x32_bf16 v[36:39], v[186:189], v[220:223], v[36:39]
	v_mfma_f32_16x16x32_bf16 v[28:31], v[162:165], v[228:231], v[28:31]
	v_mfma_f32_16x16x32_bf16 v[20:23], v[186:189], v[228:231], v[20:23]
	v_mfma_f32_16x16x32_bf16 v[12:15], v[162:165], v[236:239], v[12:15]
	v_mfma_f32_16x16x32_bf16 v[4:7], v[186:189], v[236:239], v[4:7]
	v_mfma_f32_16x16x32_bf16 v[60:63], v[182:185], v[216:219], v[60:63]
	v_mfma_f32_16x16x32_bf16 v[52:55], v[190:193], v[216:219], v[52:55]
	v_mfma_f32_16x16x32_bf16 v[44:47], v[182:185], v[224:227], v[44:47]
	v_mfma_f32_16x16x32_bf16 v[36:39], v[190:193], v[224:227], v[36:39]
	v_mfma_f32_16x16x32_bf16 v[28:31], v[182:185], v[232:235], v[28:31]
	v_mfma_f32_16x16x32_bf16 v[20:23], v[190:193], v[232:235], v[20:23]
	v_mfma_f32_16x16x32_bf16 v[12:15], v[182:185], v[240:243], v[12:15]
	v_mfma_f32_16x16x32_bf16 v[4:7], v[190:193], v[240:243], v[4:7]
	v_mfma_f32_16x16x32_bf16 v[56:59], v[194:197], v[210:213], v[56:59]
	v_mfma_f32_16x16x32_bf16 v[48:51], v[202:205], v[210:213], v[48:51]
	v_mfma_f32_16x16x32_bf16 v[40:43], v[194:197], v[220:223], v[40:43]
	v_mfma_f32_16x16x32_bf16 v[32:35], v[202:205], v[220:223], v[32:35]
	v_mfma_f32_16x16x32_bf16 v[24:27], v[194:197], v[228:231], v[24:27]
	v_mfma_f32_16x16x32_bf16 v[16:19], v[202:205], v[228:231], v[16:19]
	v_mfma_f32_16x16x32_bf16 v[8:11], v[194:197], v[236:239], v[8:11]
	v_mfma_f32_16x16x32_bf16 v[0:3], v[202:205], v[236:239], v[0:3]
	v_mfma_f32_16x16x32_bf16 v[56:59], v[198:201], v[216:219], v[56:59]
	v_mfma_f32_16x16x32_bf16 v[48:51], v[206:209], v[216:219], v[48:51]
	v_mfma_f32_16x16x32_bf16 v[40:43], v[198:201], v[224:227], v[40:43]
	v_mfma_f32_16x16x32_bf16 v[32:35], v[206:209], v[224:227], v[32:35]
	v_mfma_f32_16x16x32_bf16 v[24:27], v[198:201], v[232:235], v[24:27]
	v_mfma_f32_16x16x32_bf16 v[16:19], v[206:209], v[232:235], v[16:19]
	v_mfma_f32_16x16x32_bf16 v[8:11], v[198:201], v[240:243], v[8:11]
	v_mfma_f32_16x16x32_bf16 v[0:3], v[206:209], v[240:243], v[0:3]
	s_setprio 0
	s_barrier
	v_lshl_add_u64 v[158:159], v[158:159], 0, s[26:27]
	s_cmp_ge_i32 s10, s52
	v_lshl_add_u64 v[160:161], v[160:161], 0, s[26:27]
	s_cbranch_scc0 .LBB0_1776

; #define PG8_STAGE(bufoff, gbase, voff) do { _Pragma("unroll") for (int _i = 0; _i < 2; ++_i) \
;         __builtin_amdgcn_global_load_lds((const unsigned*)((const char*)(gbase) + (voff)[_i]), (PG8_LAS unsigned*)(lds + (bufoff) + ldsw + _i * 8192), 16, 0, 0); } while (0)
; #define PG8_LDA(dst, b, h) do { _Pragma("unroll") for (int m = 0; m < 4; ++m) _Pragma("unroll") for (int k = 0; k < 2; ++k) dst[m][k] = *(const PG8_LAS bf16x8*)(lds + PG8_SA(b, h) + aoff + m * 2048 + k * 1024); } while (0)
; #define PG8_LDB(dst, b, h) do { _Pragma("unroll") for (int n = 0; n < 2; ++n) _Pragma("unroll") for (int k = 0; k < 2; ++k) dst[n][k] = *(const PG8_LAS bf16x8*)(lds + PG8_SB(b, h) + boff + n * 2048 + k * 1024); } while (0)
; #define PG8_MMA(ai, bj, At, Bt) do { __builtin_amdgcn_s_setprio(1); _Pragma("unroll") for (int m = 0; m < 4; ++m) _Pragma("unroll") for (int n = 0; n < 2; ++n) _Pragma("unroll") for (int k = 0; k < 2; ++k) \
;         acc[ai][bj][m][n] = __builtin_amdgcn_mfma_f32_16x16x32_bf16(Bt[n][k], At[m][k], acc[ai][bj][m][n], 0, 0, 0); __builtin_amdgcn_s_setprio(0); } while (0)
; #define PG8_WAIT_V(n) asm volatile("s_waitcnt vmcnt(" #n ")" ::: "memory")
; #define PG8_WAIT_L(n) asm volatile("s_waitcnt lgkmcnt(" #n ")" ::: "memory")
; #define PG8_BAR __builtin_amdgcn_s_barrier()
; #define PG8_SCHED __builtin_amdgcn_sched_barrier(0)
; template <class Epi, class Sched, bool ALIGN_EPI = false, bool SP2 = false>
; __device__ __forceinline__ void gemm_phase(PG8_LAS unsigned char* lds, const Gemm g, const Sched& S, const Epi& E) {
;     ...
;             const bool last = (t == nt - 2);
;             const char* a1 = cA + (size_t)(t + 1) * kstep;
;             const char* a2 = last ? nA : cA + (size_t)(t + 2) * kstep; const char* b2 = last ? nB : cB + (size_t)(t + 2) * kstep;
;             const char* a3 = a2 + kstep; const char* b3 = b2 + kstep;
;             if (last && has_next) S.a_ready(nxt);
;             if constexpr (SP2) {
;             PG8_LDB(B0, 0, 0); PG8_LDB(B1, 0, 1); PG8_SCHED; PG8_LDA(At, 0, 0); PG8_STAGE(PG8_SA(1, 1), a1 + hstep, voffA);
;             PG8_WAIT_V(8); PG8_WAIT_L(0); PG8_BAR; PG8_MMA(0, 0, At, B0); PG8_MMA(0, 1, At, B1); PG8_BAR; PG8_SCHED;
;             PG8_LDA(At, 0, 1); PG8_STAGE(PG8_SB(0, 0), b2, voffB); PG8_STAGE(PG8_SB(0, 1), b2 + hstep, voffB); PG8_STAGE(PG8_SA(0, 0), a2, voffA);
.LBB0_1924:
	v_add_u32_e32 v192, s50, v161
	ds_read_b128 v[164:167], v162
	ds_read_b128 v[168:171], v162 offset:1024
	ds_read_b128 v[172:175], v162 offset:2048
	ds_read_b128 v[176:179], v162 offset:3072
	ds_read_b128 v[180:183], v192
	ds_read_b128 v[184:187], v192 offset:1024
	ds_read_b128 v[188:191], v192 offset:2048
	ds_read_b128 v[192:195], v192 offset:3072
	s_cmp_eq_u32 s49, s10
	v_lshl_add_u64 v[196:197], v[158:159], 0, s[24:25]
	s_cselect_b64 vcc, -1, 0
	s_add_i32 s10, s10, 2
	v_cndmask_b32_e32 v213, v197, v151, vcc
	v_cndmask_b32_e32 v212, v196, v150, vcc
	v_cndmask_b32_e32 v215, v155, v153, vcc
	v_cndmask_b32_e32 v214, v154, v152, vcc
	s_mov_b32 m0, s51
	v_lshl_add_u64 v[232:233], v[158:159], 0, v[146:147]
	ds_read_b128 v[196:199], v163
	ds_read_b128 v[200:203], v163 offset:1024
	ds_read_b128 v[204:207], v163 offset:2048
	ds_read_b128 v[208:211], v163 offset:3072
	ds_read_b128 v[216:219], v163 offset:4096
	ds_read_b128 v[220:223], v163 offset:5120
	ds_read_b128 v[224:227], v163 offset:6144
	ds_read_b128 v[228:231], v163 offset:7168
	global_load_lds_dwordx4 v[232:233], off
	v_lshl_add_u64 v[232:233], v[158:159], 0, v[144:145]
	s_mov_b32 m0, s52
	s_nop 0
	global_load_lds_dwordx4 v[232:233], off
	s_waitcnt vmcnt(8)
	s_waitcnt lgkmcnt(0)
	s_setprio 1
	s_barrier
	v_mfma_f32_16x16x32_bf16 v[124:127], v[164:167], v[196:199], v[124:127]
	v_mfma_f32_16x16x32_bf16 v[120:123], v[172:175], v[196:199], v[120:123]
	v_mfma_f32_16x16x32_bf16 v[108:111], v[164:167], v[204:207], v[108:111]
	v_mfma_f32_16x16x32_bf16 v[104:107], v[172:175], v[204:207], v[104:107]
	v_mfma_f32_16x16x32_bf16 v[92:95], v[164:167], v[216:219], v[92:95]
	v_mfma_f32_16x16x32_bf16 v[88:91], v[172:175], v[216:219], v[88:91]
	v_mfma_f32_16x16x32_bf16 v[76:79], v[164:167], v[224:227], v[76:79]
	v_mfma_f32_16x16x32_bf16 v[72:75], v[172:175], v[224:227], v[72:75]
	v_mfma_f32_16x16x32_bf16 v[124:127], v[168:171], v[200:203], v[124:127]
	v_mfma_f32_16x16x32_bf16 v[120:123], v[176:179], v[200:203], v[120:123]
	v_mfma_f32_16x16x32_bf16 v[108:111], v[168:171], v[208:211], v[108:111]
	v_mfma_f32_16x16x32_bf16 v[104:107], v[176:179], v[208:211], v[104:107]
	v_mfma_f32_16x16x32_bf16 v[92:95], v[168:171], v[220:223], v[92:95]
	v_mfma_f32_16x16x32_bf16 v[88:91], v[176:179], v[220:223], v[88:91]
	v_mfma_f32_16x16x32_bf16 v[76:79], v[168:171], v[228:231], v[76:79]
	v_mfma_f32_16x16x32_bf16 v[72:75], v[176:179], v[228:231], v[72:75]
	v_mfma_f32_16x16x32_bf16 v[116:119], v[180:183], v[196:199], v[116:119]
	v_mfma_f32_16x16x32_bf16 v[112:115], v[188:191], v[196:199], v[112:115]
	v_mfma_f32_16x16x32_bf16 v[100:103], v[180:183], v[204:207], v[100:103]
	v_mfma_f32_16x16x32_bf16 v[96:99], v[188:191], v[204:207], v[96:99]
	v_mfma_f32_16x16x32_bf16 v[84:87], v[180:183], v[216:219], v[84:87]
	v_mfma_f32_16x16x32_bf16 v[80:83], v[188:191], v[216:219], v[80:83]
	v_mfma_f32_16x16x32_bf16 v[68:71], v[180:183], v[224:227], v[68:71]
	v_mfma_f32_16x16x32_bf16 v[64:67], v[188:191], v[224:227], v[64:67]
	v_mfma_f32_16x16x32_bf16 v[116:119], v[184:187], v[200:203], v[116:119]
	v_mfma_f32_16x16x32_bf16 v[112:115], v[192:195], v[200:203], v[112:115]
	v_mfma_f32_16x16x32_bf16 v[100:103], v[184:187], v[208:211], v[100:103]
	v_mfma_f32_16x16x32_bf16 v[96:99], v[192:195], v[208:211], v[96:99]
	v_mfma_f32_16x16x32_bf16 v[84:87], v[184:187], v[220:223], v[84:87]
	v_mfma_f32_16x16x32_bf16 v[80:83], v[192:195], v[220:223], v[80:83]
	v_mfma_f32_16x16x32_bf16 v[68:71], v[184:187], v[228:231], v[68:71]
	v_mfma_f32_16x16x32_bf16 v[64:67], v[192:195], v[228:231], v[64:67]
	s_setprio 0
	s_barrier
	s_mov_b32 m0, s53
	v_lshl_add_u64 v[232:233], v[214:215], 0, v[138:139]
	ds_read_b128 v[196:199], v163 offset:16384
	ds_read_b128 v[200:203], v163 offset:17408
	ds_read_b128 v[204:207], v163 offset:18432
	ds_read_b128 v[208:211], v163 offset:19456
	ds_read_b128 v[216:219], v163 offset:20480
	ds_read_b128 v[220:223], v163 offset:21504
	ds_read_b128 v[224:227], v163 offset:22528
	ds_read_b128 v[228:231], v163 offset:23552
	global_load_lds_dwordx4 v[232:233], off
	v_lshl_add_u64 v[234:235], v[214:215], 0, v[134:135]
	s_mov_b32 m0, s54
	v_lshl_add_u64 v[214:215], v[214:215], 0, s[14:15]
	global_load_lds_dwordx4 v[234:235], off
	v_lshl_add_u64 v[236:237], v[214:215], 0, v[138:139]
	s_mov_b32 m0, s55
	v_lshl_add_u64 v[214:215], v[214:215], 0, v[134:135]
	global_load_lds_dwordx4 v[236:237], off
	s_mov_b32 m0, s56
	v_lshl_add_u64 v[238:239], v[212:213], 0, v[140:141]
	global_load_lds_dwordx4 v[214:215], off
	s_mov_b32 m0, s37
	v_lshl_add_u64 v[240:241], v[212:213], 0, v[136:137]
	global_load_lds_dwordx4 v[238:239], off
	s_mov_b32 m0, s41
	s_nop 0
	global_load_lds_dwordx4 v[240:241], off
	s_waitcnt vmcnt(8)
	s_waitcnt lgkmcnt(0)
	s_setprio 1
	s_barrier
; #define PG8_STAGE(bufoff, gbase, voff) do { _Pragma("unroll") for (int _i = 0; _i < 2; ++_i) \
;         __builtin_amdgcn_global_load_lds((const unsigned*)((const char*)(gbase) + (voff)[_i]), (PG8_LAS unsigned*)(lds + (bufoff) + ldsw + _i * 8192), 16, 0, 0); } while (0)
; #define PG8_LDA(dst, b, h) do { _Pragma("unroll") for (int m = 0; m < 4; ++m) _Pragma("unroll") for (int k = 0; k < 2; ++k) dst[m][k] = *(const PG8_LAS bf16x8*)(lds + PG8_SA(b, h) + aoff + m * 2048 + k * 1024); } while (0)
; #define PG8_LDB(dst, b, h) do { _Pragma("unroll") for (int n = 0; n < 2; ++n) _Pragma("unroll") for (int k = 0; k < 2; ++k) dst[n][k] = *(const PG8_LAS bf16x8*)(lds + PG8_SB(b, h) + boff + n * 2048 + k * 1024); } while (0)
; #define PG8_MMA(ai, bj, At, Bt) do { __builtin_amdgcn_s_setprio(1); _Pragma("unroll") for (int m = 0; m < 4; ++m) _Pragma("unroll") for (int n = 0; n < 2; ++n) _Pragma("unroll") for (int k = 0; k < 2; ++k) \
;         acc[ai][bj][m][n] = __builtin_amdgcn_mfma_f32_16x16x32_bf16(Bt[n][k], At[m][k], acc[ai][bj][m][n], 0, 0, 0); __builtin_amdgcn_s_setprio(0); } while (0)
; #define PG8_WAIT_V(n) asm volatile("s_waitcnt vmcnt(" #n ")" ::: "memory")
; #define PG8_WAIT_L(n) asm volatile("s_waitcnt lgkmcnt(" #n ")" ::: "memory")
; #define PG8_BAR __builtin_amdgcn_s_barrier()
; #define PG8_SCHED __builtin_amdgcn_sched_barrier(0)
; template <class Epi, class Sched, bool ALIGN_EPI = false, bool SP2 = false>
; __device__ __forceinline__ void gemm_phase(PG8_LAS unsigned char* lds, const Gemm g, const Sched& S, const Epi& E) {
;     ...
;             PG8_WAIT_V(8); PG8_WAIT_L(0); PG8_BAR; PG8_MMA(1, 0, At, B0); PG8_MMA(1, 1, At, B1); PG8_BAR; PG8_SCHED;
;             PG8_LDB(B0, 1, 0); PG8_LDB(B1, 1, 1); PG8_SCHED; PG8_LDA(At, 1, 0); PG8_STAGE(PG8_SA(0, 1), a2 + hstep, voffA);
;             PG8_WAIT_V(8); PG8_WAIT_L(0); PG8_BAR; PG8_MMA(0, 0, At, B0); PG8_MMA(0, 1, At, B1); PG8_BAR; PG8_SCHED;
	v_mfma_f32_16x16x32_bf16 v[60:63], v[164:167], v[196:199], v[60:63]
	v_mfma_f32_16x16x32_bf16 v[56:59], v[172:175], v[196:199], v[56:59]
	v_mfma_f32_16x16x32_bf16 v[44:47], v[164:167], v[204:207], v[44:47]
	v_mfma_f32_16x16x32_bf16 v[40:43], v[172:175], v[204:207], v[40:43]
	v_mfma_f32_16x16x32_bf16 v[28:31], v[164:167], v[216:219], v[28:31]
	v_mfma_f32_16x16x32_bf16 v[24:27], v[172:175], v[216:219], v[24:27]
	v_mfma_f32_16x16x32_bf16 v[12:15], v[164:167], v[224:227], v[12:15]
	v_mfma_f32_16x16x32_bf16 v[8:11], v[172:175], v[224:227], v[8:11]
	v_mfma_f32_16x16x32_bf16 v[60:63], v[168:171], v[200:203], v[60:63]
	v_mfma_f32_16x16x32_bf16 v[56:59], v[176:179], v[200:203], v[56:59]
	v_mfma_f32_16x16x32_bf16 v[44:47], v[168:171], v[208:211], v[44:47]
	v_mfma_f32_16x16x32_bf16 v[40:43], v[176:179], v[208:211], v[40:43]
	v_mfma_f32_16x16x32_bf16 v[28:31], v[168:171], v[220:223], v[28:31]
	v_mfma_f32_16x16x32_bf16 v[24:27], v[176:179], v[220:223], v[24:27]
	v_mfma_f32_16x16x32_bf16 v[12:15], v[168:171], v[228:231], v[12:15]
	v_mfma_f32_16x16x32_bf16 v[8:11], v[176:179], v[228:231], v[8:11]
	v_mfma_f32_16x16x32_bf16 v[52:55], v[180:183], v[196:199], v[52:55]
	v_mfma_f32_16x16x32_bf16 v[48:51], v[188:191], v[196:199], v[48:51]
	v_mfma_f32_16x16x32_bf16 v[36:39], v[180:183], v[204:207], v[36:39]
	v_mfma_f32_16x16x32_bf16 v[32:35], v[188:191], v[204:207], v[32:35]
	v_mfma_f32_16x16x32_bf16 v[20:23], v[180:183], v[216:219], v[20:23]
	v_mfma_f32_16x16x32_bf16 v[16:19], v[188:191], v[216:219], v[16:19]
	v_mfma_f32_16x16x32_bf16 v[4:7], v[180:183], v[224:227], v[4:7]
	v_mfma_f32_16x16x32_bf16 v[0:3], v[188:191], v[224:227], v[0:3]
	v_mfma_f32_16x16x32_bf16 v[52:55], v[184:187], v[200:203], v[52:55]
	v_mfma_f32_16x16x32_bf16 v[48:51], v[192:195], v[200:203], v[48:51]
	v_mfma_f32_16x16x32_bf16 v[36:39], v[184:187], v[208:211], v[36:39]
	v_mfma_f32_16x16x32_bf16 v[32:35], v[192:195], v[208:211], v[32:35]
	v_mfma_f32_16x16x32_bf16 v[20:23], v[184:187], v[220:223], v[20:23]
	v_mfma_f32_16x16x32_bf16 v[16:19], v[192:195], v[220:223], v[16:19]
	v_mfma_f32_16x16x32_bf16 v[4:7], v[184:187], v[228:231], v[4:7]
	v_mfma_f32_16x16x32_bf16 v[0:3], v[192:195], v[228:231], v[0:3]
	s_setprio 0
	s_barrier
	v_add_u32_e32 v176, s57, v161
	v_add_u32_e32 v192, s58, v161
	ds_read_b128 v[164:167], v176
	ds_read_b128 v[168:171], v176 offset:1024
	ds_read_b128 v[172:175], v176 offset:2048
	ds_read_b128 v[176:179], v176 offset:3072
	ds_read_b128 v[180:183], v192
	ds_read_b128 v[184:187], v192 offset:1024
	ds_read_b128 v[188:191], v192 offset:2048
	ds_read_b128 v[192:195], v192 offset:3072
	v_lshl_add_u64 v[212:213], v[212:213], 0, s[14:15]
	s_mov_b32 m0, s44
	v_lshl_add_u64 v[242:243], v[212:213], 0, v[140:141]
	ds_read_b128 v[196:199], v163 offset:32768
	ds_read_b128 v[200:203], v163 offset:33792
	ds_read_b128 v[204:207], v163 offset:34816
	ds_read_b128 v[208:211], v163 offset:35840
	ds_read_b128 v[216:219], v163 offset:36864
	ds_read_b128 v[220:223], v163 offset:37888
	ds_read_b128 v[224:227], v163 offset:38912
	ds_read_b128 v[228:231], v163 offset:39936
	global_load_lds_dwordx4 v[242:243], off
	v_lshl_add_u64 v[212:213], v[212:213], 0, v[136:137]
	s_mov_b32 m0, s45
	s_nop 0
	global_load_lds_dwordx4 v[212:213], off
	s_waitcnt vmcnt(8)
	s_waitcnt lgkmcnt(0)
	s_setprio 1
	s_barrier
	v_mfma_f32_16x16x32_bf16 v[124:127], v[164:167], v[196:199], v[124:127]
	v_mfma_f32_16x16x32_bf16 v[120:123], v[172:175], v[196:199], v[120:123]
	v_mfma_f32_16x16x32_bf16 v[108:111], v[164:167], v[204:207], v[108:111]
	v_mfma_f32_16x16x32_bf16 v[104:107], v[172:175], v[204:207], v[104:107]
	v_mfma_f32_16x16x32_bf16 v[92:95], v[164:167], v[216:219], v[92:95]
	v_mfma_f32_16x16x32_bf16 v[88:91], v[172:175], v[216:219], v[88:91]
	v_mfma_f32_16x16x32_bf16 v[76:79], v[164:167], v[224:227], v[76:79]
	v_mfma_f32_16x16x32_bf16 v[72:75], v[172:175], v[224:227], v[72:75]
	v_mfma_f32_16x16x32_bf16 v[124:127], v[168:171], v[200:203], v[124:127]
	v_mfma_f32_16x16x32_bf16 v[120:123], v[176:179], v[200:203], v[120:123]
	v_mfma_f32_16x16x32_bf16 v[108:111], v[168:171], v[208:211], v[108:111]
	v_mfma_f32_16x16x32_bf16 v[104:107], v[176:179], v[208:211], v[104:107]
	v_mfma_f32_16x16x32_bf16 v[92:95], v[168:171], v[220:223], v[92:95]
	v_mfma_f32_16x16x32_bf16 v[88:91], v[176:179], v[220:223], v[88:91]
	v_mfma_f32_16x16x32_bf16 v[76:79], v[168:171], v[228:231], v[76:79]
	v_mfma_f32_16x16x32_bf16 v[72:75], v[176:179], v[228:231], v[72:75]
	v_mfma_f32_16x16x32_bf16 v[116:119], v[180:183], v[196:199], v[116:119]
	v_mfma_f32_16x16x32_bf16 v[112:115], v[188:191], v[196:199], v[112:115]
	v_mfma_f32_16x16x32_bf16 v[100:103], v[180:183], v[204:207], v[100:103]
	v_mfma_f32_16x16x32_bf16 v[96:99], v[188:191], v[204:207], v[96:99]
	v_mfma_f32_16x16x32_bf16 v[84:87], v[180:183], v[216:219], v[84:87]
	v_mfma_f32_16x16x32_bf16 v[80:83], v[188:191], v[216:219], v[80:83]
	v_mfma_f32_16x16x32_bf16 v[68:71], v[180:183], v[224:227], v[68:71]
	v_mfma_f32_16x16x32_bf16 v[64:67], v[188:191], v[224:227], v[64:67]
	v_mfma_f32_16x16x32_bf16 v[116:119], v[184:187], v[200:203], v[116:119]
	v_mfma_f32_16x16x32_bf16 v[112:115], v[192:195], v[200:203], v[112:115]
	v_mfma_f32_16x16x32_bf16 v[100:103], v[184:187], v[208:211], v[100:103]
	v_mfma_f32_16x16x32_bf16 v[96:99], v[192:195], v[208:211], v[96:99]
	v_mfma_f32_16x16x32_bf16 v[84:87], v[184:187], v[220:223], v[84:87]
	v_mfma_f32_16x16x32_bf16 v[80:83], v[192:195], v[220:223], v[80:83]
	v_mfma_f32_16x16x32_bf16 v[68:71], v[184:187], v[228:231], v[68:71]
	v_mfma_f32_16x16x32_bf16 v[64:67], v[192:195], v[228:231], v[64:67]
	s_setprio 0
	s_barrier
; #define PG8_STAGE(bufoff, gbase, voff) do { _Pragma("unroll") for (int _i = 0; _i < 2; ++_i) \
;         __builtin_amdgcn_global_load_lds((const unsigned*)((const char*)(gbase) + (voff)[_i]), (PG8_LAS unsigned*)(lds + (bufoff) + ldsw + _i * 8192), 16, 0, 0); } while (0)
; #define PG8_LDA(dst, b, h) do { _Pragma("unroll") for (int m = 0; m < 4; ++m) _Pragma("unroll") for (int k = 0; k < 2; ++k) dst[m][k] = *(const PG8_LAS bf16x8*)(lds + PG8_SA(b, h) + aoff + m * 2048 + k * 1024); } while (0)
; #define PG8_MMA(ai, bj, At, Bt) do { __builtin_amdgcn_s_setprio(1); _Pragma("unroll") for (int m = 0; m < 4; ++m) _Pragma("unroll") for (int n = 0; n < 2; ++n) _Pragma("unroll") for (int k = 0; k < 2; ++k) \
;         acc[ai][bj][m][n] = __builtin_amdgcn_mfma_f32_16x16x32_bf16(Bt[n][k], At[m][k], acc[ai][bj][m][n], 0, 0, 0); __builtin_amdgcn_s_setprio(0); } while (0)
; #define PG8_WAIT_V(n) asm volatile("s_waitcnt vmcnt(" #n ")" ::: "memory")
; #define PG8_WAIT_L(n) asm volatile("s_waitcnt lgkmcnt(" #n ")" ::: "memory")
; #define PG8_BAR __builtin_amdgcn_s_barrier()
; #define PG8_SCHED __builtin_amdgcn_sched_barrier(0)
; template <class Epi, class Sched, bool ALIGN_EPI = false, bool SP2 = false>
; __device__ __forceinline__ void gemm_phase(PG8_LAS unsigned char* lds, const Gemm g, const Sched& S, const Epi& E) {
;     ...
;             PG8_LDA(At, 1, 1); PG8_STAGE(PG8_SB(1, 0), b3, voffB); PG8_STAGE(PG8_SB(1, 1), b3 + hstep, voffB); PG8_STAGE(PG8_SA(1, 0), a3, voffA);
;             PG8_WAIT_V(8); PG8_WAIT_L(0); PG8_BAR; PG8_MMA(1, 0, At, B0); PG8_MMA(1, 1, At, B1); PG8_BAR; PG8_SCHED;
	s_mov_b32 m0, s59
	v_lshl_add_u64 v[212:213], v[232:233], 0, s[24:25]
	ds_read_b128 v[196:199], v163 offset:49152
	ds_read_b128 v[200:203], v163 offset:50176
	ds_read_b128 v[204:207], v163 offset:51200
	ds_read_b128 v[208:211], v163 offset:52224
	ds_read_b128 v[216:219], v163 offset:53248
	ds_read_b128 v[220:223], v163 offset:54272
	ds_read_b128 v[224:227], v163 offset:55296
	ds_read_b128 v[228:231], v163 offset:56320
	global_load_lds_dwordx4 v[212:213], off
	v_lshl_add_u64 v[212:213], v[234:235], 0, s[24:25]
	s_mov_b32 m0, s60
	s_nop 0
	global_load_lds_dwordx4 v[212:213], off
	v_lshl_add_u64 v[212:213], v[236:237], 0, s[24:25]
	s_mov_b32 m0, s61
	s_nop 0
	global_load_lds_dwordx4 v[212:213], off
	v_lshl_add_u64 v[212:213], v[214:215], 0, s[24:25]
	s_mov_b32 m0, s62
	s_nop 0
	global_load_lds_dwordx4 v[212:213], off
	v_lshl_add_u64 v[212:213], v[238:239], 0, s[24:25]
	s_mov_b32 m0, s46
	s_nop 0
	global_load_lds_dwordx4 v[212:213], off
	v_lshl_add_u64 v[212:213], v[240:241], 0, s[24:25]
	s_mov_b32 m0, s47
	s_nop 0
	global_load_lds_dwordx4 v[212:213], off
	s_waitcnt vmcnt(8)
	s_waitcnt lgkmcnt(0)
	s_setprio 1
	s_barrier
	v_mfma_f32_16x16x32_bf16 v[60:63], v[164:167], v[196:199], v[60:63]
	v_mfma_f32_16x16x32_bf16 v[56:59], v[172:175], v[196:199], v[56:59]
	v_mfma_f32_16x16x32_bf16 v[44:47], v[164:167], v[204:207], v[44:47]
	v_mfma_f32_16x16x32_bf16 v[40:43], v[172:175], v[204:207], v[40:43]
	v_mfma_f32_16x16x32_bf16 v[28:31], v[164:167], v[216:219], v[28:31]
	v_mfma_f32_16x16x32_bf16 v[24:27], v[172:175], v[216:219], v[24:27]
	v_mfma_f32_16x16x32_bf16 v[12:15], v[164:167], v[224:227], v[12:15]
	v_mfma_f32_16x16x32_bf16 v[8:11], v[172:175], v[224:227], v[8:11]
	v_mfma_f32_16x16x32_bf16 v[60:63], v[168:171], v[200:203], v[60:63]
	v_mfma_f32_16x16x32_bf16 v[56:59], v[176:179], v[200:203], v[56:59]
	v_mfma_f32_16x16x32_bf16 v[44:47], v[168:171], v[208:211], v[44:47]
	v_mfma_f32_16x16x32_bf16 v[40:43], v[176:179], v[208:211], v[40:43]
	v_mfma_f32_16x16x32_bf16 v[28:31], v[168:171], v[220:223], v[28:31]
	v_mfma_f32_16x16x32_bf16 v[24:27], v[176:179], v[220:223], v[24:27]
	v_mfma_f32_16x16x32_bf16 v[12:15], v[168:171], v[228:231], v[12:15]
	v_mfma_f32_16x16x32_bf16 v[8:11], v[176:179], v[228:231], v[8:11]
	v_mfma_f32_16x16x32_bf16 v[52:55], v[180:183], v[196:199], v[52:55]
	v_mfma_f32_16x16x32_bf16 v[48:51], v[188:191], v[196:199], v[48:51]
	v_mfma_f32_16x16x32_bf16 v[36:39], v[180:183], v[204:207], v[36:39]
	v_mfma_f32_16x16x32_bf16 v[32:35], v[188:191], v[204:207], v[32:35]
	v_mfma_f32_16x16x32_bf16 v[20:23], v[180:183], v[216:219], v[20:23]
	v_mfma_f32_16x16x32_bf16 v[16:19], v[188:191], v[216:219], v[16:19]
	v_mfma_f32_16x16x32_bf16 v[4:7], v[180:183], v[224:227], v[4:7]
	v_mfma_f32_16x16x32_bf16 v[0:3], v[188:191], v[224:227], v[0:3]
	v_mfma_f32_16x16x32_bf16 v[52:55], v[184:187], v[200:203], v[52:55]
	v_mfma_f32_16x16x32_bf16 v[48:51], v[192:195], v[200:203], v[48:51]
	v_mfma_f32_16x16x32_bf16 v[36:39], v[184:187], v[208:211], v[36:39]
	v_mfma_f32_16x16x32_bf16 v[32:35], v[192:195], v[208:211], v[32:35]
	v_mfma_f32_16x16x32_bf16 v[20:23], v[184:187], v[220:223], v[20:23]
	v_mfma_f32_16x16x32_bf16 v[16:19], v[192:195], v[220:223], v[16:19]
	v_mfma_f32_16x16x32_bf16 v[4:7], v[184:187], v[228:231], v[4:7]
	v_mfma_f32_16x16x32_bf16 v[0:3], v[192:195], v[228:231], v[0:3]
	s_setprio 0
	s_barrier
	v_lshl_add_u64 v[154:155], v[154:155], 0, s[28:29]
	s_cmp_ge_i32 s10, s48
	v_lshl_add_u64 v[158:159], v[158:159], 0, s[28:29]
	s_cbranch_scc0 .LBB0_1924

; #define PG8_STAGE(bufoff, gbase, voff) do { _Pragma("unroll") for (int _i = 0; _i < 2; ++_i) \
;         __builtin_amdgcn_global_load_lds((const unsigned*)((const char*)(gbase) + (voff)[_i]), (PG8_LAS unsigned*)(lds + (bufoff) + ldsw + _i * 8192), 16, 0, 0); } while (0)
; #define PG8_LDA(dst, b, h) do { _Pragma("unroll") for (int m = 0; m < 4; ++m) _Pragma("unroll") for (int k = 0; k < 2; ++k) dst[m][k] = *(const PG8_LAS bf16x8*)(lds + PG8_SA(b, h) + aoff + m * 2048 + k * 1024); } while (0)
; #define PG8_LDB(dst, b, h) do { _Pragma("unroll") for (int n = 0; n < 2; ++n) _Pragma("unroll") for (int k = 0; k < 2; ++k) dst[n][k] = *(const PG8_LAS bf16x8*)(lds + PG8_SB(b, h) + boff + n * 2048 + k * 1024); } while (0)
; #define PG8_MMA(ai, bj, At, Bt) do { __builtin_amdgcn_s_setprio(1); _Pragma("unroll") for (int m = 0; m < 4; ++m) _Pragma("unroll") for (int n = 0; n < 2; ++n) _Pragma("unroll") for (int k = 0; k < 2; ++k) \
;         acc[ai][bj][m][n] = __builtin_amdgcn_mfma_f32_16x16x32_bf16(Bt[n][k], At[m][k], acc[ai][bj][m][n], 0, 0, 0); __builtin_amdgcn_s_setprio(0); } while (0)
; #define PG8_WAIT_V(n) asm volatile("s_waitcnt vmcnt(" #n ")" ::: "memory")
; #define PG8_WAIT_L(n) asm volatile("s_waitcnt lgkmcnt(" #n ")" ::: "memory")
; #define PG8_BAR __builtin_amdgcn_s_barrier()
; #define PG8_SCHED __builtin_amdgcn_sched_barrier(0)
; template <class Epi, class Sched, bool ALIGN_EPI = false, bool SP2 = false>
; __device__ __forceinline__ void gemm_phase(PG8_LAS unsigned char* lds, const Gemm g, const Sched& S, const Epi& E) {
;     ...
;             const bool last = (t == nt - 2);
;             const char* a1 = cA + (size_t)(t + 1) * kstep;
;             const char* a2 = last ? nA : cA + (size_t)(t + 2) * kstep; const char* b2 = last ? nB : cB + (size_t)(t + 2) * kstep;
;             const char* a3 = a2 + kstep; const char* b3 = b2 + kstep;
;             if (last && has_next) S.a_ready(nxt);
;             if constexpr (SP2) {
;             PG8_LDB(B0, 0, 0); PG8_LDB(B1, 0, 1); PG8_SCHED; PG8_LDA(At, 0, 0); PG8_STAGE(PG8_SA(1, 1), a1 + hstep, voffA);
;             PG8_WAIT_V(8); PG8_WAIT_L(0); PG8_BAR; PG8_MMA(0, 0, At, B0); PG8_MMA(0, 1, At, B1); PG8_BAR; PG8_SCHED;
;             PG8_LDA(At, 0, 1); PG8_STAGE(PG8_SB(0, 0), b2, voffB); PG8_STAGE(PG8_SB(0, 1), b2 + hstep, voffB); PG8_STAGE(PG8_SA(0, 0), a2, voffA);
.LBB0_1947:
	v_add_u32_e32 v178, s53, v216
	v_add_u32_e32 v194, s54, v216
	ds_read_b128 v[138:141], v178
	ds_read_b128 v[142:145], v178 offset:1024
	ds_read_b128 v[146:149], v178 offset:2048
	ds_read_b128 v[178:181], v178 offset:3072
	ds_read_b128 v[182:185], v194
	ds_read_b128 v[186:189], v194 offset:1024
	ds_read_b128 v[190:193], v194 offset:2048
	ds_read_b128 v[194:197], v194 offset:3072
	s_cmp_eq_u32 s47, s10
	v_lshl_add_u64 v[198:199], v[136:137], 0, s[20:21]
	s_cselect_b64 vcc, -1, 0
	s_add_i32 s10, s10, 2
	v_cndmask_b32_e32 v215, v199, v175, vcc
	v_cndmask_b32_e32 v214, v198, v174, vcc
	v_cndmask_b32_e32 v237, v135, v177, vcc
	v_cndmask_b32_e32 v236, v134, v176, vcc
	v_lshl_add_u64 v[238:239], v[136:137], 0, v[168:169]
	s_add_i32 m0, s34, 0xc000
	ds_read_b128 v[198:201], v218
	ds_read_b128 v[202:205], v218 offset:1024
	ds_read_b128 v[206:209], v218 offset:2048
	ds_read_b128 v[210:213], v218 offset:3072
	ds_read_b128 v[220:223], v218 offset:4096
	ds_read_b128 v[224:227], v218 offset:5120
	ds_read_b128 v[228:231], v218 offset:6144
	ds_read_b128 v[232:235], v218 offset:7168
	global_load_lds_dwordx4 v[238:239], off
	v_lshl_add_u64 v[238:239], v[136:137], 0, v[166:167]
	s_add_i32 m0, s34, 0xe000
	s_nop 0
	global_load_lds_dwordx4 v[238:239], off
	s_waitcnt vmcnt(8)
	s_waitcnt lgkmcnt(0)
	s_setprio 1
	s_barrier
	v_mfma_f32_16x16x32_bf16 v[130:133], v[138:141], v[198:201], v[130:133]
	v_mfma_f32_16x16x32_bf16 v[126:129], v[146:149], v[198:201], v[126:129]
	v_mfma_f32_16x16x32_bf16 v[114:117], v[138:141], v[206:209], v[114:117]
	v_mfma_f32_16x16x32_bf16 v[110:113], v[146:149], v[206:209], v[110:113]
	v_mfma_f32_16x16x32_bf16 v[98:101], v[138:141], v[220:223], v[98:101]
	v_mfma_f32_16x16x32_bf16 v[94:97], v[146:149], v[220:223], v[94:97]
	v_mfma_f32_16x16x32_bf16 v[82:85], v[138:141], v[228:231], v[82:85]
	v_mfma_f32_16x16x32_bf16 v[78:81], v[146:149], v[228:231], v[78:81]
	v_mfma_f32_16x16x32_bf16 v[130:133], v[142:145], v[202:205], v[130:133]
	v_mfma_f32_16x16x32_bf16 v[126:129], v[178:181], v[202:205], v[126:129]
	v_mfma_f32_16x16x32_bf16 v[114:117], v[142:145], v[210:213], v[114:117]
	v_mfma_f32_16x16x32_bf16 v[110:113], v[178:181], v[210:213], v[110:113]
	v_mfma_f32_16x16x32_bf16 v[98:101], v[142:145], v[224:227], v[98:101]
	v_mfma_f32_16x16x32_bf16 v[94:97], v[178:181], v[224:227], v[94:97]
	v_mfma_f32_16x16x32_bf16 v[82:85], v[142:145], v[232:235], v[82:85]
	v_mfma_f32_16x16x32_bf16 v[78:81], v[178:181], v[232:235], v[78:81]
	v_mfma_f32_16x16x32_bf16 v[122:125], v[182:185], v[198:201], v[122:125]
	v_mfma_f32_16x16x32_bf16 v[118:121], v[190:193], v[198:201], v[118:121]
	v_mfma_f32_16x16x32_bf16 v[106:109], v[182:185], v[206:209], v[106:109]
	v_mfma_f32_16x16x32_bf16 v[102:105], v[190:193], v[206:209], v[102:105]
	v_mfma_f32_16x16x32_bf16 v[90:93], v[182:185], v[220:223], v[90:93]
	v_mfma_f32_16x16x32_bf16 v[86:89], v[190:193], v[220:223], v[86:89]
	v_mfma_f32_16x16x32_bf16 v[74:77], v[182:185], v[228:231], v[74:77]
	v_mfma_f32_16x16x32_bf16 v[70:73], v[190:193], v[228:231], v[70:73]
	v_mfma_f32_16x16x32_bf16 v[122:125], v[186:189], v[202:205], v[122:125]
	v_mfma_f32_16x16x32_bf16 v[118:121], v[194:197], v[202:205], v[118:121]
	v_mfma_f32_16x16x32_bf16 v[106:109], v[186:189], v[210:213], v[106:109]
	v_mfma_f32_16x16x32_bf16 v[102:105], v[194:197], v[210:213], v[102:105]
	v_mfma_f32_16x16x32_bf16 v[90:93], v[186:189], v[224:227], v[90:93]
	v_mfma_f32_16x16x32_bf16 v[86:89], v[194:197], v[224:227], v[86:89]
	v_mfma_f32_16x16x32_bf16 v[74:77], v[186:189], v[232:235], v[74:77]
	v_mfma_f32_16x16x32_bf16 v[70:73], v[194:197], v[232:235], v[70:73]
	s_setprio 0
	s_barrier
	s_add_i32 s11, s53, s29
	v_lshl_add_u64 v[238:239], v[236:237], 0, v[158:159]
	s_mov_b32 m0, s11
	ds_read_b128 v[198:201], v218 offset:16384
	ds_read_b128 v[202:205], v218 offset:17408
	ds_read_b128 v[206:209], v218 offset:18432
	ds_read_b128 v[210:213], v218 offset:19456
	ds_read_b128 v[220:223], v218 offset:20480
	ds_read_b128 v[224:227], v218 offset:21504
	ds_read_b128 v[228:231], v218 offset:22528
	ds_read_b128 v[232:235], v218 offset:23552
	global_load_lds_dwordx4 v[238:239], off
	v_lshl_add_u64 v[240:241], v[236:237], 0, v[162:163]
	s_add_i32 m0, s11, 0x2000
	v_lshl_add_u64 v[236:237], v[236:237], 0, s[12:13]
	s_add_i32 s11, s54, s29
	global_load_lds_dwordx4 v[240:241], off
	v_lshl_add_u64 v[242:243], v[236:237], 0, v[158:159]
	s_mov_b32 m0, s11
	v_lshl_add_u64 v[236:237], v[236:237], 0, v[162:163]
	global_load_lds_dwordx4 v[242:243], off
	s_add_i32 m0, s11, 0x2000
	v_lshl_add_u64 v[244:245], v[214:215], 0, v[154:155]
	global_load_lds_dwordx4 v[236:237], off
	s_mov_b32 m0, s34
	v_lshl_add_u64 v[246:247], v[214:215], 0, v[160:161]
	global_load_lds_dwordx4 v[244:245], off
	s_mov_b32 m0, s35
	s_nop 0
	global_load_lds_dwordx4 v[246:247], off
	s_waitcnt vmcnt(8)
	s_waitcnt lgkmcnt(0)
	s_setprio 1
	s_barrier
; #define PG8_STAGE(bufoff, gbase, voff) do { _Pragma("unroll") for (int _i = 0; _i < 2; ++_i) \
;         __builtin_amdgcn_global_load_lds((const unsigned*)((const char*)(gbase) + (voff)[_i]), (PG8_LAS unsigned*)(lds + (bufoff) + ldsw + _i * 8192), 16, 0, 0); } while (0)
; #define PG8_LDA(dst, b, h) do { _Pragma("unroll") for (int m = 0; m < 4; ++m) _Pragma("unroll") for (int k = 0; k < 2; ++k) dst[m][k] = *(const PG8_LAS bf16x8*)(lds + PG8_SA(b, h) + aoff + m * 2048 + k * 1024); } while (0)
; #define PG8_LDB(dst, b, h) do { _Pragma("unroll") for (int n = 0; n < 2; ++n) _Pragma("unroll") for (int k = 0; k < 2; ++k) dst[n][k] = *(const PG8_LAS bf16x8*)(lds + PG8_SB(b, h) + boff + n * 2048 + k * 1024); } while (0)
; #define PG8_MMA(ai, bj, At, Bt) do { __builtin_amdgcn_s_setprio(1); _Pragma("unroll") for (int m = 0; m < 4; ++m) _Pragma("unroll") for (int n = 0; n < 2; ++n) _Pragma("unroll") for (int k = 0; k < 2; ++k) \
;         acc[ai][bj][m][n] = __builtin_amdgcn_mfma_f32_16x16x32_bf16(Bt[n][k], At[m][k], acc[ai][bj][m][n], 0, 0, 0); __builtin_amdgcn_s_setprio(0); } while (0)
; #define PG8_WAIT_V(n) asm volatile("s_waitcnt vmcnt(" #n ")" ::: "memory")
; #define PG8_WAIT_L(n) asm volatile("s_waitcnt lgkmcnt(" #n ")" ::: "memory")
; #define PG8_BAR __builtin_amdgcn_s_barrier()
; #define PG8_SCHED __builtin_amdgcn_sched_barrier(0)
; template <class Epi, class Sched, bool ALIGN_EPI = false, bool SP2 = false>
; __device__ __forceinline__ void gemm_phase(PG8_LAS unsigned char* lds, const Gemm g, const Sched& S, const Epi& E) {
;     ...
;             PG8_WAIT_V(8); PG8_WAIT_L(0); PG8_BAR; PG8_MMA(1, 0, At, B0); PG8_MMA(1, 1, At, B1); PG8_BAR; PG8_SCHED;
;             PG8_LDB(B0, 1, 0); PG8_LDB(B1, 1, 1); PG8_SCHED; PG8_LDA(At, 1, 0); PG8_STAGE(PG8_SA(0, 1), a2 + hstep, voffA);
;             PG8_WAIT_V(8); PG8_WAIT_L(0); PG8_BAR; PG8_MMA(0, 0, At, B0); PG8_MMA(0, 1, At, B1); PG8_BAR; PG8_SCHED;
	v_mfma_f32_16x16x32_bf16 v[66:69], v[138:141], v[198:201], v[66:69]
	v_mfma_f32_16x16x32_bf16 v[62:65], v[146:149], v[198:201], v[62:65]
	v_mfma_f32_16x16x32_bf16 v[50:53], v[138:141], v[206:209], v[50:53]
	v_mfma_f32_16x16x32_bf16 v[46:49], v[146:149], v[206:209], v[46:49]
	v_mfma_f32_16x16x32_bf16 v[34:37], v[138:141], v[220:223], v[34:37]
	v_mfma_f32_16x16x32_bf16 v[30:33], v[146:149], v[220:223], v[30:33]
	v_mfma_f32_16x16x32_bf16 v[18:21], v[138:141], v[228:231], v[18:21]
	v_mfma_f32_16x16x32_bf16 v[14:17], v[146:149], v[228:231], v[14:17]
	v_mfma_f32_16x16x32_bf16 v[66:69], v[142:145], v[202:205], v[66:69]
	v_mfma_f32_16x16x32_bf16 v[62:65], v[178:181], v[202:205], v[62:65]
	v_mfma_f32_16x16x32_bf16 v[50:53], v[142:145], v[210:213], v[50:53]
	v_mfma_f32_16x16x32_bf16 v[46:49], v[178:181], v[210:213], v[46:49]
	v_mfma_f32_16x16x32_bf16 v[34:37], v[142:145], v[224:227], v[34:37]
	v_mfma_f32_16x16x32_bf16 v[30:33], v[178:181], v[224:227], v[30:33]
	v_mfma_f32_16x16x32_bf16 v[18:21], v[142:145], v[232:235], v[18:21]
	v_mfma_f32_16x16x32_bf16 v[14:17], v[178:181], v[232:235], v[14:17]
	v_mfma_f32_16x16x32_bf16 v[58:61], v[182:185], v[198:201], v[58:61]
	v_mfma_f32_16x16x32_bf16 v[54:57], v[190:193], v[198:201], v[54:57]
	v_mfma_f32_16x16x32_bf16 v[42:45], v[182:185], v[206:209], v[42:45]
	v_mfma_f32_16x16x32_bf16 v[38:41], v[190:193], v[206:209], v[38:41]
	v_mfma_f32_16x16x32_bf16 v[26:29], v[182:185], v[220:223], v[26:29]
	v_mfma_f32_16x16x32_bf16 v[22:25], v[190:193], v[220:223], v[22:25]
	v_mfma_f32_16x16x32_bf16 v[10:13], v[182:185], v[228:231], v[10:13]
	v_mfma_f32_16x16x32_bf16 v[6:9], v[190:193], v[228:231], v[6:9]
	v_mfma_f32_16x16x32_bf16 v[58:61], v[186:189], v[202:205], v[58:61]
	v_mfma_f32_16x16x32_bf16 v[54:57], v[194:197], v[202:205], v[54:57]
	v_mfma_f32_16x16x32_bf16 v[42:45], v[186:189], v[210:213], v[42:45]
	v_mfma_f32_16x16x32_bf16 v[38:41], v[194:197], v[210:213], v[38:41]
	v_mfma_f32_16x16x32_bf16 v[26:29], v[186:189], v[224:227], v[26:29]
	v_mfma_f32_16x16x32_bf16 v[22:25], v[194:197], v[224:227], v[22:25]
	v_mfma_f32_16x16x32_bf16 v[10:13], v[186:189], v[232:235], v[10:13]
	v_mfma_f32_16x16x32_bf16 v[6:9], v[194:197], v[232:235], v[6:9]
	s_setprio 0
	s_barrier
	s_add_i32 s11, 0, 0x18000
	s_add_i32 s31, 0, 0x1c000
	v_add_u32_e32 v178, s11, v216
	v_add_u32_e32 v194, s31, v216
	ds_read_b128 v[138:141], v178
	ds_read_b128 v[142:145], v178 offset:1024
	ds_read_b128 v[146:149], v178 offset:2048
	ds_read_b128 v[178:181], v178 offset:3072
	ds_read_b128 v[182:185], v194
	ds_read_b128 v[186:189], v194 offset:1024
	ds_read_b128 v[190:193], v194 offset:2048
	ds_read_b128 v[194:197], v194 offset:3072
	v_lshl_add_u64 v[214:215], v[214:215], 0, s[12:13]
	s_mov_b32 m0, s36
	v_lshl_add_u64 v[248:249], v[214:215], 0, v[154:155]
	ds_read_b128 v[198:201], v218 offset:32768
	ds_read_b128 v[202:205], v218 offset:33792
	ds_read_b128 v[206:209], v218 offset:34816
	ds_read_b128 v[210:213], v218 offset:35840
	ds_read_b128 v[220:223], v218 offset:36864
	ds_read_b128 v[224:227], v218 offset:37888
	ds_read_b128 v[228:231], v218 offset:38912
	ds_read_b128 v[232:235], v218 offset:39936
	global_load_lds_dwordx4 v[248:249], off
	v_lshl_add_u64 v[214:215], v[214:215], 0, v[160:161]
	s_mov_b32 m0, s37
	s_nop 0
	global_load_lds_dwordx4 v[214:215], off
	s_waitcnt vmcnt(8)
	s_waitcnt lgkmcnt(0)
	s_setprio 1
	s_barrier
	v_mfma_f32_16x16x32_bf16 v[130:133], v[138:141], v[198:201], v[130:133]
	v_mfma_f32_16x16x32_bf16 v[126:129], v[146:149], v[198:201], v[126:129]
	v_mfma_f32_16x16x32_bf16 v[114:117], v[138:141], v[206:209], v[114:117]
	v_mfma_f32_16x16x32_bf16 v[110:113], v[146:149], v[206:209], v[110:113]
	v_mfma_f32_16x16x32_bf16 v[98:101], v[138:141], v[220:223], v[98:101]
	v_mfma_f32_16x16x32_bf16 v[94:97], v[146:149], v[220:223], v[94:97]
	v_mfma_f32_16x16x32_bf16 v[82:85], v[138:141], v[228:231], v[82:85]
	v_mfma_f32_16x16x32_bf16 v[78:81], v[146:149], v[228:231], v[78:81]
	v_mfma_f32_16x16x32_bf16 v[130:133], v[142:145], v[202:205], v[130:133]
	v_mfma_f32_16x16x32_bf16 v[126:129], v[178:181], v[202:205], v[126:129]
	v_mfma_f32_16x16x32_bf16 v[114:117], v[142:145], v[210:213], v[114:117]
	v_mfma_f32_16x16x32_bf16 v[110:113], v[178:181], v[210:213], v[110:113]
	v_mfma_f32_16x16x32_bf16 v[98:101], v[142:145], v[224:227], v[98:101]
	v_mfma_f32_16x16x32_bf16 v[94:97], v[178:181], v[224:227], v[94:97]
	v_mfma_f32_16x16x32_bf16 v[82:85], v[142:145], v[232:235], v[82:85]
	v_mfma_f32_16x16x32_bf16 v[78:81], v[178:181], v[232:235], v[78:81]
	v_mfma_f32_16x16x32_bf16 v[122:125], v[182:185], v[198:201], v[122:125]
	v_mfma_f32_16x16x32_bf16 v[118:121], v[190:193], v[198:201], v[118:121]
	v_mfma_f32_16x16x32_bf16 v[106:109], v[182:185], v[206:209], v[106:109]
	v_mfma_f32_16x16x32_bf16 v[102:105], v[190:193], v[206:209], v[102:105]
	v_mfma_f32_16x16x32_bf16 v[90:93], v[182:185], v[220:223], v[90:93]
	v_mfma_f32_16x16x32_bf16 v[86:89], v[190:193], v[220:223], v[86:89]
	v_mfma_f32_16x16x32_bf16 v[74:77], v[182:185], v[228:231], v[74:77]
	v_mfma_f32_16x16x32_bf16 v[70:73], v[190:193], v[228:231], v[70:73]
	v_mfma_f32_16x16x32_bf16 v[122:125], v[186:189], v[202:205], v[122:125]
	v_mfma_f32_16x16x32_bf16 v[118:121], v[194:197], v[202:205], v[118:121]
	v_mfma_f32_16x16x32_bf16 v[106:109], v[186:189], v[210:213], v[106:109]
	v_mfma_f32_16x16x32_bf16 v[102:105], v[194:197], v[210:213], v[102:105]
	v_mfma_f32_16x16x32_bf16 v[90:93], v[186:189], v[224:227], v[90:93]
	v_mfma_f32_16x16x32_bf16 v[86:89], v[194:197], v[224:227], v[86:89]
	v_mfma_f32_16x16x32_bf16 v[74:77], v[186:189], v[232:235], v[74:77]
	v_mfma_f32_16x16x32_bf16 v[70:73], v[194:197], v[232:235], v[70:73]
	s_setprio 0
	s_barrier
; #define PG8_STAGE(bufoff, gbase, voff) do { _Pragma("unroll") for (int _i = 0; _i < 2; ++_i) \
;         __builtin_amdgcn_global_load_lds((const unsigned*)((const char*)(gbase) + (voff)[_i]), (PG8_LAS unsigned*)(lds + (bufoff) + ldsw + _i * 8192), 16, 0, 0); } while (0)
; #define PG8_LDA(dst, b, h) do { _Pragma("unroll") for (int m = 0; m < 4; ++m) _Pragma("unroll") for (int k = 0; k < 2; ++k) dst[m][k] = *(const PG8_LAS bf16x8*)(lds + PG8_SA(b, h) + aoff + m * 2048 + k * 1024); } while (0)
; #define PG8_MMA(ai, bj, At, Bt) do { __builtin_amdgcn_s_setprio(1); _Pragma("unroll") for (int m = 0; m < 4; ++m) _Pragma("unroll") for (int n = 0; n < 2; ++n) _Pragma("unroll") for (int k = 0; k < 2; ++k) \
;         acc[ai][bj][m][n] = __builtin_amdgcn_mfma_f32_16x16x32_bf16(Bt[n][k], At[m][k], acc[ai][bj][m][n], 0, 0, 0); __builtin_amdgcn_s_setprio(0); } while (0)
; #define PG8_WAIT_V(n) asm volatile("s_waitcnt vmcnt(" #n ")" ::: "memory")
; #define PG8_WAIT_L(n) asm volatile("s_waitcnt lgkmcnt(" #n ")" ::: "memory")
; #define PG8_BAR __builtin_amdgcn_s_barrier()
; #define PG8_SCHED __builtin_amdgcn_sched_barrier(0)
; template <class Epi, class Sched, bool ALIGN_EPI = false, bool SP2 = false>
; __device__ __forceinline__ void gemm_phase(PG8_LAS unsigned char* lds, const Gemm g, const Sched& S, const Epi& E) {
;     ...
;             PG8_LDA(At, 1, 1); PG8_STAGE(PG8_SB(1, 0), b3, voffB); PG8_STAGE(PG8_SB(1, 1), b3 + hstep, voffB); PG8_STAGE(PG8_SA(1, 0), a3, voffA);
;             PG8_WAIT_V(8); PG8_WAIT_L(0); PG8_BAR; PG8_MMA(1, 0, At, B0); PG8_MMA(1, 1, At, B1); PG8_BAR; PG8_SCHED;
	s_add_i32 s11, s11, s29
	v_lshl_add_u64 v[214:215], v[238:239], 0, s[20:21]
	s_mov_b32 m0, s11
	ds_read_b128 v[198:201], v218 offset:49152
	ds_read_b128 v[202:205], v218 offset:50176
	ds_read_b128 v[206:209], v218 offset:51200
	ds_read_b128 v[210:213], v218 offset:52224
	ds_read_b128 v[220:223], v218 offset:53248
	ds_read_b128 v[224:227], v218 offset:54272
	ds_read_b128 v[228:231], v218 offset:55296
	ds_read_b128 v[232:235], v218 offset:56320
	global_load_lds_dwordx4 v[214:215], off
	v_lshl_add_u64 v[214:215], v[240:241], 0, s[20:21]
	s_add_i32 m0, s11, 0x2000
	s_add_i32 s11, s31, s29
	global_load_lds_dwordx4 v[214:215], off
	v_lshl_add_u64 v[214:215], v[242:243], 0, s[20:21]
	s_mov_b32 m0, s11
	s_nop 0
	global_load_lds_dwordx4 v[214:215], off
	v_lshl_add_u64 v[214:215], v[236:237], 0, s[20:21]
	s_add_i32 m0, s11, 0x2000
	s_nop 0
	global_load_lds_dwordx4 v[214:215], off
	v_lshl_add_u64 v[214:215], v[244:245], 0, s[20:21]
	s_mov_b32 m0, s41
	s_nop 0
	global_load_lds_dwordx4 v[214:215], off
	v_lshl_add_u64 v[214:215], v[246:247], 0, s[20:21]
	s_mov_b32 m0, s44
	s_nop 0
	global_load_lds_dwordx4 v[214:215], off
	s_waitcnt vmcnt(8)
	s_waitcnt lgkmcnt(0)
	s_setprio 1
	s_barrier
	v_mfma_f32_16x16x32_bf16 v[66:69], v[138:141], v[198:201], v[66:69]
	v_mfma_f32_16x16x32_bf16 v[62:65], v[146:149], v[198:201], v[62:65]
	v_mfma_f32_16x16x32_bf16 v[50:53], v[138:141], v[206:209], v[50:53]
	v_mfma_f32_16x16x32_bf16 v[46:49], v[146:149], v[206:209], v[46:49]
	v_mfma_f32_16x16x32_bf16 v[34:37], v[138:141], v[220:223], v[34:37]
	v_mfma_f32_16x16x32_bf16 v[30:33], v[146:149], v[220:223], v[30:33]
	v_mfma_f32_16x16x32_bf16 v[18:21], v[138:141], v[228:231], v[18:21]
	v_mfma_f32_16x16x32_bf16 v[14:17], v[146:149], v[228:231], v[14:17]
	v_mfma_f32_16x16x32_bf16 v[66:69], v[142:145], v[202:205], v[66:69]
	v_mfma_f32_16x16x32_bf16 v[62:65], v[178:181], v[202:205], v[62:65]
	v_mfma_f32_16x16x32_bf16 v[50:53], v[142:145], v[210:213], v[50:53]
	v_mfma_f32_16x16x32_bf16 v[46:49], v[178:181], v[210:213], v[46:49]
	v_mfma_f32_16x16x32_bf16 v[34:37], v[142:145], v[224:227], v[34:37]
	v_mfma_f32_16x16x32_bf16 v[30:33], v[178:181], v[224:227], v[30:33]
	v_mfma_f32_16x16x32_bf16 v[18:21], v[142:145], v[232:235], v[18:21]
	v_mfma_f32_16x16x32_bf16 v[14:17], v[178:181], v[232:235], v[14:17]
	v_mfma_f32_16x16x32_bf16 v[58:61], v[182:185], v[198:201], v[58:61]
	v_mfma_f32_16x16x32_bf16 v[54:57], v[190:193], v[198:201], v[54:57]
	v_mfma_f32_16x16x32_bf16 v[42:45], v[182:185], v[206:209], v[42:45]
	v_mfma_f32_16x16x32_bf16 v[38:41], v[190:193], v[206:209], v[38:41]
	v_mfma_f32_16x16x32_bf16 v[26:29], v[182:185], v[220:223], v[26:29]
	v_mfma_f32_16x16x32_bf16 v[22:25], v[190:193], v[220:223], v[22:25]
	v_mfma_f32_16x16x32_bf16 v[10:13], v[182:185], v[228:231], v[10:13]
	v_mfma_f32_16x16x32_bf16 v[6:9], v[190:193], v[228:231], v[6:9]
	v_mfma_f32_16x16x32_bf16 v[58:61], v[186:189], v[202:205], v[58:61]
	v_mfma_f32_16x16x32_bf16 v[54:57], v[194:197], v[202:205], v[54:57]
	v_mfma_f32_16x16x32_bf16 v[42:45], v[186:189], v[210:213], v[42:45]
	v_mfma_f32_16x16x32_bf16 v[38:41], v[194:197], v[210:213], v[38:41]
	v_mfma_f32_16x16x32_bf16 v[26:29], v[186:189], v[224:227], v[26:29]
	v_mfma_f32_16x16x32_bf16 v[22:25], v[194:197], v[224:227], v[22:25]
	v_mfma_f32_16x16x32_bf16 v[10:13], v[186:189], v[232:235], v[10:13]
	v_mfma_f32_16x16x32_bf16 v[6:9], v[194:197], v[232:235], v[6:9]
	s_setprio 0
	s_barrier
	v_lshl_add_u64 v[134:135], v[134:135], 0, s[26:27]
	s_cmp_ge_i32 s10, s46
	v_lshl_add_u64 v[136:137], v[136:137], 0, s[26:27]
	s_cbranch_scc0 .LBB0_1947
